# mLSTM/HGRN2 step sections: LDS reads for step t+2 issued as soon as their registers are consumed inside step t (longer lead)
# baseline (speedup 1.0000x reference)
.LBB0_1156:
	s_or_b64 exec, exec, s[8:9]
	s_waitcnt lgkmcnt(0)
	s_barrier
	v_mov_b32_e32 v196, v88
	v_mov_b32_e32 v197, v89
	v_mov_b32_e32 v198, v90
	v_mov_b32_e32 v199, v100
	v_mov_b32_e32 v200, v91
	v_mov_b32_e32 v201, v101
	v_mov_b32_e32 v202, v102
	v_mov_b32_e32 v203, v104
	v_mov_b32_e32 v204, v103
	v_mov_b32_e32 v205, v105
	v_mov_b32_e32 v206, v106
	v_mov_b32_e32 v207, v109
	v_mov_b32_e32 v208, v107
	v_mov_b32_e32 v209, v110
	v_mov_b32_e32 v210, v108
	v_mov_b32_e32 v211, v111
	v_mov_b32_e32 v214, 0
	v_mov_b32_e32 v215, 0
	ds_read_b128 v[80:83], v194 offset:8192
	ds_read_b128 v[84:87], v194 offset:8448
	ds_read_b128 v[88:91], v194 offset:8704
	ds_read_b128 v[92:95], v194 offset:8960
	ds_read_b32 v134, v140 offset:35136
	ds_read_b32 v135, v190 offset:16384
	ds_read_b32 v132, v140 offset:35072
	ds_read_b128 v[64:67], v194
	ds_read_b128 v[68:71], v194 offset:256
	ds_read_b128 v[72:75], v194 offset:512
	ds_read_b128 v[76:79], v194 offset:768
	ds_read_b128 v[112:115], v194 offset:9216
	ds_read_b128 v[116:119], v194 offset:9472
	ds_read_b128 v[120:123], v194 offset:9728
	ds_read_b128 v[124:127], v194 offset:9984
	ds_read_b32 v156, v140 offset:35140
	ds_read_b32 v157, v190 offset:16448
	ds_read_b32 v154, v140 offset:35076
	ds_read_b128 v[96:99], v194 offset:1024
	ds_read_b128 v[100:103], v194 offset:1280
	ds_read_b128 v[104:107], v194 offset:1536
	ds_read_b128 v[108:111], v194 offset:1792
	s_waitcnt lgkmcnt(15)
	v_mul_f32_e32 v133, v134, v135
	v_pk_mul_f32 v[80:81], v[80:81], v[132:133] op_sel:[0,1] op_sel_hi:[1,1]
	v_pk_mul_f32 v[82:83], v[82:83], v[132:133] op_sel:[0,1] op_sel_hi:[1,1]
	v_pk_mul_f32 v[84:85], v[84:85], v[132:133] op_sel:[0,1] op_sel_hi:[1,1]
	v_pk_mul_f32 v[86:87], v[86:87], v[132:133] op_sel:[0,1] op_sel_hi:[1,1]
	v_pk_mul_f32 v[88:89], v[88:89], v[132:133] op_sel:[0,1] op_sel_hi:[1,1]
	v_pk_mul_f32 v[90:91], v[90:91], v[132:133] op_sel:[0,1] op_sel_hi:[1,1]
	v_pk_mul_f32 v[92:93], v[92:93], v[132:133] op_sel:[0,1] op_sel_hi:[1,1]
	v_pk_mul_f32 v[94:95], v[94:95], v[132:133] op_sel:[0,1] op_sel_hi:[1,1]
	v_pk_fma_f32 v[196:197], v[132:133], v[196:197], v[80:81] op_sel_hi:[0,1,1]
	v_pk_fma_f32 v[198:199], v[132:133], v[198:199], v[82:83] op_sel_hi:[0,1,1]
	v_pk_fma_f32 v[200:201], v[132:133], v[200:201], v[84:85] op_sel_hi:[0,1,1]
	v_pk_fma_f32 v[202:203], v[132:133], v[202:203], v[86:87] op_sel_hi:[0,1,1]
	v_pk_fma_f32 v[204:205], v[132:133], v[204:205], v[88:89] op_sel_hi:[0,1,1]
	v_pk_fma_f32 v[206:207], v[132:133], v[206:207], v[90:91] op_sel_hi:[0,1,1]
	v_pk_fma_f32 v[208:209], v[132:133], v[208:209], v[92:93] op_sel_hi:[0,1,1]
	v_pk_fma_f32 v[210:211], v[132:133], v[210:211], v[94:95] op_sel_hi:[0,1,1]
	ds_read_b128 v[80:83], v194 offset:10240
	ds_read_b128 v[84:87], v194 offset:10496
	ds_read_b128 v[88:91], v194 offset:10752
	ds_read_b128 v[92:95], v194 offset:11008
	ds_read_b32 v134, v140 offset:35144
	ds_read_b32 v135, v190 offset:16512
	ds_read_b32 v132, v140 offset:35080
	s_waitcnt lgkmcnt(15)
	v_pk_fma_f32 v[128:129], v[64:65], v[196:197], v[214:215]
	v_pk_fma_f32 v[130:131], v[66:67], v[198:199], v[214:215]
	ds_read_b128 v[64:67], v194 offset:2048
	s_waitcnt lgkmcnt(15)
	v_pk_fma_f32 v[128:129], v[68:69], v[200:201], v[128:129]
	v_pk_fma_f32 v[130:131], v[70:71], v[202:203], v[130:131]
	ds_read_b128 v[68:71], v194 offset:2304
	s_waitcnt lgkmcnt(15)
	v_pk_fma_f32 v[128:129], v[72:73], v[204:205], v[128:129]
	v_pk_fma_f32 v[130:131], v[74:75], v[206:207], v[130:131]
	ds_read_b128 v[72:75], v194 offset:2560
	s_waitcnt lgkmcnt(15)
	v_pk_fma_f32 v[128:129], v[76:77], v[208:209], v[128:129]
	v_pk_fma_f32 v[130:131], v[78:79], v[210:211], v[130:131]
	ds_read_b128 v[76:79], v194 offset:2816
	v_add_f32_e32 v128, v128, v129
	v_add_f32_e32 v130, v130, v131
	v_add_f32_e32 v212, v128, v130
	s_waitcnt lgkmcnt(15)
	v_mul_f32_e32 v155, v156, v157
	v_pk_mul_f32 v[112:113], v[112:113], v[154:155] op_sel:[0,1] op_sel_hi:[1,1]
	v_add_f32_dpp v212, v212, v212 row_ror:8 row_mask:0xf bank_mask:0xf bound_ctrl:1
	v_pk_mul_f32 v[114:115], v[114:115], v[154:155] op_sel:[0,1] op_sel_hi:[1,1]
	v_pk_mul_f32 v[116:117], v[116:117], v[154:155] op_sel:[0,1] op_sel_hi:[1,1]
	v_add_f32_dpp v212, v212, v212 row_ror:4 row_mask:0xf bank_mask:0xf bound_ctrl:1
	v_pk_mul_f32 v[118:119], v[118:119], v[154:155] op_sel:[0,1] op_sel_hi:[1,1]
	v_pk_mul_f32 v[120:121], v[120:121], v[154:155] op_sel:[0,1] op_sel_hi:[1,1]
	v_add_f32_dpp v212, v212, v212 row_ror:2 row_mask:0xf bank_mask:0xf bound_ctrl:1
	v_pk_mul_f32 v[122:123], v[122:123], v[154:155] op_sel:[0,1] op_sel_hi:[1,1]
	v_pk_mul_f32 v[124:125], v[124:125], v[154:155] op_sel:[0,1] op_sel_hi:[1,1]
	v_add_f32_dpp v212, v212, v212 row_ror:1 row_mask:0xf bank_mask:0xf bound_ctrl:1
	v_pk_mul_f32 v[126:127], v[126:127], v[154:155] op_sel:[0,1] op_sel_hi:[1,1]
	v_pk_fma_f32 v[196:197], v[154:155], v[196:197], v[112:113] op_sel_hi:[0,1,1]
	s_and_saveexec_b64 s[8:9], s[44:45]
	ds_write_b32 v190, v212 offset:34048
	s_mov_b64 exec, s[8:9]
	v_pk_fma_f32 v[198:199], v[154:155], v[198:199], v[114:115] op_sel_hi:[0,1,1]
	v_pk_fma_f32 v[200:201], v[154:155], v[200:201], v[116:117] op_sel_hi:[0,1,1]
	v_pk_fma_f32 v[202:203], v[154:155], v[202:203], v[118:119] op_sel_hi:[0,1,1]
	v_pk_fma_f32 v[204:205], v[154:155], v[204:205], v[120:121] op_sel_hi:[0,1,1]
	v_pk_fma_f32 v[206:207], v[154:155], v[206:207], v[122:123] op_sel_hi:[0,1,1]
	v_pk_fma_f32 v[208:209], v[154:155], v[208:209], v[124:125] op_sel_hi:[0,1,1]
	v_pk_fma_f32 v[210:211], v[154:155], v[210:211], v[126:127] op_sel_hi:[0,1,1]
	ds_read_b128 v[112:115], v194 offset:11264
	ds_read_b128 v[116:119], v194 offset:11520
	ds_read_b128 v[120:123], v194 offset:11776
	ds_read_b128 v[124:127], v194 offset:12032
	ds_read_b32 v156, v140 offset:35148
	ds_read_b32 v157, v190 offset:16576
	ds_read_b32 v154, v140 offset:35084
	s_waitcnt lgkmcnt(15)
	v_pk_fma_f32 v[128:129], v[96:97], v[196:197], v[214:215]
	v_pk_fma_f32 v[130:131], v[98:99], v[198:199], v[214:215]
	ds_read_b128 v[96:99], v194 offset:3072
	s_waitcnt lgkmcnt(15)
	v_pk_fma_f32 v[128:129], v[100:101], v[200:201], v[128:129]
	v_pk_fma_f32 v[130:131], v[102:103], v[202:203], v[130:131]
	ds_read_b128 v[100:103], v194 offset:3328
	s_waitcnt lgkmcnt(15)
	v_pk_fma_f32 v[128:129], v[104:105], v[204:205], v[128:129]
	v_pk_fma_f32 v[130:131], v[106:107], v[206:207], v[130:131]
	ds_read_b128 v[104:107], v194 offset:3584
	s_waitcnt lgkmcnt(15)
	v_pk_fma_f32 v[128:129], v[108:109], v[208:209], v[128:129]
	v_pk_fma_f32 v[130:131], v[110:111], v[210:211], v[130:131]
	ds_read_b128 v[108:111], v194 offset:3840
	v_add_f32_e32 v128, v128, v129
	v_add_f32_e32 v130, v130, v131
	v_add_f32_e32 v213, v128, v130
	s_waitcnt lgkmcnt(15)
	v_mul_f32_e32 v133, v134, v135
	v_pk_mul_f32 v[80:81], v[80:81], v[132:133] op_sel:[0,1] op_sel_hi:[1,1]
	v_add_f32_dpp v213, v213, v213 row_ror:8 row_mask:0xf bank_mask:0xf bound_ctrl:1
	v_pk_mul_f32 v[82:83], v[82:83], v[132:133] op_sel:[0,1] op_sel_hi:[1,1]
	v_pk_mul_f32 v[84:85], v[84:85], v[132:133] op_sel:[0,1] op_sel_hi:[1,1]
	v_add_f32_dpp v213, v213, v213 row_ror:4 row_mask:0xf bank_mask:0xf bound_ctrl:1
	v_pk_mul_f32 v[86:87], v[86:87], v[132:133] op_sel:[0,1] op_sel_hi:[1,1]
	v_pk_mul_f32 v[88:89], v[88:89], v[132:133] op_sel:[0,1] op_sel_hi:[1,1]
	v_add_f32_dpp v213, v213, v213 row_ror:2 row_mask:0xf bank_mask:0xf bound_ctrl:1
	v_pk_mul_f32 v[90:91], v[90:91], v[132:133] op_sel:[0,1] op_sel_hi:[1,1]
	v_pk_mul_f32 v[92:93], v[92:93], v[132:133] op_sel:[0,1] op_sel_hi:[1,1]
	v_add_f32_dpp v213, v213, v213 row_ror:1 row_mask:0xf bank_mask:0xf bound_ctrl:1
	v_pk_mul_f32 v[94:95], v[94:95], v[132:133] op_sel:[0,1] op_sel_hi:[1,1]
	v_pk_fma_f32 v[196:197], v[132:133], v[196:197], v[80:81] op_sel_hi:[0,1,1]
	s_and_saveexec_b64 s[8:9], s[44:45]
	ds_write_b32 v190, v213 offset:34112
	s_mov_b64 exec, s[8:9]
	v_pk_fma_f32 v[198:199], v[132:133], v[198:199], v[82:83] op_sel_hi:[0,1,1]
	v_pk_fma_f32 v[200:201], v[132:133], v[200:201], v[84:85] op_sel_hi:[0,1,1]
	v_pk_fma_f32 v[202:203], v[132:133], v[202:203], v[86:87] op_sel_hi:[0,1,1]
	v_pk_fma_f32 v[204:205], v[132:133], v[204:205], v[88:89] op_sel_hi:[0,1,1]
	v_pk_fma_f32 v[206:207], v[132:133], v[206:207], v[90:91] op_sel_hi:[0,1,1]
	v_pk_fma_f32 v[208:209], v[132:133], v[208:209], v[92:93] op_sel_hi:[0,1,1]
	v_pk_fma_f32 v[210:211], v[132:133], v[210:211], v[94:95] op_sel_hi:[0,1,1]
	ds_read_b128 v[80:83], v194 offset:12288
	ds_read_b128 v[84:87], v194 offset:12544
	ds_read_b128 v[88:91], v194 offset:12800
	ds_read_b128 v[92:95], v194 offset:13056
	ds_read_b32 v134, v140 offset:35152
	ds_read_b32 v135, v190 offset:16640
	ds_read_b32 v132, v140 offset:35088
	s_waitcnt lgkmcnt(15)
	v_pk_fma_f32 v[128:129], v[64:65], v[196:197], v[214:215]
	v_pk_fma_f32 v[130:131], v[66:67], v[198:199], v[214:215]
	ds_read_b128 v[64:67], v194 offset:4096
	s_waitcnt lgkmcnt(15)
	v_pk_fma_f32 v[128:129], v[68:69], v[200:201], v[128:129]
	v_pk_fma_f32 v[130:131], v[70:71], v[202:203], v[130:131]
	ds_read_b128 v[68:71], v194 offset:4352
	s_waitcnt lgkmcnt(15)
	v_pk_fma_f32 v[128:129], v[72:73], v[204:205], v[128:129]
	v_pk_fma_f32 v[130:131], v[74:75], v[206:207], v[130:131]
	ds_read_b128 v[72:75], v194 offset:4608
	s_waitcnt lgkmcnt(15)
	v_pk_fma_f32 v[128:129], v[76:77], v[208:209], v[128:129]
	v_pk_fma_f32 v[130:131], v[78:79], v[210:211], v[130:131]
	ds_read_b128 v[76:79], v194 offset:4864
	v_add_f32_e32 v128, v128, v129
	v_add_f32_e32 v130, v130, v131
	v_add_f32_e32 v212, v128, v130
	s_waitcnt lgkmcnt(15)
	v_mul_f32_e32 v155, v156, v157
	v_pk_mul_f32 v[112:113], v[112:113], v[154:155] op_sel:[0,1] op_sel_hi:[1,1]
	v_add_f32_dpp v212, v212, v212 row_ror:8 row_mask:0xf bank_mask:0xf bound_ctrl:1
	v_pk_mul_f32 v[114:115], v[114:115], v[154:155] op_sel:[0,1] op_sel_hi:[1,1]
	v_pk_mul_f32 v[116:117], v[116:117], v[154:155] op_sel:[0,1] op_sel_hi:[1,1]
	v_add_f32_dpp v212, v212, v212 row_ror:4 row_mask:0xf bank_mask:0xf bound_ctrl:1
	v_pk_mul_f32 v[118:119], v[118:119], v[154:155] op_sel:[0,1] op_sel_hi:[1,1]
	v_pk_mul_f32 v[120:121], v[120:121], v[154:155] op_sel:[0,1] op_sel_hi:[1,1]
	v_add_f32_dpp v212, v212, v212 row_ror:2 row_mask:0xf bank_mask:0xf bound_ctrl:1
	v_pk_mul_f32 v[122:123], v[122:123], v[154:155] op_sel:[0,1] op_sel_hi:[1,1]
	v_pk_mul_f32 v[124:125], v[124:125], v[154:155] op_sel:[0,1] op_sel_hi:[1,1]
	v_add_f32_dpp v212, v212, v212 row_ror:1 row_mask:0xf bank_mask:0xf bound_ctrl:1
	v_pk_mul_f32 v[126:127], v[126:127], v[154:155] op_sel:[0,1] op_sel_hi:[1,1]
	v_pk_fma_f32 v[196:197], v[154:155], v[196:197], v[112:113] op_sel_hi:[0,1,1]
	s_and_saveexec_b64 s[8:9], s[44:45]
	ds_write_b32 v190, v212 offset:34176
	s_mov_b64 exec, s[8:9]
	v_pk_fma_f32 v[198:199], v[154:155], v[198:199], v[114:115] op_sel_hi:[0,1,1]
	v_pk_fma_f32 v[200:201], v[154:155], v[200:201], v[116:117] op_sel_hi:[0,1,1]
	v_pk_fma_f32 v[202:203], v[154:155], v[202:203], v[118:119] op_sel_hi:[0,1,1]
	v_pk_fma_f32 v[204:205], v[154:155], v[204:205], v[120:121] op_sel_hi:[0,1,1]
	v_pk_fma_f32 v[206:207], v[154:155], v[206:207], v[122:123] op_sel_hi:[0,1,1]
	v_pk_fma_f32 v[208:209], v[154:155], v[208:209], v[124:125] op_sel_hi:[0,1,1]
	v_pk_fma_f32 v[210:211], v[154:155], v[210:211], v[126:127] op_sel_hi:[0,1,1]
	ds_read_b128 v[112:115], v194 offset:13312
	ds_read_b128 v[116:119], v194 offset:13568
	ds_read_b128 v[120:123], v194 offset:13824
	ds_read_b128 v[124:127], v194 offset:14080
	ds_read_b32 v156, v140 offset:35156
	ds_read_b32 v157, v190 offset:16704
	ds_read_b32 v154, v140 offset:35092
	s_waitcnt lgkmcnt(15)
	v_pk_fma_f32 v[128:129], v[96:97], v[196:197], v[214:215]
	v_pk_fma_f32 v[130:131], v[98:99], v[198:199], v[214:215]
	ds_read_b128 v[96:99], v194 offset:5120
	s_waitcnt lgkmcnt(15)
	v_pk_fma_f32 v[128:129], v[100:101], v[200:201], v[128:129]
	v_pk_fma_f32 v[130:131], v[102:103], v[202:203], v[130:131]
	ds_read_b128 v[100:103], v194 offset:5376
	s_waitcnt lgkmcnt(15)
	v_pk_fma_f32 v[128:129], v[104:105], v[204:205], v[128:129]
	v_pk_fma_f32 v[130:131], v[106:107], v[206:207], v[130:131]
	ds_read_b128 v[104:107], v194 offset:5632
	s_waitcnt lgkmcnt(15)
	v_pk_fma_f32 v[128:129], v[108:109], v[208:209], v[128:129]
	v_pk_fma_f32 v[130:131], v[110:111], v[210:211], v[130:131]
	ds_read_b128 v[108:111], v194 offset:5888
	v_add_f32_e32 v128, v128, v129
	v_add_f32_e32 v130, v130, v131
	v_add_f32_e32 v213, v128, v130
	s_waitcnt lgkmcnt(15)
	v_mul_f32_e32 v133, v134, v135
	v_pk_mul_f32 v[80:81], v[80:81], v[132:133] op_sel:[0,1] op_sel_hi:[1,1]
	v_add_f32_dpp v213, v213, v213 row_ror:8 row_mask:0xf bank_mask:0xf bound_ctrl:1
	v_pk_mul_f32 v[82:83], v[82:83], v[132:133] op_sel:[0,1] op_sel_hi:[1,1]
	v_pk_mul_f32 v[84:85], v[84:85], v[132:133] op_sel:[0,1] op_sel_hi:[1,1]
	v_add_f32_dpp v213, v213, v213 row_ror:4 row_mask:0xf bank_mask:0xf bound_ctrl:1
	v_pk_mul_f32 v[86:87], v[86:87], v[132:133] op_sel:[0,1] op_sel_hi:[1,1]
	v_pk_mul_f32 v[88:89], v[88:89], v[132:133] op_sel:[0,1] op_sel_hi:[1,1]
	v_add_f32_dpp v213, v213, v213 row_ror:2 row_mask:0xf bank_mask:0xf bound_ctrl:1
	v_pk_mul_f32 v[90:91], v[90:91], v[132:133] op_sel:[0,1] op_sel_hi:[1,1]
	v_pk_mul_f32 v[92:93], v[92:93], v[132:133] op_sel:[0,1] op_sel_hi:[1,1]
	v_add_f32_dpp v213, v213, v213 row_ror:1 row_mask:0xf bank_mask:0xf bound_ctrl:1
	v_pk_mul_f32 v[94:95], v[94:95], v[132:133] op_sel:[0,1] op_sel_hi:[1,1]
	v_pk_fma_f32 v[196:197], v[132:133], v[196:197], v[80:81] op_sel_hi:[0,1,1]
	s_and_saveexec_b64 s[8:9], s[44:45]
	ds_write_b32 v190, v213 offset:34240
	s_mov_b64 exec, s[8:9]
	v_pk_fma_f32 v[198:199], v[132:133], v[198:199], v[82:83] op_sel_hi:[0,1,1]
	v_pk_fma_f32 v[200:201], v[132:133], v[200:201], v[84:85] op_sel_hi:[0,1,1]
	v_pk_fma_f32 v[202:203], v[132:133], v[202:203], v[86:87] op_sel_hi:[0,1,1]
	v_pk_fma_f32 v[204:205], v[132:133], v[204:205], v[88:89] op_sel_hi:[0,1,1]
	v_pk_fma_f32 v[206:207], v[132:133], v[206:207], v[90:91] op_sel_hi:[0,1,1]
	v_pk_fma_f32 v[208:209], v[132:133], v[208:209], v[92:93] op_sel_hi:[0,1,1]
	v_pk_fma_f32 v[210:211], v[132:133], v[210:211], v[94:95] op_sel_hi:[0,1,1]
	ds_read_b128 v[80:83], v194 offset:14336
	ds_read_b128 v[84:87], v194 offset:14592
	ds_read_b128 v[88:91], v194 offset:14848
	ds_read_b128 v[92:95], v194 offset:15104
	ds_read_b32 v134, v140 offset:35160
	ds_read_b32 v135, v190 offset:16768
	ds_read_b32 v132, v140 offset:35096
	s_waitcnt lgkmcnt(15)
	v_pk_fma_f32 v[128:129], v[64:65], v[196:197], v[214:215]
	v_pk_fma_f32 v[130:131], v[66:67], v[198:199], v[214:215]
	ds_read_b128 v[64:67], v194 offset:6144
	s_waitcnt lgkmcnt(15)
	v_pk_fma_f32 v[128:129], v[68:69], v[200:201], v[128:129]
	v_pk_fma_f32 v[130:131], v[70:71], v[202:203], v[130:131]
	ds_read_b128 v[68:71], v194 offset:6400
	s_waitcnt lgkmcnt(15)
	v_pk_fma_f32 v[128:129], v[72:73], v[204:205], v[128:129]
	v_pk_fma_f32 v[130:131], v[74:75], v[206:207], v[130:131]
	ds_read_b128 v[72:75], v194 offset:6656
	s_waitcnt lgkmcnt(15)
	v_pk_fma_f32 v[128:129], v[76:77], v[208:209], v[128:129]
	v_pk_fma_f32 v[130:131], v[78:79], v[210:211], v[130:131]
	ds_read_b128 v[76:79], v194 offset:6912
	v_add_f32_e32 v128, v128, v129
	v_add_f32_e32 v130, v130, v131
	v_add_f32_e32 v212, v128, v130
	s_waitcnt lgkmcnt(15)
	v_mul_f32_e32 v155, v156, v157
	v_pk_mul_f32 v[112:113], v[112:113], v[154:155] op_sel:[0,1] op_sel_hi:[1,1]
	v_add_f32_dpp v212, v212, v212 row_ror:8 row_mask:0xf bank_mask:0xf bound_ctrl:1
	v_pk_mul_f32 v[114:115], v[114:115], v[154:155] op_sel:[0,1] op_sel_hi:[1,1]
	v_pk_mul_f32 v[116:117], v[116:117], v[154:155] op_sel:[0,1] op_sel_hi:[1,1]
	v_add_f32_dpp v212, v212, v212 row_ror:4 row_mask:0xf bank_mask:0xf bound_ctrl:1
	v_pk_mul_f32 v[118:119], v[118:119], v[154:155] op_sel:[0,1] op_sel_hi:[1,1]
	v_pk_mul_f32 v[120:121], v[120:121], v[154:155] op_sel:[0,1] op_sel_hi:[1,1]
	v_add_f32_dpp v212, v212, v212 row_ror:2 row_mask:0xf bank_mask:0xf bound_ctrl:1
	v_pk_mul_f32 v[122:123], v[122:123], v[154:155] op_sel:[0,1] op_sel_hi:[1,1]
	v_pk_mul_f32 v[124:125], v[124:125], v[154:155] op_sel:[0,1] op_sel_hi:[1,1]
	v_add_f32_dpp v212, v212, v212 row_ror:1 row_mask:0xf bank_mask:0xf bound_ctrl:1
	v_pk_mul_f32 v[126:127], v[126:127], v[154:155] op_sel:[0,1] op_sel_hi:[1,1]
	v_pk_fma_f32 v[196:197], v[154:155], v[196:197], v[112:113] op_sel_hi:[0,1,1]
	s_and_saveexec_b64 s[8:9], s[44:45]
	ds_write_b32 v190, v212 offset:34304
	s_mov_b64 exec, s[8:9]
	v_pk_fma_f32 v[198:199], v[154:155], v[198:199], v[114:115] op_sel_hi:[0,1,1]
	v_pk_fma_f32 v[200:201], v[154:155], v[200:201], v[116:117] op_sel_hi:[0,1,1]
	v_pk_fma_f32 v[202:203], v[154:155], v[202:203], v[118:119] op_sel_hi:[0,1,1]
	v_pk_fma_f32 v[204:205], v[154:155], v[204:205], v[120:121] op_sel_hi:[0,1,1]
	v_pk_fma_f32 v[206:207], v[154:155], v[206:207], v[122:123] op_sel_hi:[0,1,1]
	v_pk_fma_f32 v[208:209], v[154:155], v[208:209], v[124:125] op_sel_hi:[0,1,1]
	v_pk_fma_f32 v[210:211], v[154:155], v[210:211], v[126:127] op_sel_hi:[0,1,1]
	ds_read_b128 v[112:115], v194 offset:15360
	ds_read_b128 v[116:119], v194 offset:15616
	ds_read_b128 v[120:123], v194 offset:15872
	ds_read_b128 v[124:127], v194 offset:16128
	ds_read_b32 v156, v140 offset:35164
	ds_read_b32 v157, v190 offset:16832
	ds_read_b32 v154, v140 offset:35100
	s_waitcnt lgkmcnt(15)
	v_pk_fma_f32 v[128:129], v[96:97], v[196:197], v[214:215]
	v_pk_fma_f32 v[130:131], v[98:99], v[198:199], v[214:215]
	ds_read_b128 v[96:99], v194 offset:7168
	s_waitcnt lgkmcnt(15)
	v_pk_fma_f32 v[128:129], v[100:101], v[200:201], v[128:129]
	v_pk_fma_f32 v[130:131], v[102:103], v[202:203], v[130:131]
	ds_read_b128 v[100:103], v194 offset:7424
	s_waitcnt lgkmcnt(15)
	v_pk_fma_f32 v[128:129], v[104:105], v[204:205], v[128:129]
	v_pk_fma_f32 v[130:131], v[106:107], v[206:207], v[130:131]
	ds_read_b128 v[104:107], v194 offset:7680
	s_waitcnt lgkmcnt(15)
	v_pk_fma_f32 v[128:129], v[108:109], v[208:209], v[128:129]
	v_pk_fma_f32 v[130:131], v[110:111], v[210:211], v[130:131]
	ds_read_b128 v[108:111], v194 offset:7936
	v_add_f32_e32 v128, v128, v129
	v_add_f32_e32 v130, v130, v131
	v_add_f32_e32 v213, v128, v130
	s_waitcnt lgkmcnt(15)
	v_mul_f32_e32 v133, v134, v135
	v_pk_mul_f32 v[80:81], v[80:81], v[132:133] op_sel:[0,1] op_sel_hi:[1,1]
	v_add_f32_dpp v213, v213, v213 row_ror:8 row_mask:0xf bank_mask:0xf bound_ctrl:1
	v_pk_mul_f32 v[82:83], v[82:83], v[132:133] op_sel:[0,1] op_sel_hi:[1,1]
	v_pk_mul_f32 v[84:85], v[84:85], v[132:133] op_sel:[0,1] op_sel_hi:[1,1]
	v_add_f32_dpp v213, v213, v213 row_ror:4 row_mask:0xf bank_mask:0xf bound_ctrl:1
	v_pk_mul_f32 v[86:87], v[86:87], v[132:133] op_sel:[0,1] op_sel_hi:[1,1]
	v_pk_mul_f32 v[88:89], v[88:89], v[132:133] op_sel:[0,1] op_sel_hi:[1,1]
	v_add_f32_dpp v213, v213, v213 row_ror:2 row_mask:0xf bank_mask:0xf bound_ctrl:1
	v_pk_mul_f32 v[90:91], v[90:91], v[132:133] op_sel:[0,1] op_sel_hi:[1,1]
	v_pk_mul_f32 v[92:93], v[92:93], v[132:133] op_sel:[0,1] op_sel_hi:[1,1]
	v_add_f32_dpp v213, v213, v213 row_ror:1 row_mask:0xf bank_mask:0xf bound_ctrl:1
	v_pk_mul_f32 v[94:95], v[94:95], v[132:133] op_sel:[0,1] op_sel_hi:[1,1]
	v_pk_fma_f32 v[196:197], v[132:133], v[196:197], v[80:81] op_sel_hi:[0,1,1]
	s_and_saveexec_b64 s[8:9], s[44:45]
	ds_write_b32 v190, v213 offset:34368
	s_mov_b64 exec, s[8:9]
	v_pk_fma_f32 v[198:199], v[132:133], v[198:199], v[82:83] op_sel_hi:[0,1,1]
	v_pk_fma_f32 v[200:201], v[132:133], v[200:201], v[84:85] op_sel_hi:[0,1,1]
	v_pk_fma_f32 v[202:203], v[132:133], v[202:203], v[86:87] op_sel_hi:[0,1,1]
	v_pk_fma_f32 v[204:205], v[132:133], v[204:205], v[88:89] op_sel_hi:[0,1,1]
	v_pk_fma_f32 v[206:207], v[132:133], v[206:207], v[90:91] op_sel_hi:[0,1,1]
	v_pk_fma_f32 v[208:209], v[132:133], v[208:209], v[92:93] op_sel_hi:[0,1,1]
	v_pk_fma_f32 v[210:211], v[132:133], v[210:211], v[94:95] op_sel_hi:[0,1,1]
	s_waitcnt lgkmcnt(15)
	v_pk_fma_f32 v[128:129], v[64:65], v[196:197], v[214:215]
	v_pk_fma_f32 v[130:131], v[66:67], v[198:199], v[214:215]
	v_pk_fma_f32 v[128:129], v[68:69], v[200:201], v[128:129]
	v_pk_fma_f32 v[130:131], v[70:71], v[202:203], v[130:131]
	s_waitcnt lgkmcnt(14)
	v_pk_fma_f32 v[128:129], v[72:73], v[204:205], v[128:129]
	v_pk_fma_f32 v[130:131], v[74:75], v[206:207], v[130:131]
	s_waitcnt lgkmcnt(13)
	v_pk_fma_f32 v[128:129], v[76:77], v[208:209], v[128:129]
	v_pk_fma_f32 v[130:131], v[78:79], v[210:211], v[130:131]
	v_add_f32_e32 v128, v128, v129
	v_add_f32_e32 v130, v130, v131
	v_add_f32_e32 v212, v128, v130
	s_waitcnt lgkmcnt(6)
	v_mul_f32_e32 v155, v156, v157
	v_pk_mul_f32 v[112:113], v[112:113], v[154:155] op_sel:[0,1] op_sel_hi:[1,1]
	v_add_f32_dpp v212, v212, v212 row_ror:8 row_mask:0xf bank_mask:0xf bound_ctrl:1
	v_pk_mul_f32 v[114:115], v[114:115], v[154:155] op_sel:[0,1] op_sel_hi:[1,1]
	v_pk_mul_f32 v[116:117], v[116:117], v[154:155] op_sel:[0,1] op_sel_hi:[1,1]
	v_add_f32_dpp v212, v212, v212 row_ror:4 row_mask:0xf bank_mask:0xf bound_ctrl:1
	v_pk_mul_f32 v[118:119], v[118:119], v[154:155] op_sel:[0,1] op_sel_hi:[1,1]
	v_pk_mul_f32 v[120:121], v[120:121], v[154:155] op_sel:[0,1] op_sel_hi:[1,1]
	v_add_f32_dpp v212, v212, v212 row_ror:2 row_mask:0xf bank_mask:0xf bound_ctrl:1
	v_pk_mul_f32 v[122:123], v[122:123], v[154:155] op_sel:[0,1] op_sel_hi:[1,1]
	v_pk_mul_f32 v[124:125], v[124:125], v[154:155] op_sel:[0,1] op_sel_hi:[1,1]
	v_add_f32_dpp v212, v212, v212 row_ror:1 row_mask:0xf bank_mask:0xf bound_ctrl:1
	v_pk_mul_f32 v[126:127], v[126:127], v[154:155] op_sel:[0,1] op_sel_hi:[1,1]
	s_waitcnt lgkmcnt(5)
	v_pk_fma_f32 v[196:197], v[154:155], v[196:197], v[112:113] op_sel_hi:[0,1,1]
	s_and_saveexec_b64 s[8:9], s[44:45]
	ds_write_b32 v190, v212 offset:34432
	s_mov_b64 exec, s[8:9]
	v_pk_fma_f32 v[198:199], v[154:155], v[198:199], v[114:115] op_sel_hi:[0,1,1]
	v_pk_fma_f32 v[200:201], v[154:155], v[200:201], v[116:117] op_sel_hi:[0,1,1]
	v_pk_fma_f32 v[202:203], v[154:155], v[202:203], v[118:119] op_sel_hi:[0,1,1]
	v_pk_fma_f32 v[204:205], v[154:155], v[204:205], v[120:121] op_sel_hi:[0,1,1]
	v_pk_fma_f32 v[206:207], v[154:155], v[206:207], v[122:123] op_sel_hi:[0,1,1]
	v_pk_fma_f32 v[208:209], v[154:155], v[208:209], v[124:125] op_sel_hi:[0,1,1]
	v_pk_fma_f32 v[210:211], v[154:155], v[210:211], v[126:127] op_sel_hi:[0,1,1]
	s_waitcnt lgkmcnt(5)
	v_pk_fma_f32 v[128:129], v[96:97], v[196:197], v[214:215]
	v_pk_fma_f32 v[130:131], v[98:99], v[198:199], v[214:215]
	s_waitcnt lgkmcnt(4)
	v_pk_fma_f32 v[128:129], v[100:101], v[200:201], v[128:129]
	v_pk_fma_f32 v[130:131], v[102:103], v[202:203], v[130:131]
	s_waitcnt lgkmcnt(3)
	v_pk_fma_f32 v[128:129], v[104:105], v[204:205], v[128:129]
	v_pk_fma_f32 v[130:131], v[106:107], v[206:207], v[130:131]
	s_waitcnt lgkmcnt(2)
	v_pk_fma_f32 v[128:129], v[108:109], v[208:209], v[128:129]
	v_pk_fma_f32 v[130:131], v[110:111], v[210:211], v[130:131]
	v_add_f32_e32 v128, v128, v129
	v_add_f32_e32 v130, v130, v131
	v_add_f32_e32 v213, v128, v130
	s_nop 1
	v_add_f32_dpp v213, v213, v213 row_ror:8 row_mask:0xf bank_mask:0xf bound_ctrl:1
	s_nop 1
	v_add_f32_dpp v213, v213, v213 row_ror:4 row_mask:0xf bank_mask:0xf bound_ctrl:1
	s_nop 1
	v_add_f32_dpp v213, v213, v213 row_ror:2 row_mask:0xf bank_mask:0xf bound_ctrl:1
	s_nop 1
	v_add_f32_dpp v213, v213, v213 row_ror:1 row_mask:0xf bank_mask:0xf bound_ctrl:1
	s_and_saveexec_b64 s[8:9], s[44:45]
	ds_write_b32 v190, v213 offset:34496
	s_mov_b64 exec, s[8:9]
	s_waitcnt vmcnt(11)
	ds_write_b128 v188, v[16:19] offset:17024
	s_waitcnt vmcnt(9)
	ds_write_b128 v191, v[24:27] offset:17024
	ds_write_b128 v188, v[20:23] offset:25216
	s_waitcnt vmcnt(8)
	ds_write_b128 v191, v[28:31] offset:25216
	s_and_saveexec_b64 s[8:9], s[40:41]
	ds_write_b32 v145, v183 offset:33408
	s_or_b64 exec, exec, s[8:9]
	s_and_saveexec_b64 s[8:9], s[42:43]
	s_cbranch_execz .LBB0_1176
	v_add_f32_e32 v64, v178, v185
	v_mul_f32_e64 v65, |v64|, s62
	v_exp_f32_e32 v65, v65
	v_min_f32_e32 v64, 0, v64
	v_add_f32_e32 v65, 1.0, v65
	v_cmp_gt_f32_e32 vcc, s5, v65
	s_nop 1
	v_cndmask_b32_e64 v66, 0, 32, vcc
	v_ldexp_f32 v65, v65, v66
	v_log_f32_e32 v65, v65
	v_cndmask_b32_e32 v67, 0, v171, vcc
	v_add_f32_e32 v66, v147, v184
	v_mul_f32_e32 v68, 0x3f317217, v65
	v_fma_f32 v68, v65, s76, -v68
	v_fmac_f32_e32 v68, 0x3377d1cf, v65
	v_fmac_f32_e32 v68, 0x3f317217, v65
	v_cmp_lt_f32_e64 vcc, |v65|, s77
	s_nop 1
	v_cndmask_b32_e32 v65, v65, v68, vcc
	v_sub_f32_e32 v65, v65, v67
	v_sub_f32_e32 v64, v64, v65
	v_add_u32_e32 v65, 0x8400, v145
	ds_write2_b32 v65, v66, v64 offset0:32 offset1:48

.LBB0_1189:
	s_or_b64 exec, exec, s[8:9]
	s_waitcnt lgkmcnt(0)
	s_barrier
	v_mov_b32_e32 v214, 0
	v_mov_b32_e32 v215, 0
	ds_read_b128 v[80:83], v194 offset:25216
	ds_read_b128 v[84:87], v194 offset:25472
	ds_read_b128 v[88:91], v194 offset:25728
	ds_read_b128 v[92:95], v194 offset:25984
	ds_read_b32 v134, v140 offset:35136
	ds_read_b32 v135, v190 offset:33408
	ds_read_b32 v132, v140 offset:35072
	ds_read_b128 v[64:67], v194 offset:17024
	ds_read_b128 v[68:71], v194 offset:17280
	ds_read_b128 v[72:75], v194 offset:17536
	ds_read_b128 v[76:79], v194 offset:17792
	ds_read_b128 v[112:115], v194 offset:26240
	ds_read_b128 v[116:119], v194 offset:26496
	ds_read_b128 v[120:123], v194 offset:26752
	ds_read_b128 v[124:127], v194 offset:27008
	ds_read_b32 v156, v140 offset:35140
	ds_read_b32 v157, v190 offset:33472
	ds_read_b32 v154, v140 offset:35076
	ds_read_b128 v[96:99], v194 offset:18048
	ds_read_b128 v[100:103], v194 offset:18304
	ds_read_b128 v[104:107], v194 offset:18560
	ds_read_b128 v[108:111], v194 offset:18816
	s_waitcnt lgkmcnt(15)
	v_mul_f32_e32 v133, v134, v135
	v_pk_mul_f32 v[80:81], v[80:81], v[132:133] op_sel:[0,1] op_sel_hi:[1,1]
	v_pk_mul_f32 v[82:83], v[82:83], v[132:133] op_sel:[0,1] op_sel_hi:[1,1]
	v_pk_mul_f32 v[84:85], v[84:85], v[132:133] op_sel:[0,1] op_sel_hi:[1,1]
	v_pk_mul_f32 v[86:87], v[86:87], v[132:133] op_sel:[0,1] op_sel_hi:[1,1]
	v_pk_mul_f32 v[88:89], v[88:89], v[132:133] op_sel:[0,1] op_sel_hi:[1,1]
	v_pk_mul_f32 v[90:91], v[90:91], v[132:133] op_sel:[0,1] op_sel_hi:[1,1]
	v_pk_mul_f32 v[92:93], v[92:93], v[132:133] op_sel:[0,1] op_sel_hi:[1,1]
	v_pk_mul_f32 v[94:95], v[94:95], v[132:133] op_sel:[0,1] op_sel_hi:[1,1]
	v_pk_fma_f32 v[196:197], v[132:133], v[196:197], v[80:81] op_sel_hi:[0,1,1]
	v_pk_fma_f32 v[198:199], v[132:133], v[198:199], v[82:83] op_sel_hi:[0,1,1]
	v_pk_fma_f32 v[200:201], v[132:133], v[200:201], v[84:85] op_sel_hi:[0,1,1]
	v_pk_fma_f32 v[202:203], v[132:133], v[202:203], v[86:87] op_sel_hi:[0,1,1]
	v_pk_fma_f32 v[204:205], v[132:133], v[204:205], v[88:89] op_sel_hi:[0,1,1]
	v_pk_fma_f32 v[206:207], v[132:133], v[206:207], v[90:91] op_sel_hi:[0,1,1]
	v_pk_fma_f32 v[208:209], v[132:133], v[208:209], v[92:93] op_sel_hi:[0,1,1]
	v_pk_fma_f32 v[210:211], v[132:133], v[210:211], v[94:95] op_sel_hi:[0,1,1]
	ds_read_b128 v[80:83], v194 offset:27264
	ds_read_b128 v[84:87], v194 offset:27520
	ds_read_b128 v[88:91], v194 offset:27776
	ds_read_b128 v[92:95], v194 offset:28032
	ds_read_b32 v134, v140 offset:35144
	ds_read_b32 v135, v190 offset:33536
	ds_read_b32 v132, v140 offset:35080
	s_waitcnt lgkmcnt(15)
	v_pk_fma_f32 v[128:129], v[64:65], v[196:197], v[214:215]
	v_pk_fma_f32 v[130:131], v[66:67], v[198:199], v[214:215]
	ds_read_b128 v[64:67], v194 offset:19072
	s_waitcnt lgkmcnt(15)
	v_pk_fma_f32 v[128:129], v[68:69], v[200:201], v[128:129]
	v_pk_fma_f32 v[130:131], v[70:71], v[202:203], v[130:131]
	ds_read_b128 v[68:71], v194 offset:19328
	s_waitcnt lgkmcnt(15)
	v_pk_fma_f32 v[128:129], v[72:73], v[204:205], v[128:129]
	v_pk_fma_f32 v[130:131], v[74:75], v[206:207], v[130:131]
	ds_read_b128 v[72:75], v194 offset:19584
	s_waitcnt lgkmcnt(15)
	v_pk_fma_f32 v[128:129], v[76:77], v[208:209], v[128:129]
	v_pk_fma_f32 v[130:131], v[78:79], v[210:211], v[130:131]
	ds_read_b128 v[76:79], v194 offset:19840
	v_add_f32_e32 v128, v128, v129
	v_add_f32_e32 v130, v130, v131
	v_add_f32_e32 v212, v128, v130
	s_waitcnt lgkmcnt(15)
	v_mul_f32_e32 v155, v156, v157
	v_pk_mul_f32 v[112:113], v[112:113], v[154:155] op_sel:[0,1] op_sel_hi:[1,1]
	v_add_f32_dpp v212, v212, v212 row_ror:8 row_mask:0xf bank_mask:0xf bound_ctrl:1
	v_pk_mul_f32 v[114:115], v[114:115], v[154:155] op_sel:[0,1] op_sel_hi:[1,1]
	v_pk_mul_f32 v[116:117], v[116:117], v[154:155] op_sel:[0,1] op_sel_hi:[1,1]
	v_add_f32_dpp v212, v212, v212 row_ror:4 row_mask:0xf bank_mask:0xf bound_ctrl:1
	v_pk_mul_f32 v[118:119], v[118:119], v[154:155] op_sel:[0,1] op_sel_hi:[1,1]
	v_pk_mul_f32 v[120:121], v[120:121], v[154:155] op_sel:[0,1] op_sel_hi:[1,1]
	v_add_f32_dpp v212, v212, v212 row_ror:2 row_mask:0xf bank_mask:0xf bound_ctrl:1
	v_pk_mul_f32 v[122:123], v[122:123], v[154:155] op_sel:[0,1] op_sel_hi:[1,1]
	v_pk_mul_f32 v[124:125], v[124:125], v[154:155] op_sel:[0,1] op_sel_hi:[1,1]
	v_add_f32_dpp v212, v212, v212 row_ror:1 row_mask:0xf bank_mask:0xf bound_ctrl:1
	v_pk_mul_f32 v[126:127], v[126:127], v[154:155] op_sel:[0,1] op_sel_hi:[1,1]
	v_pk_fma_f32 v[196:197], v[154:155], v[196:197], v[112:113] op_sel_hi:[0,1,1]
	s_and_saveexec_b64 s[8:9], s[44:45]
	ds_write_b32 v190, v212 offset:34560
	s_mov_b64 exec, s[8:9]
	v_pk_fma_f32 v[198:199], v[154:155], v[198:199], v[114:115] op_sel_hi:[0,1,1]
	v_pk_fma_f32 v[200:201], v[154:155], v[200:201], v[116:117] op_sel_hi:[0,1,1]
	v_pk_fma_f32 v[202:203], v[154:155], v[202:203], v[118:119] op_sel_hi:[0,1,1]
	v_pk_fma_f32 v[204:205], v[154:155], v[204:205], v[120:121] op_sel_hi:[0,1,1]
	v_pk_fma_f32 v[206:207], v[154:155], v[206:207], v[122:123] op_sel_hi:[0,1,1]
	v_pk_fma_f32 v[208:209], v[154:155], v[208:209], v[124:125] op_sel_hi:[0,1,1]
	v_pk_fma_f32 v[210:211], v[154:155], v[210:211], v[126:127] op_sel_hi:[0,1,1]
	ds_read_b128 v[112:115], v194 offset:28288
	ds_read_b128 v[116:119], v194 offset:28544
	ds_read_b128 v[120:123], v194 offset:28800
	ds_read_b128 v[124:127], v194 offset:29056
	ds_read_b32 v156, v140 offset:35148
	ds_read_b32 v157, v190 offset:33600
	ds_read_b32 v154, v140 offset:35084
	s_waitcnt lgkmcnt(15)
	v_pk_fma_f32 v[128:129], v[96:97], v[196:197], v[214:215]
	v_pk_fma_f32 v[130:131], v[98:99], v[198:199], v[214:215]
	ds_read_b128 v[96:99], v194 offset:20096
	s_waitcnt lgkmcnt(15)
	v_pk_fma_f32 v[128:129], v[100:101], v[200:201], v[128:129]
	v_pk_fma_f32 v[130:131], v[102:103], v[202:203], v[130:131]
	ds_read_b128 v[100:103], v194 offset:20352
	s_waitcnt lgkmcnt(15)
	v_pk_fma_f32 v[128:129], v[104:105], v[204:205], v[128:129]
	v_pk_fma_f32 v[130:131], v[106:107], v[206:207], v[130:131]
	ds_read_b128 v[104:107], v194 offset:20608
	s_waitcnt lgkmcnt(15)
	v_pk_fma_f32 v[128:129], v[108:109], v[208:209], v[128:129]
	v_pk_fma_f32 v[130:131], v[110:111], v[210:211], v[130:131]
	ds_read_b128 v[108:111], v194 offset:20864
	v_add_f32_e32 v128, v128, v129
	v_add_f32_e32 v130, v130, v131
	v_add_f32_e32 v213, v128, v130
	s_waitcnt lgkmcnt(15)
	v_mul_f32_e32 v133, v134, v135
	v_pk_mul_f32 v[80:81], v[80:81], v[132:133] op_sel:[0,1] op_sel_hi:[1,1]
	v_add_f32_dpp v213, v213, v213 row_ror:8 row_mask:0xf bank_mask:0xf bound_ctrl:1
	v_pk_mul_f32 v[82:83], v[82:83], v[132:133] op_sel:[0,1] op_sel_hi:[1,1]
	v_pk_mul_f32 v[84:85], v[84:85], v[132:133] op_sel:[0,1] op_sel_hi:[1,1]
	v_add_f32_dpp v213, v213, v213 row_ror:4 row_mask:0xf bank_mask:0xf bound_ctrl:1
	v_pk_mul_f32 v[86:87], v[86:87], v[132:133] op_sel:[0,1] op_sel_hi:[1,1]
	v_pk_mul_f32 v[88:89], v[88:89], v[132:133] op_sel:[0,1] op_sel_hi:[1,1]
	v_add_f32_dpp v213, v213, v213 row_ror:2 row_mask:0xf bank_mask:0xf bound_ctrl:1
	v_pk_mul_f32 v[90:91], v[90:91], v[132:133] op_sel:[0,1] op_sel_hi:[1,1]
	v_pk_mul_f32 v[92:93], v[92:93], v[132:133] op_sel:[0,1] op_sel_hi:[1,1]
	v_add_f32_dpp v213, v213, v213 row_ror:1 row_mask:0xf bank_mask:0xf bound_ctrl:1
	v_pk_mul_f32 v[94:95], v[94:95], v[132:133] op_sel:[0,1] op_sel_hi:[1,1]
	v_pk_fma_f32 v[196:197], v[132:133], v[196:197], v[80:81] op_sel_hi:[0,1,1]
	s_and_saveexec_b64 s[8:9], s[44:45]
	ds_write_b32 v190, v213 offset:34624
	s_mov_b64 exec, s[8:9]
	v_pk_fma_f32 v[198:199], v[132:133], v[198:199], v[82:83] op_sel_hi:[0,1,1]
	v_pk_fma_f32 v[200:201], v[132:133], v[200:201], v[84:85] op_sel_hi:[0,1,1]
	v_pk_fma_f32 v[202:203], v[132:133], v[202:203], v[86:87] op_sel_hi:[0,1,1]
	v_pk_fma_f32 v[204:205], v[132:133], v[204:205], v[88:89] op_sel_hi:[0,1,1]
	v_pk_fma_f32 v[206:207], v[132:133], v[206:207], v[90:91] op_sel_hi:[0,1,1]
	v_pk_fma_f32 v[208:209], v[132:133], v[208:209], v[92:93] op_sel_hi:[0,1,1]
	v_pk_fma_f32 v[210:211], v[132:133], v[210:211], v[94:95] op_sel_hi:[0,1,1]
	ds_read_b128 v[80:83], v194 offset:29312
	ds_read_b128 v[84:87], v194 offset:29568
	ds_read_b128 v[88:91], v194 offset:29824
	ds_read_b128 v[92:95], v194 offset:30080
	ds_read_b32 v134, v140 offset:35152
	ds_read_b32 v135, v190 offset:33664
	ds_read_b32 v132, v140 offset:35088
	s_waitcnt lgkmcnt(15)
	v_pk_fma_f32 v[128:129], v[64:65], v[196:197], v[214:215]
	v_pk_fma_f32 v[130:131], v[66:67], v[198:199], v[214:215]
	ds_read_b128 v[64:67], v194 offset:21120
	s_waitcnt lgkmcnt(15)
	v_pk_fma_f32 v[128:129], v[68:69], v[200:201], v[128:129]
	v_pk_fma_f32 v[130:131], v[70:71], v[202:203], v[130:131]
	ds_read_b128 v[68:71], v194 offset:21376
	s_waitcnt lgkmcnt(15)
	v_pk_fma_f32 v[128:129], v[72:73], v[204:205], v[128:129]
	v_pk_fma_f32 v[130:131], v[74:75], v[206:207], v[130:131]
	ds_read_b128 v[72:75], v194 offset:21632
	s_waitcnt lgkmcnt(15)
	v_pk_fma_f32 v[128:129], v[76:77], v[208:209], v[128:129]
	v_pk_fma_f32 v[130:131], v[78:79], v[210:211], v[130:131]
	ds_read_b128 v[76:79], v194 offset:21888
	v_add_f32_e32 v128, v128, v129
	v_add_f32_e32 v130, v130, v131
	v_add_f32_e32 v212, v128, v130
	s_waitcnt lgkmcnt(15)
	v_mul_f32_e32 v155, v156, v157
	v_pk_mul_f32 v[112:113], v[112:113], v[154:155] op_sel:[0,1] op_sel_hi:[1,1]
	v_add_f32_dpp v212, v212, v212 row_ror:8 row_mask:0xf bank_mask:0xf bound_ctrl:1
	v_pk_mul_f32 v[114:115], v[114:115], v[154:155] op_sel:[0,1] op_sel_hi:[1,1]
	v_pk_mul_f32 v[116:117], v[116:117], v[154:155] op_sel:[0,1] op_sel_hi:[1,1]
	v_add_f32_dpp v212, v212, v212 row_ror:4 row_mask:0xf bank_mask:0xf bound_ctrl:1
	v_pk_mul_f32 v[118:119], v[118:119], v[154:155] op_sel:[0,1] op_sel_hi:[1,1]
	v_pk_mul_f32 v[120:121], v[120:121], v[154:155] op_sel:[0,1] op_sel_hi:[1,1]
	v_add_f32_dpp v212, v212, v212 row_ror:2 row_mask:0xf bank_mask:0xf bound_ctrl:1
	v_pk_mul_f32 v[122:123], v[122:123], v[154:155] op_sel:[0,1] op_sel_hi:[1,1]
	v_pk_mul_f32 v[124:125], v[124:125], v[154:155] op_sel:[0,1] op_sel_hi:[1,1]
	v_add_f32_dpp v212, v212, v212 row_ror:1 row_mask:0xf bank_mask:0xf bound_ctrl:1
	v_pk_mul_f32 v[126:127], v[126:127], v[154:155] op_sel:[0,1] op_sel_hi:[1,1]
	v_pk_fma_f32 v[196:197], v[154:155], v[196:197], v[112:113] op_sel_hi:[0,1,1]
	s_and_saveexec_b64 s[8:9], s[44:45]
	ds_write_b32 v190, v212 offset:34688
	s_mov_b64 exec, s[8:9]
	v_pk_fma_f32 v[198:199], v[154:155], v[198:199], v[114:115] op_sel_hi:[0,1,1]
	v_pk_fma_f32 v[200:201], v[154:155], v[200:201], v[116:117] op_sel_hi:[0,1,1]
	v_pk_fma_f32 v[202:203], v[154:155], v[202:203], v[118:119] op_sel_hi:[0,1,1]
	v_pk_fma_f32 v[204:205], v[154:155], v[204:205], v[120:121] op_sel_hi:[0,1,1]
	v_pk_fma_f32 v[206:207], v[154:155], v[206:207], v[122:123] op_sel_hi:[0,1,1]
	v_pk_fma_f32 v[208:209], v[154:155], v[208:209], v[124:125] op_sel_hi:[0,1,1]
	v_pk_fma_f32 v[210:211], v[154:155], v[210:211], v[126:127] op_sel_hi:[0,1,1]
	ds_read_b128 v[112:115], v194 offset:30336
	ds_read_b128 v[116:119], v194 offset:30592
	ds_read_b128 v[120:123], v194 offset:30848
	ds_read_b128 v[124:127], v194 offset:31104
	ds_read_b32 v156, v140 offset:35156
	ds_read_b32 v157, v190 offset:33728
	ds_read_b32 v154, v140 offset:35092
	s_waitcnt lgkmcnt(15)
	v_pk_fma_f32 v[128:129], v[96:97], v[196:197], v[214:215]
	v_pk_fma_f32 v[130:131], v[98:99], v[198:199], v[214:215]
	ds_read_b128 v[96:99], v194 offset:22144
	s_waitcnt lgkmcnt(15)
	v_pk_fma_f32 v[128:129], v[100:101], v[200:201], v[128:129]
	v_pk_fma_f32 v[130:131], v[102:103], v[202:203], v[130:131]
	ds_read_b128 v[100:103], v194 offset:22400
	s_waitcnt lgkmcnt(15)
	v_pk_fma_f32 v[128:129], v[104:105], v[204:205], v[128:129]
	v_pk_fma_f32 v[130:131], v[106:107], v[206:207], v[130:131]
	ds_read_b128 v[104:107], v194 offset:22656
	s_waitcnt lgkmcnt(15)
	v_pk_fma_f32 v[128:129], v[108:109], v[208:209], v[128:129]
	v_pk_fma_f32 v[130:131], v[110:111], v[210:211], v[130:131]
	ds_read_b128 v[108:111], v194 offset:22912
	v_add_f32_e32 v128, v128, v129
	v_add_f32_e32 v130, v130, v131
	v_add_f32_e32 v213, v128, v130
	s_waitcnt lgkmcnt(15)
	v_mul_f32_e32 v133, v134, v135
	v_pk_mul_f32 v[80:81], v[80:81], v[132:133] op_sel:[0,1] op_sel_hi:[1,1]
	v_add_f32_dpp v213, v213, v213 row_ror:8 row_mask:0xf bank_mask:0xf bound_ctrl:1
	v_pk_mul_f32 v[82:83], v[82:83], v[132:133] op_sel:[0,1] op_sel_hi:[1,1]
	v_pk_mul_f32 v[84:85], v[84:85], v[132:133] op_sel:[0,1] op_sel_hi:[1,1]
	v_add_f32_dpp v213, v213, v213 row_ror:4 row_mask:0xf bank_mask:0xf bound_ctrl:1
	v_pk_mul_f32 v[86:87], v[86:87], v[132:133] op_sel:[0,1] op_sel_hi:[1,1]
	v_pk_mul_f32 v[88:89], v[88:89], v[132:133] op_sel:[0,1] op_sel_hi:[1,1]
	v_add_f32_dpp v213, v213, v213 row_ror:2 row_mask:0xf bank_mask:0xf bound_ctrl:1
	v_pk_mul_f32 v[90:91], v[90:91], v[132:133] op_sel:[0,1] op_sel_hi:[1,1]
	v_pk_mul_f32 v[92:93], v[92:93], v[132:133] op_sel:[0,1] op_sel_hi:[1,1]
	v_add_f32_dpp v213, v213, v213 row_ror:1 row_mask:0xf bank_mask:0xf bound_ctrl:1
	v_pk_mul_f32 v[94:95], v[94:95], v[132:133] op_sel:[0,1] op_sel_hi:[1,1]
	v_pk_fma_f32 v[196:197], v[132:133], v[196:197], v[80:81] op_sel_hi:[0,1,1]
	s_and_saveexec_b64 s[8:9], s[44:45]
	ds_write_b32 v190, v213 offset:34752
	s_mov_b64 exec, s[8:9]
	v_pk_fma_f32 v[198:199], v[132:133], v[198:199], v[82:83] op_sel_hi:[0,1,1]
	v_pk_fma_f32 v[200:201], v[132:133], v[200:201], v[84:85] op_sel_hi:[0,1,1]
	v_pk_fma_f32 v[202:203], v[132:133], v[202:203], v[86:87] op_sel_hi:[0,1,1]
	v_pk_fma_f32 v[204:205], v[132:133], v[204:205], v[88:89] op_sel_hi:[0,1,1]
	v_pk_fma_f32 v[206:207], v[132:133], v[206:207], v[90:91] op_sel_hi:[0,1,1]
	v_pk_fma_f32 v[208:209], v[132:133], v[208:209], v[92:93] op_sel_hi:[0,1,1]
	v_pk_fma_f32 v[210:211], v[132:133], v[210:211], v[94:95] op_sel_hi:[0,1,1]
	ds_read_b128 v[80:83], v194 offset:31360
	ds_read_b128 v[84:87], v194 offset:31616
	ds_read_b128 v[88:91], v194 offset:31872
	ds_read_b128 v[92:95], v194 offset:32128
	ds_read_b32 v134, v140 offset:35160
	ds_read_b32 v135, v190 offset:33792
	ds_read_b32 v132, v140 offset:35096
	s_waitcnt lgkmcnt(15)
	v_pk_fma_f32 v[128:129], v[64:65], v[196:197], v[214:215]
	v_pk_fma_f32 v[130:131], v[66:67], v[198:199], v[214:215]
	ds_read_b128 v[64:67], v194 offset:23168
	s_waitcnt lgkmcnt(15)
	v_pk_fma_f32 v[128:129], v[68:69], v[200:201], v[128:129]
	v_pk_fma_f32 v[130:131], v[70:71], v[202:203], v[130:131]
	ds_read_b128 v[68:71], v194 offset:23424
	s_waitcnt lgkmcnt(15)
	v_pk_fma_f32 v[128:129], v[72:73], v[204:205], v[128:129]
	v_pk_fma_f32 v[130:131], v[74:75], v[206:207], v[130:131]
	ds_read_b128 v[72:75], v194 offset:23680
	s_waitcnt lgkmcnt(15)
	v_pk_fma_f32 v[128:129], v[76:77], v[208:209], v[128:129]
	v_pk_fma_f32 v[130:131], v[78:79], v[210:211], v[130:131]
	ds_read_b128 v[76:79], v194 offset:23936
	v_add_f32_e32 v128, v128, v129
	v_add_f32_e32 v130, v130, v131
	v_add_f32_e32 v212, v128, v130
	s_waitcnt lgkmcnt(15)
	v_mul_f32_e32 v155, v156, v157
	v_pk_mul_f32 v[112:113], v[112:113], v[154:155] op_sel:[0,1] op_sel_hi:[1,1]
	v_add_f32_dpp v212, v212, v212 row_ror:8 row_mask:0xf bank_mask:0xf bound_ctrl:1
	v_pk_mul_f32 v[114:115], v[114:115], v[154:155] op_sel:[0,1] op_sel_hi:[1,1]
	v_pk_mul_f32 v[116:117], v[116:117], v[154:155] op_sel:[0,1] op_sel_hi:[1,1]
	v_add_f32_dpp v212, v212, v212 row_ror:4 row_mask:0xf bank_mask:0xf bound_ctrl:1
	v_pk_mul_f32 v[118:119], v[118:119], v[154:155] op_sel:[0,1] op_sel_hi:[1,1]
	v_pk_mul_f32 v[120:121], v[120:121], v[154:155] op_sel:[0,1] op_sel_hi:[1,1]
	v_add_f32_dpp v212, v212, v212 row_ror:2 row_mask:0xf bank_mask:0xf bound_ctrl:1
	v_pk_mul_f32 v[122:123], v[122:123], v[154:155] op_sel:[0,1] op_sel_hi:[1,1]
	v_pk_mul_f32 v[124:125], v[124:125], v[154:155] op_sel:[0,1] op_sel_hi:[1,1]
	v_add_f32_dpp v212, v212, v212 row_ror:1 row_mask:0xf bank_mask:0xf bound_ctrl:1
	v_pk_mul_f32 v[126:127], v[126:127], v[154:155] op_sel:[0,1] op_sel_hi:[1,1]
	v_pk_fma_f32 v[196:197], v[154:155], v[196:197], v[112:113] op_sel_hi:[0,1,1]
	s_and_saveexec_b64 s[8:9], s[44:45]
	ds_write_b32 v190, v212 offset:34816
	s_mov_b64 exec, s[8:9]
	v_pk_fma_f32 v[198:199], v[154:155], v[198:199], v[114:115] op_sel_hi:[0,1,1]
	v_pk_fma_f32 v[200:201], v[154:155], v[200:201], v[116:117] op_sel_hi:[0,1,1]
	v_pk_fma_f32 v[202:203], v[154:155], v[202:203], v[118:119] op_sel_hi:[0,1,1]
	v_pk_fma_f32 v[204:205], v[154:155], v[204:205], v[120:121] op_sel_hi:[0,1,1]
	v_pk_fma_f32 v[206:207], v[154:155], v[206:207], v[122:123] op_sel_hi:[0,1,1]
	v_pk_fma_f32 v[208:209], v[154:155], v[208:209], v[124:125] op_sel_hi:[0,1,1]
	v_pk_fma_f32 v[210:211], v[154:155], v[210:211], v[126:127] op_sel_hi:[0,1,1]
	ds_read_b128 v[112:115], v194 offset:32384
	ds_read_b128 v[116:119], v194 offset:32640
	ds_read_b128 v[120:123], v194 offset:32896
	ds_read_b128 v[124:127], v194 offset:33152
	ds_read_b32 v156, v140 offset:35164
	ds_read_b32 v157, v190 offset:33856
	ds_read_b32 v154, v140 offset:35100
	s_waitcnt lgkmcnt(15)
	v_pk_fma_f32 v[128:129], v[96:97], v[196:197], v[214:215]
	v_pk_fma_f32 v[130:131], v[98:99], v[198:199], v[214:215]
	ds_read_b128 v[96:99], v194 offset:24192
	s_waitcnt lgkmcnt(15)
	v_pk_fma_f32 v[128:129], v[100:101], v[200:201], v[128:129]
	v_pk_fma_f32 v[130:131], v[102:103], v[202:203], v[130:131]
	ds_read_b128 v[100:103], v194 offset:24448
	s_waitcnt lgkmcnt(15)
	v_pk_fma_f32 v[128:129], v[104:105], v[204:205], v[128:129]
	v_pk_fma_f32 v[130:131], v[106:107], v[206:207], v[130:131]
	ds_read_b128 v[104:107], v194 offset:24704
	s_waitcnt lgkmcnt(15)
	v_pk_fma_f32 v[128:129], v[108:109], v[208:209], v[128:129]
	v_pk_fma_f32 v[130:131], v[110:111], v[210:211], v[130:131]
	ds_read_b128 v[108:111], v194 offset:24960
	v_add_f32_e32 v128, v128, v129
	v_add_f32_e32 v130, v130, v131
	v_add_f32_e32 v213, v128, v130
	s_waitcnt lgkmcnt(15)
	v_mul_f32_e32 v133, v134, v135
	v_pk_mul_f32 v[80:81], v[80:81], v[132:133] op_sel:[0,1] op_sel_hi:[1,1]
	v_add_f32_dpp v213, v213, v213 row_ror:8 row_mask:0xf bank_mask:0xf bound_ctrl:1
	v_pk_mul_f32 v[82:83], v[82:83], v[132:133] op_sel:[0,1] op_sel_hi:[1,1]
	v_pk_mul_f32 v[84:85], v[84:85], v[132:133] op_sel:[0,1] op_sel_hi:[1,1]
	v_add_f32_dpp v213, v213, v213 row_ror:4 row_mask:0xf bank_mask:0xf bound_ctrl:1
	v_pk_mul_f32 v[86:87], v[86:87], v[132:133] op_sel:[0,1] op_sel_hi:[1,1]
	v_pk_mul_f32 v[88:89], v[88:89], v[132:133] op_sel:[0,1] op_sel_hi:[1,1]
	v_add_f32_dpp v213, v213, v213 row_ror:2 row_mask:0xf bank_mask:0xf bound_ctrl:1
	v_pk_mul_f32 v[90:91], v[90:91], v[132:133] op_sel:[0,1] op_sel_hi:[1,1]
	v_pk_mul_f32 v[92:93], v[92:93], v[132:133] op_sel:[0,1] op_sel_hi:[1,1]
	v_add_f32_dpp v213, v213, v213 row_ror:1 row_mask:0xf bank_mask:0xf bound_ctrl:1
	v_pk_mul_f32 v[94:95], v[94:95], v[132:133] op_sel:[0,1] op_sel_hi:[1,1]
	v_pk_fma_f32 v[196:197], v[132:133], v[196:197], v[80:81] op_sel_hi:[0,1,1]
	s_and_saveexec_b64 s[8:9], s[44:45]
	ds_write_b32 v190, v213 offset:34880
	s_mov_b64 exec, s[8:9]
	v_pk_fma_f32 v[198:199], v[132:133], v[198:199], v[82:83] op_sel_hi:[0,1,1]
	v_pk_fma_f32 v[200:201], v[132:133], v[200:201], v[84:85] op_sel_hi:[0,1,1]
	v_pk_fma_f32 v[202:203], v[132:133], v[202:203], v[86:87] op_sel_hi:[0,1,1]
	v_pk_fma_f32 v[204:205], v[132:133], v[204:205], v[88:89] op_sel_hi:[0,1,1]
	v_pk_fma_f32 v[206:207], v[132:133], v[206:207], v[90:91] op_sel_hi:[0,1,1]
	v_pk_fma_f32 v[208:209], v[132:133], v[208:209], v[92:93] op_sel_hi:[0,1,1]
	v_pk_fma_f32 v[210:211], v[132:133], v[210:211], v[94:95] op_sel_hi:[0,1,1]
	s_waitcnt lgkmcnt(15)
	v_pk_fma_f32 v[128:129], v[64:65], v[196:197], v[214:215]
	v_pk_fma_f32 v[130:131], v[66:67], v[198:199], v[214:215]
	v_pk_fma_f32 v[128:129], v[68:69], v[200:201], v[128:129]
	v_pk_fma_f32 v[130:131], v[70:71], v[202:203], v[130:131]
	s_waitcnt lgkmcnt(14)
	v_pk_fma_f32 v[128:129], v[72:73], v[204:205], v[128:129]
	v_pk_fma_f32 v[130:131], v[74:75], v[206:207], v[130:131]
	s_waitcnt lgkmcnt(13)
	v_pk_fma_f32 v[128:129], v[76:77], v[208:209], v[128:129]
	v_pk_fma_f32 v[130:131], v[78:79], v[210:211], v[130:131]
	v_add_f32_e32 v128, v128, v129
	v_add_f32_e32 v130, v130, v131
	v_add_f32_e32 v212, v128, v130
	s_waitcnt lgkmcnt(6)
	v_mul_f32_e32 v155, v156, v157
	v_pk_mul_f32 v[112:113], v[112:113], v[154:155] op_sel:[0,1] op_sel_hi:[1,1]
	v_add_f32_dpp v212, v212, v212 row_ror:8 row_mask:0xf bank_mask:0xf bound_ctrl:1
	v_pk_mul_f32 v[114:115], v[114:115], v[154:155] op_sel:[0,1] op_sel_hi:[1,1]
	v_pk_mul_f32 v[116:117], v[116:117], v[154:155] op_sel:[0,1] op_sel_hi:[1,1]
	v_add_f32_dpp v212, v212, v212 row_ror:4 row_mask:0xf bank_mask:0xf bound_ctrl:1
	v_pk_mul_f32 v[118:119], v[118:119], v[154:155] op_sel:[0,1] op_sel_hi:[1,1]
	v_pk_mul_f32 v[120:121], v[120:121], v[154:155] op_sel:[0,1] op_sel_hi:[1,1]
	v_add_f32_dpp v212, v212, v212 row_ror:2 row_mask:0xf bank_mask:0xf bound_ctrl:1
	v_pk_mul_f32 v[122:123], v[122:123], v[154:155] op_sel:[0,1] op_sel_hi:[1,1]
	v_pk_mul_f32 v[124:125], v[124:125], v[154:155] op_sel:[0,1] op_sel_hi:[1,1]
	v_add_f32_dpp v212, v212, v212 row_ror:1 row_mask:0xf bank_mask:0xf bound_ctrl:1
	v_pk_mul_f32 v[126:127], v[126:127], v[154:155] op_sel:[0,1] op_sel_hi:[1,1]
	s_waitcnt lgkmcnt(5)
	v_pk_fma_f32 v[196:197], v[154:155], v[196:197], v[112:113] op_sel_hi:[0,1,1]
	s_and_saveexec_b64 s[8:9], s[44:45]
	ds_write_b32 v190, v212 offset:34944
	s_mov_b64 exec, s[8:9]
	v_pk_fma_f32 v[198:199], v[154:155], v[198:199], v[114:115] op_sel_hi:[0,1,1]
	v_pk_fma_f32 v[200:201], v[154:155], v[200:201], v[116:117] op_sel_hi:[0,1,1]
	v_pk_fma_f32 v[202:203], v[154:155], v[202:203], v[118:119] op_sel_hi:[0,1,1]
	v_pk_fma_f32 v[204:205], v[154:155], v[204:205], v[120:121] op_sel_hi:[0,1,1]
	v_pk_fma_f32 v[206:207], v[154:155], v[206:207], v[122:123] op_sel_hi:[0,1,1]
	v_pk_fma_f32 v[208:209], v[154:155], v[208:209], v[124:125] op_sel_hi:[0,1,1]
	v_pk_fma_f32 v[210:211], v[154:155], v[210:211], v[126:127] op_sel_hi:[0,1,1]
	s_waitcnt lgkmcnt(5)
	v_pk_fma_f32 v[128:129], v[96:97], v[196:197], v[214:215]
	v_pk_fma_f32 v[130:131], v[98:99], v[198:199], v[214:215]
	s_waitcnt lgkmcnt(4)
	v_pk_fma_f32 v[128:129], v[100:101], v[200:201], v[128:129]
	v_pk_fma_f32 v[130:131], v[102:103], v[202:203], v[130:131]
	s_waitcnt lgkmcnt(3)
	v_pk_fma_f32 v[128:129], v[104:105], v[204:205], v[128:129]
	v_pk_fma_f32 v[130:131], v[106:107], v[206:207], v[130:131]
	s_waitcnt lgkmcnt(2)
	v_pk_fma_f32 v[128:129], v[108:109], v[208:209], v[128:129]
	v_pk_fma_f32 v[130:131], v[110:111], v[210:211], v[130:131]
	v_add_f32_e32 v128, v128, v129
	v_add_f32_e32 v130, v130, v131
	v_add_f32_e32 v213, v128, v130
	s_nop 1
	v_add_f32_dpp v213, v213, v213 row_ror:8 row_mask:0xf bank_mask:0xf bound_ctrl:1
	s_nop 1
	v_add_f32_dpp v213, v213, v213 row_ror:4 row_mask:0xf bank_mask:0xf bound_ctrl:1
	s_nop 1
	v_add_f32_dpp v213, v213, v213 row_ror:2 row_mask:0xf bank_mask:0xf bound_ctrl:1
	s_nop 1
	v_add_f32_dpp v213, v213, v213 row_ror:1 row_mask:0xf bank_mask:0xf bound_ctrl:1
	s_and_saveexec_b64 s[8:9], s[44:45]
	ds_write_b32 v190, v213 offset:35008
	s_mov_b64 exec, s[8:9]
	s_waitcnt vmcnt(7)
	ds_write_b128 v188, v[32:35]
	s_waitcnt vmcnt(5)
	ds_write_b128 v191, v[40:43]
	ds_write_b128 v188, v[36:39] offset:8192
	s_waitcnt vmcnt(4)
	ds_write_b128 v191, v[44:47] offset:8192
	s_and_saveexec_b64 s[8:9], s[40:41]
	ds_write_b32 v145, v186 offset:16384
	s_or_b64 exec, exec, s[8:9]
	s_and_saveexec_b64 s[8:9], s[42:43]
	s_cbranch_execz .LBB0_1209
	v_add_f32_e32 v64, v178, v189
	v_mul_f32_e64 v65, |v64|, s62
	v_exp_f32_e32 v65, v65
	v_min_f32_e32 v64, 0, v64
	v_add_f32_e32 v65, 1.0, v65
	v_cmp_gt_f32_e32 vcc, s5, v65
	s_nop 1
	v_cndmask_b32_e64 v66, 0, 32, vcc
	v_ldexp_f32 v65, v65, v66
	v_log_f32_e32 v65, v65
	v_cndmask_b32_e32 v67, 0, v171, vcc
	v_add_f32_e32 v66, v147, v187
	v_mul_f32_e32 v68, 0x3f317217, v65
	v_fma_f32 v68, v65, s76, -v68
	v_fmac_f32_e32 v68, 0x3377d1cf, v65
	v_fmac_f32_e32 v68, 0x3f317217, v65
	v_cmp_lt_f32_e64 vcc, |v65|, s77
	s_nop 1
	v_cndmask_b32_e32 v65, v65, v68, vcc
	v_sub_f32_e32 v65, v65, v67
	v_sub_f32_e32 v64, v64, v65
	v_add_u32_e32 v65, 0x4000, v145
	ds_write2_b32 v65, v66, v64 offset0:128 offset1:144

.LBB0_1222:
	s_or_b64 exec, exec, s[8:9]
	s_waitcnt lgkmcnt(0)
	s_barrier
	v_mov_b32_e32 v214, 0
	v_mov_b32_e32 v215, 0
	ds_read_b128 v[80:83], v194 offset:8192
	ds_read_b128 v[84:87], v194 offset:8448
	ds_read_b128 v[88:91], v194 offset:8704
	ds_read_b128 v[92:95], v194 offset:8960
	ds_read_b32 v134, v140 offset:35136
	ds_read_b32 v135, v190 offset:16384
	ds_read_b32 v132, v140 offset:35072
	ds_read_b128 v[64:67], v194
	ds_read_b128 v[68:71], v194 offset:256
	ds_read_b128 v[72:75], v194 offset:512
	ds_read_b128 v[76:79], v194 offset:768
	ds_read_b128 v[112:115], v194 offset:9216
	ds_read_b128 v[116:119], v194 offset:9472
	ds_read_b128 v[120:123], v194 offset:9728
	ds_read_b128 v[124:127], v194 offset:9984
	ds_read_b32 v156, v140 offset:35140
	ds_read_b32 v157, v190 offset:16448
	ds_read_b32 v154, v140 offset:35076
	ds_read_b128 v[96:99], v194 offset:1024
	ds_read_b128 v[100:103], v194 offset:1280
	ds_read_b128 v[104:107], v194 offset:1536
	ds_read_b128 v[108:111], v194 offset:1792
	s_waitcnt lgkmcnt(15)
	v_mul_f32_e32 v133, v134, v135
	v_pk_mul_f32 v[80:81], v[80:81], v[132:133] op_sel:[0,1] op_sel_hi:[1,1]
	v_pk_mul_f32 v[82:83], v[82:83], v[132:133] op_sel:[0,1] op_sel_hi:[1,1]
	v_pk_mul_f32 v[84:85], v[84:85], v[132:133] op_sel:[0,1] op_sel_hi:[1,1]
	v_pk_mul_f32 v[86:87], v[86:87], v[132:133] op_sel:[0,1] op_sel_hi:[1,1]
	v_pk_mul_f32 v[88:89], v[88:89], v[132:133] op_sel:[0,1] op_sel_hi:[1,1]
	v_pk_mul_f32 v[90:91], v[90:91], v[132:133] op_sel:[0,1] op_sel_hi:[1,1]
	v_pk_mul_f32 v[92:93], v[92:93], v[132:133] op_sel:[0,1] op_sel_hi:[1,1]
	v_pk_mul_f32 v[94:95], v[94:95], v[132:133] op_sel:[0,1] op_sel_hi:[1,1]
	v_pk_fma_f32 v[196:197], v[132:133], v[196:197], v[80:81] op_sel_hi:[0,1,1]
	v_pk_fma_f32 v[198:199], v[132:133], v[198:199], v[82:83] op_sel_hi:[0,1,1]
	v_pk_fma_f32 v[200:201], v[132:133], v[200:201], v[84:85] op_sel_hi:[0,1,1]
	v_pk_fma_f32 v[202:203], v[132:133], v[202:203], v[86:87] op_sel_hi:[0,1,1]
	v_pk_fma_f32 v[204:205], v[132:133], v[204:205], v[88:89] op_sel_hi:[0,1,1]
	v_pk_fma_f32 v[206:207], v[132:133], v[206:207], v[90:91] op_sel_hi:[0,1,1]
	v_pk_fma_f32 v[208:209], v[132:133], v[208:209], v[92:93] op_sel_hi:[0,1,1]
	v_pk_fma_f32 v[210:211], v[132:133], v[210:211], v[94:95] op_sel_hi:[0,1,1]
	ds_read_b128 v[80:83], v194 offset:10240
	ds_read_b128 v[84:87], v194 offset:10496
	ds_read_b128 v[88:91], v194 offset:10752
	ds_read_b128 v[92:95], v194 offset:11008
	ds_read_b32 v134, v140 offset:35144
	ds_read_b32 v135, v190 offset:16512
	ds_read_b32 v132, v140 offset:35080
	s_waitcnt lgkmcnt(15)
	v_pk_fma_f32 v[128:129], v[64:65], v[196:197], v[214:215]
	v_pk_fma_f32 v[130:131], v[66:67], v[198:199], v[214:215]
	ds_read_b128 v[64:67], v194 offset:2048
	s_waitcnt lgkmcnt(15)
	v_pk_fma_f32 v[128:129], v[68:69], v[200:201], v[128:129]
	v_pk_fma_f32 v[130:131], v[70:71], v[202:203], v[130:131]
	ds_read_b128 v[68:71], v194 offset:2304
	s_waitcnt lgkmcnt(15)
	v_pk_fma_f32 v[128:129], v[72:73], v[204:205], v[128:129]
	v_pk_fma_f32 v[130:131], v[74:75], v[206:207], v[130:131]
	ds_read_b128 v[72:75], v194 offset:2560
	s_waitcnt lgkmcnt(15)
	v_pk_fma_f32 v[128:129], v[76:77], v[208:209], v[128:129]
	v_pk_fma_f32 v[130:131], v[78:79], v[210:211], v[130:131]
	ds_read_b128 v[76:79], v194 offset:2816
	v_add_f32_e32 v128, v128, v129
	v_add_f32_e32 v130, v130, v131
	v_add_f32_e32 v212, v128, v130
	s_waitcnt lgkmcnt(15)
	v_mul_f32_e32 v155, v156, v157
	v_pk_mul_f32 v[112:113], v[112:113], v[154:155] op_sel:[0,1] op_sel_hi:[1,1]
	v_add_f32_dpp v212, v212, v212 row_ror:8 row_mask:0xf bank_mask:0xf bound_ctrl:1
	v_pk_mul_f32 v[114:115], v[114:115], v[154:155] op_sel:[0,1] op_sel_hi:[1,1]
	v_pk_mul_f32 v[116:117], v[116:117], v[154:155] op_sel:[0,1] op_sel_hi:[1,1]
	v_add_f32_dpp v212, v212, v212 row_ror:4 row_mask:0xf bank_mask:0xf bound_ctrl:1
	v_pk_mul_f32 v[118:119], v[118:119], v[154:155] op_sel:[0,1] op_sel_hi:[1,1]
	v_pk_mul_f32 v[120:121], v[120:121], v[154:155] op_sel:[0,1] op_sel_hi:[1,1]
	v_add_f32_dpp v212, v212, v212 row_ror:2 row_mask:0xf bank_mask:0xf bound_ctrl:1
	v_pk_mul_f32 v[122:123], v[122:123], v[154:155] op_sel:[0,1] op_sel_hi:[1,1]
	v_pk_mul_f32 v[124:125], v[124:125], v[154:155] op_sel:[0,1] op_sel_hi:[1,1]
	v_add_f32_dpp v212, v212, v212 row_ror:1 row_mask:0xf bank_mask:0xf bound_ctrl:1
	v_pk_mul_f32 v[126:127], v[126:127], v[154:155] op_sel:[0,1] op_sel_hi:[1,1]
	v_pk_fma_f32 v[196:197], v[154:155], v[196:197], v[112:113] op_sel_hi:[0,1,1]
	s_and_saveexec_b64 s[8:9], s[44:45]
	ds_write_b32 v190, v212 offset:34048
	s_mov_b64 exec, s[8:9]
	v_pk_fma_f32 v[198:199], v[154:155], v[198:199], v[114:115] op_sel_hi:[0,1,1]
	v_pk_fma_f32 v[200:201], v[154:155], v[200:201], v[116:117] op_sel_hi:[0,1,1]
	v_pk_fma_f32 v[202:203], v[154:155], v[202:203], v[118:119] op_sel_hi:[0,1,1]
	v_pk_fma_f32 v[204:205], v[154:155], v[204:205], v[120:121] op_sel_hi:[0,1,1]
	v_pk_fma_f32 v[206:207], v[154:155], v[206:207], v[122:123] op_sel_hi:[0,1,1]
	v_pk_fma_f32 v[208:209], v[154:155], v[208:209], v[124:125] op_sel_hi:[0,1,1]
	v_pk_fma_f32 v[210:211], v[154:155], v[210:211], v[126:127] op_sel_hi:[0,1,1]
	ds_read_b128 v[112:115], v194 offset:11264
	ds_read_b128 v[116:119], v194 offset:11520
	ds_read_b128 v[120:123], v194 offset:11776
	ds_read_b128 v[124:127], v194 offset:12032
	ds_read_b32 v156, v140 offset:35148
	ds_read_b32 v157, v190 offset:16576
	ds_read_b32 v154, v140 offset:35084
	s_waitcnt lgkmcnt(15)
	v_pk_fma_f32 v[128:129], v[96:97], v[196:197], v[214:215]
	v_pk_fma_f32 v[130:131], v[98:99], v[198:199], v[214:215]
	ds_read_b128 v[96:99], v194 offset:3072
	s_waitcnt lgkmcnt(15)
	v_pk_fma_f32 v[128:129], v[100:101], v[200:201], v[128:129]
	v_pk_fma_f32 v[130:131], v[102:103], v[202:203], v[130:131]
	ds_read_b128 v[100:103], v194 offset:3328
	s_waitcnt lgkmcnt(15)
	v_pk_fma_f32 v[128:129], v[104:105], v[204:205], v[128:129]
	v_pk_fma_f32 v[130:131], v[106:107], v[206:207], v[130:131]
	ds_read_b128 v[104:107], v194 offset:3584
	s_waitcnt lgkmcnt(15)
	v_pk_fma_f32 v[128:129], v[108:109], v[208:209], v[128:129]
	v_pk_fma_f32 v[130:131], v[110:111], v[210:211], v[130:131]
	ds_read_b128 v[108:111], v194 offset:3840
	v_add_f32_e32 v128, v128, v129
	v_add_f32_e32 v130, v130, v131
	v_add_f32_e32 v213, v128, v130
	s_waitcnt lgkmcnt(15)
	v_mul_f32_e32 v133, v134, v135
	v_pk_mul_f32 v[80:81], v[80:81], v[132:133] op_sel:[0,1] op_sel_hi:[1,1]
	v_add_f32_dpp v213, v213, v213 row_ror:8 row_mask:0xf bank_mask:0xf bound_ctrl:1
	v_pk_mul_f32 v[82:83], v[82:83], v[132:133] op_sel:[0,1] op_sel_hi:[1,1]
	v_pk_mul_f32 v[84:85], v[84:85], v[132:133] op_sel:[0,1] op_sel_hi:[1,1]
	v_add_f32_dpp v213, v213, v213 row_ror:4 row_mask:0xf bank_mask:0xf bound_ctrl:1
	v_pk_mul_f32 v[86:87], v[86:87], v[132:133] op_sel:[0,1] op_sel_hi:[1,1]
	v_pk_mul_f32 v[88:89], v[88:89], v[132:133] op_sel:[0,1] op_sel_hi:[1,1]
	v_add_f32_dpp v213, v213, v213 row_ror:2 row_mask:0xf bank_mask:0xf bound_ctrl:1
	v_pk_mul_f32 v[90:91], v[90:91], v[132:133] op_sel:[0,1] op_sel_hi:[1,1]
	v_pk_mul_f32 v[92:93], v[92:93], v[132:133] op_sel:[0,1] op_sel_hi:[1,1]
	v_add_f32_dpp v213, v213, v213 row_ror:1 row_mask:0xf bank_mask:0xf bound_ctrl:1
	v_pk_mul_f32 v[94:95], v[94:95], v[132:133] op_sel:[0,1] op_sel_hi:[1,1]
	v_pk_fma_f32 v[196:197], v[132:133], v[196:197], v[80:81] op_sel_hi:[0,1,1]
	s_and_saveexec_b64 s[8:9], s[44:45]
	ds_write_b32 v190, v213 offset:34112
	s_mov_b64 exec, s[8:9]
	v_pk_fma_f32 v[198:199], v[132:133], v[198:199], v[82:83] op_sel_hi:[0,1,1]
	v_pk_fma_f32 v[200:201], v[132:133], v[200:201], v[84:85] op_sel_hi:[0,1,1]
	v_pk_fma_f32 v[202:203], v[132:133], v[202:203], v[86:87] op_sel_hi:[0,1,1]
	v_pk_fma_f32 v[204:205], v[132:133], v[204:205], v[88:89] op_sel_hi:[0,1,1]
	v_pk_fma_f32 v[206:207], v[132:133], v[206:207], v[90:91] op_sel_hi:[0,1,1]
	v_pk_fma_f32 v[208:209], v[132:133], v[208:209], v[92:93] op_sel_hi:[0,1,1]
	v_pk_fma_f32 v[210:211], v[132:133], v[210:211], v[94:95] op_sel_hi:[0,1,1]
	ds_read_b128 v[80:83], v194 offset:12288
	ds_read_b128 v[84:87], v194 offset:12544
	ds_read_b128 v[88:91], v194 offset:12800
	ds_read_b128 v[92:95], v194 offset:13056
	ds_read_b32 v134, v140 offset:35152
	ds_read_b32 v135, v190 offset:16640
	ds_read_b32 v132, v140 offset:35088
	s_waitcnt lgkmcnt(15)
	v_pk_fma_f32 v[128:129], v[64:65], v[196:197], v[214:215]
	v_pk_fma_f32 v[130:131], v[66:67], v[198:199], v[214:215]
	ds_read_b128 v[64:67], v194 offset:4096
	s_waitcnt lgkmcnt(15)
	v_pk_fma_f32 v[128:129], v[68:69], v[200:201], v[128:129]
	v_pk_fma_f32 v[130:131], v[70:71], v[202:203], v[130:131]
	ds_read_b128 v[68:71], v194 offset:4352
	s_waitcnt lgkmcnt(15)
	v_pk_fma_f32 v[128:129], v[72:73], v[204:205], v[128:129]
	v_pk_fma_f32 v[130:131], v[74:75], v[206:207], v[130:131]
	ds_read_b128 v[72:75], v194 offset:4608
	s_waitcnt lgkmcnt(15)
	v_pk_fma_f32 v[128:129], v[76:77], v[208:209], v[128:129]
	v_pk_fma_f32 v[130:131], v[78:79], v[210:211], v[130:131]
	ds_read_b128 v[76:79], v194 offset:4864
	v_add_f32_e32 v128, v128, v129
	v_add_f32_e32 v130, v130, v131
	v_add_f32_e32 v212, v128, v130
	s_waitcnt lgkmcnt(15)
	v_mul_f32_e32 v155, v156, v157
	v_pk_mul_f32 v[112:113], v[112:113], v[154:155] op_sel:[0,1] op_sel_hi:[1,1]
	v_add_f32_dpp v212, v212, v212 row_ror:8 row_mask:0xf bank_mask:0xf bound_ctrl:1
	v_pk_mul_f32 v[114:115], v[114:115], v[154:155] op_sel:[0,1] op_sel_hi:[1,1]
	v_pk_mul_f32 v[116:117], v[116:117], v[154:155] op_sel:[0,1] op_sel_hi:[1,1]
	v_add_f32_dpp v212, v212, v212 row_ror:4 row_mask:0xf bank_mask:0xf bound_ctrl:1
	v_pk_mul_f32 v[118:119], v[118:119], v[154:155] op_sel:[0,1] op_sel_hi:[1,1]
	v_pk_mul_f32 v[120:121], v[120:121], v[154:155] op_sel:[0,1] op_sel_hi:[1,1]
	v_add_f32_dpp v212, v212, v212 row_ror:2 row_mask:0xf bank_mask:0xf bound_ctrl:1
	v_pk_mul_f32 v[122:123], v[122:123], v[154:155] op_sel:[0,1] op_sel_hi:[1,1]
	v_pk_mul_f32 v[124:125], v[124:125], v[154:155] op_sel:[0,1] op_sel_hi:[1,1]
	v_add_f32_dpp v212, v212, v212 row_ror:1 row_mask:0xf bank_mask:0xf bound_ctrl:1
	v_pk_mul_f32 v[126:127], v[126:127], v[154:155] op_sel:[0,1] op_sel_hi:[1,1]
	v_pk_fma_f32 v[196:197], v[154:155], v[196:197], v[112:113] op_sel_hi:[0,1,1]
	s_and_saveexec_b64 s[8:9], s[44:45]
	ds_write_b32 v190, v212 offset:34176
	s_mov_b64 exec, s[8:9]
	v_pk_fma_f32 v[198:199], v[154:155], v[198:199], v[114:115] op_sel_hi:[0,1,1]
	v_pk_fma_f32 v[200:201], v[154:155], v[200:201], v[116:117] op_sel_hi:[0,1,1]
	v_pk_fma_f32 v[202:203], v[154:155], v[202:203], v[118:119] op_sel_hi:[0,1,1]
	v_pk_fma_f32 v[204:205], v[154:155], v[204:205], v[120:121] op_sel_hi:[0,1,1]
	v_pk_fma_f32 v[206:207], v[154:155], v[206:207], v[122:123] op_sel_hi:[0,1,1]
	v_pk_fma_f32 v[208:209], v[154:155], v[208:209], v[124:125] op_sel_hi:[0,1,1]
	v_pk_fma_f32 v[210:211], v[154:155], v[210:211], v[126:127] op_sel_hi:[0,1,1]
	ds_read_b128 v[112:115], v194 offset:13312
	ds_read_b128 v[116:119], v194 offset:13568
	ds_read_b128 v[120:123], v194 offset:13824
	ds_read_b128 v[124:127], v194 offset:14080
	ds_read_b32 v156, v140 offset:35156
	ds_read_b32 v157, v190 offset:16704
	ds_read_b32 v154, v140 offset:35092
	s_waitcnt lgkmcnt(15)
	v_pk_fma_f32 v[128:129], v[96:97], v[196:197], v[214:215]
	v_pk_fma_f32 v[130:131], v[98:99], v[198:199], v[214:215]
	ds_read_b128 v[96:99], v194 offset:5120
	s_waitcnt lgkmcnt(15)
	v_pk_fma_f32 v[128:129], v[100:101], v[200:201], v[128:129]
	v_pk_fma_f32 v[130:131], v[102:103], v[202:203], v[130:131]
	ds_read_b128 v[100:103], v194 offset:5376
	s_waitcnt lgkmcnt(15)
	v_pk_fma_f32 v[128:129], v[104:105], v[204:205], v[128:129]
	v_pk_fma_f32 v[130:131], v[106:107], v[206:207], v[130:131]
	ds_read_b128 v[104:107], v194 offset:5632
	s_waitcnt lgkmcnt(15)
	v_pk_fma_f32 v[128:129], v[108:109], v[208:209], v[128:129]
	v_pk_fma_f32 v[130:131], v[110:111], v[210:211], v[130:131]
	ds_read_b128 v[108:111], v194 offset:5888
	v_add_f32_e32 v128, v128, v129
	v_add_f32_e32 v130, v130, v131
	v_add_f32_e32 v213, v128, v130
	s_waitcnt lgkmcnt(15)
	v_mul_f32_e32 v133, v134, v135
	v_pk_mul_f32 v[80:81], v[80:81], v[132:133] op_sel:[0,1] op_sel_hi:[1,1]
	v_add_f32_dpp v213, v213, v213 row_ror:8 row_mask:0xf bank_mask:0xf bound_ctrl:1
	v_pk_mul_f32 v[82:83], v[82:83], v[132:133] op_sel:[0,1] op_sel_hi:[1,1]
	v_pk_mul_f32 v[84:85], v[84:85], v[132:133] op_sel:[0,1] op_sel_hi:[1,1]
	v_add_f32_dpp v213, v213, v213 row_ror:4 row_mask:0xf bank_mask:0xf bound_ctrl:1
	v_pk_mul_f32 v[86:87], v[86:87], v[132:133] op_sel:[0,1] op_sel_hi:[1,1]
	v_pk_mul_f32 v[88:89], v[88:89], v[132:133] op_sel:[0,1] op_sel_hi:[1,1]
	v_add_f32_dpp v213, v213, v213 row_ror:2 row_mask:0xf bank_mask:0xf bound_ctrl:1
	v_pk_mul_f32 v[90:91], v[90:91], v[132:133] op_sel:[0,1] op_sel_hi:[1,1]
	v_pk_mul_f32 v[92:93], v[92:93], v[132:133] op_sel:[0,1] op_sel_hi:[1,1]
	v_add_f32_dpp v213, v213, v213 row_ror:1 row_mask:0xf bank_mask:0xf bound_ctrl:1
	v_pk_mul_f32 v[94:95], v[94:95], v[132:133] op_sel:[0,1] op_sel_hi:[1,1]
	v_pk_fma_f32 v[196:197], v[132:133], v[196:197], v[80:81] op_sel_hi:[0,1,1]
	s_and_saveexec_b64 s[8:9], s[44:45]
	ds_write_b32 v190, v213 offset:34240
	s_mov_b64 exec, s[8:9]
	v_pk_fma_f32 v[198:199], v[132:133], v[198:199], v[82:83] op_sel_hi:[0,1,1]
	v_pk_fma_f32 v[200:201], v[132:133], v[200:201], v[84:85] op_sel_hi:[0,1,1]
	v_pk_fma_f32 v[202:203], v[132:133], v[202:203], v[86:87] op_sel_hi:[0,1,1]
	v_pk_fma_f32 v[204:205], v[132:133], v[204:205], v[88:89] op_sel_hi:[0,1,1]
	v_pk_fma_f32 v[206:207], v[132:133], v[206:207], v[90:91] op_sel_hi:[0,1,1]
	v_pk_fma_f32 v[208:209], v[132:133], v[208:209], v[92:93] op_sel_hi:[0,1,1]
	v_pk_fma_f32 v[210:211], v[132:133], v[210:211], v[94:95] op_sel_hi:[0,1,1]
	ds_read_b128 v[80:83], v194 offset:14336
	ds_read_b128 v[84:87], v194 offset:14592
	ds_read_b128 v[88:91], v194 offset:14848
	ds_read_b128 v[92:95], v194 offset:15104
	ds_read_b32 v134, v140 offset:35160
	ds_read_b32 v135, v190 offset:16768
	ds_read_b32 v132, v140 offset:35096
	s_waitcnt lgkmcnt(15)
	v_pk_fma_f32 v[128:129], v[64:65], v[196:197], v[214:215]
	v_pk_fma_f32 v[130:131], v[66:67], v[198:199], v[214:215]
	ds_read_b128 v[64:67], v194 offset:6144
	s_waitcnt lgkmcnt(15)
	v_pk_fma_f32 v[128:129], v[68:69], v[200:201], v[128:129]
	v_pk_fma_f32 v[130:131], v[70:71], v[202:203], v[130:131]
	ds_read_b128 v[68:71], v194 offset:6400
	s_waitcnt lgkmcnt(15)
	v_pk_fma_f32 v[128:129], v[72:73], v[204:205], v[128:129]
	v_pk_fma_f32 v[130:131], v[74:75], v[206:207], v[130:131]
	ds_read_b128 v[72:75], v194 offset:6656
	s_waitcnt lgkmcnt(15)
	v_pk_fma_f32 v[128:129], v[76:77], v[208:209], v[128:129]
	v_pk_fma_f32 v[130:131], v[78:79], v[210:211], v[130:131]
	ds_read_b128 v[76:79], v194 offset:6912
	v_add_f32_e32 v128, v128, v129
	v_add_f32_e32 v130, v130, v131
	v_add_f32_e32 v212, v128, v130
	s_waitcnt lgkmcnt(15)
	v_mul_f32_e32 v155, v156, v157
	v_pk_mul_f32 v[112:113], v[112:113], v[154:155] op_sel:[0,1] op_sel_hi:[1,1]
	v_add_f32_dpp v212, v212, v212 row_ror:8 row_mask:0xf bank_mask:0xf bound_ctrl:1
	v_pk_mul_f32 v[114:115], v[114:115], v[154:155] op_sel:[0,1] op_sel_hi:[1,1]
	v_pk_mul_f32 v[116:117], v[116:117], v[154:155] op_sel:[0,1] op_sel_hi:[1,1]
	v_add_f32_dpp v212, v212, v212 row_ror:4 row_mask:0xf bank_mask:0xf bound_ctrl:1
	v_pk_mul_f32 v[118:119], v[118:119], v[154:155] op_sel:[0,1] op_sel_hi:[1,1]
	v_pk_mul_f32 v[120:121], v[120:121], v[154:155] op_sel:[0,1] op_sel_hi:[1,1]
	v_add_f32_dpp v212, v212, v212 row_ror:2 row_mask:0xf bank_mask:0xf bound_ctrl:1
	v_pk_mul_f32 v[122:123], v[122:123], v[154:155] op_sel:[0,1] op_sel_hi:[1,1]
	v_pk_mul_f32 v[124:125], v[124:125], v[154:155] op_sel:[0,1] op_sel_hi:[1,1]
	v_add_f32_dpp v212, v212, v212 row_ror:1 row_mask:0xf bank_mask:0xf bound_ctrl:1
	v_pk_mul_f32 v[126:127], v[126:127], v[154:155] op_sel:[0,1] op_sel_hi:[1,1]
	v_pk_fma_f32 v[196:197], v[154:155], v[196:197], v[112:113] op_sel_hi:[0,1,1]
	s_and_saveexec_b64 s[8:9], s[44:45]
	ds_write_b32 v190, v212 offset:34304
	s_mov_b64 exec, s[8:9]
	v_pk_fma_f32 v[198:199], v[154:155], v[198:199], v[114:115] op_sel_hi:[0,1,1]
	v_pk_fma_f32 v[200:201], v[154:155], v[200:201], v[116:117] op_sel_hi:[0,1,1]
	v_pk_fma_f32 v[202:203], v[154:155], v[202:203], v[118:119] op_sel_hi:[0,1,1]
	v_pk_fma_f32 v[204:205], v[154:155], v[204:205], v[120:121] op_sel_hi:[0,1,1]
	v_pk_fma_f32 v[206:207], v[154:155], v[206:207], v[122:123] op_sel_hi:[0,1,1]
	v_pk_fma_f32 v[208:209], v[154:155], v[208:209], v[124:125] op_sel_hi:[0,1,1]
	v_pk_fma_f32 v[210:211], v[154:155], v[210:211], v[126:127] op_sel_hi:[0,1,1]
	ds_read_b128 v[112:115], v194 offset:15360
	ds_read_b128 v[116:119], v194 offset:15616
	ds_read_b128 v[120:123], v194 offset:15872
	ds_read_b128 v[124:127], v194 offset:16128
	ds_read_b32 v156, v140 offset:35164
	ds_read_b32 v157, v190 offset:16832
	ds_read_b32 v154, v140 offset:35100
	s_waitcnt lgkmcnt(15)
	v_pk_fma_f32 v[128:129], v[96:97], v[196:197], v[214:215]
	v_pk_fma_f32 v[130:131], v[98:99], v[198:199], v[214:215]
	ds_read_b128 v[96:99], v194 offset:7168
	s_waitcnt lgkmcnt(15)
	v_pk_fma_f32 v[128:129], v[100:101], v[200:201], v[128:129]
	v_pk_fma_f32 v[130:131], v[102:103], v[202:203], v[130:131]
	ds_read_b128 v[100:103], v194 offset:7424
	s_waitcnt lgkmcnt(15)
	v_pk_fma_f32 v[128:129], v[104:105], v[204:205], v[128:129]
	v_pk_fma_f32 v[130:131], v[106:107], v[206:207], v[130:131]
	ds_read_b128 v[104:107], v194 offset:7680
	s_waitcnt lgkmcnt(15)
	v_pk_fma_f32 v[128:129], v[108:109], v[208:209], v[128:129]
	v_pk_fma_f32 v[130:131], v[110:111], v[210:211], v[130:131]
	ds_read_b128 v[108:111], v194 offset:7936
	v_add_f32_e32 v128, v128, v129
	v_add_f32_e32 v130, v130, v131
	v_add_f32_e32 v213, v128, v130
	s_waitcnt lgkmcnt(15)
	v_mul_f32_e32 v133, v134, v135
	v_pk_mul_f32 v[80:81], v[80:81], v[132:133] op_sel:[0,1] op_sel_hi:[1,1]
	v_add_f32_dpp v213, v213, v213 row_ror:8 row_mask:0xf bank_mask:0xf bound_ctrl:1
	v_pk_mul_f32 v[82:83], v[82:83], v[132:133] op_sel:[0,1] op_sel_hi:[1,1]
	v_pk_mul_f32 v[84:85], v[84:85], v[132:133] op_sel:[0,1] op_sel_hi:[1,1]
	v_add_f32_dpp v213, v213, v213 row_ror:4 row_mask:0xf bank_mask:0xf bound_ctrl:1
	v_pk_mul_f32 v[86:87], v[86:87], v[132:133] op_sel:[0,1] op_sel_hi:[1,1]
	v_pk_mul_f32 v[88:89], v[88:89], v[132:133] op_sel:[0,1] op_sel_hi:[1,1]
	v_add_f32_dpp v213, v213, v213 row_ror:2 row_mask:0xf bank_mask:0xf bound_ctrl:1
	v_pk_mul_f32 v[90:91], v[90:91], v[132:133] op_sel:[0,1] op_sel_hi:[1,1]
	v_pk_mul_f32 v[92:93], v[92:93], v[132:133] op_sel:[0,1] op_sel_hi:[1,1]
	v_add_f32_dpp v213, v213, v213 row_ror:1 row_mask:0xf bank_mask:0xf bound_ctrl:1
	v_pk_mul_f32 v[94:95], v[94:95], v[132:133] op_sel:[0,1] op_sel_hi:[1,1]
	v_pk_fma_f32 v[196:197], v[132:133], v[196:197], v[80:81] op_sel_hi:[0,1,1]
	s_and_saveexec_b64 s[8:9], s[44:45]
	ds_write_b32 v190, v213 offset:34368
	s_mov_b64 exec, s[8:9]
	v_pk_fma_f32 v[198:199], v[132:133], v[198:199], v[82:83] op_sel_hi:[0,1,1]
	v_pk_fma_f32 v[200:201], v[132:133], v[200:201], v[84:85] op_sel_hi:[0,1,1]
	v_pk_fma_f32 v[202:203], v[132:133], v[202:203], v[86:87] op_sel_hi:[0,1,1]
	v_pk_fma_f32 v[204:205], v[132:133], v[204:205], v[88:89] op_sel_hi:[0,1,1]
	v_pk_fma_f32 v[206:207], v[132:133], v[206:207], v[90:91] op_sel_hi:[0,1,1]
	v_pk_fma_f32 v[208:209], v[132:133], v[208:209], v[92:93] op_sel_hi:[0,1,1]
	v_pk_fma_f32 v[210:211], v[132:133], v[210:211], v[94:95] op_sel_hi:[0,1,1]
	s_waitcnt lgkmcnt(15)
	v_pk_fma_f32 v[128:129], v[64:65], v[196:197], v[214:215]
	v_pk_fma_f32 v[130:131], v[66:67], v[198:199], v[214:215]
	v_pk_fma_f32 v[128:129], v[68:69], v[200:201], v[128:129]
	v_pk_fma_f32 v[130:131], v[70:71], v[202:203], v[130:131]
	s_waitcnt lgkmcnt(14)
	v_pk_fma_f32 v[128:129], v[72:73], v[204:205], v[128:129]
	v_pk_fma_f32 v[130:131], v[74:75], v[206:207], v[130:131]
	s_waitcnt lgkmcnt(13)
	v_pk_fma_f32 v[128:129], v[76:77], v[208:209], v[128:129]
	v_pk_fma_f32 v[130:131], v[78:79], v[210:211], v[130:131]
	v_add_f32_e32 v128, v128, v129
	v_add_f32_e32 v130, v130, v131
	v_add_f32_e32 v212, v128, v130
	s_waitcnt lgkmcnt(6)
	v_mul_f32_e32 v155, v156, v157
	v_pk_mul_f32 v[112:113], v[112:113], v[154:155] op_sel:[0,1] op_sel_hi:[1,1]
	v_add_f32_dpp v212, v212, v212 row_ror:8 row_mask:0xf bank_mask:0xf bound_ctrl:1
	v_pk_mul_f32 v[114:115], v[114:115], v[154:155] op_sel:[0,1] op_sel_hi:[1,1]
	v_pk_mul_f32 v[116:117], v[116:117], v[154:155] op_sel:[0,1] op_sel_hi:[1,1]
	v_add_f32_dpp v212, v212, v212 row_ror:4 row_mask:0xf bank_mask:0xf bound_ctrl:1
	v_pk_mul_f32 v[118:119], v[118:119], v[154:155] op_sel:[0,1] op_sel_hi:[1,1]
	v_pk_mul_f32 v[120:121], v[120:121], v[154:155] op_sel:[0,1] op_sel_hi:[1,1]
	v_add_f32_dpp v212, v212, v212 row_ror:2 row_mask:0xf bank_mask:0xf bound_ctrl:1
	v_pk_mul_f32 v[122:123], v[122:123], v[154:155] op_sel:[0,1] op_sel_hi:[1,1]
	v_pk_mul_f32 v[124:125], v[124:125], v[154:155] op_sel:[0,1] op_sel_hi:[1,1]
	v_add_f32_dpp v212, v212, v212 row_ror:1 row_mask:0xf bank_mask:0xf bound_ctrl:1
	v_pk_mul_f32 v[126:127], v[126:127], v[154:155] op_sel:[0,1] op_sel_hi:[1,1]
	s_waitcnt lgkmcnt(5)
	v_pk_fma_f32 v[196:197], v[154:155], v[196:197], v[112:113] op_sel_hi:[0,1,1]
	s_and_saveexec_b64 s[8:9], s[44:45]
	ds_write_b32 v190, v212 offset:34432
	s_mov_b64 exec, s[8:9]
	v_pk_fma_f32 v[198:199], v[154:155], v[198:199], v[114:115] op_sel_hi:[0,1,1]
	v_pk_fma_f32 v[200:201], v[154:155], v[200:201], v[116:117] op_sel_hi:[0,1,1]
	v_pk_fma_f32 v[202:203], v[154:155], v[202:203], v[118:119] op_sel_hi:[0,1,1]
	v_pk_fma_f32 v[204:205], v[154:155], v[204:205], v[120:121] op_sel_hi:[0,1,1]
	v_pk_fma_f32 v[206:207], v[154:155], v[206:207], v[122:123] op_sel_hi:[0,1,1]
	v_pk_fma_f32 v[208:209], v[154:155], v[208:209], v[124:125] op_sel_hi:[0,1,1]
	v_pk_fma_f32 v[210:211], v[154:155], v[210:211], v[126:127] op_sel_hi:[0,1,1]
	s_waitcnt lgkmcnt(5)
	v_pk_fma_f32 v[128:129], v[96:97], v[196:197], v[214:215]
	v_pk_fma_f32 v[130:131], v[98:99], v[198:199], v[214:215]
	s_waitcnt lgkmcnt(4)
	v_pk_fma_f32 v[128:129], v[100:101], v[200:201], v[128:129]
	v_pk_fma_f32 v[130:131], v[102:103], v[202:203], v[130:131]
	s_waitcnt lgkmcnt(3)
	v_pk_fma_f32 v[128:129], v[104:105], v[204:205], v[128:129]
	v_pk_fma_f32 v[130:131], v[106:107], v[206:207], v[130:131]
	s_waitcnt lgkmcnt(2)
	v_pk_fma_f32 v[128:129], v[108:109], v[208:209], v[128:129]
	v_pk_fma_f32 v[130:131], v[110:111], v[210:211], v[130:131]
	v_add_f32_e32 v128, v128, v129
	v_add_f32_e32 v130, v130, v131
	v_add_f32_e32 v213, v128, v130
	s_nop 1
	v_add_f32_dpp v213, v213, v213 row_ror:8 row_mask:0xf bank_mask:0xf bound_ctrl:1
	s_nop 1
	v_add_f32_dpp v213, v213, v213 row_ror:4 row_mask:0xf bank_mask:0xf bound_ctrl:1
	s_nop 1
	v_add_f32_dpp v213, v213, v213 row_ror:2 row_mask:0xf bank_mask:0xf bound_ctrl:1
	s_nop 1
	v_add_f32_dpp v213, v213, v213 row_ror:1 row_mask:0xf bank_mask:0xf bound_ctrl:1
	s_and_saveexec_b64 s[8:9], s[44:45]
	ds_write_b32 v190, v213 offset:34496
	s_mov_b64 exec, s[8:9]
	s_waitcnt vmcnt(3)
	ds_write_b128 v188, v[48:51] offset:17024
	s_waitcnt vmcnt(1)
	ds_write_b128 v191, v[56:59] offset:17024
	ds_write_b128 v188, v[52:55] offset:25216
	s_waitcnt vmcnt(0)
	ds_write_b128 v191, v[60:63] offset:25216
	s_and_saveexec_b64 s[8:9], s[40:41]
	ds_write_b32 v145, v192 offset:33408
	s_or_b64 exec, exec, s[8:9]
	s_and_saveexec_b64 s[8:9], s[42:43]
	s_cbranch_execz .LBB0_1242
	v_add_f32_e32 v64, v178, v195
	v_mul_f32_e64 v65, |v64|, s62
	v_exp_f32_e32 v65, v65
	v_min_f32_e32 v64, 0, v64
	v_add_f32_e32 v65, 1.0, v65
	v_cmp_gt_f32_e32 vcc, s5, v65
	s_nop 1
	v_cndmask_b32_e64 v66, 0, 32, vcc
	v_ldexp_f32 v65, v65, v66
	v_log_f32_e32 v65, v65
	v_cndmask_b32_e32 v67, 0, v171, vcc
	v_add_f32_e32 v66, v147, v193
	v_mul_f32_e32 v68, 0x3f317217, v65
	v_fma_f32 v68, v65, s76, -v68
	v_fmac_f32_e32 v68, 0x3377d1cf, v65
	v_fmac_f32_e32 v68, 0x3f317217, v65
	v_cmp_lt_f32_e64 vcc, |v65|, s77
	s_nop 1
	v_cndmask_b32_e32 v65, v65, v68, vcc
	v_sub_f32_e32 v65, v65, v67
	v_sub_f32_e32 v64, v64, v65
	v_add_u32_e32 v65, 0x8400, v145
	ds_write2_b32 v65, v66, v64 offset0:32 offset1:48

.LBB0_1255:
	s_or_b64 exec, exec, s[8:9]
	s_waitcnt lgkmcnt(0)
	s_barrier
	v_mov_b32_e32 v214, 0
	v_mov_b32_e32 v215, 0
	ds_read_b128 v[80:83], v194 offset:25216
	ds_read_b128 v[84:87], v194 offset:25472
	ds_read_b128 v[88:91], v194 offset:25728
	ds_read_b128 v[92:95], v194 offset:25984
	ds_read_b32 v134, v140 offset:35136
	ds_read_b32 v135, v190 offset:33408
	ds_read_b32 v132, v140 offset:35072
	ds_read_b128 v[64:67], v194 offset:17024
	ds_read_b128 v[68:71], v194 offset:17280
	ds_read_b128 v[72:75], v194 offset:17536
	ds_read_b128 v[76:79], v194 offset:17792
	ds_read_b128 v[112:115], v194 offset:26240
	ds_read_b128 v[116:119], v194 offset:26496
	ds_read_b128 v[120:123], v194 offset:26752
	ds_read_b128 v[124:127], v194 offset:27008
	ds_read_b32 v156, v140 offset:35140
	ds_read_b32 v157, v190 offset:33472
	ds_read_b32 v154, v140 offset:35076
	ds_read_b128 v[96:99], v194 offset:18048
	ds_read_b128 v[100:103], v194 offset:18304
	ds_read_b128 v[104:107], v194 offset:18560
	ds_read_b128 v[108:111], v194 offset:18816
	s_waitcnt lgkmcnt(15)
	v_mul_f32_e32 v133, v134, v135
	v_pk_mul_f32 v[80:81], v[80:81], v[132:133] op_sel:[0,1] op_sel_hi:[1,1]
	v_pk_mul_f32 v[82:83], v[82:83], v[132:133] op_sel:[0,1] op_sel_hi:[1,1]
	v_pk_mul_f32 v[84:85], v[84:85], v[132:133] op_sel:[0,1] op_sel_hi:[1,1]
	v_pk_mul_f32 v[86:87], v[86:87], v[132:133] op_sel:[0,1] op_sel_hi:[1,1]
	v_pk_mul_f32 v[88:89], v[88:89], v[132:133] op_sel:[0,1] op_sel_hi:[1,1]
	v_pk_mul_f32 v[90:91], v[90:91], v[132:133] op_sel:[0,1] op_sel_hi:[1,1]
	v_pk_mul_f32 v[92:93], v[92:93], v[132:133] op_sel:[0,1] op_sel_hi:[1,1]
	v_pk_mul_f32 v[94:95], v[94:95], v[132:133] op_sel:[0,1] op_sel_hi:[1,1]
	v_pk_fma_f32 v[196:197], v[132:133], v[196:197], v[80:81] op_sel_hi:[0,1,1]
	v_pk_fma_f32 v[198:199], v[132:133], v[198:199], v[82:83] op_sel_hi:[0,1,1]
	v_pk_fma_f32 v[200:201], v[132:133], v[200:201], v[84:85] op_sel_hi:[0,1,1]
	v_pk_fma_f32 v[202:203], v[132:133], v[202:203], v[86:87] op_sel_hi:[0,1,1]
	v_pk_fma_f32 v[204:205], v[132:133], v[204:205], v[88:89] op_sel_hi:[0,1,1]
	v_pk_fma_f32 v[206:207], v[132:133], v[206:207], v[90:91] op_sel_hi:[0,1,1]
	v_pk_fma_f32 v[208:209], v[132:133], v[208:209], v[92:93] op_sel_hi:[0,1,1]
	v_pk_fma_f32 v[210:211], v[132:133], v[210:211], v[94:95] op_sel_hi:[0,1,1]
	ds_read_b128 v[80:83], v194 offset:27264
	ds_read_b128 v[84:87], v194 offset:27520
	ds_read_b128 v[88:91], v194 offset:27776
	ds_read_b128 v[92:95], v194 offset:28032
	ds_read_b32 v134, v140 offset:35144
	ds_read_b32 v135, v190 offset:33536
	ds_read_b32 v132, v140 offset:35080
	s_waitcnt lgkmcnt(15)
	v_pk_fma_f32 v[128:129], v[64:65], v[196:197], v[214:215]
	v_pk_fma_f32 v[130:131], v[66:67], v[198:199], v[214:215]
	ds_read_b128 v[64:67], v194 offset:19072
	s_waitcnt lgkmcnt(15)
	v_pk_fma_f32 v[128:129], v[68:69], v[200:201], v[128:129]
	v_pk_fma_f32 v[130:131], v[70:71], v[202:203], v[130:131]
	ds_read_b128 v[68:71], v194 offset:19328
	s_waitcnt lgkmcnt(15)
	v_pk_fma_f32 v[128:129], v[72:73], v[204:205], v[128:129]
	v_pk_fma_f32 v[130:131], v[74:75], v[206:207], v[130:131]
	ds_read_b128 v[72:75], v194 offset:19584
	s_waitcnt lgkmcnt(15)
	v_pk_fma_f32 v[128:129], v[76:77], v[208:209], v[128:129]
	v_pk_fma_f32 v[130:131], v[78:79], v[210:211], v[130:131]
	ds_read_b128 v[76:79], v194 offset:19840
	v_add_f32_e32 v128, v128, v129
	v_add_f32_e32 v130, v130, v131
	v_add_f32_e32 v212, v128, v130
	s_waitcnt lgkmcnt(15)
	v_mul_f32_e32 v155, v156, v157
	v_pk_mul_f32 v[112:113], v[112:113], v[154:155] op_sel:[0,1] op_sel_hi:[1,1]
	v_add_f32_dpp v212, v212, v212 row_ror:8 row_mask:0xf bank_mask:0xf bound_ctrl:1
	v_pk_mul_f32 v[114:115], v[114:115], v[154:155] op_sel:[0,1] op_sel_hi:[1,1]
	v_pk_mul_f32 v[116:117], v[116:117], v[154:155] op_sel:[0,1] op_sel_hi:[1,1]
	v_add_f32_dpp v212, v212, v212 row_ror:4 row_mask:0xf bank_mask:0xf bound_ctrl:1
	v_pk_mul_f32 v[118:119], v[118:119], v[154:155] op_sel:[0,1] op_sel_hi:[1,1]
	v_pk_mul_f32 v[120:121], v[120:121], v[154:155] op_sel:[0,1] op_sel_hi:[1,1]
	v_add_f32_dpp v212, v212, v212 row_ror:2 row_mask:0xf bank_mask:0xf bound_ctrl:1
	v_pk_mul_f32 v[122:123], v[122:123], v[154:155] op_sel:[0,1] op_sel_hi:[1,1]
	v_pk_mul_f32 v[124:125], v[124:125], v[154:155] op_sel:[0,1] op_sel_hi:[1,1]
	v_add_f32_dpp v212, v212, v212 row_ror:1 row_mask:0xf bank_mask:0xf bound_ctrl:1
	v_pk_mul_f32 v[126:127], v[126:127], v[154:155] op_sel:[0,1] op_sel_hi:[1,1]
	v_pk_fma_f32 v[196:197], v[154:155], v[196:197], v[112:113] op_sel_hi:[0,1,1]
	s_and_saveexec_b64 s[8:9], s[44:45]
	ds_write_b32 v190, v212 offset:34560
	s_mov_b64 exec, s[8:9]
	v_pk_fma_f32 v[198:199], v[154:155], v[198:199], v[114:115] op_sel_hi:[0,1,1]
	v_pk_fma_f32 v[200:201], v[154:155], v[200:201], v[116:117] op_sel_hi:[0,1,1]
	v_pk_fma_f32 v[202:203], v[154:155], v[202:203], v[118:119] op_sel_hi:[0,1,1]
	v_pk_fma_f32 v[204:205], v[154:155], v[204:205], v[120:121] op_sel_hi:[0,1,1]
	v_pk_fma_f32 v[206:207], v[154:155], v[206:207], v[122:123] op_sel_hi:[0,1,1]
	v_pk_fma_f32 v[208:209], v[154:155], v[208:209], v[124:125] op_sel_hi:[0,1,1]
	v_pk_fma_f32 v[210:211], v[154:155], v[210:211], v[126:127] op_sel_hi:[0,1,1]
	ds_read_b128 v[112:115], v194 offset:28288
	ds_read_b128 v[116:119], v194 offset:28544
	ds_read_b128 v[120:123], v194 offset:28800
	ds_read_b128 v[124:127], v194 offset:29056
	ds_read_b32 v156, v140 offset:35148
	ds_read_b32 v157, v190 offset:33600
	ds_read_b32 v154, v140 offset:35084
	s_waitcnt lgkmcnt(15)
	v_pk_fma_f32 v[128:129], v[96:97], v[196:197], v[214:215]
	v_pk_fma_f32 v[130:131], v[98:99], v[198:199], v[214:215]
	ds_read_b128 v[96:99], v194 offset:20096
	s_waitcnt lgkmcnt(15)
	v_pk_fma_f32 v[128:129], v[100:101], v[200:201], v[128:129]
	v_pk_fma_f32 v[130:131], v[102:103], v[202:203], v[130:131]
	ds_read_b128 v[100:103], v194 offset:20352
	s_waitcnt lgkmcnt(15)
	v_pk_fma_f32 v[128:129], v[104:105], v[204:205], v[128:129]
	v_pk_fma_f32 v[130:131], v[106:107], v[206:207], v[130:131]
	ds_read_b128 v[104:107], v194 offset:20608
	s_waitcnt lgkmcnt(15)
	v_pk_fma_f32 v[128:129], v[108:109], v[208:209], v[128:129]
	v_pk_fma_f32 v[130:131], v[110:111], v[210:211], v[130:131]
	ds_read_b128 v[108:111], v194 offset:20864
	v_add_f32_e32 v128, v128, v129
	v_add_f32_e32 v130, v130, v131
	v_add_f32_e32 v213, v128, v130
	s_waitcnt lgkmcnt(15)
	v_mul_f32_e32 v133, v134, v135
	v_pk_mul_f32 v[80:81], v[80:81], v[132:133] op_sel:[0,1] op_sel_hi:[1,1]
	v_add_f32_dpp v213, v213, v213 row_ror:8 row_mask:0xf bank_mask:0xf bound_ctrl:1
	v_pk_mul_f32 v[82:83], v[82:83], v[132:133] op_sel:[0,1] op_sel_hi:[1,1]
	v_pk_mul_f32 v[84:85], v[84:85], v[132:133] op_sel:[0,1] op_sel_hi:[1,1]
	v_add_f32_dpp v213, v213, v213 row_ror:4 row_mask:0xf bank_mask:0xf bound_ctrl:1
	v_pk_mul_f32 v[86:87], v[86:87], v[132:133] op_sel:[0,1] op_sel_hi:[1,1]
	v_pk_mul_f32 v[88:89], v[88:89], v[132:133] op_sel:[0,1] op_sel_hi:[1,1]
	v_add_f32_dpp v213, v213, v213 row_ror:2 row_mask:0xf bank_mask:0xf bound_ctrl:1
	v_pk_mul_f32 v[90:91], v[90:91], v[132:133] op_sel:[0,1] op_sel_hi:[1,1]
	v_pk_mul_f32 v[92:93], v[92:93], v[132:133] op_sel:[0,1] op_sel_hi:[1,1]
	v_add_f32_dpp v213, v213, v213 row_ror:1 row_mask:0xf bank_mask:0xf bound_ctrl:1
	v_pk_mul_f32 v[94:95], v[94:95], v[132:133] op_sel:[0,1] op_sel_hi:[1,1]
	v_pk_fma_f32 v[196:197], v[132:133], v[196:197], v[80:81] op_sel_hi:[0,1,1]
	s_and_saveexec_b64 s[8:9], s[44:45]
	ds_write_b32 v190, v213 offset:34624
	s_mov_b64 exec, s[8:9]
	v_pk_fma_f32 v[198:199], v[132:133], v[198:199], v[82:83] op_sel_hi:[0,1,1]
	v_pk_fma_f32 v[200:201], v[132:133], v[200:201], v[84:85] op_sel_hi:[0,1,1]
	v_pk_fma_f32 v[202:203], v[132:133], v[202:203], v[86:87] op_sel_hi:[0,1,1]
	v_pk_fma_f32 v[204:205], v[132:133], v[204:205], v[88:89] op_sel_hi:[0,1,1]
	v_pk_fma_f32 v[206:207], v[132:133], v[206:207], v[90:91] op_sel_hi:[0,1,1]
	v_pk_fma_f32 v[208:209], v[132:133], v[208:209], v[92:93] op_sel_hi:[0,1,1]
	v_pk_fma_f32 v[210:211], v[132:133], v[210:211], v[94:95] op_sel_hi:[0,1,1]
	ds_read_b128 v[80:83], v194 offset:29312
	ds_read_b128 v[84:87], v194 offset:29568
	ds_read_b128 v[88:91], v194 offset:29824
	ds_read_b128 v[92:95], v194 offset:30080
	ds_read_b32 v134, v140 offset:35152
	ds_read_b32 v135, v190 offset:33664
	ds_read_b32 v132, v140 offset:35088
	s_waitcnt lgkmcnt(15)
	v_pk_fma_f32 v[128:129], v[64:65], v[196:197], v[214:215]
	v_pk_fma_f32 v[130:131], v[66:67], v[198:199], v[214:215]
	ds_read_b128 v[64:67], v194 offset:21120
	s_waitcnt lgkmcnt(15)
	v_pk_fma_f32 v[128:129], v[68:69], v[200:201], v[128:129]
	v_pk_fma_f32 v[130:131], v[70:71], v[202:203], v[130:131]
	ds_read_b128 v[68:71], v194 offset:21376
	s_waitcnt lgkmcnt(15)
	v_pk_fma_f32 v[128:129], v[72:73], v[204:205], v[128:129]
	v_pk_fma_f32 v[130:131], v[74:75], v[206:207], v[130:131]
	ds_read_b128 v[72:75], v194 offset:21632
	s_waitcnt lgkmcnt(15)
	v_pk_fma_f32 v[128:129], v[76:77], v[208:209], v[128:129]
	v_pk_fma_f32 v[130:131], v[78:79], v[210:211], v[130:131]
	ds_read_b128 v[76:79], v194 offset:21888
	v_add_f32_e32 v128, v128, v129
	v_add_f32_e32 v130, v130, v131
	v_add_f32_e32 v212, v128, v130
	s_waitcnt lgkmcnt(15)
	v_mul_f32_e32 v155, v156, v157
	v_pk_mul_f32 v[112:113], v[112:113], v[154:155] op_sel:[0,1] op_sel_hi:[1,1]
	v_add_f32_dpp v212, v212, v212 row_ror:8 row_mask:0xf bank_mask:0xf bound_ctrl:1
	v_pk_mul_f32 v[114:115], v[114:115], v[154:155] op_sel:[0,1] op_sel_hi:[1,1]
	v_pk_mul_f32 v[116:117], v[116:117], v[154:155] op_sel:[0,1] op_sel_hi:[1,1]
	v_add_f32_dpp v212, v212, v212 row_ror:4 row_mask:0xf bank_mask:0xf bound_ctrl:1
	v_pk_mul_f32 v[118:119], v[118:119], v[154:155] op_sel:[0,1] op_sel_hi:[1,1]
	v_pk_mul_f32 v[120:121], v[120:121], v[154:155] op_sel:[0,1] op_sel_hi:[1,1]
	v_add_f32_dpp v212, v212, v212 row_ror:2 row_mask:0xf bank_mask:0xf bound_ctrl:1
	v_pk_mul_f32 v[122:123], v[122:123], v[154:155] op_sel:[0,1] op_sel_hi:[1,1]
	v_pk_mul_f32 v[124:125], v[124:125], v[154:155] op_sel:[0,1] op_sel_hi:[1,1]
	v_add_f32_dpp v212, v212, v212 row_ror:1 row_mask:0xf bank_mask:0xf bound_ctrl:1
	v_pk_mul_f32 v[126:127], v[126:127], v[154:155] op_sel:[0,1] op_sel_hi:[1,1]
	v_pk_fma_f32 v[196:197], v[154:155], v[196:197], v[112:113] op_sel_hi:[0,1,1]
	s_and_saveexec_b64 s[8:9], s[44:45]
	ds_write_b32 v190, v212 offset:34688
	s_mov_b64 exec, s[8:9]
	v_pk_fma_f32 v[198:199], v[154:155], v[198:199], v[114:115] op_sel_hi:[0,1,1]
	v_pk_fma_f32 v[200:201], v[154:155], v[200:201], v[116:117] op_sel_hi:[0,1,1]
	v_pk_fma_f32 v[202:203], v[154:155], v[202:203], v[118:119] op_sel_hi:[0,1,1]
	v_pk_fma_f32 v[204:205], v[154:155], v[204:205], v[120:121] op_sel_hi:[0,1,1]
	v_pk_fma_f32 v[206:207], v[154:155], v[206:207], v[122:123] op_sel_hi:[0,1,1]
	v_pk_fma_f32 v[208:209], v[154:155], v[208:209], v[124:125] op_sel_hi:[0,1,1]
	v_pk_fma_f32 v[210:211], v[154:155], v[210:211], v[126:127] op_sel_hi:[0,1,1]
	ds_read_b128 v[112:115], v194 offset:30336
	ds_read_b128 v[116:119], v194 offset:30592
	ds_read_b128 v[120:123], v194 offset:30848
	ds_read_b128 v[124:127], v194 offset:31104
	ds_read_b32 v156, v140 offset:35156
	ds_read_b32 v157, v190 offset:33728
	ds_read_b32 v154, v140 offset:35092
	s_waitcnt lgkmcnt(15)
	v_pk_fma_f32 v[128:129], v[96:97], v[196:197], v[214:215]
	v_pk_fma_f32 v[130:131], v[98:99], v[198:199], v[214:215]
	ds_read_b128 v[96:99], v194 offset:22144
	s_waitcnt lgkmcnt(15)
	v_pk_fma_f32 v[128:129], v[100:101], v[200:201], v[128:129]
	v_pk_fma_f32 v[130:131], v[102:103], v[202:203], v[130:131]
	ds_read_b128 v[100:103], v194 offset:22400
	s_waitcnt lgkmcnt(15)
	v_pk_fma_f32 v[128:129], v[104:105], v[204:205], v[128:129]
	v_pk_fma_f32 v[130:131], v[106:107], v[206:207], v[130:131]
	ds_read_b128 v[104:107], v194 offset:22656
	s_waitcnt lgkmcnt(15)
	v_pk_fma_f32 v[128:129], v[108:109], v[208:209], v[128:129]
	v_pk_fma_f32 v[130:131], v[110:111], v[210:211], v[130:131]
	ds_read_b128 v[108:111], v194 offset:22912
	v_add_f32_e32 v128, v128, v129
	v_add_f32_e32 v130, v130, v131
	v_add_f32_e32 v213, v128, v130
	s_waitcnt lgkmcnt(15)
	v_mul_f32_e32 v133, v134, v135
	v_pk_mul_f32 v[80:81], v[80:81], v[132:133] op_sel:[0,1] op_sel_hi:[1,1]
	v_add_f32_dpp v213, v213, v213 row_ror:8 row_mask:0xf bank_mask:0xf bound_ctrl:1
	v_pk_mul_f32 v[82:83], v[82:83], v[132:133] op_sel:[0,1] op_sel_hi:[1,1]
	v_pk_mul_f32 v[84:85], v[84:85], v[132:133] op_sel:[0,1] op_sel_hi:[1,1]
	v_add_f32_dpp v213, v213, v213 row_ror:4 row_mask:0xf bank_mask:0xf bound_ctrl:1
	v_pk_mul_f32 v[86:87], v[86:87], v[132:133] op_sel:[0,1] op_sel_hi:[1,1]
	v_pk_mul_f32 v[88:89], v[88:89], v[132:133] op_sel:[0,1] op_sel_hi:[1,1]
	v_add_f32_dpp v213, v213, v213 row_ror:2 row_mask:0xf bank_mask:0xf bound_ctrl:1
	v_pk_mul_f32 v[90:91], v[90:91], v[132:133] op_sel:[0,1] op_sel_hi:[1,1]
	v_pk_mul_f32 v[92:93], v[92:93], v[132:133] op_sel:[0,1] op_sel_hi:[1,1]
	v_add_f32_dpp v213, v213, v213 row_ror:1 row_mask:0xf bank_mask:0xf bound_ctrl:1
	v_pk_mul_f32 v[94:95], v[94:95], v[132:133] op_sel:[0,1] op_sel_hi:[1,1]
	v_pk_fma_f32 v[196:197], v[132:133], v[196:197], v[80:81] op_sel_hi:[0,1,1]
	s_and_saveexec_b64 s[8:9], s[44:45]
	ds_write_b32 v190, v213 offset:34752
	s_mov_b64 exec, s[8:9]
	v_pk_fma_f32 v[198:199], v[132:133], v[198:199], v[82:83] op_sel_hi:[0,1,1]
	v_pk_fma_f32 v[200:201], v[132:133], v[200:201], v[84:85] op_sel_hi:[0,1,1]
	v_pk_fma_f32 v[202:203], v[132:133], v[202:203], v[86:87] op_sel_hi:[0,1,1]
	v_pk_fma_f32 v[204:205], v[132:133], v[204:205], v[88:89] op_sel_hi:[0,1,1]
	v_pk_fma_f32 v[206:207], v[132:133], v[206:207], v[90:91] op_sel_hi:[0,1,1]
	v_pk_fma_f32 v[208:209], v[132:133], v[208:209], v[92:93] op_sel_hi:[0,1,1]
	v_pk_fma_f32 v[210:211], v[132:133], v[210:211], v[94:95] op_sel_hi:[0,1,1]
	ds_read_b128 v[80:83], v194 offset:31360
	ds_read_b128 v[84:87], v194 offset:31616
	ds_read_b128 v[88:91], v194 offset:31872
	ds_read_b128 v[92:95], v194 offset:32128
	ds_read_b32 v134, v140 offset:35160
	ds_read_b32 v135, v190 offset:33792
	ds_read_b32 v132, v140 offset:35096
	s_waitcnt lgkmcnt(15)
	v_pk_fma_f32 v[128:129], v[64:65], v[196:197], v[214:215]
	v_pk_fma_f32 v[130:131], v[66:67], v[198:199], v[214:215]
	ds_read_b128 v[64:67], v194 offset:23168
	s_waitcnt lgkmcnt(15)
	v_pk_fma_f32 v[128:129], v[68:69], v[200:201], v[128:129]
	v_pk_fma_f32 v[130:131], v[70:71], v[202:203], v[130:131]
	ds_read_b128 v[68:71], v194 offset:23424
	s_waitcnt lgkmcnt(15)
	v_pk_fma_f32 v[128:129], v[72:73], v[204:205], v[128:129]
	v_pk_fma_f32 v[130:131], v[74:75], v[206:207], v[130:131]
	ds_read_b128 v[72:75], v194 offset:23680
	s_waitcnt lgkmcnt(15)
	v_pk_fma_f32 v[128:129], v[76:77], v[208:209], v[128:129]
	v_pk_fma_f32 v[130:131], v[78:79], v[210:211], v[130:131]
	ds_read_b128 v[76:79], v194 offset:23936
	v_add_f32_e32 v128, v128, v129
	v_add_f32_e32 v130, v130, v131
	v_add_f32_e32 v212, v128, v130
	s_waitcnt lgkmcnt(15)
	v_mul_f32_e32 v155, v156, v157
	v_pk_mul_f32 v[112:113], v[112:113], v[154:155] op_sel:[0,1] op_sel_hi:[1,1]
	v_add_f32_dpp v212, v212, v212 row_ror:8 row_mask:0xf bank_mask:0xf bound_ctrl:1
	v_pk_mul_f32 v[114:115], v[114:115], v[154:155] op_sel:[0,1] op_sel_hi:[1,1]
	v_pk_mul_f32 v[116:117], v[116:117], v[154:155] op_sel:[0,1] op_sel_hi:[1,1]
	v_add_f32_dpp v212, v212, v212 row_ror:4 row_mask:0xf bank_mask:0xf bound_ctrl:1
	v_pk_mul_f32 v[118:119], v[118:119], v[154:155] op_sel:[0,1] op_sel_hi:[1,1]
	v_pk_mul_f32 v[120:121], v[120:121], v[154:155] op_sel:[0,1] op_sel_hi:[1,1]
	v_add_f32_dpp v212, v212, v212 row_ror:2 row_mask:0xf bank_mask:0xf bound_ctrl:1
	v_pk_mul_f32 v[122:123], v[122:123], v[154:155] op_sel:[0,1] op_sel_hi:[1,1]
	v_pk_mul_f32 v[124:125], v[124:125], v[154:155] op_sel:[0,1] op_sel_hi:[1,1]
	v_add_f32_dpp v212, v212, v212 row_ror:1 row_mask:0xf bank_mask:0xf bound_ctrl:1
	v_pk_mul_f32 v[126:127], v[126:127], v[154:155] op_sel:[0,1] op_sel_hi:[1,1]
	v_pk_fma_f32 v[196:197], v[154:155], v[196:197], v[112:113] op_sel_hi:[0,1,1]
	s_and_saveexec_b64 s[8:9], s[44:45]
	ds_write_b32 v190, v212 offset:34816
	s_mov_b64 exec, s[8:9]
	v_pk_fma_f32 v[198:199], v[154:155], v[198:199], v[114:115] op_sel_hi:[0,1,1]
	v_pk_fma_f32 v[200:201], v[154:155], v[200:201], v[116:117] op_sel_hi:[0,1,1]
	v_pk_fma_f32 v[202:203], v[154:155], v[202:203], v[118:119] op_sel_hi:[0,1,1]
	v_pk_fma_f32 v[204:205], v[154:155], v[204:205], v[120:121] op_sel_hi:[0,1,1]
	v_pk_fma_f32 v[206:207], v[154:155], v[206:207], v[122:123] op_sel_hi:[0,1,1]
	v_pk_fma_f32 v[208:209], v[154:155], v[208:209], v[124:125] op_sel_hi:[0,1,1]
	v_pk_fma_f32 v[210:211], v[154:155], v[210:211], v[126:127] op_sel_hi:[0,1,1]
	ds_read_b128 v[112:115], v194 offset:32384
	ds_read_b128 v[116:119], v194 offset:32640
	ds_read_b128 v[120:123], v194 offset:32896
	ds_read_b128 v[124:127], v194 offset:33152
	ds_read_b32 v156, v140 offset:35164
	ds_read_b32 v157, v190 offset:33856
	ds_read_b32 v154, v140 offset:35100
	s_waitcnt lgkmcnt(15)
	v_pk_fma_f32 v[128:129], v[96:97], v[196:197], v[214:215]
	v_pk_fma_f32 v[130:131], v[98:99], v[198:199], v[214:215]
	ds_read_b128 v[96:99], v194 offset:24192
	s_waitcnt lgkmcnt(15)
	v_pk_fma_f32 v[128:129], v[100:101], v[200:201], v[128:129]
	v_pk_fma_f32 v[130:131], v[102:103], v[202:203], v[130:131]
	ds_read_b128 v[100:103], v194 offset:24448
	s_waitcnt lgkmcnt(15)
	v_pk_fma_f32 v[128:129], v[104:105], v[204:205], v[128:129]
	v_pk_fma_f32 v[130:131], v[106:107], v[206:207], v[130:131]
	ds_read_b128 v[104:107], v194 offset:24704
	s_waitcnt lgkmcnt(15)
	v_pk_fma_f32 v[128:129], v[108:109], v[208:209], v[128:129]
	v_pk_fma_f32 v[130:131], v[110:111], v[210:211], v[130:131]
	ds_read_b128 v[108:111], v194 offset:24960
	v_add_f32_e32 v128, v128, v129
	v_add_f32_e32 v130, v130, v131
	v_add_f32_e32 v213, v128, v130
	s_waitcnt lgkmcnt(15)
	v_mul_f32_e32 v133, v134, v135
	v_pk_mul_f32 v[80:81], v[80:81], v[132:133] op_sel:[0,1] op_sel_hi:[1,1]
	v_add_f32_dpp v213, v213, v213 row_ror:8 row_mask:0xf bank_mask:0xf bound_ctrl:1
	v_pk_mul_f32 v[82:83], v[82:83], v[132:133] op_sel:[0,1] op_sel_hi:[1,1]
	v_pk_mul_f32 v[84:85], v[84:85], v[132:133] op_sel:[0,1] op_sel_hi:[1,1]
	v_add_f32_dpp v213, v213, v213 row_ror:4 row_mask:0xf bank_mask:0xf bound_ctrl:1
	v_pk_mul_f32 v[86:87], v[86:87], v[132:133] op_sel:[0,1] op_sel_hi:[1,1]
	v_pk_mul_f32 v[88:89], v[88:89], v[132:133] op_sel:[0,1] op_sel_hi:[1,1]
	v_add_f32_dpp v213, v213, v213 row_ror:2 row_mask:0xf bank_mask:0xf bound_ctrl:1
	v_pk_mul_f32 v[90:91], v[90:91], v[132:133] op_sel:[0,1] op_sel_hi:[1,1]
	v_pk_mul_f32 v[92:93], v[92:93], v[132:133] op_sel:[0,1] op_sel_hi:[1,1]
	v_add_f32_dpp v213, v213, v213 row_ror:1 row_mask:0xf bank_mask:0xf bound_ctrl:1
	v_pk_mul_f32 v[94:95], v[94:95], v[132:133] op_sel:[0,1] op_sel_hi:[1,1]
	v_pk_fma_f32 v[196:197], v[132:133], v[196:197], v[80:81] op_sel_hi:[0,1,1]
	s_and_saveexec_b64 s[8:9], s[44:45]
	ds_write_b32 v190, v213 offset:34880
	s_mov_b64 exec, s[8:9]
	v_pk_fma_f32 v[198:199], v[132:133], v[198:199], v[82:83] op_sel_hi:[0,1,1]
	v_pk_fma_f32 v[200:201], v[132:133], v[200:201], v[84:85] op_sel_hi:[0,1,1]
	v_pk_fma_f32 v[202:203], v[132:133], v[202:203], v[86:87] op_sel_hi:[0,1,1]
	v_pk_fma_f32 v[204:205], v[132:133], v[204:205], v[88:89] op_sel_hi:[0,1,1]
	v_pk_fma_f32 v[206:207], v[132:133], v[206:207], v[90:91] op_sel_hi:[0,1,1]
	v_pk_fma_f32 v[208:209], v[132:133], v[208:209], v[92:93] op_sel_hi:[0,1,1]
	v_pk_fma_f32 v[210:211], v[132:133], v[210:211], v[94:95] op_sel_hi:[0,1,1]
	s_waitcnt lgkmcnt(15)
	v_pk_fma_f32 v[128:129], v[64:65], v[196:197], v[214:215]
	v_pk_fma_f32 v[130:131], v[66:67], v[198:199], v[214:215]
	v_pk_fma_f32 v[128:129], v[68:69], v[200:201], v[128:129]
	v_pk_fma_f32 v[130:131], v[70:71], v[202:203], v[130:131]
	s_waitcnt lgkmcnt(14)
	v_pk_fma_f32 v[128:129], v[72:73], v[204:205], v[128:129]
	v_pk_fma_f32 v[130:131], v[74:75], v[206:207], v[130:131]
	s_waitcnt lgkmcnt(13)
	v_pk_fma_f32 v[128:129], v[76:77], v[208:209], v[128:129]
	v_pk_fma_f32 v[130:131], v[78:79], v[210:211], v[130:131]
	v_add_f32_e32 v128, v128, v129
	v_add_f32_e32 v130, v130, v131
	v_add_f32_e32 v212, v128, v130
	s_waitcnt lgkmcnt(6)
	v_mul_f32_e32 v155, v156, v157
	v_pk_mul_f32 v[112:113], v[112:113], v[154:155] op_sel:[0,1] op_sel_hi:[1,1]
	v_add_f32_dpp v212, v212, v212 row_ror:8 row_mask:0xf bank_mask:0xf bound_ctrl:1
	v_pk_mul_f32 v[114:115], v[114:115], v[154:155] op_sel:[0,1] op_sel_hi:[1,1]
	v_pk_mul_f32 v[116:117], v[116:117], v[154:155] op_sel:[0,1] op_sel_hi:[1,1]
	v_add_f32_dpp v212, v212, v212 row_ror:4 row_mask:0xf bank_mask:0xf bound_ctrl:1
	v_pk_mul_f32 v[118:119], v[118:119], v[154:155] op_sel:[0,1] op_sel_hi:[1,1]
	v_pk_mul_f32 v[120:121], v[120:121], v[154:155] op_sel:[0,1] op_sel_hi:[1,1]
	v_add_f32_dpp v212, v212, v212 row_ror:2 row_mask:0xf bank_mask:0xf bound_ctrl:1
	v_pk_mul_f32 v[122:123], v[122:123], v[154:155] op_sel:[0,1] op_sel_hi:[1,1]
	v_pk_mul_f32 v[124:125], v[124:125], v[154:155] op_sel:[0,1] op_sel_hi:[1,1]
	v_add_f32_dpp v212, v212, v212 row_ror:1 row_mask:0xf bank_mask:0xf bound_ctrl:1
	v_pk_mul_f32 v[126:127], v[126:127], v[154:155] op_sel:[0,1] op_sel_hi:[1,1]
	s_waitcnt lgkmcnt(5)
	v_pk_fma_f32 v[196:197], v[154:155], v[196:197], v[112:113] op_sel_hi:[0,1,1]
	s_and_saveexec_b64 s[8:9], s[44:45]
	ds_write_b32 v190, v212 offset:34944
	s_mov_b64 exec, s[8:9]
	v_pk_fma_f32 v[198:199], v[154:155], v[198:199], v[114:115] op_sel_hi:[0,1,1]
	v_pk_fma_f32 v[200:201], v[154:155], v[200:201], v[116:117] op_sel_hi:[0,1,1]
	v_pk_fma_f32 v[202:203], v[154:155], v[202:203], v[118:119] op_sel_hi:[0,1,1]
	v_pk_fma_f32 v[204:205], v[154:155], v[204:205], v[120:121] op_sel_hi:[0,1,1]
	v_pk_fma_f32 v[206:207], v[154:155], v[206:207], v[122:123] op_sel_hi:[0,1,1]
	v_pk_fma_f32 v[208:209], v[154:155], v[208:209], v[124:125] op_sel_hi:[0,1,1]
	v_pk_fma_f32 v[210:211], v[154:155], v[210:211], v[126:127] op_sel_hi:[0,1,1]
	s_waitcnt lgkmcnt(5)
	v_pk_fma_f32 v[128:129], v[96:97], v[196:197], v[214:215]
	v_pk_fma_f32 v[130:131], v[98:99], v[198:199], v[214:215]
	s_waitcnt lgkmcnt(4)
	v_pk_fma_f32 v[128:129], v[100:101], v[200:201], v[128:129]
	v_pk_fma_f32 v[130:131], v[102:103], v[202:203], v[130:131]
	s_waitcnt lgkmcnt(3)
	v_pk_fma_f32 v[128:129], v[104:105], v[204:205], v[128:129]
	v_pk_fma_f32 v[130:131], v[106:107], v[206:207], v[130:131]
	s_waitcnt lgkmcnt(2)
	v_pk_fma_f32 v[128:129], v[108:109], v[208:209], v[128:129]
	v_pk_fma_f32 v[130:131], v[110:111], v[210:211], v[130:131]
	v_add_f32_e32 v128, v128, v129
	v_add_f32_e32 v130, v130, v131
	v_add_f32_e32 v213, v128, v130
	s_nop 1
	v_add_f32_dpp v213, v213, v213 row_ror:8 row_mask:0xf bank_mask:0xf bound_ctrl:1
	s_nop 1
	v_add_f32_dpp v213, v213, v213 row_ror:4 row_mask:0xf bank_mask:0xf bound_ctrl:1
	s_nop 1
	v_add_f32_dpp v213, v213, v213 row_ror:2 row_mask:0xf bank_mask:0xf bound_ctrl:1
	s_nop 1
	v_add_f32_dpp v213, v213, v213 row_ror:1 row_mask:0xf bank_mask:0xf bound_ctrl:1
	s_and_saveexec_b64 s[8:9], s[44:45]
	ds_write_b32 v190, v213 offset:35008
	s_mov_b64 exec, s[8:9]
	s_waitcnt lgkmcnt(0)
	v_mov_b32_e32 v88, v196
	v_mov_b32_e32 v89, v197
	v_mov_b32_e32 v90, v198
	v_mov_b32_e32 v100, v199
	v_mov_b32_e32 v91, v200
	v_mov_b32_e32 v101, v201
	v_mov_b32_e32 v102, v202
	v_mov_b32_e32 v104, v203
	v_mov_b32_e32 v103, v204
	v_mov_b32_e32 v105, v205
	v_mov_b32_e32 v106, v206
	v_mov_b32_e32 v109, v207
	v_mov_b32_e32 v107, v208
	v_mov_b32_e32 v110, v209
	v_mov_b32_e32 v108, v210
	v_mov_b32_e32 v111, v211
	s_branch .LBB0_1138

.LBB0_1289:
	v_mov_b32_e32 v178, v118
	v_mov_b32_e32 v179, v119
	v_mov_b32_e32 v180, v88
	v_mov_b32_e32 v181, v89
	v_mov_b32_e32 v182, v90
	v_mov_b32_e32 v183, v80
	v_mov_b32_e32 v184, v81
	v_mov_b32_e32 v185, v82
	v_mov_b32_e32 v186, v146
	v_mov_b32_e32 v187, v120
	v_mov_b32_e32 v188, v121
	v_mov_b32_e32 v189, v91
	v_mov_b32_e32 v190, v147
	v_mov_b32_e32 v191, v148
	v_mov_b32_e32 v192, v149
	v_mov_b32_e32 v193, v83
	v_mov_b32_e32 v196, 0
	v_mov_b32_e32 v197, 0
	v_add_u32_e32 v194, 0x4000, v103
	v_add_u32_e32 v195, 0x4400, v103
	ds_read2_b32 v[118:119], v194 offset0:0 offset1:16
	ds_read_b128 v[72:75], v145 offset:8192
	ds_read_b128 v[76:79], v145 offset:8448
	ds_read_b128 v[64:67], v145
	ds_read_b128 v[68:71], v145 offset:256
	ds_read2_b32 v[120:121], v194 offset0:32 offset1:48
	ds_read_b128 v[88:91], v145 offset:8704
	ds_read_b128 v[92:95], v145 offset:8960
	ds_read_b128 v[80:83], v145 offset:512
	ds_read_b128 v[84:87], v145 offset:768
	s_waitcnt lgkmcnt(9)
	v_pk_add_f32 v[178:179], v[178:179], v[118:119] op_sel_hi:[1,0] neg_lo:[0,1] neg_hi:[0,1]
	v_pk_add_f32 v[186:187], v[186:187], v[118:119] op_sel:[0,1] op_sel_hi:[1,1] neg_lo:[0,1] neg_hi:[0,1]
	v_pk_add_f32 v[180:181], v[180:181], v[118:119] op_sel_hi:[1,0] neg_lo:[0,1] neg_hi:[0,1]
	v_pk_add_f32 v[188:189], v[188:189], v[118:119] op_sel:[0,1] op_sel_hi:[1,1] neg_lo:[0,1] neg_hi:[0,1]
	v_pk_add_f32 v[182:183], v[182:183], v[118:119] op_sel_hi:[1,0] neg_lo:[0,1] neg_hi:[0,1]
	v_pk_add_f32 v[190:191], v[190:191], v[118:119] op_sel:[0,1] op_sel_hi:[1,1] neg_lo:[0,1] neg_hi:[0,1]
	v_pk_add_f32 v[184:185], v[184:185], v[118:119] op_sel_hi:[1,0] neg_lo:[0,1] neg_hi:[0,1]
	v_pk_add_f32 v[192:193], v[192:193], v[118:119] op_sel:[0,1] op_sel_hi:[1,1] neg_lo:[0,1] neg_hi:[0,1]
	s_waitcnt lgkmcnt(8)
	v_pk_fma_f32 v[178:179], v[72:73], v[178:179], v[118:119] op_sel_hi:[1,1,0]
	v_pk_fma_f32 v[186:187], v[72:73], v[186:187], v[118:119] op_sel:[0,0,1] op_sel_hi:[1,1,1]
	v_pk_fma_f32 v[180:181], v[74:75], v[180:181], v[118:119] op_sel_hi:[1,1,0]
	v_pk_fma_f32 v[188:189], v[74:75], v[188:189], v[118:119] op_sel:[0,0,1] op_sel_hi:[1,1,1]
	s_waitcnt lgkmcnt(7)
	v_pk_fma_f32 v[182:183], v[76:77], v[182:183], v[118:119] op_sel_hi:[1,1,0]
	v_pk_fma_f32 v[190:191], v[76:77], v[190:191], v[118:119] op_sel:[0,0,1] op_sel_hi:[1,1,1]
	v_pk_fma_f32 v[184:185], v[78:79], v[184:185], v[118:119] op_sel_hi:[1,1,0]
	v_pk_fma_f32 v[192:193], v[78:79], v[192:193], v[118:119] op_sel:[0,0,1] op_sel_hi:[1,1,1]
	ds_read2_b32 v[118:119], v194 offset0:64 offset1:80
	ds_read_b128 v[72:75], v145 offset:9216
	ds_read_b128 v[76:79], v145 offset:9472
	s_waitcnt lgkmcnt(9)
	v_pk_fma_f32 v[146:147], v[64:65], v[178:179], v[196:197]
	v_pk_fma_f32 v[150:151], v[64:65], v[186:187], v[196:197]
	v_pk_fma_f32 v[148:149], v[66:67], v[180:181], v[196:197]
	v_pk_fma_f32 v[152:153], v[66:67], v[188:189], v[196:197]
	ds_read_b128 v[64:67], v145 offset:1024
	s_waitcnt lgkmcnt(9)
	v_pk_fma_f32 v[146:147], v[68:69], v[182:183], v[146:147]
	v_pk_fma_f32 v[150:151], v[68:69], v[190:191], v[150:151]
	v_pk_fma_f32 v[148:149], v[70:71], v[184:185], v[148:149]
	v_pk_fma_f32 v[152:153], v[70:71], v[192:193], v[152:153]
	ds_read_b128 v[68:71], v145 offset:1280
	v_add_f32_e32 v146, v146, v147
	v_add_f32_e32 v148, v148, v149
	v_add_f32_e32 v150, v150, v151
	v_add_f32_e32 v152, v152, v153
	v_add_f32_e32 v154, v146, v148
	v_add_f32_e32 v155, v150, v152
	s_waitcnt lgkmcnt(9)
	v_pk_add_f32 v[178:179], v[178:179], v[120:121] op_sel_hi:[1,0] neg_lo:[0,1] neg_hi:[0,1]
	v_add_f32_dpp v154, v154, v154 row_ror:8 row_mask:0xf bank_mask:0xf bound_ctrl:1
	v_pk_add_f32 v[186:187], v[186:187], v[120:121] op_sel:[0,1] op_sel_hi:[1,1] neg_lo:[0,1] neg_hi:[0,1]
	v_add_f32_dpp v155, v155, v155 row_ror:8 row_mask:0xf bank_mask:0xf bound_ctrl:1
	v_pk_add_f32 v[180:181], v[180:181], v[120:121] op_sel_hi:[1,0] neg_lo:[0,1] neg_hi:[0,1]
	v_add_f32_dpp v154, v154, v154 row_ror:4 row_mask:0xf bank_mask:0xf bound_ctrl:1
	v_pk_add_f32 v[188:189], v[188:189], v[120:121] op_sel:[0,1] op_sel_hi:[1,1] neg_lo:[0,1] neg_hi:[0,1]
	v_add_f32_dpp v155, v155, v155 row_ror:4 row_mask:0xf bank_mask:0xf bound_ctrl:1
	v_pk_add_f32 v[182:183], v[182:183], v[120:121] op_sel_hi:[1,0] neg_lo:[0,1] neg_hi:[0,1]
	v_add_f32_dpp v154, v154, v154 row_ror:2 row_mask:0xf bank_mask:0xf bound_ctrl:1
	v_pk_add_f32 v[190:191], v[190:191], v[120:121] op_sel:[0,1] op_sel_hi:[1,1] neg_lo:[0,1] neg_hi:[0,1]
	v_add_f32_dpp v155, v155, v155 row_ror:2 row_mask:0xf bank_mask:0xf bound_ctrl:1
	v_pk_add_f32 v[184:185], v[184:185], v[120:121] op_sel_hi:[1,0] neg_lo:[0,1] neg_hi:[0,1]
	v_add_f32_dpp v154, v154, v154 row_ror:1 row_mask:0xf bank_mask:0xf bound_ctrl:1
	v_pk_add_f32 v[192:193], v[192:193], v[120:121] op_sel:[0,1] op_sel_hi:[1,1] neg_lo:[0,1] neg_hi:[0,1]
	v_add_f32_dpp v155, v155, v155 row_ror:1 row_mask:0xf bank_mask:0xf bound_ctrl:1
	s_waitcnt lgkmcnt(8)
	v_pk_fma_f32 v[178:179], v[88:89], v[178:179], v[120:121] op_sel_hi:[1,1,0]
	s_and_saveexec_b64 s[8:9], s[38:39]
	ds_write_b32 v103, v154 offset:36864
	ds_write_b32 v103, v155 offset:36928
	s_mov_b64 exec, s[8:9]
	v_pk_fma_f32 v[186:187], v[88:89], v[186:187], v[120:121] op_sel:[0,0,1] op_sel_hi:[1,1,1]
	v_pk_fma_f32 v[180:181], v[90:91], v[180:181], v[120:121] op_sel_hi:[1,1,0]
	v_pk_fma_f32 v[188:189], v[90:91], v[188:189], v[120:121] op_sel:[0,0,1] op_sel_hi:[1,1,1]
	s_waitcnt lgkmcnt(9)
	v_pk_fma_f32 v[182:183], v[92:93], v[182:183], v[120:121] op_sel_hi:[1,1,0]
	v_pk_fma_f32 v[190:191], v[92:93], v[190:191], v[120:121] op_sel:[0,0,1] op_sel_hi:[1,1,1]
	v_pk_fma_f32 v[184:185], v[94:95], v[184:185], v[120:121] op_sel_hi:[1,1,0]
	v_pk_fma_f32 v[192:193], v[94:95], v[192:193], v[120:121] op_sel:[0,0,1] op_sel_hi:[1,1,1]
	ds_read2_b32 v[120:121], v194 offset0:96 offset1:112
	ds_read_b128 v[88:91], v145 offset:9728
	ds_read_b128 v[92:95], v145 offset:9984
	s_waitcnt lgkmcnt(11)
	v_pk_fma_f32 v[146:147], v[80:81], v[178:179], v[196:197]
	v_pk_fma_f32 v[150:151], v[80:81], v[186:187], v[196:197]
	v_pk_fma_f32 v[148:149], v[82:83], v[180:181], v[196:197]
	v_pk_fma_f32 v[152:153], v[82:83], v[188:189], v[196:197]
	ds_read_b128 v[80:83], v145 offset:1536
	s_waitcnt lgkmcnt(11)
	v_pk_fma_f32 v[146:147], v[84:85], v[182:183], v[146:147]
	v_pk_fma_f32 v[150:151], v[84:85], v[190:191], v[150:151]
	v_pk_fma_f32 v[148:149], v[86:87], v[184:185], v[148:149]
	v_pk_fma_f32 v[152:153], v[86:87], v[192:193], v[152:153]
	ds_read_b128 v[84:87], v145 offset:1792
	v_add_f32_e32 v146, v146, v147
	v_add_f32_e32 v148, v148, v149
	v_add_f32_e32 v150, v150, v151
	v_add_f32_e32 v152, v152, v153
	v_add_f32_e32 v156, v146, v148
	v_add_f32_e32 v157, v150, v152
	s_waitcnt lgkmcnt(11)
	v_pk_add_f32 v[178:179], v[178:179], v[118:119] op_sel_hi:[1,0] neg_lo:[0,1] neg_hi:[0,1]
	v_add_f32_dpp v156, v156, v156 row_ror:8 row_mask:0xf bank_mask:0xf bound_ctrl:1
	v_pk_add_f32 v[186:187], v[186:187], v[118:119] op_sel:[0,1] op_sel_hi:[1,1] neg_lo:[0,1] neg_hi:[0,1]
	v_add_f32_dpp v157, v157, v157 row_ror:8 row_mask:0xf bank_mask:0xf bound_ctrl:1
	v_pk_add_f32 v[180:181], v[180:181], v[118:119] op_sel_hi:[1,0] neg_lo:[0,1] neg_hi:[0,1]
	v_add_f32_dpp v156, v156, v156 row_ror:4 row_mask:0xf bank_mask:0xf bound_ctrl:1
	v_pk_add_f32 v[188:189], v[188:189], v[118:119] op_sel:[0,1] op_sel_hi:[1,1] neg_lo:[0,1] neg_hi:[0,1]
	v_add_f32_dpp v157, v157, v157 row_ror:4 row_mask:0xf bank_mask:0xf bound_ctrl:1
	v_pk_add_f32 v[182:183], v[182:183], v[118:119] op_sel_hi:[1,0] neg_lo:[0,1] neg_hi:[0,1]
	v_add_f32_dpp v156, v156, v156 row_ror:2 row_mask:0xf bank_mask:0xf bound_ctrl:1
	v_pk_add_f32 v[190:191], v[190:191], v[118:119] op_sel:[0,1] op_sel_hi:[1,1] neg_lo:[0,1] neg_hi:[0,1]
	v_add_f32_dpp v157, v157, v157 row_ror:2 row_mask:0xf bank_mask:0xf bound_ctrl:1
	v_pk_add_f32 v[184:185], v[184:185], v[118:119] op_sel_hi:[1,0] neg_lo:[0,1] neg_hi:[0,1]
	v_add_f32_dpp v156, v156, v156 row_ror:1 row_mask:0xf bank_mask:0xf bound_ctrl:1
	v_pk_add_f32 v[192:193], v[192:193], v[118:119] op_sel:[0,1] op_sel_hi:[1,1] neg_lo:[0,1] neg_hi:[0,1]
	v_add_f32_dpp v157, v157, v157 row_ror:1 row_mask:0xf bank_mask:0xf bound_ctrl:1
	s_waitcnt lgkmcnt(10)
	v_pk_fma_f32 v[178:179], v[72:73], v[178:179], v[118:119] op_sel_hi:[1,1,0]
	s_and_saveexec_b64 s[8:9], s[38:39]
	ds_write_b32 v103, v156 offset:36992
	ds_write_b32 v103, v157 offset:37056
	s_mov_b64 exec, s[8:9]
	v_pk_fma_f32 v[186:187], v[72:73], v[186:187], v[118:119] op_sel:[0,0,1] op_sel_hi:[1,1,1]
	v_pk_fma_f32 v[180:181], v[74:75], v[180:181], v[118:119] op_sel_hi:[1,1,0]
	v_pk_fma_f32 v[188:189], v[74:75], v[188:189], v[118:119] op_sel:[0,0,1] op_sel_hi:[1,1,1]
	s_waitcnt lgkmcnt(11)
	v_pk_fma_f32 v[182:183], v[76:77], v[182:183], v[118:119] op_sel_hi:[1,1,0]
	v_pk_fma_f32 v[190:191], v[76:77], v[190:191], v[118:119] op_sel:[0,0,1] op_sel_hi:[1,1,1]
	v_pk_fma_f32 v[184:185], v[78:79], v[184:185], v[118:119] op_sel_hi:[1,1,0]
	v_pk_fma_f32 v[192:193], v[78:79], v[192:193], v[118:119] op_sel:[0,0,1] op_sel_hi:[1,1,1]
	ds_read2_b32 v[118:119], v194 offset0:128 offset1:144
	ds_read_b128 v[72:75], v145 offset:10240
	ds_read_b128 v[76:79], v145 offset:10496
	s_waitcnt lgkmcnt(13)
	v_pk_fma_f32 v[146:147], v[64:65], v[178:179], v[196:197]
	v_pk_fma_f32 v[150:151], v[64:65], v[186:187], v[196:197]
	v_pk_fma_f32 v[148:149], v[66:67], v[180:181], v[196:197]
	v_pk_fma_f32 v[152:153], v[66:67], v[188:189], v[196:197]
	ds_read_b128 v[64:67], v145 offset:2048
	s_waitcnt lgkmcnt(13)
	v_pk_fma_f32 v[146:147], v[68:69], v[182:183], v[146:147]
	v_pk_fma_f32 v[150:151], v[68:69], v[190:191], v[150:151]
	v_pk_fma_f32 v[148:149], v[70:71], v[184:185], v[148:149]
	v_pk_fma_f32 v[152:153], v[70:71], v[192:193], v[152:153]
	ds_read_b128 v[68:71], v145 offset:2304
	v_add_f32_e32 v146, v146, v147
	v_add_f32_e32 v148, v148, v149
	v_add_f32_e32 v150, v150, v151
	v_add_f32_e32 v152, v152, v153
	v_add_f32_e32 v154, v146, v148
	v_add_f32_e32 v155, v150, v152
	s_waitcnt lgkmcnt(11)
	v_pk_add_f32 v[178:179], v[178:179], v[120:121] op_sel_hi:[1,0] neg_lo:[0,1] neg_hi:[0,1]
	v_add_f32_dpp v154, v154, v154 row_ror:8 row_mask:0xf bank_mask:0xf bound_ctrl:1
	v_pk_add_f32 v[186:187], v[186:187], v[120:121] op_sel:[0,1] op_sel_hi:[1,1] neg_lo:[0,1] neg_hi:[0,1]
	v_add_f32_dpp v155, v155, v155 row_ror:8 row_mask:0xf bank_mask:0xf bound_ctrl:1
	v_pk_add_f32 v[180:181], v[180:181], v[120:121] op_sel_hi:[1,0] neg_lo:[0,1] neg_hi:[0,1]
	v_add_f32_dpp v154, v154, v154 row_ror:4 row_mask:0xf bank_mask:0xf bound_ctrl:1
	v_pk_add_f32 v[188:189], v[188:189], v[120:121] op_sel:[0,1] op_sel_hi:[1,1] neg_lo:[0,1] neg_hi:[0,1]
	v_add_f32_dpp v155, v155, v155 row_ror:4 row_mask:0xf bank_mask:0xf bound_ctrl:1
	v_pk_add_f32 v[182:183], v[182:183], v[120:121] op_sel_hi:[1,0] neg_lo:[0,1] neg_hi:[0,1]
	v_add_f32_dpp v154, v154, v154 row_ror:2 row_mask:0xf bank_mask:0xf bound_ctrl:1
	v_pk_add_f32 v[190:191], v[190:191], v[120:121] op_sel:[0,1] op_sel_hi:[1,1] neg_lo:[0,1] neg_hi:[0,1]
	v_add_f32_dpp v155, v155, v155 row_ror:2 row_mask:0xf bank_mask:0xf bound_ctrl:1
	v_pk_add_f32 v[184:185], v[184:185], v[120:121] op_sel_hi:[1,0] neg_lo:[0,1] neg_hi:[0,1]
	v_add_f32_dpp v154, v154, v154 row_ror:1 row_mask:0xf bank_mask:0xf bound_ctrl:1
	v_pk_add_f32 v[192:193], v[192:193], v[120:121] op_sel:[0,1] op_sel_hi:[1,1] neg_lo:[0,1] neg_hi:[0,1]
	v_add_f32_dpp v155, v155, v155 row_ror:1 row_mask:0xf bank_mask:0xf bound_ctrl:1
	s_waitcnt lgkmcnt(10)
	v_pk_fma_f32 v[178:179], v[88:89], v[178:179], v[120:121] op_sel_hi:[1,1,0]
	s_and_saveexec_b64 s[8:9], s[38:39]
	ds_write_b32 v103, v154 offset:37120
	ds_write_b32 v103, v155 offset:37184
	s_mov_b64 exec, s[8:9]
	v_pk_fma_f32 v[186:187], v[88:89], v[186:187], v[120:121] op_sel:[0,0,1] op_sel_hi:[1,1,1]
	v_pk_fma_f32 v[180:181], v[90:91], v[180:181], v[120:121] op_sel_hi:[1,1,0]
	v_pk_fma_f32 v[188:189], v[90:91], v[188:189], v[120:121] op_sel:[0,0,1] op_sel_hi:[1,1,1]
	s_waitcnt lgkmcnt(11)
	v_pk_fma_f32 v[182:183], v[92:93], v[182:183], v[120:121] op_sel_hi:[1,1,0]
	v_pk_fma_f32 v[190:191], v[92:93], v[190:191], v[120:121] op_sel:[0,0,1] op_sel_hi:[1,1,1]
	v_pk_fma_f32 v[184:185], v[94:95], v[184:185], v[120:121] op_sel_hi:[1,1,0]
	v_pk_fma_f32 v[192:193], v[94:95], v[192:193], v[120:121] op_sel:[0,0,1] op_sel_hi:[1,1,1]
	ds_read2_b32 v[120:121], v194 offset0:160 offset1:176
	ds_read_b128 v[88:91], v145 offset:10752
	ds_read_b128 v[92:95], v145 offset:11008
	s_waitcnt lgkmcnt(13)
	v_pk_fma_f32 v[146:147], v[80:81], v[178:179], v[196:197]
	v_pk_fma_f32 v[150:151], v[80:81], v[186:187], v[196:197]
	v_pk_fma_f32 v[148:149], v[82:83], v[180:181], v[196:197]
	v_pk_fma_f32 v[152:153], v[82:83], v[188:189], v[196:197]
	ds_read_b128 v[80:83], v145 offset:2560
	s_waitcnt lgkmcnt(13)
	v_pk_fma_f32 v[146:147], v[84:85], v[182:183], v[146:147]
	v_pk_fma_f32 v[150:151], v[84:85], v[190:191], v[150:151]
	v_pk_fma_f32 v[148:149], v[86:87], v[184:185], v[148:149]
	v_pk_fma_f32 v[152:153], v[86:87], v[192:193], v[152:153]
	ds_read_b128 v[84:87], v145 offset:2816
	v_add_f32_e32 v146, v146, v147
	v_add_f32_e32 v148, v148, v149
	v_add_f32_e32 v150, v150, v151
	v_add_f32_e32 v152, v152, v153
	v_add_f32_e32 v156, v146, v148
	v_add_f32_e32 v157, v150, v152
	s_waitcnt lgkmcnt(11)
	v_pk_add_f32 v[178:179], v[178:179], v[118:119] op_sel_hi:[1,0] neg_lo:[0,1] neg_hi:[0,1]
	v_add_f32_dpp v156, v156, v156 row_ror:8 row_mask:0xf bank_mask:0xf bound_ctrl:1
	v_pk_add_f32 v[186:187], v[186:187], v[118:119] op_sel:[0,1] op_sel_hi:[1,1] neg_lo:[0,1] neg_hi:[0,1]
	v_add_f32_dpp v157, v157, v157 row_ror:8 row_mask:0xf bank_mask:0xf bound_ctrl:1
	v_pk_add_f32 v[180:181], v[180:181], v[118:119] op_sel_hi:[1,0] neg_lo:[0,1] neg_hi:[0,1]
	v_add_f32_dpp v156, v156, v156 row_ror:4 row_mask:0xf bank_mask:0xf bound_ctrl:1
	v_pk_add_f32 v[188:189], v[188:189], v[118:119] op_sel:[0,1] op_sel_hi:[1,1] neg_lo:[0,1] neg_hi:[0,1]
	v_add_f32_dpp v157, v157, v157 row_ror:4 row_mask:0xf bank_mask:0xf bound_ctrl:1
	v_pk_add_f32 v[182:183], v[182:183], v[118:119] op_sel_hi:[1,0] neg_lo:[0,1] neg_hi:[0,1]
	v_add_f32_dpp v156, v156, v156 row_ror:2 row_mask:0xf bank_mask:0xf bound_ctrl:1
	v_pk_add_f32 v[190:191], v[190:191], v[118:119] op_sel:[0,1] op_sel_hi:[1,1] neg_lo:[0,1] neg_hi:[0,1]
	v_add_f32_dpp v157, v157, v157 row_ror:2 row_mask:0xf bank_mask:0xf bound_ctrl:1
	v_pk_add_f32 v[184:185], v[184:185], v[118:119] op_sel_hi:[1,0] neg_lo:[0,1] neg_hi:[0,1]
	v_add_f32_dpp v156, v156, v156 row_ror:1 row_mask:0xf bank_mask:0xf bound_ctrl:1
	v_pk_add_f32 v[192:193], v[192:193], v[118:119] op_sel:[0,1] op_sel_hi:[1,1] neg_lo:[0,1] neg_hi:[0,1]
	v_add_f32_dpp v157, v157, v157 row_ror:1 row_mask:0xf bank_mask:0xf bound_ctrl:1
	s_waitcnt lgkmcnt(10)
	v_pk_fma_f32 v[178:179], v[72:73], v[178:179], v[118:119] op_sel_hi:[1,1,0]
	s_and_saveexec_b64 s[8:9], s[38:39]
	ds_write_b32 v103, v156 offset:37248
	ds_write_b32 v103, v157 offset:37312
	s_mov_b64 exec, s[8:9]
	v_pk_fma_f32 v[186:187], v[72:73], v[186:187], v[118:119] op_sel:[0,0,1] op_sel_hi:[1,1,1]
	v_pk_fma_f32 v[180:181], v[74:75], v[180:181], v[118:119] op_sel_hi:[1,1,0]
	v_pk_fma_f32 v[188:189], v[74:75], v[188:189], v[118:119] op_sel:[0,0,1] op_sel_hi:[1,1,1]
	s_waitcnt lgkmcnt(11)
	v_pk_fma_f32 v[182:183], v[76:77], v[182:183], v[118:119] op_sel_hi:[1,1,0]
	v_pk_fma_f32 v[190:191], v[76:77], v[190:191], v[118:119] op_sel:[0,0,1] op_sel_hi:[1,1,1]
	v_pk_fma_f32 v[184:185], v[78:79], v[184:185], v[118:119] op_sel_hi:[1,1,0]
	v_pk_fma_f32 v[192:193], v[78:79], v[192:193], v[118:119] op_sel:[0,0,1] op_sel_hi:[1,1,1]
	ds_read2_b32 v[118:119], v194 offset0:192 offset1:208
	ds_read_b128 v[72:75], v145 offset:11264
	ds_read_b128 v[76:79], v145 offset:11520
	s_waitcnt lgkmcnt(13)
	v_pk_fma_f32 v[146:147], v[64:65], v[178:179], v[196:197]
	v_pk_fma_f32 v[150:151], v[64:65], v[186:187], v[196:197]
	v_pk_fma_f32 v[148:149], v[66:67], v[180:181], v[196:197]
	v_pk_fma_f32 v[152:153], v[66:67], v[188:189], v[196:197]
	ds_read_b128 v[64:67], v145 offset:3072
	s_waitcnt lgkmcnt(13)
	v_pk_fma_f32 v[146:147], v[68:69], v[182:183], v[146:147]
	v_pk_fma_f32 v[150:151], v[68:69], v[190:191], v[150:151]
	v_pk_fma_f32 v[148:149], v[70:71], v[184:185], v[148:149]
	v_pk_fma_f32 v[152:153], v[70:71], v[192:193], v[152:153]
	ds_read_b128 v[68:71], v145 offset:3328
	v_add_f32_e32 v146, v146, v147
	v_add_f32_e32 v148, v148, v149
	v_add_f32_e32 v150, v150, v151
	v_add_f32_e32 v152, v152, v153
	v_add_f32_e32 v154, v146, v148
	v_add_f32_e32 v155, v150, v152
	s_waitcnt lgkmcnt(11)
	v_pk_add_f32 v[178:179], v[178:179], v[120:121] op_sel_hi:[1,0] neg_lo:[0,1] neg_hi:[0,1]
	v_add_f32_dpp v154, v154, v154 row_ror:8 row_mask:0xf bank_mask:0xf bound_ctrl:1
	v_pk_add_f32 v[186:187], v[186:187], v[120:121] op_sel:[0,1] op_sel_hi:[1,1] neg_lo:[0,1] neg_hi:[0,1]
	v_add_f32_dpp v155, v155, v155 row_ror:8 row_mask:0xf bank_mask:0xf bound_ctrl:1
	v_pk_add_f32 v[180:181], v[180:181], v[120:121] op_sel_hi:[1,0] neg_lo:[0,1] neg_hi:[0,1]
	v_add_f32_dpp v154, v154, v154 row_ror:4 row_mask:0xf bank_mask:0xf bound_ctrl:1
	v_pk_add_f32 v[188:189], v[188:189], v[120:121] op_sel:[0,1] op_sel_hi:[1,1] neg_lo:[0,1] neg_hi:[0,1]
	v_add_f32_dpp v155, v155, v155 row_ror:4 row_mask:0xf bank_mask:0xf bound_ctrl:1
	v_pk_add_f32 v[182:183], v[182:183], v[120:121] op_sel_hi:[1,0] neg_lo:[0,1] neg_hi:[0,1]
	v_add_f32_dpp v154, v154, v154 row_ror:2 row_mask:0xf bank_mask:0xf bound_ctrl:1
	v_pk_add_f32 v[190:191], v[190:191], v[120:121] op_sel:[0,1] op_sel_hi:[1,1] neg_lo:[0,1] neg_hi:[0,1]
	v_add_f32_dpp v155, v155, v155 row_ror:2 row_mask:0xf bank_mask:0xf bound_ctrl:1
	v_pk_add_f32 v[184:185], v[184:185], v[120:121] op_sel_hi:[1,0] neg_lo:[0,1] neg_hi:[0,1]
	v_add_f32_dpp v154, v154, v154 row_ror:1 row_mask:0xf bank_mask:0xf bound_ctrl:1
	v_pk_add_f32 v[192:193], v[192:193], v[120:121] op_sel:[0,1] op_sel_hi:[1,1] neg_lo:[0,1] neg_hi:[0,1]
	v_add_f32_dpp v155, v155, v155 row_ror:1 row_mask:0xf bank_mask:0xf bound_ctrl:1
	s_waitcnt lgkmcnt(10)
	v_pk_fma_f32 v[178:179], v[88:89], v[178:179], v[120:121] op_sel_hi:[1,1,0]
	s_and_saveexec_b64 s[8:9], s[38:39]
	ds_write_b32 v103, v154 offset:37376
	ds_write_b32 v103, v155 offset:37440
	s_mov_b64 exec, s[8:9]
	v_pk_fma_f32 v[186:187], v[88:89], v[186:187], v[120:121] op_sel:[0,0,1] op_sel_hi:[1,1,1]
	v_pk_fma_f32 v[180:181], v[90:91], v[180:181], v[120:121] op_sel_hi:[1,1,0]
	v_pk_fma_f32 v[188:189], v[90:91], v[188:189], v[120:121] op_sel:[0,0,1] op_sel_hi:[1,1,1]
	s_waitcnt lgkmcnt(11)
	v_pk_fma_f32 v[182:183], v[92:93], v[182:183], v[120:121] op_sel_hi:[1,1,0]
	v_pk_fma_f32 v[190:191], v[92:93], v[190:191], v[120:121] op_sel:[0,0,1] op_sel_hi:[1,1,1]
	v_pk_fma_f32 v[184:185], v[94:95], v[184:185], v[120:121] op_sel_hi:[1,1,0]
	v_pk_fma_f32 v[192:193], v[94:95], v[192:193], v[120:121] op_sel:[0,0,1] op_sel_hi:[1,1,1]
	ds_read2_b32 v[120:121], v194 offset0:224 offset1:240
	ds_read_b128 v[88:91], v145 offset:11776
	ds_read_b128 v[92:95], v145 offset:12032
	s_waitcnt lgkmcnt(13)
	v_pk_fma_f32 v[146:147], v[80:81], v[178:179], v[196:197]
	v_pk_fma_f32 v[150:151], v[80:81], v[186:187], v[196:197]
	v_pk_fma_f32 v[148:149], v[82:83], v[180:181], v[196:197]
	v_pk_fma_f32 v[152:153], v[82:83], v[188:189], v[196:197]
	ds_read_b128 v[80:83], v145 offset:3584
	s_waitcnt lgkmcnt(13)
	v_pk_fma_f32 v[146:147], v[84:85], v[182:183], v[146:147]
	v_pk_fma_f32 v[150:151], v[84:85], v[190:191], v[150:151]
	v_pk_fma_f32 v[148:149], v[86:87], v[184:185], v[148:149]
	v_pk_fma_f32 v[152:153], v[86:87], v[192:193], v[152:153]
	ds_read_b128 v[84:87], v145 offset:3840
	v_add_f32_e32 v146, v146, v147
	v_add_f32_e32 v148, v148, v149
	v_add_f32_e32 v150, v150, v151
	v_add_f32_e32 v152, v152, v153
	v_add_f32_e32 v156, v146, v148
	v_add_f32_e32 v157, v150, v152
	s_waitcnt lgkmcnt(11)
	v_pk_add_f32 v[178:179], v[178:179], v[118:119] op_sel_hi:[1,0] neg_lo:[0,1] neg_hi:[0,1]
	v_add_f32_dpp v156, v156, v156 row_ror:8 row_mask:0xf bank_mask:0xf bound_ctrl:1
	v_pk_add_f32 v[186:187], v[186:187], v[118:119] op_sel:[0,1] op_sel_hi:[1,1] neg_lo:[0,1] neg_hi:[0,1]
	v_add_f32_dpp v157, v157, v157 row_ror:8 row_mask:0xf bank_mask:0xf bound_ctrl:1
	v_pk_add_f32 v[180:181], v[180:181], v[118:119] op_sel_hi:[1,0] neg_lo:[0,1] neg_hi:[0,1]
	v_add_f32_dpp v156, v156, v156 row_ror:4 row_mask:0xf bank_mask:0xf bound_ctrl:1
	v_pk_add_f32 v[188:189], v[188:189], v[118:119] op_sel:[0,1] op_sel_hi:[1,1] neg_lo:[0,1] neg_hi:[0,1]
	v_add_f32_dpp v157, v157, v157 row_ror:4 row_mask:0xf bank_mask:0xf bound_ctrl:1
	v_pk_add_f32 v[182:183], v[182:183], v[118:119] op_sel_hi:[1,0] neg_lo:[0,1] neg_hi:[0,1]
	v_add_f32_dpp v156, v156, v156 row_ror:2 row_mask:0xf bank_mask:0xf bound_ctrl:1
	v_pk_add_f32 v[190:191], v[190:191], v[118:119] op_sel:[0,1] op_sel_hi:[1,1] neg_lo:[0,1] neg_hi:[0,1]
	v_add_f32_dpp v157, v157, v157 row_ror:2 row_mask:0xf bank_mask:0xf bound_ctrl:1
	v_pk_add_f32 v[184:185], v[184:185], v[118:119] op_sel_hi:[1,0] neg_lo:[0,1] neg_hi:[0,1]
	v_add_f32_dpp v156, v156, v156 row_ror:1 row_mask:0xf bank_mask:0xf bound_ctrl:1
	v_pk_add_f32 v[192:193], v[192:193], v[118:119] op_sel:[0,1] op_sel_hi:[1,1] neg_lo:[0,1] neg_hi:[0,1]
	v_add_f32_dpp v157, v157, v157 row_ror:1 row_mask:0xf bank_mask:0xf bound_ctrl:1
	s_waitcnt lgkmcnt(10)
	v_pk_fma_f32 v[178:179], v[72:73], v[178:179], v[118:119] op_sel_hi:[1,1,0]
	s_and_saveexec_b64 s[8:9], s[38:39]
	ds_write_b32 v103, v156 offset:37504
	ds_write_b32 v103, v157 offset:37568
	s_mov_b64 exec, s[8:9]
	v_pk_fma_f32 v[186:187], v[72:73], v[186:187], v[118:119] op_sel:[0,0,1] op_sel_hi:[1,1,1]
	v_pk_fma_f32 v[180:181], v[74:75], v[180:181], v[118:119] op_sel_hi:[1,1,0]
	v_pk_fma_f32 v[188:189], v[74:75], v[188:189], v[118:119] op_sel:[0,0,1] op_sel_hi:[1,1,1]
	s_waitcnt lgkmcnt(11)
	v_pk_fma_f32 v[182:183], v[76:77], v[182:183], v[118:119] op_sel_hi:[1,1,0]
	v_pk_fma_f32 v[190:191], v[76:77], v[190:191], v[118:119] op_sel:[0,0,1] op_sel_hi:[1,1,1]
	v_pk_fma_f32 v[184:185], v[78:79], v[184:185], v[118:119] op_sel_hi:[1,1,0]
	v_pk_fma_f32 v[192:193], v[78:79], v[192:193], v[118:119] op_sel:[0,0,1] op_sel_hi:[1,1,1]
	ds_read2_b32 v[118:119], v195 offset0:0 offset1:16
	ds_read_b128 v[72:75], v145 offset:12288
	ds_read_b128 v[76:79], v145 offset:12544
	s_waitcnt lgkmcnt(13)
	v_pk_fma_f32 v[146:147], v[64:65], v[178:179], v[196:197]
	v_pk_fma_f32 v[150:151], v[64:65], v[186:187], v[196:197]
	v_pk_fma_f32 v[148:149], v[66:67], v[180:181], v[196:197]
	v_pk_fma_f32 v[152:153], v[66:67], v[188:189], v[196:197]
	ds_read_b128 v[64:67], v145 offset:4096
	s_waitcnt lgkmcnt(13)
	v_pk_fma_f32 v[146:147], v[68:69], v[182:183], v[146:147]
	v_pk_fma_f32 v[150:151], v[68:69], v[190:191], v[150:151]
	v_pk_fma_f32 v[148:149], v[70:71], v[184:185], v[148:149]
	v_pk_fma_f32 v[152:153], v[70:71], v[192:193], v[152:153]
	ds_read_b128 v[68:71], v145 offset:4352
	v_add_f32_e32 v146, v146, v147
	v_add_f32_e32 v148, v148, v149
	v_add_f32_e32 v150, v150, v151
	v_add_f32_e32 v152, v152, v153
	v_add_f32_e32 v154, v146, v148
	v_add_f32_e32 v155, v150, v152
	s_waitcnt lgkmcnt(11)
	v_pk_add_f32 v[178:179], v[178:179], v[120:121] op_sel_hi:[1,0] neg_lo:[0,1] neg_hi:[0,1]
	v_add_f32_dpp v154, v154, v154 row_ror:8 row_mask:0xf bank_mask:0xf bound_ctrl:1
	v_pk_add_f32 v[186:187], v[186:187], v[120:121] op_sel:[0,1] op_sel_hi:[1,1] neg_lo:[0,1] neg_hi:[0,1]
	v_add_f32_dpp v155, v155, v155 row_ror:8 row_mask:0xf bank_mask:0xf bound_ctrl:1
	v_pk_add_f32 v[180:181], v[180:181], v[120:121] op_sel_hi:[1,0] neg_lo:[0,1] neg_hi:[0,1]
	v_add_f32_dpp v154, v154, v154 row_ror:4 row_mask:0xf bank_mask:0xf bound_ctrl:1
	v_pk_add_f32 v[188:189], v[188:189], v[120:121] op_sel:[0,1] op_sel_hi:[1,1] neg_lo:[0,1] neg_hi:[0,1]
	v_add_f32_dpp v155, v155, v155 row_ror:4 row_mask:0xf bank_mask:0xf bound_ctrl:1
	v_pk_add_f32 v[182:183], v[182:183], v[120:121] op_sel_hi:[1,0] neg_lo:[0,1] neg_hi:[0,1]
	v_add_f32_dpp v154, v154, v154 row_ror:2 row_mask:0xf bank_mask:0xf bound_ctrl:1
	v_pk_add_f32 v[190:191], v[190:191], v[120:121] op_sel:[0,1] op_sel_hi:[1,1] neg_lo:[0,1] neg_hi:[0,1]
	v_add_f32_dpp v155, v155, v155 row_ror:2 row_mask:0xf bank_mask:0xf bound_ctrl:1
	v_pk_add_f32 v[184:185], v[184:185], v[120:121] op_sel_hi:[1,0] neg_lo:[0,1] neg_hi:[0,1]
	v_add_f32_dpp v154, v154, v154 row_ror:1 row_mask:0xf bank_mask:0xf bound_ctrl:1
	v_pk_add_f32 v[192:193], v[192:193], v[120:121] op_sel:[0,1] op_sel_hi:[1,1] neg_lo:[0,1] neg_hi:[0,1]
	v_add_f32_dpp v155, v155, v155 row_ror:1 row_mask:0xf bank_mask:0xf bound_ctrl:1
	s_waitcnt lgkmcnt(10)
	v_pk_fma_f32 v[178:179], v[88:89], v[178:179], v[120:121] op_sel_hi:[1,1,0]
	s_and_saveexec_b64 s[8:9], s[38:39]
	ds_write_b32 v103, v154 offset:37632
	ds_write_b32 v103, v155 offset:37696
	s_mov_b64 exec, s[8:9]
	v_pk_fma_f32 v[186:187], v[88:89], v[186:187], v[120:121] op_sel:[0,0,1] op_sel_hi:[1,1,1]
	v_pk_fma_f32 v[180:181], v[90:91], v[180:181], v[120:121] op_sel_hi:[1,1,0]
	v_pk_fma_f32 v[188:189], v[90:91], v[188:189], v[120:121] op_sel:[0,0,1] op_sel_hi:[1,1,1]
	s_waitcnt lgkmcnt(11)
	v_pk_fma_f32 v[182:183], v[92:93], v[182:183], v[120:121] op_sel_hi:[1,1,0]
	v_pk_fma_f32 v[190:191], v[92:93], v[190:191], v[120:121] op_sel:[0,0,1] op_sel_hi:[1,1,1]
	v_pk_fma_f32 v[184:185], v[94:95], v[184:185], v[120:121] op_sel_hi:[1,1,0]
	v_pk_fma_f32 v[192:193], v[94:95], v[192:193], v[120:121] op_sel:[0,0,1] op_sel_hi:[1,1,1]
	ds_read2_b32 v[120:121], v195 offset0:32 offset1:48
	ds_read_b128 v[88:91], v145 offset:12800
	ds_read_b128 v[92:95], v145 offset:13056
	s_waitcnt lgkmcnt(13)
	v_pk_fma_f32 v[146:147], v[80:81], v[178:179], v[196:197]
	v_pk_fma_f32 v[150:151], v[80:81], v[186:187], v[196:197]
	v_pk_fma_f32 v[148:149], v[82:83], v[180:181], v[196:197]
	v_pk_fma_f32 v[152:153], v[82:83], v[188:189], v[196:197]
	ds_read_b128 v[80:83], v145 offset:4608
	s_waitcnt lgkmcnt(13)
	v_pk_fma_f32 v[146:147], v[84:85], v[182:183], v[146:147]
	v_pk_fma_f32 v[150:151], v[84:85], v[190:191], v[150:151]
	v_pk_fma_f32 v[148:149], v[86:87], v[184:185], v[148:149]
	v_pk_fma_f32 v[152:153], v[86:87], v[192:193], v[152:153]
	ds_read_b128 v[84:87], v145 offset:4864
	v_add_f32_e32 v146, v146, v147
	v_add_f32_e32 v148, v148, v149
	v_add_f32_e32 v150, v150, v151
	v_add_f32_e32 v152, v152, v153
	v_add_f32_e32 v156, v146, v148
	v_add_f32_e32 v157, v150, v152
	s_waitcnt lgkmcnt(11)
	v_pk_add_f32 v[178:179], v[178:179], v[118:119] op_sel_hi:[1,0] neg_lo:[0,1] neg_hi:[0,1]
	v_add_f32_dpp v156, v156, v156 row_ror:8 row_mask:0xf bank_mask:0xf bound_ctrl:1
	v_pk_add_f32 v[186:187], v[186:187], v[118:119] op_sel:[0,1] op_sel_hi:[1,1] neg_lo:[0,1] neg_hi:[0,1]
	v_add_f32_dpp v157, v157, v157 row_ror:8 row_mask:0xf bank_mask:0xf bound_ctrl:1
	v_pk_add_f32 v[180:181], v[180:181], v[118:119] op_sel_hi:[1,0] neg_lo:[0,1] neg_hi:[0,1]
	v_add_f32_dpp v156, v156, v156 row_ror:4 row_mask:0xf bank_mask:0xf bound_ctrl:1
	v_pk_add_f32 v[188:189], v[188:189], v[118:119] op_sel:[0,1] op_sel_hi:[1,1] neg_lo:[0,1] neg_hi:[0,1]
	v_add_f32_dpp v157, v157, v157 row_ror:4 row_mask:0xf bank_mask:0xf bound_ctrl:1
	v_pk_add_f32 v[182:183], v[182:183], v[118:119] op_sel_hi:[1,0] neg_lo:[0,1] neg_hi:[0,1]
	v_add_f32_dpp v156, v156, v156 row_ror:2 row_mask:0xf bank_mask:0xf bound_ctrl:1
	v_pk_add_f32 v[190:191], v[190:191], v[118:119] op_sel:[0,1] op_sel_hi:[1,1] neg_lo:[0,1] neg_hi:[0,1]
	v_add_f32_dpp v157, v157, v157 row_ror:2 row_mask:0xf bank_mask:0xf bound_ctrl:1
	v_pk_add_f32 v[184:185], v[184:185], v[118:119] op_sel_hi:[1,0] neg_lo:[0,1] neg_hi:[0,1]
	v_add_f32_dpp v156, v156, v156 row_ror:1 row_mask:0xf bank_mask:0xf bound_ctrl:1
	v_pk_add_f32 v[192:193], v[192:193], v[118:119] op_sel:[0,1] op_sel_hi:[1,1] neg_lo:[0,1] neg_hi:[0,1]
	v_add_f32_dpp v157, v157, v157 row_ror:1 row_mask:0xf bank_mask:0xf bound_ctrl:1
	s_waitcnt lgkmcnt(10)
	v_pk_fma_f32 v[178:179], v[72:73], v[178:179], v[118:119] op_sel_hi:[1,1,0]
	s_and_saveexec_b64 s[8:9], s[38:39]
	ds_write_b32 v103, v156 offset:37760
	ds_write_b32 v103, v157 offset:37824
	s_mov_b64 exec, s[8:9]
	v_pk_fma_f32 v[186:187], v[72:73], v[186:187], v[118:119] op_sel:[0,0,1] op_sel_hi:[1,1,1]
	v_pk_fma_f32 v[180:181], v[74:75], v[180:181], v[118:119] op_sel_hi:[1,1,0]
	v_pk_fma_f32 v[188:189], v[74:75], v[188:189], v[118:119] op_sel:[0,0,1] op_sel_hi:[1,1,1]
	s_waitcnt lgkmcnt(11)
	v_pk_fma_f32 v[182:183], v[76:77], v[182:183], v[118:119] op_sel_hi:[1,1,0]
	v_pk_fma_f32 v[190:191], v[76:77], v[190:191], v[118:119] op_sel:[0,0,1] op_sel_hi:[1,1,1]
	v_pk_fma_f32 v[184:185], v[78:79], v[184:185], v[118:119] op_sel_hi:[1,1,0]
	v_pk_fma_f32 v[192:193], v[78:79], v[192:193], v[118:119] op_sel:[0,0,1] op_sel_hi:[1,1,1]
	ds_read2_b32 v[118:119], v195 offset0:64 offset1:80
	ds_read_b128 v[72:75], v145 offset:13312
	ds_read_b128 v[76:79], v145 offset:13568
	s_waitcnt lgkmcnt(13)
	v_pk_fma_f32 v[146:147], v[64:65], v[178:179], v[196:197]
	v_pk_fma_f32 v[150:151], v[64:65], v[186:187], v[196:197]
	v_pk_fma_f32 v[148:149], v[66:67], v[180:181], v[196:197]
	v_pk_fma_f32 v[152:153], v[66:67], v[188:189], v[196:197]
	ds_read_b128 v[64:67], v145 offset:5120
	s_waitcnt lgkmcnt(13)
	v_pk_fma_f32 v[146:147], v[68:69], v[182:183], v[146:147]
	v_pk_fma_f32 v[150:151], v[68:69], v[190:191], v[150:151]
	v_pk_fma_f32 v[148:149], v[70:71], v[184:185], v[148:149]
	v_pk_fma_f32 v[152:153], v[70:71], v[192:193], v[152:153]
	ds_read_b128 v[68:71], v145 offset:5376
	v_add_f32_e32 v146, v146, v147
	v_add_f32_e32 v148, v148, v149
	v_add_f32_e32 v150, v150, v151
	v_add_f32_e32 v152, v152, v153
	v_add_f32_e32 v154, v146, v148
	v_add_f32_e32 v155, v150, v152
	s_waitcnt lgkmcnt(11)
	v_pk_add_f32 v[178:179], v[178:179], v[120:121] op_sel_hi:[1,0] neg_lo:[0,1] neg_hi:[0,1]
	v_add_f32_dpp v154, v154, v154 row_ror:8 row_mask:0xf bank_mask:0xf bound_ctrl:1
	v_pk_add_f32 v[186:187], v[186:187], v[120:121] op_sel:[0,1] op_sel_hi:[1,1] neg_lo:[0,1] neg_hi:[0,1]
	v_add_f32_dpp v155, v155, v155 row_ror:8 row_mask:0xf bank_mask:0xf bound_ctrl:1
	v_pk_add_f32 v[180:181], v[180:181], v[120:121] op_sel_hi:[1,0] neg_lo:[0,1] neg_hi:[0,1]
	v_add_f32_dpp v154, v154, v154 row_ror:4 row_mask:0xf bank_mask:0xf bound_ctrl:1
	v_pk_add_f32 v[188:189], v[188:189], v[120:121] op_sel:[0,1] op_sel_hi:[1,1] neg_lo:[0,1] neg_hi:[0,1]
	v_add_f32_dpp v155, v155, v155 row_ror:4 row_mask:0xf bank_mask:0xf bound_ctrl:1
	v_pk_add_f32 v[182:183], v[182:183], v[120:121] op_sel_hi:[1,0] neg_lo:[0,1] neg_hi:[0,1]
	v_add_f32_dpp v154, v154, v154 row_ror:2 row_mask:0xf bank_mask:0xf bound_ctrl:1
	v_pk_add_f32 v[190:191], v[190:191], v[120:121] op_sel:[0,1] op_sel_hi:[1,1] neg_lo:[0,1] neg_hi:[0,1]
	v_add_f32_dpp v155, v155, v155 row_ror:2 row_mask:0xf bank_mask:0xf bound_ctrl:1
	v_pk_add_f32 v[184:185], v[184:185], v[120:121] op_sel_hi:[1,0] neg_lo:[0,1] neg_hi:[0,1]
	v_add_f32_dpp v154, v154, v154 row_ror:1 row_mask:0xf bank_mask:0xf bound_ctrl:1
	v_pk_add_f32 v[192:193], v[192:193], v[120:121] op_sel:[0,1] op_sel_hi:[1,1] neg_lo:[0,1] neg_hi:[0,1]
	v_add_f32_dpp v155, v155, v155 row_ror:1 row_mask:0xf bank_mask:0xf bound_ctrl:1
	s_waitcnt lgkmcnt(10)
	v_pk_fma_f32 v[178:179], v[88:89], v[178:179], v[120:121] op_sel_hi:[1,1,0]
	s_and_saveexec_b64 s[8:9], s[38:39]
	ds_write_b32 v103, v154 offset:37888
	ds_write_b32 v103, v155 offset:37952
	s_mov_b64 exec, s[8:9]
	v_pk_fma_f32 v[186:187], v[88:89], v[186:187], v[120:121] op_sel:[0,0,1] op_sel_hi:[1,1,1]
	v_pk_fma_f32 v[180:181], v[90:91], v[180:181], v[120:121] op_sel_hi:[1,1,0]
	v_pk_fma_f32 v[188:189], v[90:91], v[188:189], v[120:121] op_sel:[0,0,1] op_sel_hi:[1,1,1]
	s_waitcnt lgkmcnt(11)
	v_pk_fma_f32 v[182:183], v[92:93], v[182:183], v[120:121] op_sel_hi:[1,1,0]
	v_pk_fma_f32 v[190:191], v[92:93], v[190:191], v[120:121] op_sel:[0,0,1] op_sel_hi:[1,1,1]
	v_pk_fma_f32 v[184:185], v[94:95], v[184:185], v[120:121] op_sel_hi:[1,1,0]
	v_pk_fma_f32 v[192:193], v[94:95], v[192:193], v[120:121] op_sel:[0,0,1] op_sel_hi:[1,1,1]
	ds_read2_b32 v[120:121], v195 offset0:96 offset1:112
	ds_read_b128 v[88:91], v145 offset:13824
	ds_read_b128 v[92:95], v145 offset:14080
	s_waitcnt lgkmcnt(13)
	v_pk_fma_f32 v[146:147], v[80:81], v[178:179], v[196:197]
	v_pk_fma_f32 v[150:151], v[80:81], v[186:187], v[196:197]
	v_pk_fma_f32 v[148:149], v[82:83], v[180:181], v[196:197]
	v_pk_fma_f32 v[152:153], v[82:83], v[188:189], v[196:197]
	ds_read_b128 v[80:83], v145 offset:5632
	s_waitcnt lgkmcnt(13)
	v_pk_fma_f32 v[146:147], v[84:85], v[182:183], v[146:147]
	v_pk_fma_f32 v[150:151], v[84:85], v[190:191], v[150:151]
	v_pk_fma_f32 v[148:149], v[86:87], v[184:185], v[148:149]
	v_pk_fma_f32 v[152:153], v[86:87], v[192:193], v[152:153]
	ds_read_b128 v[84:87], v145 offset:5888
	v_add_f32_e32 v146, v146, v147
	v_add_f32_e32 v148, v148, v149
	v_add_f32_e32 v150, v150, v151
	v_add_f32_e32 v152, v152, v153
	v_add_f32_e32 v156, v146, v148
	v_add_f32_e32 v157, v150, v152
	s_waitcnt lgkmcnt(11)
	v_pk_add_f32 v[178:179], v[178:179], v[118:119] op_sel_hi:[1,0] neg_lo:[0,1] neg_hi:[0,1]
	v_add_f32_dpp v156, v156, v156 row_ror:8 row_mask:0xf bank_mask:0xf bound_ctrl:1
	v_pk_add_f32 v[186:187], v[186:187], v[118:119] op_sel:[0,1] op_sel_hi:[1,1] neg_lo:[0,1] neg_hi:[0,1]
	v_add_f32_dpp v157, v157, v157 row_ror:8 row_mask:0xf bank_mask:0xf bound_ctrl:1
	v_pk_add_f32 v[180:181], v[180:181], v[118:119] op_sel_hi:[1,0] neg_lo:[0,1] neg_hi:[0,1]
	v_add_f32_dpp v156, v156, v156 row_ror:4 row_mask:0xf bank_mask:0xf bound_ctrl:1
	v_pk_add_f32 v[188:189], v[188:189], v[118:119] op_sel:[0,1] op_sel_hi:[1,1] neg_lo:[0,1] neg_hi:[0,1]
	v_add_f32_dpp v157, v157, v157 row_ror:4 row_mask:0xf bank_mask:0xf bound_ctrl:1
	v_pk_add_f32 v[182:183], v[182:183], v[118:119] op_sel_hi:[1,0] neg_lo:[0,1] neg_hi:[0,1]
	v_add_f32_dpp v156, v156, v156 row_ror:2 row_mask:0xf bank_mask:0xf bound_ctrl:1
	v_pk_add_f32 v[190:191], v[190:191], v[118:119] op_sel:[0,1] op_sel_hi:[1,1] neg_lo:[0,1] neg_hi:[0,1]
	v_add_f32_dpp v157, v157, v157 row_ror:2 row_mask:0xf bank_mask:0xf bound_ctrl:1
	v_pk_add_f32 v[184:185], v[184:185], v[118:119] op_sel_hi:[1,0] neg_lo:[0,1] neg_hi:[0,1]
	v_add_f32_dpp v156, v156, v156 row_ror:1 row_mask:0xf bank_mask:0xf bound_ctrl:1
	v_pk_add_f32 v[192:193], v[192:193], v[118:119] op_sel:[0,1] op_sel_hi:[1,1] neg_lo:[0,1] neg_hi:[0,1]
	v_add_f32_dpp v157, v157, v157 row_ror:1 row_mask:0xf bank_mask:0xf bound_ctrl:1
	s_waitcnt lgkmcnt(10)
	v_pk_fma_f32 v[178:179], v[72:73], v[178:179], v[118:119] op_sel_hi:[1,1,0]
	s_and_saveexec_b64 s[8:9], s[38:39]
	ds_write_b32 v103, v156 offset:38016
	ds_write_b32 v103, v157 offset:38080
	s_mov_b64 exec, s[8:9]
	v_pk_fma_f32 v[186:187], v[72:73], v[186:187], v[118:119] op_sel:[0,0,1] op_sel_hi:[1,1,1]
	v_pk_fma_f32 v[180:181], v[74:75], v[180:181], v[118:119] op_sel_hi:[1,1,0]
	v_pk_fma_f32 v[188:189], v[74:75], v[188:189], v[118:119] op_sel:[0,0,1] op_sel_hi:[1,1,1]
	s_waitcnt lgkmcnt(11)
	v_pk_fma_f32 v[182:183], v[76:77], v[182:183], v[118:119] op_sel_hi:[1,1,0]
	v_pk_fma_f32 v[190:191], v[76:77], v[190:191], v[118:119] op_sel:[0,0,1] op_sel_hi:[1,1,1]
	v_pk_fma_f32 v[184:185], v[78:79], v[184:185], v[118:119] op_sel_hi:[1,1,0]
	v_pk_fma_f32 v[192:193], v[78:79], v[192:193], v[118:119] op_sel:[0,0,1] op_sel_hi:[1,1,1]
	ds_read2_b32 v[118:119], v195 offset0:128 offset1:144
	ds_read_b128 v[72:75], v145 offset:14336
	ds_read_b128 v[76:79], v145 offset:14592
	s_waitcnt lgkmcnt(13)
	v_pk_fma_f32 v[146:147], v[64:65], v[178:179], v[196:197]
	v_pk_fma_f32 v[150:151], v[64:65], v[186:187], v[196:197]
	v_pk_fma_f32 v[148:149], v[66:67], v[180:181], v[196:197]
	v_pk_fma_f32 v[152:153], v[66:67], v[188:189], v[196:197]
	ds_read_b128 v[64:67], v145 offset:6144
	s_waitcnt lgkmcnt(13)
	v_pk_fma_f32 v[146:147], v[68:69], v[182:183], v[146:147]
	v_pk_fma_f32 v[150:151], v[68:69], v[190:191], v[150:151]
	v_pk_fma_f32 v[148:149], v[70:71], v[184:185], v[148:149]
	v_pk_fma_f32 v[152:153], v[70:71], v[192:193], v[152:153]
	ds_read_b128 v[68:71], v145 offset:6400
	v_add_f32_e32 v146, v146, v147
	v_add_f32_e32 v148, v148, v149
	v_add_f32_e32 v150, v150, v151
	v_add_f32_e32 v152, v152, v153
	v_add_f32_e32 v154, v146, v148
	v_add_f32_e32 v155, v150, v152
	s_waitcnt lgkmcnt(11)
	v_pk_add_f32 v[178:179], v[178:179], v[120:121] op_sel_hi:[1,0] neg_lo:[0,1] neg_hi:[0,1]
	v_add_f32_dpp v154, v154, v154 row_ror:8 row_mask:0xf bank_mask:0xf bound_ctrl:1
	v_pk_add_f32 v[186:187], v[186:187], v[120:121] op_sel:[0,1] op_sel_hi:[1,1] neg_lo:[0,1] neg_hi:[0,1]
	v_add_f32_dpp v155, v155, v155 row_ror:8 row_mask:0xf bank_mask:0xf bound_ctrl:1
	v_pk_add_f32 v[180:181], v[180:181], v[120:121] op_sel_hi:[1,0] neg_lo:[0,1] neg_hi:[0,1]
	v_add_f32_dpp v154, v154, v154 row_ror:4 row_mask:0xf bank_mask:0xf bound_ctrl:1
	v_pk_add_f32 v[188:189], v[188:189], v[120:121] op_sel:[0,1] op_sel_hi:[1,1] neg_lo:[0,1] neg_hi:[0,1]
	v_add_f32_dpp v155, v155, v155 row_ror:4 row_mask:0xf bank_mask:0xf bound_ctrl:1
	v_pk_add_f32 v[182:183], v[182:183], v[120:121] op_sel_hi:[1,0] neg_lo:[0,1] neg_hi:[0,1]
	v_add_f32_dpp v154, v154, v154 row_ror:2 row_mask:0xf bank_mask:0xf bound_ctrl:1
	v_pk_add_f32 v[190:191], v[190:191], v[120:121] op_sel:[0,1] op_sel_hi:[1,1] neg_lo:[0,1] neg_hi:[0,1]
	v_add_f32_dpp v155, v155, v155 row_ror:2 row_mask:0xf bank_mask:0xf bound_ctrl:1
	v_pk_add_f32 v[184:185], v[184:185], v[120:121] op_sel_hi:[1,0] neg_lo:[0,1] neg_hi:[0,1]
	v_add_f32_dpp v154, v154, v154 row_ror:1 row_mask:0xf bank_mask:0xf bound_ctrl:1
	v_pk_add_f32 v[192:193], v[192:193], v[120:121] op_sel:[0,1] op_sel_hi:[1,1] neg_lo:[0,1] neg_hi:[0,1]
	v_add_f32_dpp v155, v155, v155 row_ror:1 row_mask:0xf bank_mask:0xf bound_ctrl:1
	s_waitcnt lgkmcnt(10)
	v_pk_fma_f32 v[178:179], v[88:89], v[178:179], v[120:121] op_sel_hi:[1,1,0]
	s_and_saveexec_b64 s[8:9], s[38:39]
	ds_write_b32 v103, v154 offset:38144
	ds_write_b32 v103, v155 offset:38208
	s_mov_b64 exec, s[8:9]
	v_pk_fma_f32 v[186:187], v[88:89], v[186:187], v[120:121] op_sel:[0,0,1] op_sel_hi:[1,1,1]
	v_pk_fma_f32 v[180:181], v[90:91], v[180:181], v[120:121] op_sel_hi:[1,1,0]
	v_pk_fma_f32 v[188:189], v[90:91], v[188:189], v[120:121] op_sel:[0,0,1] op_sel_hi:[1,1,1]
	s_waitcnt lgkmcnt(11)
	v_pk_fma_f32 v[182:183], v[92:93], v[182:183], v[120:121] op_sel_hi:[1,1,0]
	v_pk_fma_f32 v[190:191], v[92:93], v[190:191], v[120:121] op_sel:[0,0,1] op_sel_hi:[1,1,1]
	v_pk_fma_f32 v[184:185], v[94:95], v[184:185], v[120:121] op_sel_hi:[1,1,0]
	v_pk_fma_f32 v[192:193], v[94:95], v[192:193], v[120:121] op_sel:[0,0,1] op_sel_hi:[1,1,1]
	ds_read2_b32 v[120:121], v195 offset0:160 offset1:176
	ds_read_b128 v[88:91], v145 offset:14848
	ds_read_b128 v[92:95], v145 offset:15104
	s_waitcnt lgkmcnt(13)
	v_pk_fma_f32 v[146:147], v[80:81], v[178:179], v[196:197]
	v_pk_fma_f32 v[150:151], v[80:81], v[186:187], v[196:197]
	v_pk_fma_f32 v[148:149], v[82:83], v[180:181], v[196:197]
	v_pk_fma_f32 v[152:153], v[82:83], v[188:189], v[196:197]
	ds_read_b128 v[80:83], v145 offset:6656
	s_waitcnt lgkmcnt(13)
	v_pk_fma_f32 v[146:147], v[84:85], v[182:183], v[146:147]
	v_pk_fma_f32 v[150:151], v[84:85], v[190:191], v[150:151]
	v_pk_fma_f32 v[148:149], v[86:87], v[184:185], v[148:149]
	v_pk_fma_f32 v[152:153], v[86:87], v[192:193], v[152:153]
	ds_read_b128 v[84:87], v145 offset:6912
	v_add_f32_e32 v146, v146, v147
	v_add_f32_e32 v148, v148, v149
	v_add_f32_e32 v150, v150, v151
	v_add_f32_e32 v152, v152, v153
	v_add_f32_e32 v156, v146, v148
	v_add_f32_e32 v157, v150, v152
	s_waitcnt lgkmcnt(11)
	v_pk_add_f32 v[178:179], v[178:179], v[118:119] op_sel_hi:[1,0] neg_lo:[0,1] neg_hi:[0,1]
	v_add_f32_dpp v156, v156, v156 row_ror:8 row_mask:0xf bank_mask:0xf bound_ctrl:1
	v_pk_add_f32 v[186:187], v[186:187], v[118:119] op_sel:[0,1] op_sel_hi:[1,1] neg_lo:[0,1] neg_hi:[0,1]
	v_add_f32_dpp v157, v157, v157 row_ror:8 row_mask:0xf bank_mask:0xf bound_ctrl:1
	v_pk_add_f32 v[180:181], v[180:181], v[118:119] op_sel_hi:[1,0] neg_lo:[0,1] neg_hi:[0,1]
	v_add_f32_dpp v156, v156, v156 row_ror:4 row_mask:0xf bank_mask:0xf bound_ctrl:1
	v_pk_add_f32 v[188:189], v[188:189], v[118:119] op_sel:[0,1] op_sel_hi:[1,1] neg_lo:[0,1] neg_hi:[0,1]
	v_add_f32_dpp v157, v157, v157 row_ror:4 row_mask:0xf bank_mask:0xf bound_ctrl:1
	v_pk_add_f32 v[182:183], v[182:183], v[118:119] op_sel_hi:[1,0] neg_lo:[0,1] neg_hi:[0,1]
	v_add_f32_dpp v156, v156, v156 row_ror:2 row_mask:0xf bank_mask:0xf bound_ctrl:1
	v_pk_add_f32 v[190:191], v[190:191], v[118:119] op_sel:[0,1] op_sel_hi:[1,1] neg_lo:[0,1] neg_hi:[0,1]
	v_add_f32_dpp v157, v157, v157 row_ror:2 row_mask:0xf bank_mask:0xf bound_ctrl:1
	v_pk_add_f32 v[184:185], v[184:185], v[118:119] op_sel_hi:[1,0] neg_lo:[0,1] neg_hi:[0,1]
	v_add_f32_dpp v156, v156, v156 row_ror:1 row_mask:0xf bank_mask:0xf bound_ctrl:1
	v_pk_add_f32 v[192:193], v[192:193], v[118:119] op_sel:[0,1] op_sel_hi:[1,1] neg_lo:[0,1] neg_hi:[0,1]
	v_add_f32_dpp v157, v157, v157 row_ror:1 row_mask:0xf bank_mask:0xf bound_ctrl:1
	s_waitcnt lgkmcnt(10)
	v_pk_fma_f32 v[178:179], v[72:73], v[178:179], v[118:119] op_sel_hi:[1,1,0]
	s_and_saveexec_b64 s[8:9], s[38:39]
	ds_write_b32 v103, v156 offset:38272
	ds_write_b32 v103, v157 offset:38336
	s_mov_b64 exec, s[8:9]
	v_pk_fma_f32 v[186:187], v[72:73], v[186:187], v[118:119] op_sel:[0,0,1] op_sel_hi:[1,1,1]
	v_pk_fma_f32 v[180:181], v[74:75], v[180:181], v[118:119] op_sel_hi:[1,1,0]
	v_pk_fma_f32 v[188:189], v[74:75], v[188:189], v[118:119] op_sel:[0,0,1] op_sel_hi:[1,1,1]
	s_waitcnt lgkmcnt(11)
	v_pk_fma_f32 v[182:183], v[76:77], v[182:183], v[118:119] op_sel_hi:[1,1,0]
	v_pk_fma_f32 v[190:191], v[76:77], v[190:191], v[118:119] op_sel:[0,0,1] op_sel_hi:[1,1,1]
	v_pk_fma_f32 v[184:185], v[78:79], v[184:185], v[118:119] op_sel_hi:[1,1,0]
	v_pk_fma_f32 v[192:193], v[78:79], v[192:193], v[118:119] op_sel:[0,0,1] op_sel_hi:[1,1,1]
	ds_read2_b32 v[118:119], v195 offset0:192 offset1:208
	ds_read_b128 v[72:75], v145 offset:15360
	ds_read_b128 v[76:79], v145 offset:15616
	s_waitcnt lgkmcnt(13)
	v_pk_fma_f32 v[146:147], v[64:65], v[178:179], v[196:197]
	v_pk_fma_f32 v[150:151], v[64:65], v[186:187], v[196:197]
	v_pk_fma_f32 v[148:149], v[66:67], v[180:181], v[196:197]
	v_pk_fma_f32 v[152:153], v[66:67], v[188:189], v[196:197]
	ds_read_b128 v[64:67], v145 offset:7168
	s_waitcnt lgkmcnt(13)
	v_pk_fma_f32 v[146:147], v[68:69], v[182:183], v[146:147]
	v_pk_fma_f32 v[150:151], v[68:69], v[190:191], v[150:151]
	v_pk_fma_f32 v[148:149], v[70:71], v[184:185], v[148:149]
	v_pk_fma_f32 v[152:153], v[70:71], v[192:193], v[152:153]
	ds_read_b128 v[68:71], v145 offset:7424
	v_add_f32_e32 v146, v146, v147
	v_add_f32_e32 v148, v148, v149
	v_add_f32_e32 v150, v150, v151
	v_add_f32_e32 v152, v152, v153
	v_add_f32_e32 v154, v146, v148
	v_add_f32_e32 v155, v150, v152
	s_waitcnt lgkmcnt(11)
	v_pk_add_f32 v[178:179], v[178:179], v[120:121] op_sel_hi:[1,0] neg_lo:[0,1] neg_hi:[0,1]
	v_add_f32_dpp v154, v154, v154 row_ror:8 row_mask:0xf bank_mask:0xf bound_ctrl:1
	v_pk_add_f32 v[186:187], v[186:187], v[120:121] op_sel:[0,1] op_sel_hi:[1,1] neg_lo:[0,1] neg_hi:[0,1]
	v_add_f32_dpp v155, v155, v155 row_ror:8 row_mask:0xf bank_mask:0xf bound_ctrl:1
	v_pk_add_f32 v[180:181], v[180:181], v[120:121] op_sel_hi:[1,0] neg_lo:[0,1] neg_hi:[0,1]
	v_add_f32_dpp v154, v154, v154 row_ror:4 row_mask:0xf bank_mask:0xf bound_ctrl:1
	v_pk_add_f32 v[188:189], v[188:189], v[120:121] op_sel:[0,1] op_sel_hi:[1,1] neg_lo:[0,1] neg_hi:[0,1]
	v_add_f32_dpp v155, v155, v155 row_ror:4 row_mask:0xf bank_mask:0xf bound_ctrl:1
	v_pk_add_f32 v[182:183], v[182:183], v[120:121] op_sel_hi:[1,0] neg_lo:[0,1] neg_hi:[0,1]
	v_add_f32_dpp v154, v154, v154 row_ror:2 row_mask:0xf bank_mask:0xf bound_ctrl:1
	v_pk_add_f32 v[190:191], v[190:191], v[120:121] op_sel:[0,1] op_sel_hi:[1,1] neg_lo:[0,1] neg_hi:[0,1]
	v_add_f32_dpp v155, v155, v155 row_ror:2 row_mask:0xf bank_mask:0xf bound_ctrl:1
	v_pk_add_f32 v[184:185], v[184:185], v[120:121] op_sel_hi:[1,0] neg_lo:[0,1] neg_hi:[0,1]
	v_add_f32_dpp v154, v154, v154 row_ror:1 row_mask:0xf bank_mask:0xf bound_ctrl:1
	v_pk_add_f32 v[192:193], v[192:193], v[120:121] op_sel:[0,1] op_sel_hi:[1,1] neg_lo:[0,1] neg_hi:[0,1]
	v_add_f32_dpp v155, v155, v155 row_ror:1 row_mask:0xf bank_mask:0xf bound_ctrl:1
	s_waitcnt lgkmcnt(10)
	v_pk_fma_f32 v[178:179], v[88:89], v[178:179], v[120:121] op_sel_hi:[1,1,0]
	s_and_saveexec_b64 s[8:9], s[38:39]
	ds_write_b32 v103, v154 offset:38400
	ds_write_b32 v103, v155 offset:38464
	s_mov_b64 exec, s[8:9]
	v_pk_fma_f32 v[186:187], v[88:89], v[186:187], v[120:121] op_sel:[0,0,1] op_sel_hi:[1,1,1]
	v_pk_fma_f32 v[180:181], v[90:91], v[180:181], v[120:121] op_sel_hi:[1,1,0]
	v_pk_fma_f32 v[188:189], v[90:91], v[188:189], v[120:121] op_sel:[0,0,1] op_sel_hi:[1,1,1]
	s_waitcnt lgkmcnt(11)
	v_pk_fma_f32 v[182:183], v[92:93], v[182:183], v[120:121] op_sel_hi:[1,1,0]
	v_pk_fma_f32 v[190:191], v[92:93], v[190:191], v[120:121] op_sel:[0,0,1] op_sel_hi:[1,1,1]
	v_pk_fma_f32 v[184:185], v[94:95], v[184:185], v[120:121] op_sel_hi:[1,1,0]
	v_pk_fma_f32 v[192:193], v[94:95], v[192:193], v[120:121] op_sel:[0,0,1] op_sel_hi:[1,1,1]
	ds_read2_b32 v[120:121], v195 offset0:224 offset1:240
	ds_read_b128 v[88:91], v145 offset:15872
	ds_read_b128 v[92:95], v145 offset:16128
	s_waitcnt lgkmcnt(13)
	v_pk_fma_f32 v[146:147], v[80:81], v[178:179], v[196:197]
	v_pk_fma_f32 v[150:151], v[80:81], v[186:187], v[196:197]
	v_pk_fma_f32 v[148:149], v[82:83], v[180:181], v[196:197]
	v_pk_fma_f32 v[152:153], v[82:83], v[188:189], v[196:197]
	ds_read_b128 v[80:83], v145 offset:7680
	s_waitcnt lgkmcnt(13)
	v_pk_fma_f32 v[146:147], v[84:85], v[182:183], v[146:147]
	v_pk_fma_f32 v[150:151], v[84:85], v[190:191], v[150:151]
	v_pk_fma_f32 v[148:149], v[86:87], v[184:185], v[148:149]
	v_pk_fma_f32 v[152:153], v[86:87], v[192:193], v[152:153]
	ds_read_b128 v[84:87], v145 offset:7936
	v_add_f32_e32 v146, v146, v147
	v_add_f32_e32 v148, v148, v149
	v_add_f32_e32 v150, v150, v151
	v_add_f32_e32 v152, v152, v153
	v_add_f32_e32 v156, v146, v148
	v_add_f32_e32 v157, v150, v152
	s_waitcnt lgkmcnt(11)
	v_pk_add_f32 v[178:179], v[178:179], v[118:119] op_sel_hi:[1,0] neg_lo:[0,1] neg_hi:[0,1]
	v_add_f32_dpp v156, v156, v156 row_ror:8 row_mask:0xf bank_mask:0xf bound_ctrl:1
	v_pk_add_f32 v[186:187], v[186:187], v[118:119] op_sel:[0,1] op_sel_hi:[1,1] neg_lo:[0,1] neg_hi:[0,1]
	v_add_f32_dpp v157, v157, v157 row_ror:8 row_mask:0xf bank_mask:0xf bound_ctrl:1
	v_pk_add_f32 v[180:181], v[180:181], v[118:119] op_sel_hi:[1,0] neg_lo:[0,1] neg_hi:[0,1]
	v_add_f32_dpp v156, v156, v156 row_ror:4 row_mask:0xf bank_mask:0xf bound_ctrl:1
	v_pk_add_f32 v[188:189], v[188:189], v[118:119] op_sel:[0,1] op_sel_hi:[1,1] neg_lo:[0,1] neg_hi:[0,1]
	v_add_f32_dpp v157, v157, v157 row_ror:4 row_mask:0xf bank_mask:0xf bound_ctrl:1
	v_pk_add_f32 v[182:183], v[182:183], v[118:119] op_sel_hi:[1,0] neg_lo:[0,1] neg_hi:[0,1]
	v_add_f32_dpp v156, v156, v156 row_ror:2 row_mask:0xf bank_mask:0xf bound_ctrl:1
	v_pk_add_f32 v[190:191], v[190:191], v[118:119] op_sel:[0,1] op_sel_hi:[1,1] neg_lo:[0,1] neg_hi:[0,1]
	v_add_f32_dpp v157, v157, v157 row_ror:2 row_mask:0xf bank_mask:0xf bound_ctrl:1
	v_pk_add_f32 v[184:185], v[184:185], v[118:119] op_sel_hi:[1,0] neg_lo:[0,1] neg_hi:[0,1]
	v_add_f32_dpp v156, v156, v156 row_ror:1 row_mask:0xf bank_mask:0xf bound_ctrl:1
	v_pk_add_f32 v[192:193], v[192:193], v[118:119] op_sel:[0,1] op_sel_hi:[1,1] neg_lo:[0,1] neg_hi:[0,1]
	v_add_f32_dpp v157, v157, v157 row_ror:1 row_mask:0xf bank_mask:0xf bound_ctrl:1
	s_waitcnt lgkmcnt(10)
	v_pk_fma_f32 v[178:179], v[72:73], v[178:179], v[118:119] op_sel_hi:[1,1,0]
	s_and_saveexec_b64 s[8:9], s[38:39]
	ds_write_b32 v103, v156 offset:38528
	ds_write_b32 v103, v157 offset:38592
	s_mov_b64 exec, s[8:9]
	v_pk_fma_f32 v[186:187], v[72:73], v[186:187], v[118:119] op_sel:[0,0,1] op_sel_hi:[1,1,1]
	v_pk_fma_f32 v[180:181], v[74:75], v[180:181], v[118:119] op_sel_hi:[1,1,0]
	v_pk_fma_f32 v[188:189], v[74:75], v[188:189], v[118:119] op_sel:[0,0,1] op_sel_hi:[1,1,1]
	s_waitcnt lgkmcnt(11)
	v_pk_fma_f32 v[182:183], v[76:77], v[182:183], v[118:119] op_sel_hi:[1,1,0]
	v_pk_fma_f32 v[190:191], v[76:77], v[190:191], v[118:119] op_sel:[0,0,1] op_sel_hi:[1,1,1]
	v_pk_fma_f32 v[184:185], v[78:79], v[184:185], v[118:119] op_sel_hi:[1,1,0]
	v_pk_fma_f32 v[192:193], v[78:79], v[192:193], v[118:119] op_sel:[0,0,1] op_sel_hi:[1,1,1]
	s_waitcnt lgkmcnt(10)
	v_pk_fma_f32 v[146:147], v[64:65], v[178:179], v[196:197]
	v_pk_fma_f32 v[150:151], v[64:65], v[186:187], v[196:197]
	v_pk_fma_f32 v[148:149], v[66:67], v[180:181], v[196:197]
	v_pk_fma_f32 v[152:153], v[66:67], v[188:189], v[196:197]
	s_waitcnt lgkmcnt(9)
	v_pk_fma_f32 v[146:147], v[68:69], v[182:183], v[146:147]
	v_pk_fma_f32 v[150:151], v[68:69], v[190:191], v[150:151]
	v_pk_fma_f32 v[148:149], v[70:71], v[184:185], v[148:149]
	v_pk_fma_f32 v[152:153], v[70:71], v[192:193], v[152:153]
	v_add_f32_e32 v146, v146, v147
	v_add_f32_e32 v148, v148, v149
	v_add_f32_e32 v150, v150, v151
	v_add_f32_e32 v152, v152, v153
	v_add_f32_e32 v154, v146, v148
	v_add_f32_e32 v155, v150, v152
	s_waitcnt lgkmcnt(6)
	v_pk_add_f32 v[178:179], v[178:179], v[120:121] op_sel_hi:[1,0] neg_lo:[0,1] neg_hi:[0,1]
	v_add_f32_dpp v154, v154, v154 row_ror:8 row_mask:0xf bank_mask:0xf bound_ctrl:1
	v_pk_add_f32 v[186:187], v[186:187], v[120:121] op_sel:[0,1] op_sel_hi:[1,1] neg_lo:[0,1] neg_hi:[0,1]
	v_add_f32_dpp v155, v155, v155 row_ror:8 row_mask:0xf bank_mask:0xf bound_ctrl:1
	v_pk_add_f32 v[180:181], v[180:181], v[120:121] op_sel_hi:[1,0] neg_lo:[0,1] neg_hi:[0,1]
	v_add_f32_dpp v154, v154, v154 row_ror:4 row_mask:0xf bank_mask:0xf bound_ctrl:1
	v_pk_add_f32 v[188:189], v[188:189], v[120:121] op_sel:[0,1] op_sel_hi:[1,1] neg_lo:[0,1] neg_hi:[0,1]
	v_add_f32_dpp v155, v155, v155 row_ror:4 row_mask:0xf bank_mask:0xf bound_ctrl:1
	v_pk_add_f32 v[182:183], v[182:183], v[120:121] op_sel_hi:[1,0] neg_lo:[0,1] neg_hi:[0,1]
	v_add_f32_dpp v154, v154, v154 row_ror:2 row_mask:0xf bank_mask:0xf bound_ctrl:1
	v_pk_add_f32 v[190:191], v[190:191], v[120:121] op_sel:[0,1] op_sel_hi:[1,1] neg_lo:[0,1] neg_hi:[0,1]
	v_add_f32_dpp v155, v155, v155 row_ror:2 row_mask:0xf bank_mask:0xf bound_ctrl:1
	v_pk_add_f32 v[184:185], v[184:185], v[120:121] op_sel_hi:[1,0] neg_lo:[0,1] neg_hi:[0,1]
	v_add_f32_dpp v154, v154, v154 row_ror:1 row_mask:0xf bank_mask:0xf bound_ctrl:1
	v_pk_add_f32 v[192:193], v[192:193], v[120:121] op_sel:[0,1] op_sel_hi:[1,1] neg_lo:[0,1] neg_hi:[0,1]
	v_add_f32_dpp v155, v155, v155 row_ror:1 row_mask:0xf bank_mask:0xf bound_ctrl:1
	s_waitcnt lgkmcnt(5)
	v_pk_fma_f32 v[178:179], v[88:89], v[178:179], v[120:121] op_sel_hi:[1,1,0]
	s_and_saveexec_b64 s[8:9], s[38:39]
	ds_write_b32 v103, v154 offset:38656
	ds_write_b32 v103, v155 offset:38720
	s_mov_b64 exec, s[8:9]
	v_pk_fma_f32 v[186:187], v[88:89], v[186:187], v[120:121] op_sel:[0,0,1] op_sel_hi:[1,1,1]
	v_pk_fma_f32 v[180:181], v[90:91], v[180:181], v[120:121] op_sel_hi:[1,1,0]
	v_pk_fma_f32 v[188:189], v[90:91], v[188:189], v[120:121] op_sel:[0,0,1] op_sel_hi:[1,1,1]
	s_waitcnt lgkmcnt(6)
	v_pk_fma_f32 v[182:183], v[92:93], v[182:183], v[120:121] op_sel_hi:[1,1,0]
	v_pk_fma_f32 v[190:191], v[92:93], v[190:191], v[120:121] op_sel:[0,0,1] op_sel_hi:[1,1,1]
	v_pk_fma_f32 v[184:185], v[94:95], v[184:185], v[120:121] op_sel_hi:[1,1,0]
	v_pk_fma_f32 v[192:193], v[94:95], v[192:193], v[120:121] op_sel:[0,0,1] op_sel_hi:[1,1,1]
	s_waitcnt lgkmcnt(5)
	v_pk_fma_f32 v[146:147], v[80:81], v[178:179], v[196:197]
	v_pk_fma_f32 v[150:151], v[80:81], v[186:187], v[196:197]
	v_pk_fma_f32 v[148:149], v[82:83], v[180:181], v[196:197]
	v_pk_fma_f32 v[152:153], v[82:83], v[188:189], v[196:197]
	s_waitcnt lgkmcnt(4)
	v_pk_fma_f32 v[146:147], v[84:85], v[182:183], v[146:147]
	v_pk_fma_f32 v[150:151], v[84:85], v[190:191], v[150:151]
	v_pk_fma_f32 v[148:149], v[86:87], v[184:185], v[148:149]
	v_pk_fma_f32 v[152:153], v[86:87], v[192:193], v[152:153]
	v_add_f32_e32 v146, v146, v147
	v_add_f32_e32 v148, v148, v149
	v_add_f32_e32 v150, v150, v151
	v_add_f32_e32 v152, v152, v153
	v_add_f32_e32 v156, v146, v148
	v_add_f32_e32 v157, v150, v152
	s_nop 0
	v_add_f32_dpp v156, v156, v156 row_ror:8 row_mask:0xf bank_mask:0xf bound_ctrl:1
	v_add_f32_dpp v157, v157, v157 row_ror:8 row_mask:0xf bank_mask:0xf bound_ctrl:1
	s_nop 0
	v_add_f32_dpp v156, v156, v156 row_ror:4 row_mask:0xf bank_mask:0xf bound_ctrl:1
	v_add_f32_dpp v157, v157, v157 row_ror:4 row_mask:0xf bank_mask:0xf bound_ctrl:1
	s_nop 0
	v_add_f32_dpp v156, v156, v156 row_ror:2 row_mask:0xf bank_mask:0xf bound_ctrl:1
	v_add_f32_dpp v157, v157, v157 row_ror:2 row_mask:0xf bank_mask:0xf bound_ctrl:1
	s_nop 0
	v_add_f32_dpp v156, v156, v156 row_ror:1 row_mask:0xf bank_mask:0xf bound_ctrl:1
	v_add_f32_dpp v157, v157, v157 row_ror:1 row_mask:0xf bank_mask:0xf bound_ctrl:1
	s_and_saveexec_b64 s[8:9], s[38:39]
	ds_write_b32 v103, v156 offset:38784
	ds_write_b32 v103, v157 offset:38848
	s_mov_b64 exec, s[8:9]
	s_waitcnt vmcnt(9)
	v_mul_f32_e32 v64, 0xbfb8aa3b, v16
	v_mul_f32_e32 v65, 0xbfb8aa3b, v17
	v_exp_f32_e32 v64, v64
	v_exp_f32_e32 v65, v65
	v_mul_f32_e32 v66, 0xbfb8aa3b, v18
	v_mul_f32_e32 v67, 0xbfb8aa3b, v19
	v_exp_f32_e32 v66, v66
	v_pk_add_f32 v[64:65], v[64:65], 1.0 op_sel_hi:[1,0]
	v_exp_f32_e32 v67, v67
	v_div_scale_f32 v76, s[8:9], v65, v65, v17
	v_rcp_f32_e32 v77, v76
	v_pk_add_f32 v[66:67], v[66:67], 1.0 op_sel_hi:[1,0]
	s_waitcnt vmcnt(8)
	v_mul_f32_e32 v72, 0xbfb8aa3b, v20
	v_mul_f32_e32 v73, 0xbfb8aa3b, v21
	v_fma_f32 v78, -v76, v77, 1.0
	v_fmac_f32_e32 v77, v78, v77
	v_div_scale_f32 v78, vcc, v17, v65, v17
	v_mul_f32_e32 v79, v78, v77
	v_fma_f32 v80, -v76, v79, v78
	v_fmac_f32_e32 v79, v80, v77
	v_fma_f32 v76, -v76, v79, v78
	v_div_fmas_f32 v76, v76, v77, v79
	v_div_fixup_f32 v65, v76, v65, v17
	v_div_scale_f32 v76, s[8:9], v64, v64, v16
	v_rcp_f32_e32 v77, v76
	v_exp_f32_e32 v72, v72
	v_exp_f32_e32 v73, v73
	v_mul_f32_e32 v74, 0xbfb8aa3b, v22
	v_fma_f32 v78, -v76, v77, 1.0
	v_fmac_f32_e32 v77, v78, v77
	v_div_scale_f32 v78, vcc, v16, v64, v16
	v_mul_f32_e32 v79, v78, v77
	v_fma_f32 v80, -v76, v79, v78
	v_fmac_f32_e32 v79, v80, v77
	v_fma_f32 v76, -v76, v79, v78
	v_div_fmas_f32 v76, v76, v77, v79
	v_div_fixup_f32 v64, v76, v64, v16
	v_div_scale_f32 v76, s[8:9], v67, v67, v19
	v_rcp_f32_e32 v77, v76
	v_pk_mul_f32 v[64:65], v[64:65], s[18:19] op_sel_hi:[1,0]
	v_mul_f32_e32 v75, 0xbfb8aa3b, v23
	v_exp_f32_e32 v74, v74
	v_fma_f32 v78, -v76, v77, 1.0
	v_fmac_f32_e32 v77, v78, v77
	v_div_scale_f32 v78, vcc, v19, v67, v19
	v_mul_f32_e32 v79, v78, v77
	v_fma_f32 v80, -v76, v79, v78
	v_fmac_f32_e32 v79, v80, v77
	v_fma_f32 v76, -v76, v79, v78
	v_div_fmas_f32 v76, v76, v77, v79
	v_div_fixup_f32 v67, v76, v67, v19
	v_div_scale_f32 v76, s[8:9], v66, v66, v18
	v_rcp_f32_e32 v77, v76
	v_exp_f32_e32 v75, v75
	s_cmpk_lt_u32 s48, 0x7b
	v_fma_f32 v78, -v76, v77, 1.0
	v_fmac_f32_e32 v77, v78, v77
	v_div_scale_f32 v78, vcc, v18, v66, v18
	v_mul_f32_e32 v79, v78, v77
	v_fma_f32 v80, -v76, v79, v78
	v_fmac_f32_e32 v79, v80, v77
	v_fma_f32 v76, -v76, v79, v78
	v_div_fmas_f32 v76, v76, v77, v79
	v_div_fixup_f32 v66, v76, v66, v18
	v_pk_mul_f32 v[66:67], v[66:67], s[18:19] op_sel_hi:[1,0]
	ds_write_b128 v141, v[64:67] offset:18432
	v_pk_add_f32 v[64:65], v[72:73], 1.0 op_sel_hi:[1,0]
	v_div_scale_f32 v66, s[8:9], v65, v65, 1.0
	v_rcp_f32_e32 v67, v66
	s_nop 0
	v_fma_f32 v72, -v66, v67, 1.0
	v_fmac_f32_e32 v67, v72, v67
	v_div_scale_f32 v72, vcc, 1.0, v65, 1.0
	v_mul_f32_e32 v73, v72, v67
	v_fma_f32 v76, -v66, v73, v72
	v_fmac_f32_e32 v73, v76, v67
	v_fma_f32 v66, -v66, v73, v72
	v_div_fmas_f32 v66, v66, v67, v73
	v_div_fixup_f32 v65, v66, v65, 1.0
	v_div_scale_f32 v66, s[8:9], v64, v64, 1.0
	v_rcp_f32_e32 v67, v66
	s_nop 0
	v_fma_f32 v72, -v66, v67, 1.0
	v_fmac_f32_e32 v67, v72, v67
	v_div_scale_f32 v72, vcc, 1.0, v64, 1.0
	v_mul_f32_e32 v73, v72, v67
	v_fma_f32 v76, -v66, v73, v72
	v_fmac_f32_e32 v73, v76, v67
	v_fma_f32 v66, -v66, v73, v72
	v_div_fmas_f32 v66, v66, v67, v73
	v_div_fixup_f32 v64, v66, v64, 1.0
	v_pk_add_f32 v[66:67], v[74:75], 1.0 op_sel_hi:[1,0]
	v_pk_fma_f32 v[64:65], v[110:111], v[64:65], v[104:105]
	v_div_scale_f32 v72, s[8:9], v67, v67, 1.0
	v_rcp_f32_e32 v73, v72
	s_nop 0
	v_fma_f32 v74, -v72, v73, 1.0
	v_fmac_f32_e32 v73, v74, v73
	v_div_scale_f32 v74, vcc, 1.0, v67, 1.0
	v_mul_f32_e32 v75, v74, v73
	v_fma_f32 v76, -v72, v75, v74
	v_fmac_f32_e32 v75, v76, v73
	v_fma_f32 v72, -v72, v75, v74
	v_div_fmas_f32 v72, v72, v73, v75
	v_div_fixup_f32 v67, v72, v67, 1.0
	v_div_scale_f32 v72, s[8:9], v66, v66, 1.0
	v_rcp_f32_e32 v73, v72
	s_nop 0
	v_fma_f32 v74, -v72, v73, 1.0
	v_fmac_f32_e32 v73, v74, v73
	v_div_scale_f32 v74, vcc, 1.0, v66, 1.0
	v_mul_f32_e32 v75, v74, v73
	v_fma_f32 v76, -v72, v75, v74
	v_fmac_f32_e32 v75, v76, v73
	v_fma_f32 v72, -v72, v75, v74
	v_div_fmas_f32 v72, v72, v73, v75
	v_div_fixup_f32 v66, v72, v66, 1.0
	v_pk_fma_f32 v[66:67], v[112:113], v[66:67], v[106:107]
	ds_write_b128 v141, v[64:67] offset:26624
	ds_write_b32 v134, v129 offset:34816
	v_mul_f32_e32 v64, 0xbfb8aa3b, v24
	v_mul_f32_e32 v65, 0xbfb8aa3b, v25
	v_exp_f32_e32 v64, v64
	v_exp_f32_e32 v65, v65
	v_mul_f32_e32 v66, 0xbfb8aa3b, v26
	v_mul_f32_e32 v67, 0xbfb8aa3b, v27
	v_exp_f32_e32 v66, v66
	v_pk_add_f32 v[64:65], v[64:65], 1.0 op_sel_hi:[1,0]
	v_exp_f32_e32 v67, v67
	v_div_scale_f32 v76, s[8:9], v65, v65, v25
	v_rcp_f32_e32 v77, v76
	v_pk_add_f32 v[66:67], v[66:67], 1.0 op_sel_hi:[1,0]
	v_mul_f32_e32 v72, 0xbfb8aa3b, v36
	v_mul_f32_e32 v73, 0xbfb8aa3b, v37
	v_fma_f32 v78, -v76, v77, 1.0
	v_fmac_f32_e32 v77, v78, v77
	v_div_scale_f32 v78, vcc, v25, v65, v25
	v_mul_f32_e32 v79, v78, v77
	v_fma_f32 v80, -v76, v79, v78
	v_fmac_f32_e32 v79, v80, v77
	v_fma_f32 v76, -v76, v79, v78
	v_div_fmas_f32 v76, v76, v77, v79
	v_div_fixup_f32 v65, v76, v65, v25
	v_div_scale_f32 v76, s[8:9], v64, v64, v24
	v_rcp_f32_e32 v77, v76
	v_exp_f32_e32 v72, v72
	v_exp_f32_e32 v73, v73
	v_mul_f32_e32 v74, 0xbfb8aa3b, v38
	v_fma_f32 v78, -v76, v77, 1.0
	v_fmac_f32_e32 v77, v78, v77
	v_div_scale_f32 v78, vcc, v24, v64, v24
	v_mul_f32_e32 v79, v78, v77
	v_fma_f32 v80, -v76, v79, v78
	v_fmac_f32_e32 v79, v80, v77
	v_fma_f32 v76, -v76, v79, v78
	v_div_fmas_f32 v76, v76, v77, v79
	v_div_fixup_f32 v64, v76, v64, v24
	v_div_scale_f32 v76, s[8:9], v67, v67, v27
	v_rcp_f32_e32 v77, v76
	v_pk_mul_f32 v[64:65], v[64:65], s[18:19] op_sel_hi:[1,0]
	v_mul_f32_e32 v75, 0xbfb8aa3b, v39
	v_exp_f32_e32 v74, v74
	v_fma_f32 v78, -v76, v77, 1.0
	v_fmac_f32_e32 v77, v78, v77
	v_div_scale_f32 v78, vcc, v27, v67, v27
	v_mul_f32_e32 v79, v78, v77
	v_fma_f32 v80, -v76, v79, v78
	v_fmac_f32_e32 v79, v80, v77
	v_fma_f32 v76, -v76, v79, v78
	v_div_fmas_f32 v76, v76, v77, v79
	v_div_fixup_f32 v67, v76, v67, v27
	v_div_scale_f32 v76, s[8:9], v66, v66, v26
	v_rcp_f32_e32 v77, v76
	v_exp_f32_e32 v75, v75
	v_fma_f32 v78, -v76, v77, 1.0
	v_fmac_f32_e32 v77, v78, v77
	v_div_scale_f32 v78, vcc, v26, v66, v26
	v_mul_f32_e32 v79, v78, v77
	v_fma_f32 v80, -v76, v79, v78
	v_fmac_f32_e32 v79, v80, v77
	v_fma_f32 v76, -v76, v79, v78
	v_div_fmas_f32 v76, v76, v77, v79
	v_div_fixup_f32 v66, v76, v66, v26
	v_pk_mul_f32 v[66:67], v[66:67], s[18:19] op_sel_hi:[1,0]
	ds_write_b128 v144, v[64:67] offset:18432
	v_pk_add_f32 v[64:65], v[72:73], 1.0 op_sel_hi:[1,0]
	v_div_scale_f32 v66, s[8:9], v65, v65, 1.0
	v_rcp_f32_e32 v67, v66
	s_nop 0
	v_fma_f32 v72, -v66, v67, 1.0
	v_fmac_f32_e32 v67, v72, v67
	v_div_scale_f32 v72, vcc, 1.0, v65, 1.0
	v_mul_f32_e32 v73, v72, v67
	v_fma_f32 v76, -v66, v73, v72
	v_fmac_f32_e32 v73, v76, v67
	v_fma_f32 v66, -v66, v73, v72
	v_div_fmas_f32 v66, v66, v67, v73
	v_div_fixup_f32 v65, v66, v65, 1.0
	v_div_scale_f32 v66, s[8:9], v64, v64, 1.0
	v_rcp_f32_e32 v67, v66
	s_nop 0
	v_fma_f32 v72, -v66, v67, 1.0
	v_fmac_f32_e32 v67, v72, v67
	v_div_scale_f32 v72, vcc, 1.0, v64, 1.0
	v_mul_f32_e32 v73, v72, v67
	v_fma_f32 v76, -v66, v73, v72
	v_fmac_f32_e32 v73, v76, v67
	v_fma_f32 v66, -v66, v73, v72
	v_div_fmas_f32 v66, v66, v67, v73
	v_div_fixup_f32 v64, v66, v64, 1.0
	v_pk_add_f32 v[66:67], v[74:75], 1.0 op_sel_hi:[1,0]
	v_pk_fma_f32 v[64:65], v[110:111], v[64:65], v[104:105]
	v_div_scale_f32 v72, s[8:9], v67, v67, 1.0
	v_rcp_f32_e32 v73, v72
	s_nop 0
	v_fma_f32 v74, -v72, v73, 1.0
	v_fmac_f32_e32 v73, v74, v73
	v_div_scale_f32 v74, vcc, 1.0, v67, 1.0
	v_mul_f32_e32 v75, v74, v73
	v_fma_f32 v76, -v72, v75, v74
	v_fmac_f32_e32 v75, v76, v73
	v_fma_f32 v72, -v72, v75, v74
	v_div_fmas_f32 v72, v72, v73, v75
	v_div_fixup_f32 v67, v72, v67, 1.0
	v_div_scale_f32 v72, s[8:9], v66, v66, 1.0
	v_rcp_f32_e32 v73, v72
	s_mov_b64 s[8:9], -1
	v_fma_f32 v74, -v72, v73, 1.0
	v_fmac_f32_e32 v73, v74, v73
	v_div_scale_f32 v74, vcc, 1.0, v66, 1.0
	v_mul_f32_e32 v75, v74, v73
	v_fma_f32 v76, -v72, v75, v74
	v_fmac_f32_e32 v75, v76, v73
	v_fma_f32 v72, -v72, v75, v74
	v_div_fmas_f32 v72, v72, v73, v75
	v_div_fixup_f32 v66, v72, v66, 1.0
	v_pk_fma_f32 v[66:67], v[112:113], v[66:67], v[106:107]
	ds_write_b128 v144, v[64:67] offset:26624
	ds_write_b32 v134, v130 offset:35840
	s_waitcnt lgkmcnt(0)
	s_barrier
	v_add_u32_e32 v64, s47, v124
	v_add_u32_e32 v65, s47, v126
	s_cbranch_scc1 .LBB0_1323
	v_add_u32_e32 v98, s47, v124
	v_add_u32_e32 v96, s47, v126
	s_mov_b64 s[8:9], 0

.LBB0_1325:
	ds_read2st64_b32 v[64:65], v134 offset0:144 offset1:148
	v_ashrrev_i32_e32 v99, 31, v98
	v_lshlrev_b64 v[66:67], 12, v[98:99]
	v_ashrrev_i32_e32 v97, 31, v96
	v_lshl_add_u64 v[66:67], v[108:109], 0, v[66:67]
	s_waitcnt lgkmcnt(0)
	global_store_dword v[66:67], v64, off
	v_lshlrev_b64 v[66:67], 12, v[96:97]
	v_lshl_add_u64 v[66:67], v[108:109], 0, v[66:67]
	global_store_dword v[66:67], v65, off
	v_mov_b32_e32 v196, 0
	v_mov_b32_e32 v197, 0
	v_add_u32_e32 v194, 0x8800, v103
	v_add_u32_e32 v195, 0x8c00, v103
	ds_read2_b32 v[118:119], v194 offset0:0 offset1:16
	ds_read_b128 v[72:75], v145 offset:26624
	ds_read_b128 v[76:79], v145 offset:26880
	ds_read_b128 v[64:67], v145 offset:18432
	ds_read_b128 v[68:71], v145 offset:18688
	ds_read2_b32 v[120:121], v194 offset0:32 offset1:48
	ds_read_b128 v[88:91], v145 offset:27136
	ds_read_b128 v[92:95], v145 offset:27392
	ds_read_b128 v[80:83], v145 offset:18944
	ds_read_b128 v[84:87], v145 offset:19200
	s_waitcnt lgkmcnt(9)
	v_pk_add_f32 v[178:179], v[178:179], v[118:119] op_sel_hi:[1,0] neg_lo:[0,1] neg_hi:[0,1]
	v_pk_add_f32 v[186:187], v[186:187], v[118:119] op_sel:[0,1] op_sel_hi:[1,1] neg_lo:[0,1] neg_hi:[0,1]
	v_pk_add_f32 v[180:181], v[180:181], v[118:119] op_sel_hi:[1,0] neg_lo:[0,1] neg_hi:[0,1]
	v_pk_add_f32 v[188:189], v[188:189], v[118:119] op_sel:[0,1] op_sel_hi:[1,1] neg_lo:[0,1] neg_hi:[0,1]
	v_pk_add_f32 v[182:183], v[182:183], v[118:119] op_sel_hi:[1,0] neg_lo:[0,1] neg_hi:[0,1]
	v_pk_add_f32 v[190:191], v[190:191], v[118:119] op_sel:[0,1] op_sel_hi:[1,1] neg_lo:[0,1] neg_hi:[0,1]
	v_pk_add_f32 v[184:185], v[184:185], v[118:119] op_sel_hi:[1,0] neg_lo:[0,1] neg_hi:[0,1]
	v_pk_add_f32 v[192:193], v[192:193], v[118:119] op_sel:[0,1] op_sel_hi:[1,1] neg_lo:[0,1] neg_hi:[0,1]
	s_waitcnt lgkmcnt(8)
	v_pk_fma_f32 v[178:179], v[72:73], v[178:179], v[118:119] op_sel_hi:[1,1,0]
	v_pk_fma_f32 v[186:187], v[72:73], v[186:187], v[118:119] op_sel:[0,0,1] op_sel_hi:[1,1,1]
	v_pk_fma_f32 v[180:181], v[74:75], v[180:181], v[118:119] op_sel_hi:[1,1,0]
	v_pk_fma_f32 v[188:189], v[74:75], v[188:189], v[118:119] op_sel:[0,0,1] op_sel_hi:[1,1,1]
	s_waitcnt lgkmcnt(7)
	v_pk_fma_f32 v[182:183], v[76:77], v[182:183], v[118:119] op_sel_hi:[1,1,0]
	v_pk_fma_f32 v[190:191], v[76:77], v[190:191], v[118:119] op_sel:[0,0,1] op_sel_hi:[1,1,1]
	v_pk_fma_f32 v[184:185], v[78:79], v[184:185], v[118:119] op_sel_hi:[1,1,0]
	v_pk_fma_f32 v[192:193], v[78:79], v[192:193], v[118:119] op_sel:[0,0,1] op_sel_hi:[1,1,1]
	ds_read2_b32 v[118:119], v194 offset0:64 offset1:80
	ds_read_b128 v[72:75], v145 offset:27648
	ds_read_b128 v[76:79], v145 offset:27904
	s_waitcnt lgkmcnt(9)
	v_pk_fma_f32 v[146:147], v[64:65], v[178:179], v[196:197]
	v_pk_fma_f32 v[150:151], v[64:65], v[186:187], v[196:197]
	v_pk_fma_f32 v[148:149], v[66:67], v[180:181], v[196:197]
	v_pk_fma_f32 v[152:153], v[66:67], v[188:189], v[196:197]
	ds_read_b128 v[64:67], v145 offset:19456
	s_waitcnt lgkmcnt(9)
	v_pk_fma_f32 v[146:147], v[68:69], v[182:183], v[146:147]
	v_pk_fma_f32 v[150:151], v[68:69], v[190:191], v[150:151]
	v_pk_fma_f32 v[148:149], v[70:71], v[184:185], v[148:149]
	v_pk_fma_f32 v[152:153], v[70:71], v[192:193], v[152:153]
	ds_read_b128 v[68:71], v145 offset:19712
	v_add_f32_e32 v146, v146, v147
	v_add_f32_e32 v148, v148, v149
	v_add_f32_e32 v150, v150, v151
	v_add_f32_e32 v152, v152, v153
	v_add_f32_e32 v154, v146, v148
	v_add_f32_e32 v155, v150, v152
	s_waitcnt lgkmcnt(9)
	v_pk_add_f32 v[178:179], v[178:179], v[120:121] op_sel_hi:[1,0] neg_lo:[0,1] neg_hi:[0,1]
	v_add_f32_dpp v154, v154, v154 row_ror:8 row_mask:0xf bank_mask:0xf bound_ctrl:1
	v_pk_add_f32 v[186:187], v[186:187], v[120:121] op_sel:[0,1] op_sel_hi:[1,1] neg_lo:[0,1] neg_hi:[0,1]
	v_add_f32_dpp v155, v155, v155 row_ror:8 row_mask:0xf bank_mask:0xf bound_ctrl:1
	v_pk_add_f32 v[180:181], v[180:181], v[120:121] op_sel_hi:[1,0] neg_lo:[0,1] neg_hi:[0,1]
	v_add_f32_dpp v154, v154, v154 row_ror:4 row_mask:0xf bank_mask:0xf bound_ctrl:1
	v_pk_add_f32 v[188:189], v[188:189], v[120:121] op_sel:[0,1] op_sel_hi:[1,1] neg_lo:[0,1] neg_hi:[0,1]
	v_add_f32_dpp v155, v155, v155 row_ror:4 row_mask:0xf bank_mask:0xf bound_ctrl:1
	v_pk_add_f32 v[182:183], v[182:183], v[120:121] op_sel_hi:[1,0] neg_lo:[0,1] neg_hi:[0,1]
	v_add_f32_dpp v154, v154, v154 row_ror:2 row_mask:0xf bank_mask:0xf bound_ctrl:1
	v_pk_add_f32 v[190:191], v[190:191], v[120:121] op_sel:[0,1] op_sel_hi:[1,1] neg_lo:[0,1] neg_hi:[0,1]
	v_add_f32_dpp v155, v155, v155 row_ror:2 row_mask:0xf bank_mask:0xf bound_ctrl:1
	v_pk_add_f32 v[184:185], v[184:185], v[120:121] op_sel_hi:[1,0] neg_lo:[0,1] neg_hi:[0,1]
	v_add_f32_dpp v154, v154, v154 row_ror:1 row_mask:0xf bank_mask:0xf bound_ctrl:1
	v_pk_add_f32 v[192:193], v[192:193], v[120:121] op_sel:[0,1] op_sel_hi:[1,1] neg_lo:[0,1] neg_hi:[0,1]
	v_add_f32_dpp v155, v155, v155 row_ror:1 row_mask:0xf bank_mask:0xf bound_ctrl:1
	s_waitcnt lgkmcnt(8)
	v_pk_fma_f32 v[178:179], v[88:89], v[178:179], v[120:121] op_sel_hi:[1,1,0]
	s_and_saveexec_b64 s[8:9], s[38:39]
	ds_write_b32 v103, v154 offset:38912
	ds_write_b32 v103, v155 offset:38976
	s_mov_b64 exec, s[8:9]
	v_pk_fma_f32 v[186:187], v[88:89], v[186:187], v[120:121] op_sel:[0,0,1] op_sel_hi:[1,1,1]
	v_pk_fma_f32 v[180:181], v[90:91], v[180:181], v[120:121] op_sel_hi:[1,1,0]
	v_pk_fma_f32 v[188:189], v[90:91], v[188:189], v[120:121] op_sel:[0,0,1] op_sel_hi:[1,1,1]
	s_waitcnt lgkmcnt(9)
	v_pk_fma_f32 v[182:183], v[92:93], v[182:183], v[120:121] op_sel_hi:[1,1,0]
	v_pk_fma_f32 v[190:191], v[92:93], v[190:191], v[120:121] op_sel:[0,0,1] op_sel_hi:[1,1,1]
	v_pk_fma_f32 v[184:185], v[94:95], v[184:185], v[120:121] op_sel_hi:[1,1,0]
	v_pk_fma_f32 v[192:193], v[94:95], v[192:193], v[120:121] op_sel:[0,0,1] op_sel_hi:[1,1,1]
	ds_read2_b32 v[120:121], v194 offset0:96 offset1:112
	ds_read_b128 v[88:91], v145 offset:28160
	ds_read_b128 v[92:95], v145 offset:28416
	s_waitcnt lgkmcnt(11)
	v_pk_fma_f32 v[146:147], v[80:81], v[178:179], v[196:197]
	v_pk_fma_f32 v[150:151], v[80:81], v[186:187], v[196:197]
	v_pk_fma_f32 v[148:149], v[82:83], v[180:181], v[196:197]
	v_pk_fma_f32 v[152:153], v[82:83], v[188:189], v[196:197]
	ds_read_b128 v[80:83], v145 offset:19968
	s_waitcnt lgkmcnt(11)
	v_pk_fma_f32 v[146:147], v[84:85], v[182:183], v[146:147]
	v_pk_fma_f32 v[150:151], v[84:85], v[190:191], v[150:151]
	v_pk_fma_f32 v[148:149], v[86:87], v[184:185], v[148:149]
	v_pk_fma_f32 v[152:153], v[86:87], v[192:193], v[152:153]
	ds_read_b128 v[84:87], v145 offset:20224
	v_add_f32_e32 v146, v146, v147
	v_add_f32_e32 v148, v148, v149
	v_add_f32_e32 v150, v150, v151
	v_add_f32_e32 v152, v152, v153
	v_add_f32_e32 v156, v146, v148
	v_add_f32_e32 v157, v150, v152
	s_waitcnt lgkmcnt(11)
	v_pk_add_f32 v[178:179], v[178:179], v[118:119] op_sel_hi:[1,0] neg_lo:[0,1] neg_hi:[0,1]
	v_add_f32_dpp v156, v156, v156 row_ror:8 row_mask:0xf bank_mask:0xf bound_ctrl:1
	v_pk_add_f32 v[186:187], v[186:187], v[118:119] op_sel:[0,1] op_sel_hi:[1,1] neg_lo:[0,1] neg_hi:[0,1]
	v_add_f32_dpp v157, v157, v157 row_ror:8 row_mask:0xf bank_mask:0xf bound_ctrl:1
	v_pk_add_f32 v[180:181], v[180:181], v[118:119] op_sel_hi:[1,0] neg_lo:[0,1] neg_hi:[0,1]
	v_add_f32_dpp v156, v156, v156 row_ror:4 row_mask:0xf bank_mask:0xf bound_ctrl:1
	v_pk_add_f32 v[188:189], v[188:189], v[118:119] op_sel:[0,1] op_sel_hi:[1,1] neg_lo:[0,1] neg_hi:[0,1]
	v_add_f32_dpp v157, v157, v157 row_ror:4 row_mask:0xf bank_mask:0xf bound_ctrl:1
	v_pk_add_f32 v[182:183], v[182:183], v[118:119] op_sel_hi:[1,0] neg_lo:[0,1] neg_hi:[0,1]
	v_add_f32_dpp v156, v156, v156 row_ror:2 row_mask:0xf bank_mask:0xf bound_ctrl:1
	v_pk_add_f32 v[190:191], v[190:191], v[118:119] op_sel:[0,1] op_sel_hi:[1,1] neg_lo:[0,1] neg_hi:[0,1]
	v_add_f32_dpp v157, v157, v157 row_ror:2 row_mask:0xf bank_mask:0xf bound_ctrl:1
	v_pk_add_f32 v[184:185], v[184:185], v[118:119] op_sel_hi:[1,0] neg_lo:[0,1] neg_hi:[0,1]
	v_add_f32_dpp v156, v156, v156 row_ror:1 row_mask:0xf bank_mask:0xf bound_ctrl:1
	v_pk_add_f32 v[192:193], v[192:193], v[118:119] op_sel:[0,1] op_sel_hi:[1,1] neg_lo:[0,1] neg_hi:[0,1]
	v_add_f32_dpp v157, v157, v157 row_ror:1 row_mask:0xf bank_mask:0xf bound_ctrl:1
	s_waitcnt lgkmcnt(10)
	v_pk_fma_f32 v[178:179], v[72:73], v[178:179], v[118:119] op_sel_hi:[1,1,0]
	s_and_saveexec_b64 s[8:9], s[38:39]
	ds_write_b32 v103, v156 offset:39040
	ds_write_b32 v103, v157 offset:39104
	s_mov_b64 exec, s[8:9]
	v_pk_fma_f32 v[186:187], v[72:73], v[186:187], v[118:119] op_sel:[0,0,1] op_sel_hi:[1,1,1]
	v_pk_fma_f32 v[180:181], v[74:75], v[180:181], v[118:119] op_sel_hi:[1,1,0]
	v_pk_fma_f32 v[188:189], v[74:75], v[188:189], v[118:119] op_sel:[0,0,1] op_sel_hi:[1,1,1]
	s_waitcnt lgkmcnt(11)
	v_pk_fma_f32 v[182:183], v[76:77], v[182:183], v[118:119] op_sel_hi:[1,1,0]
	v_pk_fma_f32 v[190:191], v[76:77], v[190:191], v[118:119] op_sel:[0,0,1] op_sel_hi:[1,1,1]
	v_pk_fma_f32 v[184:185], v[78:79], v[184:185], v[118:119] op_sel_hi:[1,1,0]
	v_pk_fma_f32 v[192:193], v[78:79], v[192:193], v[118:119] op_sel:[0,0,1] op_sel_hi:[1,1,1]
	ds_read2_b32 v[118:119], v194 offset0:128 offset1:144
	ds_read_b128 v[72:75], v145 offset:28672
	ds_read_b128 v[76:79], v145 offset:28928
	s_waitcnt lgkmcnt(13)
	v_pk_fma_f32 v[146:147], v[64:65], v[178:179], v[196:197]
	v_pk_fma_f32 v[150:151], v[64:65], v[186:187], v[196:197]
	v_pk_fma_f32 v[148:149], v[66:67], v[180:181], v[196:197]
	v_pk_fma_f32 v[152:153], v[66:67], v[188:189], v[196:197]
	ds_read_b128 v[64:67], v145 offset:20480
	s_waitcnt lgkmcnt(13)
	v_pk_fma_f32 v[146:147], v[68:69], v[182:183], v[146:147]
	v_pk_fma_f32 v[150:151], v[68:69], v[190:191], v[150:151]
	v_pk_fma_f32 v[148:149], v[70:71], v[184:185], v[148:149]
	v_pk_fma_f32 v[152:153], v[70:71], v[192:193], v[152:153]
	ds_read_b128 v[68:71], v145 offset:20736
	v_add_f32_e32 v146, v146, v147
	v_add_f32_e32 v148, v148, v149
	v_add_f32_e32 v150, v150, v151
	v_add_f32_e32 v152, v152, v153
	v_add_f32_e32 v154, v146, v148
	v_add_f32_e32 v155, v150, v152
	s_waitcnt lgkmcnt(11)
	v_pk_add_f32 v[178:179], v[178:179], v[120:121] op_sel_hi:[1,0] neg_lo:[0,1] neg_hi:[0,1]
	v_add_f32_dpp v154, v154, v154 row_ror:8 row_mask:0xf bank_mask:0xf bound_ctrl:1
	v_pk_add_f32 v[186:187], v[186:187], v[120:121] op_sel:[0,1] op_sel_hi:[1,1] neg_lo:[0,1] neg_hi:[0,1]
	v_add_f32_dpp v155, v155, v155 row_ror:8 row_mask:0xf bank_mask:0xf bound_ctrl:1
	v_pk_add_f32 v[180:181], v[180:181], v[120:121] op_sel_hi:[1,0] neg_lo:[0,1] neg_hi:[0,1]
	v_add_f32_dpp v154, v154, v154 row_ror:4 row_mask:0xf bank_mask:0xf bound_ctrl:1
	v_pk_add_f32 v[188:189], v[188:189], v[120:121] op_sel:[0,1] op_sel_hi:[1,1] neg_lo:[0,1] neg_hi:[0,1]
	v_add_f32_dpp v155, v155, v155 row_ror:4 row_mask:0xf bank_mask:0xf bound_ctrl:1
	v_pk_add_f32 v[182:183], v[182:183], v[120:121] op_sel_hi:[1,0] neg_lo:[0,1] neg_hi:[0,1]
	v_add_f32_dpp v154, v154, v154 row_ror:2 row_mask:0xf bank_mask:0xf bound_ctrl:1
	v_pk_add_f32 v[190:191], v[190:191], v[120:121] op_sel:[0,1] op_sel_hi:[1,1] neg_lo:[0,1] neg_hi:[0,1]
	v_add_f32_dpp v155, v155, v155 row_ror:2 row_mask:0xf bank_mask:0xf bound_ctrl:1
	v_pk_add_f32 v[184:185], v[184:185], v[120:121] op_sel_hi:[1,0] neg_lo:[0,1] neg_hi:[0,1]
	v_add_f32_dpp v154, v154, v154 row_ror:1 row_mask:0xf bank_mask:0xf bound_ctrl:1
	v_pk_add_f32 v[192:193], v[192:193], v[120:121] op_sel:[0,1] op_sel_hi:[1,1] neg_lo:[0,1] neg_hi:[0,1]
	v_add_f32_dpp v155, v155, v155 row_ror:1 row_mask:0xf bank_mask:0xf bound_ctrl:1
	s_waitcnt lgkmcnt(10)
	v_pk_fma_f32 v[178:179], v[88:89], v[178:179], v[120:121] op_sel_hi:[1,1,0]
	s_and_saveexec_b64 s[8:9], s[38:39]
	ds_write_b32 v103, v154 offset:39168
	ds_write_b32 v103, v155 offset:39232
	s_mov_b64 exec, s[8:9]
	v_pk_fma_f32 v[186:187], v[88:89], v[186:187], v[120:121] op_sel:[0,0,1] op_sel_hi:[1,1,1]
	v_pk_fma_f32 v[180:181], v[90:91], v[180:181], v[120:121] op_sel_hi:[1,1,0]
	v_pk_fma_f32 v[188:189], v[90:91], v[188:189], v[120:121] op_sel:[0,0,1] op_sel_hi:[1,1,1]
	s_waitcnt lgkmcnt(11)
	v_pk_fma_f32 v[182:183], v[92:93], v[182:183], v[120:121] op_sel_hi:[1,1,0]
	v_pk_fma_f32 v[190:191], v[92:93], v[190:191], v[120:121] op_sel:[0,0,1] op_sel_hi:[1,1,1]
	v_pk_fma_f32 v[184:185], v[94:95], v[184:185], v[120:121] op_sel_hi:[1,1,0]
	v_pk_fma_f32 v[192:193], v[94:95], v[192:193], v[120:121] op_sel:[0,0,1] op_sel_hi:[1,1,1]
	ds_read2_b32 v[120:121], v194 offset0:160 offset1:176
	ds_read_b128 v[88:91], v145 offset:29184
	ds_read_b128 v[92:95], v145 offset:29440
	s_waitcnt lgkmcnt(13)
	v_pk_fma_f32 v[146:147], v[80:81], v[178:179], v[196:197]
	v_pk_fma_f32 v[150:151], v[80:81], v[186:187], v[196:197]
	v_pk_fma_f32 v[148:149], v[82:83], v[180:181], v[196:197]
	v_pk_fma_f32 v[152:153], v[82:83], v[188:189], v[196:197]
	ds_read_b128 v[80:83], v145 offset:20992
	s_waitcnt lgkmcnt(13)
	v_pk_fma_f32 v[146:147], v[84:85], v[182:183], v[146:147]
	v_pk_fma_f32 v[150:151], v[84:85], v[190:191], v[150:151]
	v_pk_fma_f32 v[148:149], v[86:87], v[184:185], v[148:149]
	v_pk_fma_f32 v[152:153], v[86:87], v[192:193], v[152:153]
	ds_read_b128 v[84:87], v145 offset:21248
	v_add_f32_e32 v146, v146, v147
	v_add_f32_e32 v148, v148, v149
	v_add_f32_e32 v150, v150, v151
	v_add_f32_e32 v152, v152, v153
	v_add_f32_e32 v156, v146, v148
	v_add_f32_e32 v157, v150, v152
	s_waitcnt lgkmcnt(11)
	v_pk_add_f32 v[178:179], v[178:179], v[118:119] op_sel_hi:[1,0] neg_lo:[0,1] neg_hi:[0,1]
	v_add_f32_dpp v156, v156, v156 row_ror:8 row_mask:0xf bank_mask:0xf bound_ctrl:1
	v_pk_add_f32 v[186:187], v[186:187], v[118:119] op_sel:[0,1] op_sel_hi:[1,1] neg_lo:[0,1] neg_hi:[0,1]
	v_add_f32_dpp v157, v157, v157 row_ror:8 row_mask:0xf bank_mask:0xf bound_ctrl:1
	v_pk_add_f32 v[180:181], v[180:181], v[118:119] op_sel_hi:[1,0] neg_lo:[0,1] neg_hi:[0,1]
	v_add_f32_dpp v156, v156, v156 row_ror:4 row_mask:0xf bank_mask:0xf bound_ctrl:1
	v_pk_add_f32 v[188:189], v[188:189], v[118:119] op_sel:[0,1] op_sel_hi:[1,1] neg_lo:[0,1] neg_hi:[0,1]
	v_add_f32_dpp v157, v157, v157 row_ror:4 row_mask:0xf bank_mask:0xf bound_ctrl:1
	v_pk_add_f32 v[182:183], v[182:183], v[118:119] op_sel_hi:[1,0] neg_lo:[0,1] neg_hi:[0,1]
	v_add_f32_dpp v156, v156, v156 row_ror:2 row_mask:0xf bank_mask:0xf bound_ctrl:1
	v_pk_add_f32 v[190:191], v[190:191], v[118:119] op_sel:[0,1] op_sel_hi:[1,1] neg_lo:[0,1] neg_hi:[0,1]
	v_add_f32_dpp v157, v157, v157 row_ror:2 row_mask:0xf bank_mask:0xf bound_ctrl:1
	v_pk_add_f32 v[184:185], v[184:185], v[118:119] op_sel_hi:[1,0] neg_lo:[0,1] neg_hi:[0,1]
	v_add_f32_dpp v156, v156, v156 row_ror:1 row_mask:0xf bank_mask:0xf bound_ctrl:1
	v_pk_add_f32 v[192:193], v[192:193], v[118:119] op_sel:[0,1] op_sel_hi:[1,1] neg_lo:[0,1] neg_hi:[0,1]
	v_add_f32_dpp v157, v157, v157 row_ror:1 row_mask:0xf bank_mask:0xf bound_ctrl:1
	s_waitcnt lgkmcnt(10)
	v_pk_fma_f32 v[178:179], v[72:73], v[178:179], v[118:119] op_sel_hi:[1,1,0]
	s_and_saveexec_b64 s[8:9], s[38:39]
	ds_write_b32 v103, v156 offset:39296
	ds_write_b32 v103, v157 offset:39360
	s_mov_b64 exec, s[8:9]
	v_pk_fma_f32 v[186:187], v[72:73], v[186:187], v[118:119] op_sel:[0,0,1] op_sel_hi:[1,1,1]
	v_pk_fma_f32 v[180:181], v[74:75], v[180:181], v[118:119] op_sel_hi:[1,1,0]
	v_pk_fma_f32 v[188:189], v[74:75], v[188:189], v[118:119] op_sel:[0,0,1] op_sel_hi:[1,1,1]
	s_waitcnt lgkmcnt(11)
	v_pk_fma_f32 v[182:183], v[76:77], v[182:183], v[118:119] op_sel_hi:[1,1,0]
	v_pk_fma_f32 v[190:191], v[76:77], v[190:191], v[118:119] op_sel:[0,0,1] op_sel_hi:[1,1,1]
	v_pk_fma_f32 v[184:185], v[78:79], v[184:185], v[118:119] op_sel_hi:[1,1,0]
	v_pk_fma_f32 v[192:193], v[78:79], v[192:193], v[118:119] op_sel:[0,0,1] op_sel_hi:[1,1,1]
	ds_read2_b32 v[118:119], v194 offset0:192 offset1:208
	ds_read_b128 v[72:75], v145 offset:29696
	ds_read_b128 v[76:79], v145 offset:29952
	s_waitcnt lgkmcnt(13)
	v_pk_fma_f32 v[146:147], v[64:65], v[178:179], v[196:197]
	v_pk_fma_f32 v[150:151], v[64:65], v[186:187], v[196:197]
	v_pk_fma_f32 v[148:149], v[66:67], v[180:181], v[196:197]
	v_pk_fma_f32 v[152:153], v[66:67], v[188:189], v[196:197]
	ds_read_b128 v[64:67], v145 offset:21504
	s_waitcnt lgkmcnt(13)
	v_pk_fma_f32 v[146:147], v[68:69], v[182:183], v[146:147]
	v_pk_fma_f32 v[150:151], v[68:69], v[190:191], v[150:151]
	v_pk_fma_f32 v[148:149], v[70:71], v[184:185], v[148:149]
	v_pk_fma_f32 v[152:153], v[70:71], v[192:193], v[152:153]
	ds_read_b128 v[68:71], v145 offset:21760
	v_add_f32_e32 v146, v146, v147
	v_add_f32_e32 v148, v148, v149
	v_add_f32_e32 v150, v150, v151
	v_add_f32_e32 v152, v152, v153
	v_add_f32_e32 v154, v146, v148
	v_add_f32_e32 v155, v150, v152
	s_waitcnt lgkmcnt(11)
	v_pk_add_f32 v[178:179], v[178:179], v[120:121] op_sel_hi:[1,0] neg_lo:[0,1] neg_hi:[0,1]
	v_add_f32_dpp v154, v154, v154 row_ror:8 row_mask:0xf bank_mask:0xf bound_ctrl:1
	v_pk_add_f32 v[186:187], v[186:187], v[120:121] op_sel:[0,1] op_sel_hi:[1,1] neg_lo:[0,1] neg_hi:[0,1]
	v_add_f32_dpp v155, v155, v155 row_ror:8 row_mask:0xf bank_mask:0xf bound_ctrl:1
	v_pk_add_f32 v[180:181], v[180:181], v[120:121] op_sel_hi:[1,0] neg_lo:[0,1] neg_hi:[0,1]
	v_add_f32_dpp v154, v154, v154 row_ror:4 row_mask:0xf bank_mask:0xf bound_ctrl:1
	v_pk_add_f32 v[188:189], v[188:189], v[120:121] op_sel:[0,1] op_sel_hi:[1,1] neg_lo:[0,1] neg_hi:[0,1]
	v_add_f32_dpp v155, v155, v155 row_ror:4 row_mask:0xf bank_mask:0xf bound_ctrl:1
	v_pk_add_f32 v[182:183], v[182:183], v[120:121] op_sel_hi:[1,0] neg_lo:[0,1] neg_hi:[0,1]
	v_add_f32_dpp v154, v154, v154 row_ror:2 row_mask:0xf bank_mask:0xf bound_ctrl:1
	v_pk_add_f32 v[190:191], v[190:191], v[120:121] op_sel:[0,1] op_sel_hi:[1,1] neg_lo:[0,1] neg_hi:[0,1]
	v_add_f32_dpp v155, v155, v155 row_ror:2 row_mask:0xf bank_mask:0xf bound_ctrl:1
	v_pk_add_f32 v[184:185], v[184:185], v[120:121] op_sel_hi:[1,0] neg_lo:[0,1] neg_hi:[0,1]
	v_add_f32_dpp v154, v154, v154 row_ror:1 row_mask:0xf bank_mask:0xf bound_ctrl:1
	v_pk_add_f32 v[192:193], v[192:193], v[120:121] op_sel:[0,1] op_sel_hi:[1,1] neg_lo:[0,1] neg_hi:[0,1]
	v_add_f32_dpp v155, v155, v155 row_ror:1 row_mask:0xf bank_mask:0xf bound_ctrl:1
	s_waitcnt lgkmcnt(10)
	v_pk_fma_f32 v[178:179], v[88:89], v[178:179], v[120:121] op_sel_hi:[1,1,0]
	s_and_saveexec_b64 s[8:9], s[38:39]
	ds_write_b32 v103, v154 offset:39424
	ds_write_b32 v103, v155 offset:39488
	s_mov_b64 exec, s[8:9]
	v_pk_fma_f32 v[186:187], v[88:89], v[186:187], v[120:121] op_sel:[0,0,1] op_sel_hi:[1,1,1]
	v_pk_fma_f32 v[180:181], v[90:91], v[180:181], v[120:121] op_sel_hi:[1,1,0]
	v_pk_fma_f32 v[188:189], v[90:91], v[188:189], v[120:121] op_sel:[0,0,1] op_sel_hi:[1,1,1]
	s_waitcnt lgkmcnt(11)
	v_pk_fma_f32 v[182:183], v[92:93], v[182:183], v[120:121] op_sel_hi:[1,1,0]
	v_pk_fma_f32 v[190:191], v[92:93], v[190:191], v[120:121] op_sel:[0,0,1] op_sel_hi:[1,1,1]
	v_pk_fma_f32 v[184:185], v[94:95], v[184:185], v[120:121] op_sel_hi:[1,1,0]
	v_pk_fma_f32 v[192:193], v[94:95], v[192:193], v[120:121] op_sel:[0,0,1] op_sel_hi:[1,1,1]
	ds_read2_b32 v[120:121], v194 offset0:224 offset1:240
	ds_read_b128 v[88:91], v145 offset:30208
	ds_read_b128 v[92:95], v145 offset:30464
	s_waitcnt lgkmcnt(13)
	v_pk_fma_f32 v[146:147], v[80:81], v[178:179], v[196:197]
	v_pk_fma_f32 v[150:151], v[80:81], v[186:187], v[196:197]
	v_pk_fma_f32 v[148:149], v[82:83], v[180:181], v[196:197]
	v_pk_fma_f32 v[152:153], v[82:83], v[188:189], v[196:197]
	ds_read_b128 v[80:83], v145 offset:22016
	s_waitcnt lgkmcnt(13)
	v_pk_fma_f32 v[146:147], v[84:85], v[182:183], v[146:147]
	v_pk_fma_f32 v[150:151], v[84:85], v[190:191], v[150:151]
	v_pk_fma_f32 v[148:149], v[86:87], v[184:185], v[148:149]
	v_pk_fma_f32 v[152:153], v[86:87], v[192:193], v[152:153]
	ds_read_b128 v[84:87], v145 offset:22272
	v_add_f32_e32 v146, v146, v147
	v_add_f32_e32 v148, v148, v149
	v_add_f32_e32 v150, v150, v151
	v_add_f32_e32 v152, v152, v153
	v_add_f32_e32 v156, v146, v148
	v_add_f32_e32 v157, v150, v152
	s_waitcnt lgkmcnt(11)
	v_pk_add_f32 v[178:179], v[178:179], v[118:119] op_sel_hi:[1,0] neg_lo:[0,1] neg_hi:[0,1]
	v_add_f32_dpp v156, v156, v156 row_ror:8 row_mask:0xf bank_mask:0xf bound_ctrl:1
	v_pk_add_f32 v[186:187], v[186:187], v[118:119] op_sel:[0,1] op_sel_hi:[1,1] neg_lo:[0,1] neg_hi:[0,1]
	v_add_f32_dpp v157, v157, v157 row_ror:8 row_mask:0xf bank_mask:0xf bound_ctrl:1
	v_pk_add_f32 v[180:181], v[180:181], v[118:119] op_sel_hi:[1,0] neg_lo:[0,1] neg_hi:[0,1]
	v_add_f32_dpp v156, v156, v156 row_ror:4 row_mask:0xf bank_mask:0xf bound_ctrl:1
	v_pk_add_f32 v[188:189], v[188:189], v[118:119] op_sel:[0,1] op_sel_hi:[1,1] neg_lo:[0,1] neg_hi:[0,1]
	v_add_f32_dpp v157, v157, v157 row_ror:4 row_mask:0xf bank_mask:0xf bound_ctrl:1
	v_pk_add_f32 v[182:183], v[182:183], v[118:119] op_sel_hi:[1,0] neg_lo:[0,1] neg_hi:[0,1]
	v_add_f32_dpp v156, v156, v156 row_ror:2 row_mask:0xf bank_mask:0xf bound_ctrl:1
	v_pk_add_f32 v[190:191], v[190:191], v[118:119] op_sel:[0,1] op_sel_hi:[1,1] neg_lo:[0,1] neg_hi:[0,1]
	v_add_f32_dpp v157, v157, v157 row_ror:2 row_mask:0xf bank_mask:0xf bound_ctrl:1
	v_pk_add_f32 v[184:185], v[184:185], v[118:119] op_sel_hi:[1,0] neg_lo:[0,1] neg_hi:[0,1]
	v_add_f32_dpp v156, v156, v156 row_ror:1 row_mask:0xf bank_mask:0xf bound_ctrl:1
	v_pk_add_f32 v[192:193], v[192:193], v[118:119] op_sel:[0,1] op_sel_hi:[1,1] neg_lo:[0,1] neg_hi:[0,1]
	v_add_f32_dpp v157, v157, v157 row_ror:1 row_mask:0xf bank_mask:0xf bound_ctrl:1
	s_waitcnt lgkmcnt(10)
	v_pk_fma_f32 v[178:179], v[72:73], v[178:179], v[118:119] op_sel_hi:[1,1,0]
	s_and_saveexec_b64 s[8:9], s[38:39]
	ds_write_b32 v103, v156 offset:39552
	ds_write_b32 v103, v157 offset:39616
	s_mov_b64 exec, s[8:9]
	v_pk_fma_f32 v[186:187], v[72:73], v[186:187], v[118:119] op_sel:[0,0,1] op_sel_hi:[1,1,1]
	v_pk_fma_f32 v[180:181], v[74:75], v[180:181], v[118:119] op_sel_hi:[1,1,0]
	v_pk_fma_f32 v[188:189], v[74:75], v[188:189], v[118:119] op_sel:[0,0,1] op_sel_hi:[1,1,1]
	s_waitcnt lgkmcnt(11)
	v_pk_fma_f32 v[182:183], v[76:77], v[182:183], v[118:119] op_sel_hi:[1,1,0]
	v_pk_fma_f32 v[190:191], v[76:77], v[190:191], v[118:119] op_sel:[0,0,1] op_sel_hi:[1,1,1]
	v_pk_fma_f32 v[184:185], v[78:79], v[184:185], v[118:119] op_sel_hi:[1,1,0]
	v_pk_fma_f32 v[192:193], v[78:79], v[192:193], v[118:119] op_sel:[0,0,1] op_sel_hi:[1,1,1]
	ds_read2_b32 v[118:119], v195 offset0:0 offset1:16
	ds_read_b128 v[72:75], v145 offset:30720
	ds_read_b128 v[76:79], v145 offset:30976
	s_waitcnt lgkmcnt(13)
	v_pk_fma_f32 v[146:147], v[64:65], v[178:179], v[196:197]
	v_pk_fma_f32 v[150:151], v[64:65], v[186:187], v[196:197]
	v_pk_fma_f32 v[148:149], v[66:67], v[180:181], v[196:197]
	v_pk_fma_f32 v[152:153], v[66:67], v[188:189], v[196:197]
	ds_read_b128 v[64:67], v145 offset:22528
	s_waitcnt lgkmcnt(13)
	v_pk_fma_f32 v[146:147], v[68:69], v[182:183], v[146:147]
	v_pk_fma_f32 v[150:151], v[68:69], v[190:191], v[150:151]
	v_pk_fma_f32 v[148:149], v[70:71], v[184:185], v[148:149]
	v_pk_fma_f32 v[152:153], v[70:71], v[192:193], v[152:153]
	ds_read_b128 v[68:71], v145 offset:22784
	v_add_f32_e32 v146, v146, v147
	v_add_f32_e32 v148, v148, v149
	v_add_f32_e32 v150, v150, v151
	v_add_f32_e32 v152, v152, v153
	v_add_f32_e32 v154, v146, v148
	v_add_f32_e32 v155, v150, v152
	s_waitcnt lgkmcnt(11)
	v_pk_add_f32 v[178:179], v[178:179], v[120:121] op_sel_hi:[1,0] neg_lo:[0,1] neg_hi:[0,1]
	v_add_f32_dpp v154, v154, v154 row_ror:8 row_mask:0xf bank_mask:0xf bound_ctrl:1
	v_pk_add_f32 v[186:187], v[186:187], v[120:121] op_sel:[0,1] op_sel_hi:[1,1] neg_lo:[0,1] neg_hi:[0,1]
	v_add_f32_dpp v155, v155, v155 row_ror:8 row_mask:0xf bank_mask:0xf bound_ctrl:1
	v_pk_add_f32 v[180:181], v[180:181], v[120:121] op_sel_hi:[1,0] neg_lo:[0,1] neg_hi:[0,1]
	v_add_f32_dpp v154, v154, v154 row_ror:4 row_mask:0xf bank_mask:0xf bound_ctrl:1
	v_pk_add_f32 v[188:189], v[188:189], v[120:121] op_sel:[0,1] op_sel_hi:[1,1] neg_lo:[0,1] neg_hi:[0,1]
	v_add_f32_dpp v155, v155, v155 row_ror:4 row_mask:0xf bank_mask:0xf bound_ctrl:1
	v_pk_add_f32 v[182:183], v[182:183], v[120:121] op_sel_hi:[1,0] neg_lo:[0,1] neg_hi:[0,1]
	v_add_f32_dpp v154, v154, v154 row_ror:2 row_mask:0xf bank_mask:0xf bound_ctrl:1
	v_pk_add_f32 v[190:191], v[190:191], v[120:121] op_sel:[0,1] op_sel_hi:[1,1] neg_lo:[0,1] neg_hi:[0,1]
	v_add_f32_dpp v155, v155, v155 row_ror:2 row_mask:0xf bank_mask:0xf bound_ctrl:1
	v_pk_add_f32 v[184:185], v[184:185], v[120:121] op_sel_hi:[1,0] neg_lo:[0,1] neg_hi:[0,1]
	v_add_f32_dpp v154, v154, v154 row_ror:1 row_mask:0xf bank_mask:0xf bound_ctrl:1
	v_pk_add_f32 v[192:193], v[192:193], v[120:121] op_sel:[0,1] op_sel_hi:[1,1] neg_lo:[0,1] neg_hi:[0,1]
	v_add_f32_dpp v155, v155, v155 row_ror:1 row_mask:0xf bank_mask:0xf bound_ctrl:1
	s_waitcnt lgkmcnt(10)
	v_pk_fma_f32 v[178:179], v[88:89], v[178:179], v[120:121] op_sel_hi:[1,1,0]
	s_and_saveexec_b64 s[8:9], s[38:39]
	ds_write_b32 v103, v154 offset:39680
	ds_write_b32 v103, v155 offset:39744
	s_mov_b64 exec, s[8:9]
	v_pk_fma_f32 v[186:187], v[88:89], v[186:187], v[120:121] op_sel:[0,0,1] op_sel_hi:[1,1,1]
	v_pk_fma_f32 v[180:181], v[90:91], v[180:181], v[120:121] op_sel_hi:[1,1,0]
	v_pk_fma_f32 v[188:189], v[90:91], v[188:189], v[120:121] op_sel:[0,0,1] op_sel_hi:[1,1,1]
	s_waitcnt lgkmcnt(11)
	v_pk_fma_f32 v[182:183], v[92:93], v[182:183], v[120:121] op_sel_hi:[1,1,0]
	v_pk_fma_f32 v[190:191], v[92:93], v[190:191], v[120:121] op_sel:[0,0,1] op_sel_hi:[1,1,1]
	v_pk_fma_f32 v[184:185], v[94:95], v[184:185], v[120:121] op_sel_hi:[1,1,0]
	v_pk_fma_f32 v[192:193], v[94:95], v[192:193], v[120:121] op_sel:[0,0,1] op_sel_hi:[1,1,1]
	ds_read2_b32 v[120:121], v195 offset0:32 offset1:48
	ds_read_b128 v[88:91], v145 offset:31232
	ds_read_b128 v[92:95], v145 offset:31488
	s_waitcnt lgkmcnt(13)
	v_pk_fma_f32 v[146:147], v[80:81], v[178:179], v[196:197]
	v_pk_fma_f32 v[150:151], v[80:81], v[186:187], v[196:197]
	v_pk_fma_f32 v[148:149], v[82:83], v[180:181], v[196:197]
	v_pk_fma_f32 v[152:153], v[82:83], v[188:189], v[196:197]
	ds_read_b128 v[80:83], v145 offset:23040
	s_waitcnt lgkmcnt(13)
	v_pk_fma_f32 v[146:147], v[84:85], v[182:183], v[146:147]
	v_pk_fma_f32 v[150:151], v[84:85], v[190:191], v[150:151]
	v_pk_fma_f32 v[148:149], v[86:87], v[184:185], v[148:149]
	v_pk_fma_f32 v[152:153], v[86:87], v[192:193], v[152:153]
	ds_read_b128 v[84:87], v145 offset:23296
	v_add_f32_e32 v146, v146, v147
	v_add_f32_e32 v148, v148, v149
	v_add_f32_e32 v150, v150, v151
	v_add_f32_e32 v152, v152, v153
	v_add_f32_e32 v156, v146, v148
	v_add_f32_e32 v157, v150, v152
	s_waitcnt lgkmcnt(11)
	v_pk_add_f32 v[178:179], v[178:179], v[118:119] op_sel_hi:[1,0] neg_lo:[0,1] neg_hi:[0,1]
	v_add_f32_dpp v156, v156, v156 row_ror:8 row_mask:0xf bank_mask:0xf bound_ctrl:1
	v_pk_add_f32 v[186:187], v[186:187], v[118:119] op_sel:[0,1] op_sel_hi:[1,1] neg_lo:[0,1] neg_hi:[0,1]
	v_add_f32_dpp v157, v157, v157 row_ror:8 row_mask:0xf bank_mask:0xf bound_ctrl:1
	v_pk_add_f32 v[180:181], v[180:181], v[118:119] op_sel_hi:[1,0] neg_lo:[0,1] neg_hi:[0,1]
	v_add_f32_dpp v156, v156, v156 row_ror:4 row_mask:0xf bank_mask:0xf bound_ctrl:1
	v_pk_add_f32 v[188:189], v[188:189], v[118:119] op_sel:[0,1] op_sel_hi:[1,1] neg_lo:[0,1] neg_hi:[0,1]
	v_add_f32_dpp v157, v157, v157 row_ror:4 row_mask:0xf bank_mask:0xf bound_ctrl:1
	v_pk_add_f32 v[182:183], v[182:183], v[118:119] op_sel_hi:[1,0] neg_lo:[0,1] neg_hi:[0,1]
	v_add_f32_dpp v156, v156, v156 row_ror:2 row_mask:0xf bank_mask:0xf bound_ctrl:1
	v_pk_add_f32 v[190:191], v[190:191], v[118:119] op_sel:[0,1] op_sel_hi:[1,1] neg_lo:[0,1] neg_hi:[0,1]
	v_add_f32_dpp v157, v157, v157 row_ror:2 row_mask:0xf bank_mask:0xf bound_ctrl:1
	v_pk_add_f32 v[184:185], v[184:185], v[118:119] op_sel_hi:[1,0] neg_lo:[0,1] neg_hi:[0,1]
	v_add_f32_dpp v156, v156, v156 row_ror:1 row_mask:0xf bank_mask:0xf bound_ctrl:1
	v_pk_add_f32 v[192:193], v[192:193], v[118:119] op_sel:[0,1] op_sel_hi:[1,1] neg_lo:[0,1] neg_hi:[0,1]
	v_add_f32_dpp v157, v157, v157 row_ror:1 row_mask:0xf bank_mask:0xf bound_ctrl:1
	s_waitcnt lgkmcnt(10)
	v_pk_fma_f32 v[178:179], v[72:73], v[178:179], v[118:119] op_sel_hi:[1,1,0]
	s_and_saveexec_b64 s[8:9], s[38:39]
	ds_write_b32 v103, v156 offset:39808
	ds_write_b32 v103, v157 offset:39872
	s_mov_b64 exec, s[8:9]
	v_pk_fma_f32 v[186:187], v[72:73], v[186:187], v[118:119] op_sel:[0,0,1] op_sel_hi:[1,1,1]
	v_pk_fma_f32 v[180:181], v[74:75], v[180:181], v[118:119] op_sel_hi:[1,1,0]
	v_pk_fma_f32 v[188:189], v[74:75], v[188:189], v[118:119] op_sel:[0,0,1] op_sel_hi:[1,1,1]
	s_waitcnt lgkmcnt(11)
	v_pk_fma_f32 v[182:183], v[76:77], v[182:183], v[118:119] op_sel_hi:[1,1,0]
	v_pk_fma_f32 v[190:191], v[76:77], v[190:191], v[118:119] op_sel:[0,0,1] op_sel_hi:[1,1,1]
	v_pk_fma_f32 v[184:185], v[78:79], v[184:185], v[118:119] op_sel_hi:[1,1,0]
	v_pk_fma_f32 v[192:193], v[78:79], v[192:193], v[118:119] op_sel:[0,0,1] op_sel_hi:[1,1,1]
	ds_read2_b32 v[118:119], v195 offset0:64 offset1:80
	ds_read_b128 v[72:75], v145 offset:31744
	ds_read_b128 v[76:79], v145 offset:32000
	s_waitcnt lgkmcnt(13)
	v_pk_fma_f32 v[146:147], v[64:65], v[178:179], v[196:197]
	v_pk_fma_f32 v[150:151], v[64:65], v[186:187], v[196:197]
	v_pk_fma_f32 v[148:149], v[66:67], v[180:181], v[196:197]
	v_pk_fma_f32 v[152:153], v[66:67], v[188:189], v[196:197]
	ds_read_b128 v[64:67], v145 offset:23552
	s_waitcnt lgkmcnt(13)
	v_pk_fma_f32 v[146:147], v[68:69], v[182:183], v[146:147]
	v_pk_fma_f32 v[150:151], v[68:69], v[190:191], v[150:151]
	v_pk_fma_f32 v[148:149], v[70:71], v[184:185], v[148:149]
	v_pk_fma_f32 v[152:153], v[70:71], v[192:193], v[152:153]
	ds_read_b128 v[68:71], v145 offset:23808
	v_add_f32_e32 v146, v146, v147
	v_add_f32_e32 v148, v148, v149
	v_add_f32_e32 v150, v150, v151
	v_add_f32_e32 v152, v152, v153
	v_add_f32_e32 v154, v146, v148
	v_add_f32_e32 v155, v150, v152
	s_waitcnt lgkmcnt(11)
	v_pk_add_f32 v[178:179], v[178:179], v[120:121] op_sel_hi:[1,0] neg_lo:[0,1] neg_hi:[0,1]
	v_add_f32_dpp v154, v154, v154 row_ror:8 row_mask:0xf bank_mask:0xf bound_ctrl:1
	v_pk_add_f32 v[186:187], v[186:187], v[120:121] op_sel:[0,1] op_sel_hi:[1,1] neg_lo:[0,1] neg_hi:[0,1]
	v_add_f32_dpp v155, v155, v155 row_ror:8 row_mask:0xf bank_mask:0xf bound_ctrl:1
	v_pk_add_f32 v[180:181], v[180:181], v[120:121] op_sel_hi:[1,0] neg_lo:[0,1] neg_hi:[0,1]
	v_add_f32_dpp v154, v154, v154 row_ror:4 row_mask:0xf bank_mask:0xf bound_ctrl:1
	v_pk_add_f32 v[188:189], v[188:189], v[120:121] op_sel:[0,1] op_sel_hi:[1,1] neg_lo:[0,1] neg_hi:[0,1]
	v_add_f32_dpp v155, v155, v155 row_ror:4 row_mask:0xf bank_mask:0xf bound_ctrl:1
	v_pk_add_f32 v[182:183], v[182:183], v[120:121] op_sel_hi:[1,0] neg_lo:[0,1] neg_hi:[0,1]
	v_add_f32_dpp v154, v154, v154 row_ror:2 row_mask:0xf bank_mask:0xf bound_ctrl:1
	v_pk_add_f32 v[190:191], v[190:191], v[120:121] op_sel:[0,1] op_sel_hi:[1,1] neg_lo:[0,1] neg_hi:[0,1]
	v_add_f32_dpp v155, v155, v155 row_ror:2 row_mask:0xf bank_mask:0xf bound_ctrl:1
	v_pk_add_f32 v[184:185], v[184:185], v[120:121] op_sel_hi:[1,0] neg_lo:[0,1] neg_hi:[0,1]
	v_add_f32_dpp v154, v154, v154 row_ror:1 row_mask:0xf bank_mask:0xf bound_ctrl:1
	v_pk_add_f32 v[192:193], v[192:193], v[120:121] op_sel:[0,1] op_sel_hi:[1,1] neg_lo:[0,1] neg_hi:[0,1]
	v_add_f32_dpp v155, v155, v155 row_ror:1 row_mask:0xf bank_mask:0xf bound_ctrl:1
	s_waitcnt lgkmcnt(10)
	v_pk_fma_f32 v[178:179], v[88:89], v[178:179], v[120:121] op_sel_hi:[1,1,0]
	s_and_saveexec_b64 s[8:9], s[38:39]
	ds_write_b32 v103, v154 offset:39936
	ds_write_b32 v103, v155 offset:40000
	s_mov_b64 exec, s[8:9]
	v_pk_fma_f32 v[186:187], v[88:89], v[186:187], v[120:121] op_sel:[0,0,1] op_sel_hi:[1,1,1]
	v_pk_fma_f32 v[180:181], v[90:91], v[180:181], v[120:121] op_sel_hi:[1,1,0]
	v_pk_fma_f32 v[188:189], v[90:91], v[188:189], v[120:121] op_sel:[0,0,1] op_sel_hi:[1,1,1]
	s_waitcnt lgkmcnt(11)
	v_pk_fma_f32 v[182:183], v[92:93], v[182:183], v[120:121] op_sel_hi:[1,1,0]
	v_pk_fma_f32 v[190:191], v[92:93], v[190:191], v[120:121] op_sel:[0,0,1] op_sel_hi:[1,1,1]
	v_pk_fma_f32 v[184:185], v[94:95], v[184:185], v[120:121] op_sel_hi:[1,1,0]
	v_pk_fma_f32 v[192:193], v[94:95], v[192:193], v[120:121] op_sel:[0,0,1] op_sel_hi:[1,1,1]
	ds_read2_b32 v[120:121], v195 offset0:96 offset1:112
	ds_read_b128 v[88:91], v145 offset:32256
	ds_read_b128 v[92:95], v145 offset:32512
	s_waitcnt lgkmcnt(13)
	v_pk_fma_f32 v[146:147], v[80:81], v[178:179], v[196:197]
	v_pk_fma_f32 v[150:151], v[80:81], v[186:187], v[196:197]
	v_pk_fma_f32 v[148:149], v[82:83], v[180:181], v[196:197]
	v_pk_fma_f32 v[152:153], v[82:83], v[188:189], v[196:197]
	ds_read_b128 v[80:83], v145 offset:24064
	s_waitcnt lgkmcnt(13)
	v_pk_fma_f32 v[146:147], v[84:85], v[182:183], v[146:147]
	v_pk_fma_f32 v[150:151], v[84:85], v[190:191], v[150:151]
	v_pk_fma_f32 v[148:149], v[86:87], v[184:185], v[148:149]
	v_pk_fma_f32 v[152:153], v[86:87], v[192:193], v[152:153]
	ds_read_b128 v[84:87], v145 offset:24320
	v_add_f32_e32 v146, v146, v147
	v_add_f32_e32 v148, v148, v149
	v_add_f32_e32 v150, v150, v151
	v_add_f32_e32 v152, v152, v153
	v_add_f32_e32 v156, v146, v148
	v_add_f32_e32 v157, v150, v152
	s_waitcnt lgkmcnt(11)
	v_pk_add_f32 v[178:179], v[178:179], v[118:119] op_sel_hi:[1,0] neg_lo:[0,1] neg_hi:[0,1]
	v_add_f32_dpp v156, v156, v156 row_ror:8 row_mask:0xf bank_mask:0xf bound_ctrl:1
	v_pk_add_f32 v[186:187], v[186:187], v[118:119] op_sel:[0,1] op_sel_hi:[1,1] neg_lo:[0,1] neg_hi:[0,1]
	v_add_f32_dpp v157, v157, v157 row_ror:8 row_mask:0xf bank_mask:0xf bound_ctrl:1
	v_pk_add_f32 v[180:181], v[180:181], v[118:119] op_sel_hi:[1,0] neg_lo:[0,1] neg_hi:[0,1]
	v_add_f32_dpp v156, v156, v156 row_ror:4 row_mask:0xf bank_mask:0xf bound_ctrl:1
	v_pk_add_f32 v[188:189], v[188:189], v[118:119] op_sel:[0,1] op_sel_hi:[1,1] neg_lo:[0,1] neg_hi:[0,1]
	v_add_f32_dpp v157, v157, v157 row_ror:4 row_mask:0xf bank_mask:0xf bound_ctrl:1
	v_pk_add_f32 v[182:183], v[182:183], v[118:119] op_sel_hi:[1,0] neg_lo:[0,1] neg_hi:[0,1]
	v_add_f32_dpp v156, v156, v156 row_ror:2 row_mask:0xf bank_mask:0xf bound_ctrl:1
	v_pk_add_f32 v[190:191], v[190:191], v[118:119] op_sel:[0,1] op_sel_hi:[1,1] neg_lo:[0,1] neg_hi:[0,1]
	v_add_f32_dpp v157, v157, v157 row_ror:2 row_mask:0xf bank_mask:0xf bound_ctrl:1
	v_pk_add_f32 v[184:185], v[184:185], v[118:119] op_sel_hi:[1,0] neg_lo:[0,1] neg_hi:[0,1]
	v_add_f32_dpp v156, v156, v156 row_ror:1 row_mask:0xf bank_mask:0xf bound_ctrl:1
	v_pk_add_f32 v[192:193], v[192:193], v[118:119] op_sel:[0,1] op_sel_hi:[1,1] neg_lo:[0,1] neg_hi:[0,1]
	v_add_f32_dpp v157, v157, v157 row_ror:1 row_mask:0xf bank_mask:0xf bound_ctrl:1
	s_waitcnt lgkmcnt(10)
	v_pk_fma_f32 v[178:179], v[72:73], v[178:179], v[118:119] op_sel_hi:[1,1,0]
	s_and_saveexec_b64 s[8:9], s[38:39]
	ds_write_b32 v103, v156 offset:40064
	ds_write_b32 v103, v157 offset:40128
	s_mov_b64 exec, s[8:9]
	v_pk_fma_f32 v[186:187], v[72:73], v[186:187], v[118:119] op_sel:[0,0,1] op_sel_hi:[1,1,1]
	v_pk_fma_f32 v[180:181], v[74:75], v[180:181], v[118:119] op_sel_hi:[1,1,0]
	v_pk_fma_f32 v[188:189], v[74:75], v[188:189], v[118:119] op_sel:[0,0,1] op_sel_hi:[1,1,1]
	s_waitcnt lgkmcnt(11)
	v_pk_fma_f32 v[182:183], v[76:77], v[182:183], v[118:119] op_sel_hi:[1,1,0]
	v_pk_fma_f32 v[190:191], v[76:77], v[190:191], v[118:119] op_sel:[0,0,1] op_sel_hi:[1,1,1]
	v_pk_fma_f32 v[184:185], v[78:79], v[184:185], v[118:119] op_sel_hi:[1,1,0]
	v_pk_fma_f32 v[192:193], v[78:79], v[192:193], v[118:119] op_sel:[0,0,1] op_sel_hi:[1,1,1]
	ds_read2_b32 v[118:119], v195 offset0:128 offset1:144
	ds_read_b128 v[72:75], v145 offset:32768
	ds_read_b128 v[76:79], v145 offset:33024
	s_waitcnt lgkmcnt(13)
	v_pk_fma_f32 v[146:147], v[64:65], v[178:179], v[196:197]
	v_pk_fma_f32 v[150:151], v[64:65], v[186:187], v[196:197]
	v_pk_fma_f32 v[148:149], v[66:67], v[180:181], v[196:197]
	v_pk_fma_f32 v[152:153], v[66:67], v[188:189], v[196:197]
	ds_read_b128 v[64:67], v145 offset:24576
	s_waitcnt lgkmcnt(13)
	v_pk_fma_f32 v[146:147], v[68:69], v[182:183], v[146:147]
	v_pk_fma_f32 v[150:151], v[68:69], v[190:191], v[150:151]
	v_pk_fma_f32 v[148:149], v[70:71], v[184:185], v[148:149]
	v_pk_fma_f32 v[152:153], v[70:71], v[192:193], v[152:153]
	ds_read_b128 v[68:71], v145 offset:24832
	v_add_f32_e32 v146, v146, v147
	v_add_f32_e32 v148, v148, v149
	v_add_f32_e32 v150, v150, v151
	v_add_f32_e32 v152, v152, v153
	v_add_f32_e32 v154, v146, v148
	v_add_f32_e32 v155, v150, v152
	s_waitcnt lgkmcnt(11)
	v_pk_add_f32 v[178:179], v[178:179], v[120:121] op_sel_hi:[1,0] neg_lo:[0,1] neg_hi:[0,1]
	v_add_f32_dpp v154, v154, v154 row_ror:8 row_mask:0xf bank_mask:0xf bound_ctrl:1
	v_pk_add_f32 v[186:187], v[186:187], v[120:121] op_sel:[0,1] op_sel_hi:[1,1] neg_lo:[0,1] neg_hi:[0,1]
	v_add_f32_dpp v155, v155, v155 row_ror:8 row_mask:0xf bank_mask:0xf bound_ctrl:1
	v_pk_add_f32 v[180:181], v[180:181], v[120:121] op_sel_hi:[1,0] neg_lo:[0,1] neg_hi:[0,1]
	v_add_f32_dpp v154, v154, v154 row_ror:4 row_mask:0xf bank_mask:0xf bound_ctrl:1
	v_pk_add_f32 v[188:189], v[188:189], v[120:121] op_sel:[0,1] op_sel_hi:[1,1] neg_lo:[0,1] neg_hi:[0,1]
	v_add_f32_dpp v155, v155, v155 row_ror:4 row_mask:0xf bank_mask:0xf bound_ctrl:1
	v_pk_add_f32 v[182:183], v[182:183], v[120:121] op_sel_hi:[1,0] neg_lo:[0,1] neg_hi:[0,1]
	v_add_f32_dpp v154, v154, v154 row_ror:2 row_mask:0xf bank_mask:0xf bound_ctrl:1
	v_pk_add_f32 v[190:191], v[190:191], v[120:121] op_sel:[0,1] op_sel_hi:[1,1] neg_lo:[0,1] neg_hi:[0,1]
	v_add_f32_dpp v155, v155, v155 row_ror:2 row_mask:0xf bank_mask:0xf bound_ctrl:1
	v_pk_add_f32 v[184:185], v[184:185], v[120:121] op_sel_hi:[1,0] neg_lo:[0,1] neg_hi:[0,1]
	v_add_f32_dpp v154, v154, v154 row_ror:1 row_mask:0xf bank_mask:0xf bound_ctrl:1
	v_pk_add_f32 v[192:193], v[192:193], v[120:121] op_sel:[0,1] op_sel_hi:[1,1] neg_lo:[0,1] neg_hi:[0,1]
	v_add_f32_dpp v155, v155, v155 row_ror:1 row_mask:0xf bank_mask:0xf bound_ctrl:1
	s_waitcnt lgkmcnt(10)
	v_pk_fma_f32 v[178:179], v[88:89], v[178:179], v[120:121] op_sel_hi:[1,1,0]
	s_and_saveexec_b64 s[8:9], s[38:39]
	ds_write_b32 v103, v154 offset:40192
	ds_write_b32 v103, v155 offset:40256
	s_mov_b64 exec, s[8:9]
	v_pk_fma_f32 v[186:187], v[88:89], v[186:187], v[120:121] op_sel:[0,0,1] op_sel_hi:[1,1,1]
	v_pk_fma_f32 v[180:181], v[90:91], v[180:181], v[120:121] op_sel_hi:[1,1,0]
	v_pk_fma_f32 v[188:189], v[90:91], v[188:189], v[120:121] op_sel:[0,0,1] op_sel_hi:[1,1,1]
	s_waitcnt lgkmcnt(11)
	v_pk_fma_f32 v[182:183], v[92:93], v[182:183], v[120:121] op_sel_hi:[1,1,0]
	v_pk_fma_f32 v[190:191], v[92:93], v[190:191], v[120:121] op_sel:[0,0,1] op_sel_hi:[1,1,1]
	v_pk_fma_f32 v[184:185], v[94:95], v[184:185], v[120:121] op_sel_hi:[1,1,0]
	v_pk_fma_f32 v[192:193], v[94:95], v[192:193], v[120:121] op_sel:[0,0,1] op_sel_hi:[1,1,1]
	ds_read2_b32 v[120:121], v195 offset0:160 offset1:176
	ds_read_b128 v[88:91], v145 offset:33280
	ds_read_b128 v[92:95], v145 offset:33536
	s_waitcnt lgkmcnt(13)
	v_pk_fma_f32 v[146:147], v[80:81], v[178:179], v[196:197]
	v_pk_fma_f32 v[150:151], v[80:81], v[186:187], v[196:197]
	v_pk_fma_f32 v[148:149], v[82:83], v[180:181], v[196:197]
	v_pk_fma_f32 v[152:153], v[82:83], v[188:189], v[196:197]
	ds_read_b128 v[80:83], v145 offset:25088
	s_waitcnt lgkmcnt(13)
	v_pk_fma_f32 v[146:147], v[84:85], v[182:183], v[146:147]
	v_pk_fma_f32 v[150:151], v[84:85], v[190:191], v[150:151]
	v_pk_fma_f32 v[148:149], v[86:87], v[184:185], v[148:149]
	v_pk_fma_f32 v[152:153], v[86:87], v[192:193], v[152:153]
	ds_read_b128 v[84:87], v145 offset:25344
	v_add_f32_e32 v146, v146, v147
	v_add_f32_e32 v148, v148, v149
	v_add_f32_e32 v150, v150, v151
	v_add_f32_e32 v152, v152, v153
	v_add_f32_e32 v156, v146, v148
	v_add_f32_e32 v157, v150, v152
	s_waitcnt lgkmcnt(11)
	v_pk_add_f32 v[178:179], v[178:179], v[118:119] op_sel_hi:[1,0] neg_lo:[0,1] neg_hi:[0,1]
	v_add_f32_dpp v156, v156, v156 row_ror:8 row_mask:0xf bank_mask:0xf bound_ctrl:1
	v_pk_add_f32 v[186:187], v[186:187], v[118:119] op_sel:[0,1] op_sel_hi:[1,1] neg_lo:[0,1] neg_hi:[0,1]
	v_add_f32_dpp v157, v157, v157 row_ror:8 row_mask:0xf bank_mask:0xf bound_ctrl:1
	v_pk_add_f32 v[180:181], v[180:181], v[118:119] op_sel_hi:[1,0] neg_lo:[0,1] neg_hi:[0,1]
	v_add_f32_dpp v156, v156, v156 row_ror:4 row_mask:0xf bank_mask:0xf bound_ctrl:1
	v_pk_add_f32 v[188:189], v[188:189], v[118:119] op_sel:[0,1] op_sel_hi:[1,1] neg_lo:[0,1] neg_hi:[0,1]
	v_add_f32_dpp v157, v157, v157 row_ror:4 row_mask:0xf bank_mask:0xf bound_ctrl:1
	v_pk_add_f32 v[182:183], v[182:183], v[118:119] op_sel_hi:[1,0] neg_lo:[0,1] neg_hi:[0,1]
	v_add_f32_dpp v156, v156, v156 row_ror:2 row_mask:0xf bank_mask:0xf bound_ctrl:1
	v_pk_add_f32 v[190:191], v[190:191], v[118:119] op_sel:[0,1] op_sel_hi:[1,1] neg_lo:[0,1] neg_hi:[0,1]
	v_add_f32_dpp v157, v157, v157 row_ror:2 row_mask:0xf bank_mask:0xf bound_ctrl:1
	v_pk_add_f32 v[184:185], v[184:185], v[118:119] op_sel_hi:[1,0] neg_lo:[0,1] neg_hi:[0,1]
	v_add_f32_dpp v156, v156, v156 row_ror:1 row_mask:0xf bank_mask:0xf bound_ctrl:1
	v_pk_add_f32 v[192:193], v[192:193], v[118:119] op_sel:[0,1] op_sel_hi:[1,1] neg_lo:[0,1] neg_hi:[0,1]
	v_add_f32_dpp v157, v157, v157 row_ror:1 row_mask:0xf bank_mask:0xf bound_ctrl:1
	s_waitcnt lgkmcnt(10)
	v_pk_fma_f32 v[178:179], v[72:73], v[178:179], v[118:119] op_sel_hi:[1,1,0]
	s_and_saveexec_b64 s[8:9], s[38:39]
	ds_write_b32 v103, v156 offset:40320
	ds_write_b32 v103, v157 offset:40384
	s_mov_b64 exec, s[8:9]
	v_pk_fma_f32 v[186:187], v[72:73], v[186:187], v[118:119] op_sel:[0,0,1] op_sel_hi:[1,1,1]
	v_pk_fma_f32 v[180:181], v[74:75], v[180:181], v[118:119] op_sel_hi:[1,1,0]
	v_pk_fma_f32 v[188:189], v[74:75], v[188:189], v[118:119] op_sel:[0,0,1] op_sel_hi:[1,1,1]
	s_waitcnt lgkmcnt(11)
	v_pk_fma_f32 v[182:183], v[76:77], v[182:183], v[118:119] op_sel_hi:[1,1,0]
	v_pk_fma_f32 v[190:191], v[76:77], v[190:191], v[118:119] op_sel:[0,0,1] op_sel_hi:[1,1,1]
	v_pk_fma_f32 v[184:185], v[78:79], v[184:185], v[118:119] op_sel_hi:[1,1,0]
	v_pk_fma_f32 v[192:193], v[78:79], v[192:193], v[118:119] op_sel:[0,0,1] op_sel_hi:[1,1,1]
	ds_read2_b32 v[118:119], v195 offset0:192 offset1:208
	ds_read_b128 v[72:75], v145 offset:33792
	ds_read_b128 v[76:79], v145 offset:34048
	s_waitcnt lgkmcnt(13)
	v_pk_fma_f32 v[146:147], v[64:65], v[178:179], v[196:197]
	v_pk_fma_f32 v[150:151], v[64:65], v[186:187], v[196:197]
	v_pk_fma_f32 v[148:149], v[66:67], v[180:181], v[196:197]
	v_pk_fma_f32 v[152:153], v[66:67], v[188:189], v[196:197]
	ds_read_b128 v[64:67], v145 offset:25600
	s_waitcnt lgkmcnt(13)
	v_pk_fma_f32 v[146:147], v[68:69], v[182:183], v[146:147]
	v_pk_fma_f32 v[150:151], v[68:69], v[190:191], v[150:151]
	v_pk_fma_f32 v[148:149], v[70:71], v[184:185], v[148:149]
	v_pk_fma_f32 v[152:153], v[70:71], v[192:193], v[152:153]
	ds_read_b128 v[68:71], v145 offset:25856
	v_add_f32_e32 v146, v146, v147
	v_add_f32_e32 v148, v148, v149
	v_add_f32_e32 v150, v150, v151
	v_add_f32_e32 v152, v152, v153
	v_add_f32_e32 v154, v146, v148
	v_add_f32_e32 v155, v150, v152
	s_waitcnt lgkmcnt(11)
	v_pk_add_f32 v[178:179], v[178:179], v[120:121] op_sel_hi:[1,0] neg_lo:[0,1] neg_hi:[0,1]
	v_add_f32_dpp v154, v154, v154 row_ror:8 row_mask:0xf bank_mask:0xf bound_ctrl:1
	v_pk_add_f32 v[186:187], v[186:187], v[120:121] op_sel:[0,1] op_sel_hi:[1,1] neg_lo:[0,1] neg_hi:[0,1]
	v_add_f32_dpp v155, v155, v155 row_ror:8 row_mask:0xf bank_mask:0xf bound_ctrl:1
	v_pk_add_f32 v[180:181], v[180:181], v[120:121] op_sel_hi:[1,0] neg_lo:[0,1] neg_hi:[0,1]
	v_add_f32_dpp v154, v154, v154 row_ror:4 row_mask:0xf bank_mask:0xf bound_ctrl:1
	v_pk_add_f32 v[188:189], v[188:189], v[120:121] op_sel:[0,1] op_sel_hi:[1,1] neg_lo:[0,1] neg_hi:[0,1]
	v_add_f32_dpp v155, v155, v155 row_ror:4 row_mask:0xf bank_mask:0xf bound_ctrl:1
	v_pk_add_f32 v[182:183], v[182:183], v[120:121] op_sel_hi:[1,0] neg_lo:[0,1] neg_hi:[0,1]
	v_add_f32_dpp v154, v154, v154 row_ror:2 row_mask:0xf bank_mask:0xf bound_ctrl:1
	v_pk_add_f32 v[190:191], v[190:191], v[120:121] op_sel:[0,1] op_sel_hi:[1,1] neg_lo:[0,1] neg_hi:[0,1]
	v_add_f32_dpp v155, v155, v155 row_ror:2 row_mask:0xf bank_mask:0xf bound_ctrl:1
	v_pk_add_f32 v[184:185], v[184:185], v[120:121] op_sel_hi:[1,0] neg_lo:[0,1] neg_hi:[0,1]
	v_add_f32_dpp v154, v154, v154 row_ror:1 row_mask:0xf bank_mask:0xf bound_ctrl:1
	v_pk_add_f32 v[192:193], v[192:193], v[120:121] op_sel:[0,1] op_sel_hi:[1,1] neg_lo:[0,1] neg_hi:[0,1]
	v_add_f32_dpp v155, v155, v155 row_ror:1 row_mask:0xf bank_mask:0xf bound_ctrl:1
	s_waitcnt lgkmcnt(10)
	v_pk_fma_f32 v[178:179], v[88:89], v[178:179], v[120:121] op_sel_hi:[1,1,0]
	s_and_saveexec_b64 s[8:9], s[38:39]
	ds_write_b32 v103, v154 offset:40448
	ds_write_b32 v103, v155 offset:40512
	s_mov_b64 exec, s[8:9]
	v_pk_fma_f32 v[186:187], v[88:89], v[186:187], v[120:121] op_sel:[0,0,1] op_sel_hi:[1,1,1]
	v_pk_fma_f32 v[180:181], v[90:91], v[180:181], v[120:121] op_sel_hi:[1,1,0]
	v_pk_fma_f32 v[188:189], v[90:91], v[188:189], v[120:121] op_sel:[0,0,1] op_sel_hi:[1,1,1]
	s_waitcnt lgkmcnt(11)
	v_pk_fma_f32 v[182:183], v[92:93], v[182:183], v[120:121] op_sel_hi:[1,1,0]
	v_pk_fma_f32 v[190:191], v[92:93], v[190:191], v[120:121] op_sel:[0,0,1] op_sel_hi:[1,1,1]
	v_pk_fma_f32 v[184:185], v[94:95], v[184:185], v[120:121] op_sel_hi:[1,1,0]
	v_pk_fma_f32 v[192:193], v[94:95], v[192:193], v[120:121] op_sel:[0,0,1] op_sel_hi:[1,1,1]
	ds_read2_b32 v[120:121], v195 offset0:224 offset1:240
	ds_read_b128 v[88:91], v145 offset:34304
	ds_read_b128 v[92:95], v145 offset:34560
	s_waitcnt lgkmcnt(13)
	v_pk_fma_f32 v[146:147], v[80:81], v[178:179], v[196:197]
	v_pk_fma_f32 v[150:151], v[80:81], v[186:187], v[196:197]
	v_pk_fma_f32 v[148:149], v[82:83], v[180:181], v[196:197]
	v_pk_fma_f32 v[152:153], v[82:83], v[188:189], v[196:197]
	ds_read_b128 v[80:83], v145 offset:26112
	s_waitcnt lgkmcnt(13)
	v_pk_fma_f32 v[146:147], v[84:85], v[182:183], v[146:147]
	v_pk_fma_f32 v[150:151], v[84:85], v[190:191], v[150:151]
	v_pk_fma_f32 v[148:149], v[86:87], v[184:185], v[148:149]
	v_pk_fma_f32 v[152:153], v[86:87], v[192:193], v[152:153]
	ds_read_b128 v[84:87], v145 offset:26368
	v_add_f32_e32 v146, v146, v147
	v_add_f32_e32 v148, v148, v149
	v_add_f32_e32 v150, v150, v151
	v_add_f32_e32 v152, v152, v153
	v_add_f32_e32 v156, v146, v148
	v_add_f32_e32 v157, v150, v152
	s_waitcnt lgkmcnt(11)
	v_pk_add_f32 v[178:179], v[178:179], v[118:119] op_sel_hi:[1,0] neg_lo:[0,1] neg_hi:[0,1]
	v_add_f32_dpp v156, v156, v156 row_ror:8 row_mask:0xf bank_mask:0xf bound_ctrl:1
	v_pk_add_f32 v[186:187], v[186:187], v[118:119] op_sel:[0,1] op_sel_hi:[1,1] neg_lo:[0,1] neg_hi:[0,1]
	v_add_f32_dpp v157, v157, v157 row_ror:8 row_mask:0xf bank_mask:0xf bound_ctrl:1
	v_pk_add_f32 v[180:181], v[180:181], v[118:119] op_sel_hi:[1,0] neg_lo:[0,1] neg_hi:[0,1]
	v_add_f32_dpp v156, v156, v156 row_ror:4 row_mask:0xf bank_mask:0xf bound_ctrl:1
	v_pk_add_f32 v[188:189], v[188:189], v[118:119] op_sel:[0,1] op_sel_hi:[1,1] neg_lo:[0,1] neg_hi:[0,1]
	v_add_f32_dpp v157, v157, v157 row_ror:4 row_mask:0xf bank_mask:0xf bound_ctrl:1
	v_pk_add_f32 v[182:183], v[182:183], v[118:119] op_sel_hi:[1,0] neg_lo:[0,1] neg_hi:[0,1]
	v_add_f32_dpp v156, v156, v156 row_ror:2 row_mask:0xf bank_mask:0xf bound_ctrl:1
	v_pk_add_f32 v[190:191], v[190:191], v[118:119] op_sel:[0,1] op_sel_hi:[1,1] neg_lo:[0,1] neg_hi:[0,1]
	v_add_f32_dpp v157, v157, v157 row_ror:2 row_mask:0xf bank_mask:0xf bound_ctrl:1
	v_pk_add_f32 v[184:185], v[184:185], v[118:119] op_sel_hi:[1,0] neg_lo:[0,1] neg_hi:[0,1]
	v_add_f32_dpp v156, v156, v156 row_ror:1 row_mask:0xf bank_mask:0xf bound_ctrl:1
	v_pk_add_f32 v[192:193], v[192:193], v[118:119] op_sel:[0,1] op_sel_hi:[1,1] neg_lo:[0,1] neg_hi:[0,1]
	v_add_f32_dpp v157, v157, v157 row_ror:1 row_mask:0xf bank_mask:0xf bound_ctrl:1
	s_waitcnt lgkmcnt(10)
	v_pk_fma_f32 v[178:179], v[72:73], v[178:179], v[118:119] op_sel_hi:[1,1,0]
	s_and_saveexec_b64 s[8:9], s[38:39]
	ds_write_b32 v103, v156 offset:40576
	ds_write_b32 v103, v157 offset:40640
	s_mov_b64 exec, s[8:9]
	v_pk_fma_f32 v[186:187], v[72:73], v[186:187], v[118:119] op_sel:[0,0,1] op_sel_hi:[1,1,1]
	v_pk_fma_f32 v[180:181], v[74:75], v[180:181], v[118:119] op_sel_hi:[1,1,0]
	v_pk_fma_f32 v[188:189], v[74:75], v[188:189], v[118:119] op_sel:[0,0,1] op_sel_hi:[1,1,1]
	s_waitcnt lgkmcnt(11)
	v_pk_fma_f32 v[182:183], v[76:77], v[182:183], v[118:119] op_sel_hi:[1,1,0]
	v_pk_fma_f32 v[190:191], v[76:77], v[190:191], v[118:119] op_sel:[0,0,1] op_sel_hi:[1,1,1]
	v_pk_fma_f32 v[184:185], v[78:79], v[184:185], v[118:119] op_sel_hi:[1,1,0]
	v_pk_fma_f32 v[192:193], v[78:79], v[192:193], v[118:119] op_sel:[0,0,1] op_sel_hi:[1,1,1]
	s_waitcnt lgkmcnt(10)
	v_pk_fma_f32 v[146:147], v[64:65], v[178:179], v[196:197]
	v_pk_fma_f32 v[150:151], v[64:65], v[186:187], v[196:197]
	v_pk_fma_f32 v[148:149], v[66:67], v[180:181], v[196:197]
	v_pk_fma_f32 v[152:153], v[66:67], v[188:189], v[196:197]
	s_waitcnt lgkmcnt(9)
	v_pk_fma_f32 v[146:147], v[68:69], v[182:183], v[146:147]
	v_pk_fma_f32 v[150:151], v[68:69], v[190:191], v[150:151]
	v_pk_fma_f32 v[148:149], v[70:71], v[184:185], v[148:149]
	v_pk_fma_f32 v[152:153], v[70:71], v[192:193], v[152:153]
	v_add_f32_e32 v146, v146, v147
	v_add_f32_e32 v148, v148, v149
	v_add_f32_e32 v150, v150, v151
	v_add_f32_e32 v152, v152, v153
	v_add_f32_e32 v154, v146, v148
	v_add_f32_e32 v155, v150, v152
	s_waitcnt lgkmcnt(6)
	v_pk_add_f32 v[178:179], v[178:179], v[120:121] op_sel_hi:[1,0] neg_lo:[0,1] neg_hi:[0,1]
	v_add_f32_dpp v154, v154, v154 row_ror:8 row_mask:0xf bank_mask:0xf bound_ctrl:1
	v_pk_add_f32 v[186:187], v[186:187], v[120:121] op_sel:[0,1] op_sel_hi:[1,1] neg_lo:[0,1] neg_hi:[0,1]
	v_add_f32_dpp v155, v155, v155 row_ror:8 row_mask:0xf bank_mask:0xf bound_ctrl:1
	v_pk_add_f32 v[180:181], v[180:181], v[120:121] op_sel_hi:[1,0] neg_lo:[0,1] neg_hi:[0,1]
	v_add_f32_dpp v154, v154, v154 row_ror:4 row_mask:0xf bank_mask:0xf bound_ctrl:1
	v_pk_add_f32 v[188:189], v[188:189], v[120:121] op_sel:[0,1] op_sel_hi:[1,1] neg_lo:[0,1] neg_hi:[0,1]
	v_add_f32_dpp v155, v155, v155 row_ror:4 row_mask:0xf bank_mask:0xf bound_ctrl:1
	v_pk_add_f32 v[182:183], v[182:183], v[120:121] op_sel_hi:[1,0] neg_lo:[0,1] neg_hi:[0,1]
	v_add_f32_dpp v154, v154, v154 row_ror:2 row_mask:0xf bank_mask:0xf bound_ctrl:1
	v_pk_add_f32 v[190:191], v[190:191], v[120:121] op_sel:[0,1] op_sel_hi:[1,1] neg_lo:[0,1] neg_hi:[0,1]
	v_add_f32_dpp v155, v155, v155 row_ror:2 row_mask:0xf bank_mask:0xf bound_ctrl:1
	v_pk_add_f32 v[184:185], v[184:185], v[120:121] op_sel_hi:[1,0] neg_lo:[0,1] neg_hi:[0,1]
	v_add_f32_dpp v154, v154, v154 row_ror:1 row_mask:0xf bank_mask:0xf bound_ctrl:1
	v_pk_add_f32 v[192:193], v[192:193], v[120:121] op_sel:[0,1] op_sel_hi:[1,1] neg_lo:[0,1] neg_hi:[0,1]
	v_add_f32_dpp v155, v155, v155 row_ror:1 row_mask:0xf bank_mask:0xf bound_ctrl:1
	s_waitcnt lgkmcnt(5)
	v_pk_fma_f32 v[178:179], v[88:89], v[178:179], v[120:121] op_sel_hi:[1,1,0]
	s_and_saveexec_b64 s[8:9], s[38:39]
	ds_write_b32 v103, v154 offset:40704
	ds_write_b32 v103, v155 offset:40768
	s_mov_b64 exec, s[8:9]
	v_pk_fma_f32 v[186:187], v[88:89], v[186:187], v[120:121] op_sel:[0,0,1] op_sel_hi:[1,1,1]
	v_pk_fma_f32 v[180:181], v[90:91], v[180:181], v[120:121] op_sel_hi:[1,1,0]
	v_pk_fma_f32 v[188:189], v[90:91], v[188:189], v[120:121] op_sel:[0,0,1] op_sel_hi:[1,1,1]
	s_waitcnt lgkmcnt(6)
	v_pk_fma_f32 v[182:183], v[92:93], v[182:183], v[120:121] op_sel_hi:[1,1,0]
	v_pk_fma_f32 v[190:191], v[92:93], v[190:191], v[120:121] op_sel:[0,0,1] op_sel_hi:[1,1,1]
	v_pk_fma_f32 v[184:185], v[94:95], v[184:185], v[120:121] op_sel_hi:[1,1,0]
	v_pk_fma_f32 v[192:193], v[94:95], v[192:193], v[120:121] op_sel:[0,0,1] op_sel_hi:[1,1,1]
	s_waitcnt lgkmcnt(5)
	v_pk_fma_f32 v[146:147], v[80:81], v[178:179], v[196:197]
	v_pk_fma_f32 v[150:151], v[80:81], v[186:187], v[196:197]
	v_pk_fma_f32 v[148:149], v[82:83], v[180:181], v[196:197]
	v_pk_fma_f32 v[152:153], v[82:83], v[188:189], v[196:197]
	s_waitcnt lgkmcnt(4)
	v_pk_fma_f32 v[146:147], v[84:85], v[182:183], v[146:147]
	v_pk_fma_f32 v[150:151], v[84:85], v[190:191], v[150:151]
	v_pk_fma_f32 v[148:149], v[86:87], v[184:185], v[148:149]
	v_pk_fma_f32 v[152:153], v[86:87], v[192:193], v[152:153]
	v_add_f32_e32 v146, v146, v147
	v_add_f32_e32 v148, v148, v149
	v_add_f32_e32 v150, v150, v151
	v_add_f32_e32 v152, v152, v153
	v_add_f32_e32 v156, v146, v148
	v_add_f32_e32 v157, v150, v152
	s_nop 0
	v_add_f32_dpp v156, v156, v156 row_ror:8 row_mask:0xf bank_mask:0xf bound_ctrl:1
	v_add_f32_dpp v157, v157, v157 row_ror:8 row_mask:0xf bank_mask:0xf bound_ctrl:1
	s_nop 0
	v_add_f32_dpp v156, v156, v156 row_ror:4 row_mask:0xf bank_mask:0xf bound_ctrl:1
	v_add_f32_dpp v157, v157, v157 row_ror:4 row_mask:0xf bank_mask:0xf bound_ctrl:1
	s_nop 0
	v_add_f32_dpp v156, v156, v156 row_ror:2 row_mask:0xf bank_mask:0xf bound_ctrl:1
	v_add_f32_dpp v157, v157, v157 row_ror:2 row_mask:0xf bank_mask:0xf bound_ctrl:1
	s_nop 0
	v_add_f32_dpp v156, v156, v156 row_ror:1 row_mask:0xf bank_mask:0xf bound_ctrl:1
	v_add_f32_dpp v157, v157, v157 row_ror:1 row_mask:0xf bank_mask:0xf bound_ctrl:1
	s_and_saveexec_b64 s[8:9], s[38:39]
	ds_write_b32 v103, v156 offset:40832
	ds_write_b32 v103, v157 offset:40896
	s_mov_b64 exec, s[8:9]
	s_waitcnt vmcnt(9)
	v_mul_f32_e32 v64, 0xbfb8aa3b, v28
	v_mul_f32_e32 v65, 0xbfb8aa3b, v29
	v_exp_f32_e32 v64, v64
	v_exp_f32_e32 v65, v65
	v_mul_f32_e32 v66, 0xbfb8aa3b, v30
	v_mul_f32_e32 v67, 0xbfb8aa3b, v31
	v_exp_f32_e32 v66, v66
	v_pk_add_f32 v[64:65], v[64:65], 1.0 op_sel_hi:[1,0]
	v_exp_f32_e32 v67, v67
	v_div_scale_f32 v80, s[8:9], v65, v65, v29
	v_rcp_f32_e32 v81, v80
	v_pk_add_f32 v[66:67], v[66:67], 1.0 op_sel_hi:[1,0]
	s_waitcnt vmcnt(8)
	v_mul_f32_e32 v72, 0xbfb8aa3b, v32
	v_mul_f32_e32 v73, 0xbfb8aa3b, v33
	v_fma_f32 v82, -v80, v81, 1.0
	v_fmac_f32_e32 v81, v82, v81
	v_div_scale_f32 v82, vcc, v29, v65, v29
	v_mul_f32_e32 v83, v82, v81
	v_fma_f32 v88, -v80, v83, v82
	v_fmac_f32_e32 v83, v88, v81
	v_fma_f32 v80, -v80, v83, v82
	v_div_fmas_f32 v80, v80, v81, v83
	v_div_fixup_f32 v65, v80, v65, v29
	v_div_scale_f32 v80, s[8:9], v64, v64, v28
	v_rcp_f32_e32 v81, v80
	v_exp_f32_e32 v72, v72
	v_exp_f32_e32 v73, v73
	v_mul_f32_e32 v74, 0xbfb8aa3b, v34
	v_fma_f32 v82, -v80, v81, 1.0
	v_fmac_f32_e32 v81, v82, v81
	v_div_scale_f32 v82, vcc, v28, v64, v28
	v_mul_f32_e32 v83, v82, v81
	v_fma_f32 v88, -v80, v83, v82
	v_fmac_f32_e32 v83, v88, v81
	v_fma_f32 v80, -v80, v83, v82
	v_div_fmas_f32 v80, v80, v81, v83
	v_div_fixup_f32 v64, v80, v64, v28
	v_div_scale_f32 v80, s[8:9], v67, v67, v31
	v_rcp_f32_e32 v81, v80
	v_pk_mul_f32 v[64:65], v[64:65], s[18:19] op_sel_hi:[1,0]
	v_mul_f32_e32 v75, 0xbfb8aa3b, v35
	v_exp_f32_e32 v74, v74
	v_fma_f32 v82, -v80, v81, 1.0
	v_fmac_f32_e32 v81, v82, v81
	v_div_scale_f32 v82, vcc, v31, v67, v31
	v_mul_f32_e32 v83, v82, v81
	v_fma_f32 v88, -v80, v83, v82
	v_fmac_f32_e32 v83, v88, v81
	v_fma_f32 v80, -v80, v83, v82
	v_div_fmas_f32 v80, v80, v81, v83
	v_div_fixup_f32 v67, v80, v67, v31
	v_div_scale_f32 v80, s[8:9], v66, v66, v30
	v_rcp_f32_e32 v81, v80
	v_exp_f32_e32 v75, v75
	s_cmpk_gt_u32 s48, 0x79
	v_fma_f32 v82, -v80, v81, 1.0
	v_fmac_f32_e32 v81, v82, v81
	v_div_scale_f32 v82, vcc, v30, v66, v30
	v_mul_f32_e32 v83, v82, v81
	v_fma_f32 v88, -v80, v83, v82
	v_fmac_f32_e32 v83, v88, v81
	v_fma_f32 v80, -v80, v83, v82
	v_div_fmas_f32 v80, v80, v81, v83
	v_div_fixup_f32 v66, v80, v66, v30
	v_pk_mul_f32 v[66:67], v[66:67], s[18:19] op_sel_hi:[1,0]
	ds_write_b128 v141, v[64:67]
	v_pk_add_f32 v[64:65], v[72:73], 1.0 op_sel_hi:[1,0]
	v_div_scale_f32 v66, s[8:9], v65, v65, 1.0
	v_rcp_f32_e32 v67, v66
	s_nop 0
	v_fma_f32 v72, -v66, v67, 1.0
	v_fmac_f32_e32 v67, v72, v67
	v_div_scale_f32 v72, vcc, 1.0, v65, 1.0
	v_mul_f32_e32 v73, v72, v67
	v_fma_f32 v80, -v66, v73, v72
	v_fmac_f32_e32 v73, v80, v67
	v_fma_f32 v66, -v66, v73, v72
	v_div_fmas_f32 v66, v66, v67, v73
	v_div_fixup_f32 v65, v66, v65, 1.0
	v_div_scale_f32 v66, s[8:9], v64, v64, 1.0
	v_rcp_f32_e32 v67, v66
	s_nop 0
	v_fma_f32 v72, -v66, v67, 1.0
	v_fmac_f32_e32 v67, v72, v67
	v_div_scale_f32 v72, vcc, 1.0, v64, 1.0
	v_mul_f32_e32 v73, v72, v67
	v_fma_f32 v80, -v66, v73, v72
	v_fmac_f32_e32 v73, v80, v67
	v_fma_f32 v66, -v66, v73, v72
	v_div_fmas_f32 v66, v66, v67, v73
	v_div_fixup_f32 v64, v66, v64, 1.0
	v_pk_add_f32 v[66:67], v[74:75], 1.0 op_sel_hi:[1,0]
	v_pk_fma_f32 v[64:65], v[110:111], v[64:65], v[104:105]
	v_div_scale_f32 v72, s[8:9], v67, v67, 1.0
	v_rcp_f32_e32 v73, v72
	s_nop 0
	v_fma_f32 v74, -v72, v73, 1.0
	v_fmac_f32_e32 v73, v74, v73
	v_div_scale_f32 v74, vcc, 1.0, v67, 1.0
	v_mul_f32_e32 v75, v74, v73
	v_fma_f32 v80, -v72, v75, v74
	v_fmac_f32_e32 v75, v80, v73
	v_fma_f32 v72, -v72, v75, v74
	v_div_fmas_f32 v72, v72, v73, v75
	v_div_fixup_f32 v67, v72, v67, 1.0
	v_div_scale_f32 v72, s[8:9], v66, v66, 1.0
	v_rcp_f32_e32 v73, v72
	s_nop 0
	v_fma_f32 v74, -v72, v73, 1.0
	v_fmac_f32_e32 v73, v74, v73
	v_div_scale_f32 v74, vcc, 1.0, v66, 1.0
	v_mul_f32_e32 v75, v74, v73
	v_fma_f32 v80, -v72, v75, v74
	v_fmac_f32_e32 v75, v80, v73
	v_fma_f32 v72, -v72, v75, v74
	v_div_fmas_f32 v72, v72, v73, v75
	v_div_fixup_f32 v66, v72, v66, 1.0
	v_pk_fma_f32 v[66:67], v[112:113], v[66:67], v[106:107]
	ds_write_b128 v141, v[64:67] offset:8192
	ds_write_b32 v134, v131 offset:16384
	v_mul_f32_e32 v64, 0xbfb8aa3b, v40
	v_mul_f32_e32 v65, 0xbfb8aa3b, v41
	v_exp_f32_e32 v64, v64
	v_exp_f32_e32 v65, v65
	v_mul_f32_e32 v66, 0xbfb8aa3b, v42
	v_mul_f32_e32 v67, 0xbfb8aa3b, v43
	v_exp_f32_e32 v66, v66
	v_pk_add_f32 v[64:65], v[64:65], 1.0 op_sel_hi:[1,0]
	v_exp_f32_e32 v67, v67
	v_div_scale_f32 v80, s[8:9], v65, v65, v41
	v_rcp_f32_e32 v81, v80
	v_pk_add_f32 v[66:67], v[66:67], 1.0 op_sel_hi:[1,0]
	s_waitcnt vmcnt(7)
	v_mul_f32_e32 v72, 0xbfb8aa3b, v52
	v_mul_f32_e32 v73, 0xbfb8aa3b, v53
	v_fma_f32 v82, -v80, v81, 1.0
	v_fmac_f32_e32 v81, v82, v81
	v_div_scale_f32 v82, vcc, v41, v65, v41
	v_mul_f32_e32 v83, v82, v81
	v_fma_f32 v88, -v80, v83, v82
	v_fmac_f32_e32 v83, v88, v81
	v_fma_f32 v80, -v80, v83, v82
	v_div_fmas_f32 v80, v80, v81, v83
	v_div_fixup_f32 v65, v80, v65, v41
	v_div_scale_f32 v80, s[8:9], v64, v64, v40
	v_rcp_f32_e32 v81, v80
	v_exp_f32_e32 v72, v72
	v_exp_f32_e32 v73, v73
	v_mul_f32_e32 v74, 0xbfb8aa3b, v54
	v_fma_f32 v82, -v80, v81, 1.0
	v_fmac_f32_e32 v81, v82, v81
	v_div_scale_f32 v82, vcc, v40, v64, v40
	v_mul_f32_e32 v83, v82, v81
	v_fma_f32 v88, -v80, v83, v82
	v_fmac_f32_e32 v83, v88, v81
	v_fma_f32 v80, -v80, v83, v82
	v_div_fmas_f32 v80, v80, v81, v83
	v_div_fixup_f32 v64, v80, v64, v40
	v_div_scale_f32 v80, s[8:9], v67, v67, v43
	v_rcp_f32_e32 v81, v80
	v_pk_mul_f32 v[64:65], v[64:65], s[18:19] op_sel_hi:[1,0]
	v_mul_f32_e32 v75, 0xbfb8aa3b, v55
	v_exp_f32_e32 v74, v74
	v_fma_f32 v82, -v80, v81, 1.0
	v_fmac_f32_e32 v81, v82, v81
	v_div_scale_f32 v82, vcc, v43, v67, v43
	v_mul_f32_e32 v83, v82, v81
	v_fma_f32 v88, -v80, v83, v82
	v_fmac_f32_e32 v83, v88, v81
	v_fma_f32 v80, -v80, v83, v82
	v_div_fmas_f32 v80, v80, v81, v83
	v_div_fixup_f32 v67, v80, v67, v43
	v_div_scale_f32 v80, s[8:9], v66, v66, v42
	v_rcp_f32_e32 v81, v80
	v_exp_f32_e32 v75, v75
	v_fma_f32 v82, -v80, v81, 1.0
	v_fmac_f32_e32 v81, v82, v81
	v_div_scale_f32 v82, vcc, v42, v66, v42
	v_mul_f32_e32 v83, v82, v81
	v_fma_f32 v88, -v80, v83, v82
	v_fmac_f32_e32 v83, v88, v81
	v_fma_f32 v80, -v80, v83, v82
	v_div_fmas_f32 v80, v80, v81, v83
	v_div_fixup_f32 v66, v80, v66, v42
	v_pk_mul_f32 v[66:67], v[66:67], s[18:19] op_sel_hi:[1,0]
	ds_write_b128 v144, v[64:67]
	v_pk_add_f32 v[64:65], v[72:73], 1.0 op_sel_hi:[1,0]
	v_div_scale_f32 v66, s[8:9], v65, v65, 1.0
	v_rcp_f32_e32 v67, v66
	s_nop 0
	v_fma_f32 v72, -v66, v67, 1.0
	v_fmac_f32_e32 v67, v72, v67
	v_div_scale_f32 v72, vcc, 1.0, v65, 1.0
	v_mul_f32_e32 v73, v72, v67
	v_fma_f32 v80, -v66, v73, v72
	v_fmac_f32_e32 v73, v80, v67
	v_fma_f32 v66, -v66, v73, v72
	v_div_fmas_f32 v66, v66, v67, v73
	v_div_fixup_f32 v65, v66, v65, 1.0
	v_div_scale_f32 v66, s[8:9], v64, v64, 1.0
	v_rcp_f32_e32 v67, v66
	s_nop 0
	v_fma_f32 v72, -v66, v67, 1.0
	v_fmac_f32_e32 v67, v72, v67
	v_div_scale_f32 v72, vcc, 1.0, v64, 1.0
	v_mul_f32_e32 v73, v72, v67
	v_fma_f32 v80, -v66, v73, v72
	v_fmac_f32_e32 v73, v80, v67
	v_fma_f32 v66, -v66, v73, v72
	v_div_fmas_f32 v66, v66, v67, v73
	v_div_fixup_f32 v64, v66, v64, 1.0
	v_pk_add_f32 v[66:67], v[74:75], 1.0 op_sel_hi:[1,0]
	v_pk_fma_f32 v[64:65], v[110:111], v[64:65], v[104:105]
	v_div_scale_f32 v72, s[8:9], v67, v67, 1.0
	v_rcp_f32_e32 v73, v72
	s_nop 0
	v_fma_f32 v74, -v72, v73, 1.0
	v_fmac_f32_e32 v73, v74, v73
	v_div_scale_f32 v74, vcc, 1.0, v67, 1.0
	v_mul_f32_e32 v75, v74, v73
	v_fma_f32 v80, -v72, v75, v74
	v_fmac_f32_e32 v75, v80, v73
	v_fma_f32 v72, -v72, v75, v74
	v_div_fmas_f32 v72, v72, v73, v75
	v_div_fixup_f32 v67, v72, v67, 1.0
	v_div_scale_f32 v72, s[8:9], v66, v66, 1.0
	v_rcp_f32_e32 v73, v72
	s_nop 0
	v_fma_f32 v74, -v72, v73, 1.0
	v_fmac_f32_e32 v73, v74, v73
	v_div_scale_f32 v74, vcc, 1.0, v66, 1.0
	v_mul_f32_e32 v75, v74, v73
	v_fma_f32 v80, -v72, v75, v74
	v_fmac_f32_e32 v75, v80, v73
	v_fma_f32 v72, -v72, v75, v74
	v_div_fmas_f32 v72, v72, v73, v75
	v_div_fixup_f32 v66, v72, v66, 1.0
	v_pk_fma_f32 v[66:67], v[112:113], v[66:67], v[106:107]
	ds_write_b128 v144, v[64:67] offset:8192
	s_waitcnt vmcnt(6)
	ds_write_b32 v134, v132 offset:17408
	s_waitcnt lgkmcnt(0)
	s_barrier
	s_cbranch_scc1 .LBB0_1359
	v_add_u32_e32 v28, 0x60, v98
	v_mov_b64_e32 v[40:41], s[30:31]
	v_mad_i64_i32 v[28:29], s[8:9], v28, s25, v[40:41]
	s_lshl_b32 s94, s46, 2
	v_lshl_add_u64 v[42:43], v[28:29], 0, s[94:95]
	v_mov_b32_e32 v117, v140
	v_lshl_add_u64 v[28:29], v[42:43], 0, v[116:117]
	v_add_co_u32_e32 v30, vcc, 0x4000, v28
	s_lshl_b32 s8, s42, 2
	s_nop 0
	v_addc_co_u32_e32 v31, vcc, 0, v29, vcc
	s_mov_b32 s9, s95
	v_add_co_u32_e32 v32, vcc, 0x5000, v28
	v_lshl_add_u64 v[42:43], v[42:43], 0, s[8:9]
	v_mov_b32_e32 v115, v140
	v_add_u32_e32 v52, 0x60, v96
	v_addc_co_u32_e32 v33, vcc, 0, v29, vcc
	v_lshl_add_u64 v[42:43], v[42:43], 0, v[114:115]
	v_mad_i64_i32 v[40:41], s[22:23], v52, s25, v[40:41]
	v_add_co_u32_e32 v42, vcc, s81, v42
	v_lshl_add_u64 v[52:53], v[40:41], 0, s[94:95]
	s_nop 0
	v_addc_co_u32_e32 v43, vcc, 0, v43, vcc
	v_lshl_add_u64 v[54:55], v[52:53], 0, v[116:117]
	v_add_co_u32_e32 v40, vcc, s80, v54
	v_lshl_add_u64 v[52:53], v[52:53], 0, s[8:9]
	s_nop 0
	v_addc_co_u32_e32 v41, vcc, 0, v55, vcc
	v_add_co_u32_e32 v54, vcc, 0x5000, v54
	v_lshl_add_u64 v[52:53], v[52:53], 0, v[114:115]
	s_nop 0
	v_addc_co_u32_e32 v55, vcc, 0, v55, vcc
	v_add_co_u32_e32 v64, vcc, 0x6000, v52
	global_load_dwordx4 v[28:31], v[30:31], off offset:32
	s_nop 0
	global_load_dwordx4 v[32:35], v[32:33], off offset:32
	s_nop 0
	global_load_dword v131, v[42:43], off offset:32
	s_nop 0
	global_load_dwordx4 v[40:43], v[40:41], off offset:32
	v_addc_co_u32_e32 v65, vcc, 0, v53, vcc
	global_load_dwordx4 v[52:55], v[54:55], off offset:32
	s_nop 0
	global_load_dword v132, v[64:65], off offset:32
.LBB0_1359:
	ds_read2st64_b32 v[64:65], v134 offset0:152 offset1:156
	v_add_u32_e32 v66, 16, v98
	v_ashrrev_i32_e32 v67, 31, v66
	v_lshlrev_b64 v[66:67], 12, v[66:67]
	v_lshl_add_u64 v[66:67], v[108:109], 0, v[66:67]
	s_waitcnt lgkmcnt(0)
	global_store_dword v[66:67], v64, off
	v_add_u32_e32 v66, 16, v96
	v_ashrrev_i32_e32 v67, 31, v66
	v_lshlrev_b64 v[66:67], 12, v[66:67]
	v_lshl_add_u64 v[66:67], v[108:109], 0, v[66:67]
	global_store_dword v[66:67], v65, off
	v_mov_b32_e32 v196, 0
	v_mov_b32_e32 v197, 0
	v_add_u32_e32 v194, 0x4000, v103
	v_add_u32_e32 v195, 0x4400, v103
	ds_read2_b32 v[118:119], v194 offset0:0 offset1:16
	ds_read_b128 v[72:75], v145 offset:8192
	ds_read_b128 v[76:79], v145 offset:8448
	ds_read_b128 v[64:67], v145
	ds_read_b128 v[68:71], v145 offset:256
	ds_read2_b32 v[120:121], v194 offset0:32 offset1:48
	ds_read_b128 v[88:91], v145 offset:8704
	ds_read_b128 v[92:95], v145 offset:8960
	ds_read_b128 v[80:83], v145 offset:512
	ds_read_b128 v[84:87], v145 offset:768
	s_waitcnt lgkmcnt(9)
	v_pk_add_f32 v[178:179], v[178:179], v[118:119] op_sel_hi:[1,0] neg_lo:[0,1] neg_hi:[0,1]
	v_pk_add_f32 v[186:187], v[186:187], v[118:119] op_sel:[0,1] op_sel_hi:[1,1] neg_lo:[0,1] neg_hi:[0,1]
	v_pk_add_f32 v[180:181], v[180:181], v[118:119] op_sel_hi:[1,0] neg_lo:[0,1] neg_hi:[0,1]
	v_pk_add_f32 v[188:189], v[188:189], v[118:119] op_sel:[0,1] op_sel_hi:[1,1] neg_lo:[0,1] neg_hi:[0,1]
	v_pk_add_f32 v[182:183], v[182:183], v[118:119] op_sel_hi:[1,0] neg_lo:[0,1] neg_hi:[0,1]
	v_pk_add_f32 v[190:191], v[190:191], v[118:119] op_sel:[0,1] op_sel_hi:[1,1] neg_lo:[0,1] neg_hi:[0,1]
	v_pk_add_f32 v[184:185], v[184:185], v[118:119] op_sel_hi:[1,0] neg_lo:[0,1] neg_hi:[0,1]
	v_pk_add_f32 v[192:193], v[192:193], v[118:119] op_sel:[0,1] op_sel_hi:[1,1] neg_lo:[0,1] neg_hi:[0,1]
	s_waitcnt lgkmcnt(8)
	v_pk_fma_f32 v[178:179], v[72:73], v[178:179], v[118:119] op_sel_hi:[1,1,0]
	v_pk_fma_f32 v[186:187], v[72:73], v[186:187], v[118:119] op_sel:[0,0,1] op_sel_hi:[1,1,1]
	v_pk_fma_f32 v[180:181], v[74:75], v[180:181], v[118:119] op_sel_hi:[1,1,0]
	v_pk_fma_f32 v[188:189], v[74:75], v[188:189], v[118:119] op_sel:[0,0,1] op_sel_hi:[1,1,1]
	s_waitcnt lgkmcnt(7)
	v_pk_fma_f32 v[182:183], v[76:77], v[182:183], v[118:119] op_sel_hi:[1,1,0]
	v_pk_fma_f32 v[190:191], v[76:77], v[190:191], v[118:119] op_sel:[0,0,1] op_sel_hi:[1,1,1]
	v_pk_fma_f32 v[184:185], v[78:79], v[184:185], v[118:119] op_sel_hi:[1,1,0]
	v_pk_fma_f32 v[192:193], v[78:79], v[192:193], v[118:119] op_sel:[0,0,1] op_sel_hi:[1,1,1]
	ds_read2_b32 v[118:119], v194 offset0:64 offset1:80
	ds_read_b128 v[72:75], v145 offset:9216
	ds_read_b128 v[76:79], v145 offset:9472
	s_waitcnt lgkmcnt(9)
	v_pk_fma_f32 v[146:147], v[64:65], v[178:179], v[196:197]
	v_pk_fma_f32 v[150:151], v[64:65], v[186:187], v[196:197]
	v_pk_fma_f32 v[148:149], v[66:67], v[180:181], v[196:197]
	v_pk_fma_f32 v[152:153], v[66:67], v[188:189], v[196:197]
	ds_read_b128 v[64:67], v145 offset:1024
	s_waitcnt lgkmcnt(9)
	v_pk_fma_f32 v[146:147], v[68:69], v[182:183], v[146:147]
	v_pk_fma_f32 v[150:151], v[68:69], v[190:191], v[150:151]
	v_pk_fma_f32 v[148:149], v[70:71], v[184:185], v[148:149]
	v_pk_fma_f32 v[152:153], v[70:71], v[192:193], v[152:153]
	ds_read_b128 v[68:71], v145 offset:1280
	v_add_f32_e32 v146, v146, v147
	v_add_f32_e32 v148, v148, v149
	v_add_f32_e32 v150, v150, v151
	v_add_f32_e32 v152, v152, v153
	v_add_f32_e32 v154, v146, v148
	v_add_f32_e32 v155, v150, v152
	s_waitcnt lgkmcnt(9)
	v_pk_add_f32 v[178:179], v[178:179], v[120:121] op_sel_hi:[1,0] neg_lo:[0,1] neg_hi:[0,1]
	v_add_f32_dpp v154, v154, v154 row_ror:8 row_mask:0xf bank_mask:0xf bound_ctrl:1
	v_pk_add_f32 v[186:187], v[186:187], v[120:121] op_sel:[0,1] op_sel_hi:[1,1] neg_lo:[0,1] neg_hi:[0,1]
	v_add_f32_dpp v155, v155, v155 row_ror:8 row_mask:0xf bank_mask:0xf bound_ctrl:1
	v_pk_add_f32 v[180:181], v[180:181], v[120:121] op_sel_hi:[1,0] neg_lo:[0,1] neg_hi:[0,1]
	v_add_f32_dpp v154, v154, v154 row_ror:4 row_mask:0xf bank_mask:0xf bound_ctrl:1
	v_pk_add_f32 v[188:189], v[188:189], v[120:121] op_sel:[0,1] op_sel_hi:[1,1] neg_lo:[0,1] neg_hi:[0,1]
	v_add_f32_dpp v155, v155, v155 row_ror:4 row_mask:0xf bank_mask:0xf bound_ctrl:1
	v_pk_add_f32 v[182:183], v[182:183], v[120:121] op_sel_hi:[1,0] neg_lo:[0,1] neg_hi:[0,1]
	v_add_f32_dpp v154, v154, v154 row_ror:2 row_mask:0xf bank_mask:0xf bound_ctrl:1
	v_pk_add_f32 v[190:191], v[190:191], v[120:121] op_sel:[0,1] op_sel_hi:[1,1] neg_lo:[0,1] neg_hi:[0,1]
	v_add_f32_dpp v155, v155, v155 row_ror:2 row_mask:0xf bank_mask:0xf bound_ctrl:1
	v_pk_add_f32 v[184:185], v[184:185], v[120:121] op_sel_hi:[1,0] neg_lo:[0,1] neg_hi:[0,1]
	v_add_f32_dpp v154, v154, v154 row_ror:1 row_mask:0xf bank_mask:0xf bound_ctrl:1
	v_pk_add_f32 v[192:193], v[192:193], v[120:121] op_sel:[0,1] op_sel_hi:[1,1] neg_lo:[0,1] neg_hi:[0,1]
	v_add_f32_dpp v155, v155, v155 row_ror:1 row_mask:0xf bank_mask:0xf bound_ctrl:1
	s_waitcnt lgkmcnt(8)
	v_pk_fma_f32 v[178:179], v[88:89], v[178:179], v[120:121] op_sel_hi:[1,1,0]
	s_and_saveexec_b64 s[8:9], s[38:39]
	ds_write_b32 v103, v154 offset:36864
	ds_write_b32 v103, v155 offset:36928
	s_mov_b64 exec, s[8:9]
	v_pk_fma_f32 v[186:187], v[88:89], v[186:187], v[120:121] op_sel:[0,0,1] op_sel_hi:[1,1,1]
	v_pk_fma_f32 v[180:181], v[90:91], v[180:181], v[120:121] op_sel_hi:[1,1,0]
	v_pk_fma_f32 v[188:189], v[90:91], v[188:189], v[120:121] op_sel:[0,0,1] op_sel_hi:[1,1,1]
	s_waitcnt lgkmcnt(9)
	v_pk_fma_f32 v[182:183], v[92:93], v[182:183], v[120:121] op_sel_hi:[1,1,0]
	v_pk_fma_f32 v[190:191], v[92:93], v[190:191], v[120:121] op_sel:[0,0,1] op_sel_hi:[1,1,1]
	v_pk_fma_f32 v[184:185], v[94:95], v[184:185], v[120:121] op_sel_hi:[1,1,0]
	v_pk_fma_f32 v[192:193], v[94:95], v[192:193], v[120:121] op_sel:[0,0,1] op_sel_hi:[1,1,1]
	ds_read2_b32 v[120:121], v194 offset0:96 offset1:112
	ds_read_b128 v[88:91], v145 offset:9728
	ds_read_b128 v[92:95], v145 offset:9984
	s_waitcnt lgkmcnt(11)
	v_pk_fma_f32 v[146:147], v[80:81], v[178:179], v[196:197]
	v_pk_fma_f32 v[150:151], v[80:81], v[186:187], v[196:197]
	v_pk_fma_f32 v[148:149], v[82:83], v[180:181], v[196:197]
	v_pk_fma_f32 v[152:153], v[82:83], v[188:189], v[196:197]
	ds_read_b128 v[80:83], v145 offset:1536
	s_waitcnt lgkmcnt(11)
	v_pk_fma_f32 v[146:147], v[84:85], v[182:183], v[146:147]
	v_pk_fma_f32 v[150:151], v[84:85], v[190:191], v[150:151]
	v_pk_fma_f32 v[148:149], v[86:87], v[184:185], v[148:149]
	v_pk_fma_f32 v[152:153], v[86:87], v[192:193], v[152:153]
	ds_read_b128 v[84:87], v145 offset:1792
	v_add_f32_e32 v146, v146, v147
	v_add_f32_e32 v148, v148, v149
	v_add_f32_e32 v150, v150, v151
	v_add_f32_e32 v152, v152, v153
	v_add_f32_e32 v156, v146, v148
	v_add_f32_e32 v157, v150, v152
	s_waitcnt lgkmcnt(11)
	v_pk_add_f32 v[178:179], v[178:179], v[118:119] op_sel_hi:[1,0] neg_lo:[0,1] neg_hi:[0,1]
	v_add_f32_dpp v156, v156, v156 row_ror:8 row_mask:0xf bank_mask:0xf bound_ctrl:1
	v_pk_add_f32 v[186:187], v[186:187], v[118:119] op_sel:[0,1] op_sel_hi:[1,1] neg_lo:[0,1] neg_hi:[0,1]
	v_add_f32_dpp v157, v157, v157 row_ror:8 row_mask:0xf bank_mask:0xf bound_ctrl:1
	v_pk_add_f32 v[180:181], v[180:181], v[118:119] op_sel_hi:[1,0] neg_lo:[0,1] neg_hi:[0,1]
	v_add_f32_dpp v156, v156, v156 row_ror:4 row_mask:0xf bank_mask:0xf bound_ctrl:1
	v_pk_add_f32 v[188:189], v[188:189], v[118:119] op_sel:[0,1] op_sel_hi:[1,1] neg_lo:[0,1] neg_hi:[0,1]
	v_add_f32_dpp v157, v157, v157 row_ror:4 row_mask:0xf bank_mask:0xf bound_ctrl:1
	v_pk_add_f32 v[182:183], v[182:183], v[118:119] op_sel_hi:[1,0] neg_lo:[0,1] neg_hi:[0,1]
	v_add_f32_dpp v156, v156, v156 row_ror:2 row_mask:0xf bank_mask:0xf bound_ctrl:1
	v_pk_add_f32 v[190:191], v[190:191], v[118:119] op_sel:[0,1] op_sel_hi:[1,1] neg_lo:[0,1] neg_hi:[0,1]
	v_add_f32_dpp v157, v157, v157 row_ror:2 row_mask:0xf bank_mask:0xf bound_ctrl:1
	v_pk_add_f32 v[184:185], v[184:185], v[118:119] op_sel_hi:[1,0] neg_lo:[0,1] neg_hi:[0,1]
	v_add_f32_dpp v156, v156, v156 row_ror:1 row_mask:0xf bank_mask:0xf bound_ctrl:1
	v_pk_add_f32 v[192:193], v[192:193], v[118:119] op_sel:[0,1] op_sel_hi:[1,1] neg_lo:[0,1] neg_hi:[0,1]
	v_add_f32_dpp v157, v157, v157 row_ror:1 row_mask:0xf bank_mask:0xf bound_ctrl:1
	s_waitcnt lgkmcnt(10)
	v_pk_fma_f32 v[178:179], v[72:73], v[178:179], v[118:119] op_sel_hi:[1,1,0]
	s_and_saveexec_b64 s[8:9], s[38:39]
	ds_write_b32 v103, v156 offset:36992
	ds_write_b32 v103, v157 offset:37056
	s_mov_b64 exec, s[8:9]
	v_pk_fma_f32 v[186:187], v[72:73], v[186:187], v[118:119] op_sel:[0,0,1] op_sel_hi:[1,1,1]
	v_pk_fma_f32 v[180:181], v[74:75], v[180:181], v[118:119] op_sel_hi:[1,1,0]
	v_pk_fma_f32 v[188:189], v[74:75], v[188:189], v[118:119] op_sel:[0,0,1] op_sel_hi:[1,1,1]
	s_waitcnt lgkmcnt(11)
	v_pk_fma_f32 v[182:183], v[76:77], v[182:183], v[118:119] op_sel_hi:[1,1,0]
	v_pk_fma_f32 v[190:191], v[76:77], v[190:191], v[118:119] op_sel:[0,0,1] op_sel_hi:[1,1,1]
	v_pk_fma_f32 v[184:185], v[78:79], v[184:185], v[118:119] op_sel_hi:[1,1,0]
	v_pk_fma_f32 v[192:193], v[78:79], v[192:193], v[118:119] op_sel:[0,0,1] op_sel_hi:[1,1,1]
	ds_read2_b32 v[118:119], v194 offset0:128 offset1:144
	ds_read_b128 v[72:75], v145 offset:10240
	ds_read_b128 v[76:79], v145 offset:10496
	s_waitcnt lgkmcnt(13)
	v_pk_fma_f32 v[146:147], v[64:65], v[178:179], v[196:197]
	v_pk_fma_f32 v[150:151], v[64:65], v[186:187], v[196:197]
	v_pk_fma_f32 v[148:149], v[66:67], v[180:181], v[196:197]
	v_pk_fma_f32 v[152:153], v[66:67], v[188:189], v[196:197]
	ds_read_b128 v[64:67], v145 offset:2048
	s_waitcnt lgkmcnt(13)
	v_pk_fma_f32 v[146:147], v[68:69], v[182:183], v[146:147]
	v_pk_fma_f32 v[150:151], v[68:69], v[190:191], v[150:151]
	v_pk_fma_f32 v[148:149], v[70:71], v[184:185], v[148:149]
	v_pk_fma_f32 v[152:153], v[70:71], v[192:193], v[152:153]
	ds_read_b128 v[68:71], v145 offset:2304
	v_add_f32_e32 v146, v146, v147
	v_add_f32_e32 v148, v148, v149
	v_add_f32_e32 v150, v150, v151
	v_add_f32_e32 v152, v152, v153
	v_add_f32_e32 v154, v146, v148
	v_add_f32_e32 v155, v150, v152
	s_waitcnt lgkmcnt(11)
	v_pk_add_f32 v[178:179], v[178:179], v[120:121] op_sel_hi:[1,0] neg_lo:[0,1] neg_hi:[0,1]
	v_add_f32_dpp v154, v154, v154 row_ror:8 row_mask:0xf bank_mask:0xf bound_ctrl:1
	v_pk_add_f32 v[186:187], v[186:187], v[120:121] op_sel:[0,1] op_sel_hi:[1,1] neg_lo:[0,1] neg_hi:[0,1]
	v_add_f32_dpp v155, v155, v155 row_ror:8 row_mask:0xf bank_mask:0xf bound_ctrl:1
	v_pk_add_f32 v[180:181], v[180:181], v[120:121] op_sel_hi:[1,0] neg_lo:[0,1] neg_hi:[0,1]
	v_add_f32_dpp v154, v154, v154 row_ror:4 row_mask:0xf bank_mask:0xf bound_ctrl:1
	v_pk_add_f32 v[188:189], v[188:189], v[120:121] op_sel:[0,1] op_sel_hi:[1,1] neg_lo:[0,1] neg_hi:[0,1]
	v_add_f32_dpp v155, v155, v155 row_ror:4 row_mask:0xf bank_mask:0xf bound_ctrl:1
	v_pk_add_f32 v[182:183], v[182:183], v[120:121] op_sel_hi:[1,0] neg_lo:[0,1] neg_hi:[0,1]
	v_add_f32_dpp v154, v154, v154 row_ror:2 row_mask:0xf bank_mask:0xf bound_ctrl:1
	v_pk_add_f32 v[190:191], v[190:191], v[120:121] op_sel:[0,1] op_sel_hi:[1,1] neg_lo:[0,1] neg_hi:[0,1]
	v_add_f32_dpp v155, v155, v155 row_ror:2 row_mask:0xf bank_mask:0xf bound_ctrl:1
	v_pk_add_f32 v[184:185], v[184:185], v[120:121] op_sel_hi:[1,0] neg_lo:[0,1] neg_hi:[0,1]
	v_add_f32_dpp v154, v154, v154 row_ror:1 row_mask:0xf bank_mask:0xf bound_ctrl:1
	v_pk_add_f32 v[192:193], v[192:193], v[120:121] op_sel:[0,1] op_sel_hi:[1,1] neg_lo:[0,1] neg_hi:[0,1]
	v_add_f32_dpp v155, v155, v155 row_ror:1 row_mask:0xf bank_mask:0xf bound_ctrl:1
	s_waitcnt lgkmcnt(10)
	v_pk_fma_f32 v[178:179], v[88:89], v[178:179], v[120:121] op_sel_hi:[1,1,0]
	s_and_saveexec_b64 s[8:9], s[38:39]
	ds_write_b32 v103, v154 offset:37120
	ds_write_b32 v103, v155 offset:37184
	s_mov_b64 exec, s[8:9]
	v_pk_fma_f32 v[186:187], v[88:89], v[186:187], v[120:121] op_sel:[0,0,1] op_sel_hi:[1,1,1]
	v_pk_fma_f32 v[180:181], v[90:91], v[180:181], v[120:121] op_sel_hi:[1,1,0]
	v_pk_fma_f32 v[188:189], v[90:91], v[188:189], v[120:121] op_sel:[0,0,1] op_sel_hi:[1,1,1]
	s_waitcnt lgkmcnt(11)
	v_pk_fma_f32 v[182:183], v[92:93], v[182:183], v[120:121] op_sel_hi:[1,1,0]
	v_pk_fma_f32 v[190:191], v[92:93], v[190:191], v[120:121] op_sel:[0,0,1] op_sel_hi:[1,1,1]
	v_pk_fma_f32 v[184:185], v[94:95], v[184:185], v[120:121] op_sel_hi:[1,1,0]
	v_pk_fma_f32 v[192:193], v[94:95], v[192:193], v[120:121] op_sel:[0,0,1] op_sel_hi:[1,1,1]
	ds_read2_b32 v[120:121], v194 offset0:160 offset1:176
	ds_read_b128 v[88:91], v145 offset:10752
	ds_read_b128 v[92:95], v145 offset:11008
	s_waitcnt lgkmcnt(13)
	v_pk_fma_f32 v[146:147], v[80:81], v[178:179], v[196:197]
	v_pk_fma_f32 v[150:151], v[80:81], v[186:187], v[196:197]
	v_pk_fma_f32 v[148:149], v[82:83], v[180:181], v[196:197]
	v_pk_fma_f32 v[152:153], v[82:83], v[188:189], v[196:197]
	ds_read_b128 v[80:83], v145 offset:2560
	s_waitcnt lgkmcnt(13)
	v_pk_fma_f32 v[146:147], v[84:85], v[182:183], v[146:147]
	v_pk_fma_f32 v[150:151], v[84:85], v[190:191], v[150:151]
	v_pk_fma_f32 v[148:149], v[86:87], v[184:185], v[148:149]
	v_pk_fma_f32 v[152:153], v[86:87], v[192:193], v[152:153]
	ds_read_b128 v[84:87], v145 offset:2816
	v_add_f32_e32 v146, v146, v147
	v_add_f32_e32 v148, v148, v149
	v_add_f32_e32 v150, v150, v151
	v_add_f32_e32 v152, v152, v153
	v_add_f32_e32 v156, v146, v148
	v_add_f32_e32 v157, v150, v152
	s_waitcnt lgkmcnt(11)
	v_pk_add_f32 v[178:179], v[178:179], v[118:119] op_sel_hi:[1,0] neg_lo:[0,1] neg_hi:[0,1]
	v_add_f32_dpp v156, v156, v156 row_ror:8 row_mask:0xf bank_mask:0xf bound_ctrl:1
	v_pk_add_f32 v[186:187], v[186:187], v[118:119] op_sel:[0,1] op_sel_hi:[1,1] neg_lo:[0,1] neg_hi:[0,1]
	v_add_f32_dpp v157, v157, v157 row_ror:8 row_mask:0xf bank_mask:0xf bound_ctrl:1
	v_pk_add_f32 v[180:181], v[180:181], v[118:119] op_sel_hi:[1,0] neg_lo:[0,1] neg_hi:[0,1]
	v_add_f32_dpp v156, v156, v156 row_ror:4 row_mask:0xf bank_mask:0xf bound_ctrl:1
	v_pk_add_f32 v[188:189], v[188:189], v[118:119] op_sel:[0,1] op_sel_hi:[1,1] neg_lo:[0,1] neg_hi:[0,1]
	v_add_f32_dpp v157, v157, v157 row_ror:4 row_mask:0xf bank_mask:0xf bound_ctrl:1
	v_pk_add_f32 v[182:183], v[182:183], v[118:119] op_sel_hi:[1,0] neg_lo:[0,1] neg_hi:[0,1]
	v_add_f32_dpp v156, v156, v156 row_ror:2 row_mask:0xf bank_mask:0xf bound_ctrl:1
	v_pk_add_f32 v[190:191], v[190:191], v[118:119] op_sel:[0,1] op_sel_hi:[1,1] neg_lo:[0,1] neg_hi:[0,1]
	v_add_f32_dpp v157, v157, v157 row_ror:2 row_mask:0xf bank_mask:0xf bound_ctrl:1
	v_pk_add_f32 v[184:185], v[184:185], v[118:119] op_sel_hi:[1,0] neg_lo:[0,1] neg_hi:[0,1]
	v_add_f32_dpp v156, v156, v156 row_ror:1 row_mask:0xf bank_mask:0xf bound_ctrl:1
	v_pk_add_f32 v[192:193], v[192:193], v[118:119] op_sel:[0,1] op_sel_hi:[1,1] neg_lo:[0,1] neg_hi:[0,1]
	v_add_f32_dpp v157, v157, v157 row_ror:1 row_mask:0xf bank_mask:0xf bound_ctrl:1
	s_waitcnt lgkmcnt(10)
	v_pk_fma_f32 v[178:179], v[72:73], v[178:179], v[118:119] op_sel_hi:[1,1,0]
	s_and_saveexec_b64 s[8:9], s[38:39]
	ds_write_b32 v103, v156 offset:37248
	ds_write_b32 v103, v157 offset:37312
	s_mov_b64 exec, s[8:9]
	v_pk_fma_f32 v[186:187], v[72:73], v[186:187], v[118:119] op_sel:[0,0,1] op_sel_hi:[1,1,1]
	v_pk_fma_f32 v[180:181], v[74:75], v[180:181], v[118:119] op_sel_hi:[1,1,0]
	v_pk_fma_f32 v[188:189], v[74:75], v[188:189], v[118:119] op_sel:[0,0,1] op_sel_hi:[1,1,1]
	s_waitcnt lgkmcnt(11)
	v_pk_fma_f32 v[182:183], v[76:77], v[182:183], v[118:119] op_sel_hi:[1,1,0]
	v_pk_fma_f32 v[190:191], v[76:77], v[190:191], v[118:119] op_sel:[0,0,1] op_sel_hi:[1,1,1]
	v_pk_fma_f32 v[184:185], v[78:79], v[184:185], v[118:119] op_sel_hi:[1,1,0]
	v_pk_fma_f32 v[192:193], v[78:79], v[192:193], v[118:119] op_sel:[0,0,1] op_sel_hi:[1,1,1]
	ds_read2_b32 v[118:119], v194 offset0:192 offset1:208
	ds_read_b128 v[72:75], v145 offset:11264
	ds_read_b128 v[76:79], v145 offset:11520
	s_waitcnt lgkmcnt(13)
	v_pk_fma_f32 v[146:147], v[64:65], v[178:179], v[196:197]
	v_pk_fma_f32 v[150:151], v[64:65], v[186:187], v[196:197]
	v_pk_fma_f32 v[148:149], v[66:67], v[180:181], v[196:197]
	v_pk_fma_f32 v[152:153], v[66:67], v[188:189], v[196:197]
	ds_read_b128 v[64:67], v145 offset:3072
	s_waitcnt lgkmcnt(13)
	v_pk_fma_f32 v[146:147], v[68:69], v[182:183], v[146:147]
	v_pk_fma_f32 v[150:151], v[68:69], v[190:191], v[150:151]
	v_pk_fma_f32 v[148:149], v[70:71], v[184:185], v[148:149]
	v_pk_fma_f32 v[152:153], v[70:71], v[192:193], v[152:153]
	ds_read_b128 v[68:71], v145 offset:3328
	v_add_f32_e32 v146, v146, v147
	v_add_f32_e32 v148, v148, v149
	v_add_f32_e32 v150, v150, v151
	v_add_f32_e32 v152, v152, v153
	v_add_f32_e32 v154, v146, v148
	v_add_f32_e32 v155, v150, v152
	s_waitcnt lgkmcnt(11)
	v_pk_add_f32 v[178:179], v[178:179], v[120:121] op_sel_hi:[1,0] neg_lo:[0,1] neg_hi:[0,1]
	v_add_f32_dpp v154, v154, v154 row_ror:8 row_mask:0xf bank_mask:0xf bound_ctrl:1
	v_pk_add_f32 v[186:187], v[186:187], v[120:121] op_sel:[0,1] op_sel_hi:[1,1] neg_lo:[0,1] neg_hi:[0,1]
	v_add_f32_dpp v155, v155, v155 row_ror:8 row_mask:0xf bank_mask:0xf bound_ctrl:1
	v_pk_add_f32 v[180:181], v[180:181], v[120:121] op_sel_hi:[1,0] neg_lo:[0,1] neg_hi:[0,1]
	v_add_f32_dpp v154, v154, v154 row_ror:4 row_mask:0xf bank_mask:0xf bound_ctrl:1
	v_pk_add_f32 v[188:189], v[188:189], v[120:121] op_sel:[0,1] op_sel_hi:[1,1] neg_lo:[0,1] neg_hi:[0,1]
	v_add_f32_dpp v155, v155, v155 row_ror:4 row_mask:0xf bank_mask:0xf bound_ctrl:1
	v_pk_add_f32 v[182:183], v[182:183], v[120:121] op_sel_hi:[1,0] neg_lo:[0,1] neg_hi:[0,1]
	v_add_f32_dpp v154, v154, v154 row_ror:2 row_mask:0xf bank_mask:0xf bound_ctrl:1
	v_pk_add_f32 v[190:191], v[190:191], v[120:121] op_sel:[0,1] op_sel_hi:[1,1] neg_lo:[0,1] neg_hi:[0,1]
	v_add_f32_dpp v155, v155, v155 row_ror:2 row_mask:0xf bank_mask:0xf bound_ctrl:1
	v_pk_add_f32 v[184:185], v[184:185], v[120:121] op_sel_hi:[1,0] neg_lo:[0,1] neg_hi:[0,1]
	v_add_f32_dpp v154, v154, v154 row_ror:1 row_mask:0xf bank_mask:0xf bound_ctrl:1
	v_pk_add_f32 v[192:193], v[192:193], v[120:121] op_sel:[0,1] op_sel_hi:[1,1] neg_lo:[0,1] neg_hi:[0,1]
	v_add_f32_dpp v155, v155, v155 row_ror:1 row_mask:0xf bank_mask:0xf bound_ctrl:1
	s_waitcnt lgkmcnt(10)
	v_pk_fma_f32 v[178:179], v[88:89], v[178:179], v[120:121] op_sel_hi:[1,1,0]
	s_and_saveexec_b64 s[8:9], s[38:39]
	ds_write_b32 v103, v154 offset:37376
	ds_write_b32 v103, v155 offset:37440
	s_mov_b64 exec, s[8:9]
	v_pk_fma_f32 v[186:187], v[88:89], v[186:187], v[120:121] op_sel:[0,0,1] op_sel_hi:[1,1,1]
	v_pk_fma_f32 v[180:181], v[90:91], v[180:181], v[120:121] op_sel_hi:[1,1,0]
	v_pk_fma_f32 v[188:189], v[90:91], v[188:189], v[120:121] op_sel:[0,0,1] op_sel_hi:[1,1,1]
	s_waitcnt lgkmcnt(11)
	v_pk_fma_f32 v[182:183], v[92:93], v[182:183], v[120:121] op_sel_hi:[1,1,0]
	v_pk_fma_f32 v[190:191], v[92:93], v[190:191], v[120:121] op_sel:[0,0,1] op_sel_hi:[1,1,1]
	v_pk_fma_f32 v[184:185], v[94:95], v[184:185], v[120:121] op_sel_hi:[1,1,0]
	v_pk_fma_f32 v[192:193], v[94:95], v[192:193], v[120:121] op_sel:[0,0,1] op_sel_hi:[1,1,1]
	ds_read2_b32 v[120:121], v194 offset0:224 offset1:240
	ds_read_b128 v[88:91], v145 offset:11776
	ds_read_b128 v[92:95], v145 offset:12032
	s_waitcnt lgkmcnt(13)
	v_pk_fma_f32 v[146:147], v[80:81], v[178:179], v[196:197]
	v_pk_fma_f32 v[150:151], v[80:81], v[186:187], v[196:197]
	v_pk_fma_f32 v[148:149], v[82:83], v[180:181], v[196:197]
	v_pk_fma_f32 v[152:153], v[82:83], v[188:189], v[196:197]
	ds_read_b128 v[80:83], v145 offset:3584
	s_waitcnt lgkmcnt(13)
	v_pk_fma_f32 v[146:147], v[84:85], v[182:183], v[146:147]
	v_pk_fma_f32 v[150:151], v[84:85], v[190:191], v[150:151]
	v_pk_fma_f32 v[148:149], v[86:87], v[184:185], v[148:149]
	v_pk_fma_f32 v[152:153], v[86:87], v[192:193], v[152:153]
	ds_read_b128 v[84:87], v145 offset:3840
	v_add_f32_e32 v146, v146, v147
	v_add_f32_e32 v148, v148, v149
	v_add_f32_e32 v150, v150, v151
	v_add_f32_e32 v152, v152, v153
	v_add_f32_e32 v156, v146, v148
	v_add_f32_e32 v157, v150, v152
	s_waitcnt lgkmcnt(11)
	v_pk_add_f32 v[178:179], v[178:179], v[118:119] op_sel_hi:[1,0] neg_lo:[0,1] neg_hi:[0,1]
	v_add_f32_dpp v156, v156, v156 row_ror:8 row_mask:0xf bank_mask:0xf bound_ctrl:1
	v_pk_add_f32 v[186:187], v[186:187], v[118:119] op_sel:[0,1] op_sel_hi:[1,1] neg_lo:[0,1] neg_hi:[0,1]
	v_add_f32_dpp v157, v157, v157 row_ror:8 row_mask:0xf bank_mask:0xf bound_ctrl:1
	v_pk_add_f32 v[180:181], v[180:181], v[118:119] op_sel_hi:[1,0] neg_lo:[0,1] neg_hi:[0,1]
	v_add_f32_dpp v156, v156, v156 row_ror:4 row_mask:0xf bank_mask:0xf bound_ctrl:1
	v_pk_add_f32 v[188:189], v[188:189], v[118:119] op_sel:[0,1] op_sel_hi:[1,1] neg_lo:[0,1] neg_hi:[0,1]
	v_add_f32_dpp v157, v157, v157 row_ror:4 row_mask:0xf bank_mask:0xf bound_ctrl:1
	v_pk_add_f32 v[182:183], v[182:183], v[118:119] op_sel_hi:[1,0] neg_lo:[0,1] neg_hi:[0,1]
	v_add_f32_dpp v156, v156, v156 row_ror:2 row_mask:0xf bank_mask:0xf bound_ctrl:1
	v_pk_add_f32 v[190:191], v[190:191], v[118:119] op_sel:[0,1] op_sel_hi:[1,1] neg_lo:[0,1] neg_hi:[0,1]
	v_add_f32_dpp v157, v157, v157 row_ror:2 row_mask:0xf bank_mask:0xf bound_ctrl:1
	v_pk_add_f32 v[184:185], v[184:185], v[118:119] op_sel_hi:[1,0] neg_lo:[0,1] neg_hi:[0,1]
	v_add_f32_dpp v156, v156, v156 row_ror:1 row_mask:0xf bank_mask:0xf bound_ctrl:1
	v_pk_add_f32 v[192:193], v[192:193], v[118:119] op_sel:[0,1] op_sel_hi:[1,1] neg_lo:[0,1] neg_hi:[0,1]
	v_add_f32_dpp v157, v157, v157 row_ror:1 row_mask:0xf bank_mask:0xf bound_ctrl:1
	s_waitcnt lgkmcnt(10)
	v_pk_fma_f32 v[178:179], v[72:73], v[178:179], v[118:119] op_sel_hi:[1,1,0]
	s_and_saveexec_b64 s[8:9], s[38:39]
	ds_write_b32 v103, v156 offset:37504
	ds_write_b32 v103, v157 offset:37568
	s_mov_b64 exec, s[8:9]
	v_pk_fma_f32 v[186:187], v[72:73], v[186:187], v[118:119] op_sel:[0,0,1] op_sel_hi:[1,1,1]
	v_pk_fma_f32 v[180:181], v[74:75], v[180:181], v[118:119] op_sel_hi:[1,1,0]
	v_pk_fma_f32 v[188:189], v[74:75], v[188:189], v[118:119] op_sel:[0,0,1] op_sel_hi:[1,1,1]
	s_waitcnt lgkmcnt(11)
	v_pk_fma_f32 v[182:183], v[76:77], v[182:183], v[118:119] op_sel_hi:[1,1,0]
	v_pk_fma_f32 v[190:191], v[76:77], v[190:191], v[118:119] op_sel:[0,0,1] op_sel_hi:[1,1,1]
	v_pk_fma_f32 v[184:185], v[78:79], v[184:185], v[118:119] op_sel_hi:[1,1,0]
	v_pk_fma_f32 v[192:193], v[78:79], v[192:193], v[118:119] op_sel:[0,0,1] op_sel_hi:[1,1,1]
	ds_read2_b32 v[118:119], v195 offset0:0 offset1:16
	ds_read_b128 v[72:75], v145 offset:12288
	ds_read_b128 v[76:79], v145 offset:12544
	s_waitcnt lgkmcnt(13)
	v_pk_fma_f32 v[146:147], v[64:65], v[178:179], v[196:197]
	v_pk_fma_f32 v[150:151], v[64:65], v[186:187], v[196:197]
	v_pk_fma_f32 v[148:149], v[66:67], v[180:181], v[196:197]
	v_pk_fma_f32 v[152:153], v[66:67], v[188:189], v[196:197]
	ds_read_b128 v[64:67], v145 offset:4096
	s_waitcnt lgkmcnt(13)
	v_pk_fma_f32 v[146:147], v[68:69], v[182:183], v[146:147]
	v_pk_fma_f32 v[150:151], v[68:69], v[190:191], v[150:151]
	v_pk_fma_f32 v[148:149], v[70:71], v[184:185], v[148:149]
	v_pk_fma_f32 v[152:153], v[70:71], v[192:193], v[152:153]
	ds_read_b128 v[68:71], v145 offset:4352
	v_add_f32_e32 v146, v146, v147
	v_add_f32_e32 v148, v148, v149
	v_add_f32_e32 v150, v150, v151
	v_add_f32_e32 v152, v152, v153
	v_add_f32_e32 v154, v146, v148
	v_add_f32_e32 v155, v150, v152
	s_waitcnt lgkmcnt(11)
	v_pk_add_f32 v[178:179], v[178:179], v[120:121] op_sel_hi:[1,0] neg_lo:[0,1] neg_hi:[0,1]
	v_add_f32_dpp v154, v154, v154 row_ror:8 row_mask:0xf bank_mask:0xf bound_ctrl:1
	v_pk_add_f32 v[186:187], v[186:187], v[120:121] op_sel:[0,1] op_sel_hi:[1,1] neg_lo:[0,1] neg_hi:[0,1]
	v_add_f32_dpp v155, v155, v155 row_ror:8 row_mask:0xf bank_mask:0xf bound_ctrl:1
	v_pk_add_f32 v[180:181], v[180:181], v[120:121] op_sel_hi:[1,0] neg_lo:[0,1] neg_hi:[0,1]
	v_add_f32_dpp v154, v154, v154 row_ror:4 row_mask:0xf bank_mask:0xf bound_ctrl:1
	v_pk_add_f32 v[188:189], v[188:189], v[120:121] op_sel:[0,1] op_sel_hi:[1,1] neg_lo:[0,1] neg_hi:[0,1]
	v_add_f32_dpp v155, v155, v155 row_ror:4 row_mask:0xf bank_mask:0xf bound_ctrl:1
	v_pk_add_f32 v[182:183], v[182:183], v[120:121] op_sel_hi:[1,0] neg_lo:[0,1] neg_hi:[0,1]
	v_add_f32_dpp v154, v154, v154 row_ror:2 row_mask:0xf bank_mask:0xf bound_ctrl:1
	v_pk_add_f32 v[190:191], v[190:191], v[120:121] op_sel:[0,1] op_sel_hi:[1,1] neg_lo:[0,1] neg_hi:[0,1]
	v_add_f32_dpp v155, v155, v155 row_ror:2 row_mask:0xf bank_mask:0xf bound_ctrl:1
	v_pk_add_f32 v[184:185], v[184:185], v[120:121] op_sel_hi:[1,0] neg_lo:[0,1] neg_hi:[0,1]
	v_add_f32_dpp v154, v154, v154 row_ror:1 row_mask:0xf bank_mask:0xf bound_ctrl:1
	v_pk_add_f32 v[192:193], v[192:193], v[120:121] op_sel:[0,1] op_sel_hi:[1,1] neg_lo:[0,1] neg_hi:[0,1]
	v_add_f32_dpp v155, v155, v155 row_ror:1 row_mask:0xf bank_mask:0xf bound_ctrl:1
	s_waitcnt lgkmcnt(10)
	v_pk_fma_f32 v[178:179], v[88:89], v[178:179], v[120:121] op_sel_hi:[1,1,0]
	s_and_saveexec_b64 s[8:9], s[38:39]
	ds_write_b32 v103, v154 offset:37632
	ds_write_b32 v103, v155 offset:37696
	s_mov_b64 exec, s[8:9]
	v_pk_fma_f32 v[186:187], v[88:89], v[186:187], v[120:121] op_sel:[0,0,1] op_sel_hi:[1,1,1]
	v_pk_fma_f32 v[180:181], v[90:91], v[180:181], v[120:121] op_sel_hi:[1,1,0]
	v_pk_fma_f32 v[188:189], v[90:91], v[188:189], v[120:121] op_sel:[0,0,1] op_sel_hi:[1,1,1]
	s_waitcnt lgkmcnt(11)
	v_pk_fma_f32 v[182:183], v[92:93], v[182:183], v[120:121] op_sel_hi:[1,1,0]
	v_pk_fma_f32 v[190:191], v[92:93], v[190:191], v[120:121] op_sel:[0,0,1] op_sel_hi:[1,1,1]
	v_pk_fma_f32 v[184:185], v[94:95], v[184:185], v[120:121] op_sel_hi:[1,1,0]
	v_pk_fma_f32 v[192:193], v[94:95], v[192:193], v[120:121] op_sel:[0,0,1] op_sel_hi:[1,1,1]
	ds_read2_b32 v[120:121], v195 offset0:32 offset1:48
	ds_read_b128 v[88:91], v145 offset:12800
	ds_read_b128 v[92:95], v145 offset:13056
	s_waitcnt lgkmcnt(13)
	v_pk_fma_f32 v[146:147], v[80:81], v[178:179], v[196:197]
	v_pk_fma_f32 v[150:151], v[80:81], v[186:187], v[196:197]
	v_pk_fma_f32 v[148:149], v[82:83], v[180:181], v[196:197]
	v_pk_fma_f32 v[152:153], v[82:83], v[188:189], v[196:197]
	ds_read_b128 v[80:83], v145 offset:4608
	s_waitcnt lgkmcnt(13)
	v_pk_fma_f32 v[146:147], v[84:85], v[182:183], v[146:147]
	v_pk_fma_f32 v[150:151], v[84:85], v[190:191], v[150:151]
	v_pk_fma_f32 v[148:149], v[86:87], v[184:185], v[148:149]
	v_pk_fma_f32 v[152:153], v[86:87], v[192:193], v[152:153]
	ds_read_b128 v[84:87], v145 offset:4864
	v_add_f32_e32 v146, v146, v147
	v_add_f32_e32 v148, v148, v149
	v_add_f32_e32 v150, v150, v151
	v_add_f32_e32 v152, v152, v153
	v_add_f32_e32 v156, v146, v148
	v_add_f32_e32 v157, v150, v152
	s_waitcnt lgkmcnt(11)
	v_pk_add_f32 v[178:179], v[178:179], v[118:119] op_sel_hi:[1,0] neg_lo:[0,1] neg_hi:[0,1]
	v_add_f32_dpp v156, v156, v156 row_ror:8 row_mask:0xf bank_mask:0xf bound_ctrl:1
	v_pk_add_f32 v[186:187], v[186:187], v[118:119] op_sel:[0,1] op_sel_hi:[1,1] neg_lo:[0,1] neg_hi:[0,1]
	v_add_f32_dpp v157, v157, v157 row_ror:8 row_mask:0xf bank_mask:0xf bound_ctrl:1
	v_pk_add_f32 v[180:181], v[180:181], v[118:119] op_sel_hi:[1,0] neg_lo:[0,1] neg_hi:[0,1]
	v_add_f32_dpp v156, v156, v156 row_ror:4 row_mask:0xf bank_mask:0xf bound_ctrl:1
	v_pk_add_f32 v[188:189], v[188:189], v[118:119] op_sel:[0,1] op_sel_hi:[1,1] neg_lo:[0,1] neg_hi:[0,1]
	v_add_f32_dpp v157, v157, v157 row_ror:4 row_mask:0xf bank_mask:0xf bound_ctrl:1
	v_pk_add_f32 v[182:183], v[182:183], v[118:119] op_sel_hi:[1,0] neg_lo:[0,1] neg_hi:[0,1]
	v_add_f32_dpp v156, v156, v156 row_ror:2 row_mask:0xf bank_mask:0xf bound_ctrl:1
	v_pk_add_f32 v[190:191], v[190:191], v[118:119] op_sel:[0,1] op_sel_hi:[1,1] neg_lo:[0,1] neg_hi:[0,1]
	v_add_f32_dpp v157, v157, v157 row_ror:2 row_mask:0xf bank_mask:0xf bound_ctrl:1
	v_pk_add_f32 v[184:185], v[184:185], v[118:119] op_sel_hi:[1,0] neg_lo:[0,1] neg_hi:[0,1]
	v_add_f32_dpp v156, v156, v156 row_ror:1 row_mask:0xf bank_mask:0xf bound_ctrl:1
	v_pk_add_f32 v[192:193], v[192:193], v[118:119] op_sel:[0,1] op_sel_hi:[1,1] neg_lo:[0,1] neg_hi:[0,1]
	v_add_f32_dpp v157, v157, v157 row_ror:1 row_mask:0xf bank_mask:0xf bound_ctrl:1
	s_waitcnt lgkmcnt(10)
	v_pk_fma_f32 v[178:179], v[72:73], v[178:179], v[118:119] op_sel_hi:[1,1,0]
	s_and_saveexec_b64 s[8:9], s[38:39]
	ds_write_b32 v103, v156 offset:37760
	ds_write_b32 v103, v157 offset:37824
	s_mov_b64 exec, s[8:9]
	v_pk_fma_f32 v[186:187], v[72:73], v[186:187], v[118:119] op_sel:[0,0,1] op_sel_hi:[1,1,1]
	v_pk_fma_f32 v[180:181], v[74:75], v[180:181], v[118:119] op_sel_hi:[1,1,0]
	v_pk_fma_f32 v[188:189], v[74:75], v[188:189], v[118:119] op_sel:[0,0,1] op_sel_hi:[1,1,1]
	s_waitcnt lgkmcnt(11)
	v_pk_fma_f32 v[182:183], v[76:77], v[182:183], v[118:119] op_sel_hi:[1,1,0]
	v_pk_fma_f32 v[190:191], v[76:77], v[190:191], v[118:119] op_sel:[0,0,1] op_sel_hi:[1,1,1]
	v_pk_fma_f32 v[184:185], v[78:79], v[184:185], v[118:119] op_sel_hi:[1,1,0]
	v_pk_fma_f32 v[192:193], v[78:79], v[192:193], v[118:119] op_sel:[0,0,1] op_sel_hi:[1,1,1]
	ds_read2_b32 v[118:119], v195 offset0:64 offset1:80
	ds_read_b128 v[72:75], v145 offset:13312
	ds_read_b128 v[76:79], v145 offset:13568
	s_waitcnt lgkmcnt(13)
	v_pk_fma_f32 v[146:147], v[64:65], v[178:179], v[196:197]
	v_pk_fma_f32 v[150:151], v[64:65], v[186:187], v[196:197]
	v_pk_fma_f32 v[148:149], v[66:67], v[180:181], v[196:197]
	v_pk_fma_f32 v[152:153], v[66:67], v[188:189], v[196:197]
	ds_read_b128 v[64:67], v145 offset:5120
	s_waitcnt lgkmcnt(13)
	v_pk_fma_f32 v[146:147], v[68:69], v[182:183], v[146:147]
	v_pk_fma_f32 v[150:151], v[68:69], v[190:191], v[150:151]
	v_pk_fma_f32 v[148:149], v[70:71], v[184:185], v[148:149]
	v_pk_fma_f32 v[152:153], v[70:71], v[192:193], v[152:153]
	ds_read_b128 v[68:71], v145 offset:5376
	v_add_f32_e32 v146, v146, v147
	v_add_f32_e32 v148, v148, v149
	v_add_f32_e32 v150, v150, v151
	v_add_f32_e32 v152, v152, v153
	v_add_f32_e32 v154, v146, v148
	v_add_f32_e32 v155, v150, v152
	s_waitcnt lgkmcnt(11)
	v_pk_add_f32 v[178:179], v[178:179], v[120:121] op_sel_hi:[1,0] neg_lo:[0,1] neg_hi:[0,1]
	v_add_f32_dpp v154, v154, v154 row_ror:8 row_mask:0xf bank_mask:0xf bound_ctrl:1
	v_pk_add_f32 v[186:187], v[186:187], v[120:121] op_sel:[0,1] op_sel_hi:[1,1] neg_lo:[0,1] neg_hi:[0,1]
	v_add_f32_dpp v155, v155, v155 row_ror:8 row_mask:0xf bank_mask:0xf bound_ctrl:1
	v_pk_add_f32 v[180:181], v[180:181], v[120:121] op_sel_hi:[1,0] neg_lo:[0,1] neg_hi:[0,1]
	v_add_f32_dpp v154, v154, v154 row_ror:4 row_mask:0xf bank_mask:0xf bound_ctrl:1
	v_pk_add_f32 v[188:189], v[188:189], v[120:121] op_sel:[0,1] op_sel_hi:[1,1] neg_lo:[0,1] neg_hi:[0,1]
	v_add_f32_dpp v155, v155, v155 row_ror:4 row_mask:0xf bank_mask:0xf bound_ctrl:1
	v_pk_add_f32 v[182:183], v[182:183], v[120:121] op_sel_hi:[1,0] neg_lo:[0,1] neg_hi:[0,1]
	v_add_f32_dpp v154, v154, v154 row_ror:2 row_mask:0xf bank_mask:0xf bound_ctrl:1
	v_pk_add_f32 v[190:191], v[190:191], v[120:121] op_sel:[0,1] op_sel_hi:[1,1] neg_lo:[0,1] neg_hi:[0,1]
	v_add_f32_dpp v155, v155, v155 row_ror:2 row_mask:0xf bank_mask:0xf bound_ctrl:1
	v_pk_add_f32 v[184:185], v[184:185], v[120:121] op_sel_hi:[1,0] neg_lo:[0,1] neg_hi:[0,1]
	v_add_f32_dpp v154, v154, v154 row_ror:1 row_mask:0xf bank_mask:0xf bound_ctrl:1
	v_pk_add_f32 v[192:193], v[192:193], v[120:121] op_sel:[0,1] op_sel_hi:[1,1] neg_lo:[0,1] neg_hi:[0,1]
	v_add_f32_dpp v155, v155, v155 row_ror:1 row_mask:0xf bank_mask:0xf bound_ctrl:1
	s_waitcnt lgkmcnt(10)
	v_pk_fma_f32 v[178:179], v[88:89], v[178:179], v[120:121] op_sel_hi:[1,1,0]
	s_and_saveexec_b64 s[8:9], s[38:39]
	ds_write_b32 v103, v154 offset:37888
	ds_write_b32 v103, v155 offset:37952
	s_mov_b64 exec, s[8:9]
	v_pk_fma_f32 v[186:187], v[88:89], v[186:187], v[120:121] op_sel:[0,0,1] op_sel_hi:[1,1,1]
	v_pk_fma_f32 v[180:181], v[90:91], v[180:181], v[120:121] op_sel_hi:[1,1,0]
	v_pk_fma_f32 v[188:189], v[90:91], v[188:189], v[120:121] op_sel:[0,0,1] op_sel_hi:[1,1,1]
	s_waitcnt lgkmcnt(11)
	v_pk_fma_f32 v[182:183], v[92:93], v[182:183], v[120:121] op_sel_hi:[1,1,0]
	v_pk_fma_f32 v[190:191], v[92:93], v[190:191], v[120:121] op_sel:[0,0,1] op_sel_hi:[1,1,1]
	v_pk_fma_f32 v[184:185], v[94:95], v[184:185], v[120:121] op_sel_hi:[1,1,0]
	v_pk_fma_f32 v[192:193], v[94:95], v[192:193], v[120:121] op_sel:[0,0,1] op_sel_hi:[1,1,1]
	ds_read2_b32 v[120:121], v195 offset0:96 offset1:112
	ds_read_b128 v[88:91], v145 offset:13824
	ds_read_b128 v[92:95], v145 offset:14080
	s_waitcnt lgkmcnt(13)
	v_pk_fma_f32 v[146:147], v[80:81], v[178:179], v[196:197]
	v_pk_fma_f32 v[150:151], v[80:81], v[186:187], v[196:197]
	v_pk_fma_f32 v[148:149], v[82:83], v[180:181], v[196:197]
	v_pk_fma_f32 v[152:153], v[82:83], v[188:189], v[196:197]
	ds_read_b128 v[80:83], v145 offset:5632
	s_waitcnt lgkmcnt(13)
	v_pk_fma_f32 v[146:147], v[84:85], v[182:183], v[146:147]
	v_pk_fma_f32 v[150:151], v[84:85], v[190:191], v[150:151]
	v_pk_fma_f32 v[148:149], v[86:87], v[184:185], v[148:149]
	v_pk_fma_f32 v[152:153], v[86:87], v[192:193], v[152:153]
	ds_read_b128 v[84:87], v145 offset:5888
	v_add_f32_e32 v146, v146, v147
	v_add_f32_e32 v148, v148, v149
	v_add_f32_e32 v150, v150, v151
	v_add_f32_e32 v152, v152, v153
	v_add_f32_e32 v156, v146, v148
	v_add_f32_e32 v157, v150, v152
	s_waitcnt lgkmcnt(11)
	v_pk_add_f32 v[178:179], v[178:179], v[118:119] op_sel_hi:[1,0] neg_lo:[0,1] neg_hi:[0,1]
	v_add_f32_dpp v156, v156, v156 row_ror:8 row_mask:0xf bank_mask:0xf bound_ctrl:1
	v_pk_add_f32 v[186:187], v[186:187], v[118:119] op_sel:[0,1] op_sel_hi:[1,1] neg_lo:[0,1] neg_hi:[0,1]
	v_add_f32_dpp v157, v157, v157 row_ror:8 row_mask:0xf bank_mask:0xf bound_ctrl:1
	v_pk_add_f32 v[180:181], v[180:181], v[118:119] op_sel_hi:[1,0] neg_lo:[0,1] neg_hi:[0,1]
	v_add_f32_dpp v156, v156, v156 row_ror:4 row_mask:0xf bank_mask:0xf bound_ctrl:1
	v_pk_add_f32 v[188:189], v[188:189], v[118:119] op_sel:[0,1] op_sel_hi:[1,1] neg_lo:[0,1] neg_hi:[0,1]
	v_add_f32_dpp v157, v157, v157 row_ror:4 row_mask:0xf bank_mask:0xf bound_ctrl:1
	v_pk_add_f32 v[182:183], v[182:183], v[118:119] op_sel_hi:[1,0] neg_lo:[0,1] neg_hi:[0,1]
	v_add_f32_dpp v156, v156, v156 row_ror:2 row_mask:0xf bank_mask:0xf bound_ctrl:1
	v_pk_add_f32 v[190:191], v[190:191], v[118:119] op_sel:[0,1] op_sel_hi:[1,1] neg_lo:[0,1] neg_hi:[0,1]
	v_add_f32_dpp v157, v157, v157 row_ror:2 row_mask:0xf bank_mask:0xf bound_ctrl:1
	v_pk_add_f32 v[184:185], v[184:185], v[118:119] op_sel_hi:[1,0] neg_lo:[0,1] neg_hi:[0,1]
	v_add_f32_dpp v156, v156, v156 row_ror:1 row_mask:0xf bank_mask:0xf bound_ctrl:1
	v_pk_add_f32 v[192:193], v[192:193], v[118:119] op_sel:[0,1] op_sel_hi:[1,1] neg_lo:[0,1] neg_hi:[0,1]
	v_add_f32_dpp v157, v157, v157 row_ror:1 row_mask:0xf bank_mask:0xf bound_ctrl:1
	s_waitcnt lgkmcnt(10)
	v_pk_fma_f32 v[178:179], v[72:73], v[178:179], v[118:119] op_sel_hi:[1,1,0]
	s_and_saveexec_b64 s[8:9], s[38:39]
	ds_write_b32 v103, v156 offset:38016
	ds_write_b32 v103, v157 offset:38080
	s_mov_b64 exec, s[8:9]
	v_pk_fma_f32 v[186:187], v[72:73], v[186:187], v[118:119] op_sel:[0,0,1] op_sel_hi:[1,1,1]
	v_pk_fma_f32 v[180:181], v[74:75], v[180:181], v[118:119] op_sel_hi:[1,1,0]
	v_pk_fma_f32 v[188:189], v[74:75], v[188:189], v[118:119] op_sel:[0,0,1] op_sel_hi:[1,1,1]
	s_waitcnt lgkmcnt(11)
	v_pk_fma_f32 v[182:183], v[76:77], v[182:183], v[118:119] op_sel_hi:[1,1,0]
	v_pk_fma_f32 v[190:191], v[76:77], v[190:191], v[118:119] op_sel:[0,0,1] op_sel_hi:[1,1,1]
	v_pk_fma_f32 v[184:185], v[78:79], v[184:185], v[118:119] op_sel_hi:[1,1,0]
	v_pk_fma_f32 v[192:193], v[78:79], v[192:193], v[118:119] op_sel:[0,0,1] op_sel_hi:[1,1,1]
	ds_read2_b32 v[118:119], v195 offset0:128 offset1:144
	ds_read_b128 v[72:75], v145 offset:14336
	ds_read_b128 v[76:79], v145 offset:14592
	s_waitcnt lgkmcnt(13)
	v_pk_fma_f32 v[146:147], v[64:65], v[178:179], v[196:197]
	v_pk_fma_f32 v[150:151], v[64:65], v[186:187], v[196:197]
	v_pk_fma_f32 v[148:149], v[66:67], v[180:181], v[196:197]
	v_pk_fma_f32 v[152:153], v[66:67], v[188:189], v[196:197]
	ds_read_b128 v[64:67], v145 offset:6144
	s_waitcnt lgkmcnt(13)
	v_pk_fma_f32 v[146:147], v[68:69], v[182:183], v[146:147]
	v_pk_fma_f32 v[150:151], v[68:69], v[190:191], v[150:151]
	v_pk_fma_f32 v[148:149], v[70:71], v[184:185], v[148:149]
	v_pk_fma_f32 v[152:153], v[70:71], v[192:193], v[152:153]
	ds_read_b128 v[68:71], v145 offset:6400
	v_add_f32_e32 v146, v146, v147
	v_add_f32_e32 v148, v148, v149
	v_add_f32_e32 v150, v150, v151
	v_add_f32_e32 v152, v152, v153
	v_add_f32_e32 v154, v146, v148
	v_add_f32_e32 v155, v150, v152
	s_waitcnt lgkmcnt(11)
	v_pk_add_f32 v[178:179], v[178:179], v[120:121] op_sel_hi:[1,0] neg_lo:[0,1] neg_hi:[0,1]
	v_add_f32_dpp v154, v154, v154 row_ror:8 row_mask:0xf bank_mask:0xf bound_ctrl:1
	v_pk_add_f32 v[186:187], v[186:187], v[120:121] op_sel:[0,1] op_sel_hi:[1,1] neg_lo:[0,1] neg_hi:[0,1]
	v_add_f32_dpp v155, v155, v155 row_ror:8 row_mask:0xf bank_mask:0xf bound_ctrl:1
	v_pk_add_f32 v[180:181], v[180:181], v[120:121] op_sel_hi:[1,0] neg_lo:[0,1] neg_hi:[0,1]
	v_add_f32_dpp v154, v154, v154 row_ror:4 row_mask:0xf bank_mask:0xf bound_ctrl:1
	v_pk_add_f32 v[188:189], v[188:189], v[120:121] op_sel:[0,1] op_sel_hi:[1,1] neg_lo:[0,1] neg_hi:[0,1]
	v_add_f32_dpp v155, v155, v155 row_ror:4 row_mask:0xf bank_mask:0xf bound_ctrl:1
	v_pk_add_f32 v[182:183], v[182:183], v[120:121] op_sel_hi:[1,0] neg_lo:[0,1] neg_hi:[0,1]
	v_add_f32_dpp v154, v154, v154 row_ror:2 row_mask:0xf bank_mask:0xf bound_ctrl:1
	v_pk_add_f32 v[190:191], v[190:191], v[120:121] op_sel:[0,1] op_sel_hi:[1,1] neg_lo:[0,1] neg_hi:[0,1]
	v_add_f32_dpp v155, v155, v155 row_ror:2 row_mask:0xf bank_mask:0xf bound_ctrl:1
	v_pk_add_f32 v[184:185], v[184:185], v[120:121] op_sel_hi:[1,0] neg_lo:[0,1] neg_hi:[0,1]
	v_add_f32_dpp v154, v154, v154 row_ror:1 row_mask:0xf bank_mask:0xf bound_ctrl:1
	v_pk_add_f32 v[192:193], v[192:193], v[120:121] op_sel:[0,1] op_sel_hi:[1,1] neg_lo:[0,1] neg_hi:[0,1]
	v_add_f32_dpp v155, v155, v155 row_ror:1 row_mask:0xf bank_mask:0xf bound_ctrl:1
	s_waitcnt lgkmcnt(10)
	v_pk_fma_f32 v[178:179], v[88:89], v[178:179], v[120:121] op_sel_hi:[1,1,0]
	s_and_saveexec_b64 s[8:9], s[38:39]
	ds_write_b32 v103, v154 offset:38144
	ds_write_b32 v103, v155 offset:38208
	s_mov_b64 exec, s[8:9]
	v_pk_fma_f32 v[186:187], v[88:89], v[186:187], v[120:121] op_sel:[0,0,1] op_sel_hi:[1,1,1]
	v_pk_fma_f32 v[180:181], v[90:91], v[180:181], v[120:121] op_sel_hi:[1,1,0]
	v_pk_fma_f32 v[188:189], v[90:91], v[188:189], v[120:121] op_sel:[0,0,1] op_sel_hi:[1,1,1]
	s_waitcnt lgkmcnt(11)
	v_pk_fma_f32 v[182:183], v[92:93], v[182:183], v[120:121] op_sel_hi:[1,1,0]
	v_pk_fma_f32 v[190:191], v[92:93], v[190:191], v[120:121] op_sel:[0,0,1] op_sel_hi:[1,1,1]
	v_pk_fma_f32 v[184:185], v[94:95], v[184:185], v[120:121] op_sel_hi:[1,1,0]
	v_pk_fma_f32 v[192:193], v[94:95], v[192:193], v[120:121] op_sel:[0,0,1] op_sel_hi:[1,1,1]
	ds_read2_b32 v[120:121], v195 offset0:160 offset1:176
	ds_read_b128 v[88:91], v145 offset:14848
	ds_read_b128 v[92:95], v145 offset:15104
	s_waitcnt lgkmcnt(13)
	v_pk_fma_f32 v[146:147], v[80:81], v[178:179], v[196:197]
	v_pk_fma_f32 v[150:151], v[80:81], v[186:187], v[196:197]
	v_pk_fma_f32 v[148:149], v[82:83], v[180:181], v[196:197]
	v_pk_fma_f32 v[152:153], v[82:83], v[188:189], v[196:197]
	ds_read_b128 v[80:83], v145 offset:6656
	s_waitcnt lgkmcnt(13)
	v_pk_fma_f32 v[146:147], v[84:85], v[182:183], v[146:147]
	v_pk_fma_f32 v[150:151], v[84:85], v[190:191], v[150:151]
	v_pk_fma_f32 v[148:149], v[86:87], v[184:185], v[148:149]
	v_pk_fma_f32 v[152:153], v[86:87], v[192:193], v[152:153]
	ds_read_b128 v[84:87], v145 offset:6912
	v_add_f32_e32 v146, v146, v147
	v_add_f32_e32 v148, v148, v149
	v_add_f32_e32 v150, v150, v151
	v_add_f32_e32 v152, v152, v153
	v_add_f32_e32 v156, v146, v148
	v_add_f32_e32 v157, v150, v152
	s_waitcnt lgkmcnt(11)
	v_pk_add_f32 v[178:179], v[178:179], v[118:119] op_sel_hi:[1,0] neg_lo:[0,1] neg_hi:[0,1]
	v_add_f32_dpp v156, v156, v156 row_ror:8 row_mask:0xf bank_mask:0xf bound_ctrl:1
	v_pk_add_f32 v[186:187], v[186:187], v[118:119] op_sel:[0,1] op_sel_hi:[1,1] neg_lo:[0,1] neg_hi:[0,1]
	v_add_f32_dpp v157, v157, v157 row_ror:8 row_mask:0xf bank_mask:0xf bound_ctrl:1
	v_pk_add_f32 v[180:181], v[180:181], v[118:119] op_sel_hi:[1,0] neg_lo:[0,1] neg_hi:[0,1]
	v_add_f32_dpp v156, v156, v156 row_ror:4 row_mask:0xf bank_mask:0xf bound_ctrl:1
	v_pk_add_f32 v[188:189], v[188:189], v[118:119] op_sel:[0,1] op_sel_hi:[1,1] neg_lo:[0,1] neg_hi:[0,1]
	v_add_f32_dpp v157, v157, v157 row_ror:4 row_mask:0xf bank_mask:0xf bound_ctrl:1
	v_pk_add_f32 v[182:183], v[182:183], v[118:119] op_sel_hi:[1,0] neg_lo:[0,1] neg_hi:[0,1]
	v_add_f32_dpp v156, v156, v156 row_ror:2 row_mask:0xf bank_mask:0xf bound_ctrl:1
	v_pk_add_f32 v[190:191], v[190:191], v[118:119] op_sel:[0,1] op_sel_hi:[1,1] neg_lo:[0,1] neg_hi:[0,1]
	v_add_f32_dpp v157, v157, v157 row_ror:2 row_mask:0xf bank_mask:0xf bound_ctrl:1
	v_pk_add_f32 v[184:185], v[184:185], v[118:119] op_sel_hi:[1,0] neg_lo:[0,1] neg_hi:[0,1]
	v_add_f32_dpp v156, v156, v156 row_ror:1 row_mask:0xf bank_mask:0xf bound_ctrl:1
	v_pk_add_f32 v[192:193], v[192:193], v[118:119] op_sel:[0,1] op_sel_hi:[1,1] neg_lo:[0,1] neg_hi:[0,1]
	v_add_f32_dpp v157, v157, v157 row_ror:1 row_mask:0xf bank_mask:0xf bound_ctrl:1
	s_waitcnt lgkmcnt(10)
	v_pk_fma_f32 v[178:179], v[72:73], v[178:179], v[118:119] op_sel_hi:[1,1,0]
	s_and_saveexec_b64 s[8:9], s[38:39]
	ds_write_b32 v103, v156 offset:38272
	ds_write_b32 v103, v157 offset:38336
	s_mov_b64 exec, s[8:9]
	v_pk_fma_f32 v[186:187], v[72:73], v[186:187], v[118:119] op_sel:[0,0,1] op_sel_hi:[1,1,1]
	v_pk_fma_f32 v[180:181], v[74:75], v[180:181], v[118:119] op_sel_hi:[1,1,0]
	v_pk_fma_f32 v[188:189], v[74:75], v[188:189], v[118:119] op_sel:[0,0,1] op_sel_hi:[1,1,1]
	s_waitcnt lgkmcnt(11)
	v_pk_fma_f32 v[182:183], v[76:77], v[182:183], v[118:119] op_sel_hi:[1,1,0]
	v_pk_fma_f32 v[190:191], v[76:77], v[190:191], v[118:119] op_sel:[0,0,1] op_sel_hi:[1,1,1]
	v_pk_fma_f32 v[184:185], v[78:79], v[184:185], v[118:119] op_sel_hi:[1,1,0]
	v_pk_fma_f32 v[192:193], v[78:79], v[192:193], v[118:119] op_sel:[0,0,1] op_sel_hi:[1,1,1]
	ds_read2_b32 v[118:119], v195 offset0:192 offset1:208
	ds_read_b128 v[72:75], v145 offset:15360
	ds_read_b128 v[76:79], v145 offset:15616
	s_waitcnt lgkmcnt(13)
	v_pk_fma_f32 v[146:147], v[64:65], v[178:179], v[196:197]
	v_pk_fma_f32 v[150:151], v[64:65], v[186:187], v[196:197]
	v_pk_fma_f32 v[148:149], v[66:67], v[180:181], v[196:197]
	v_pk_fma_f32 v[152:153], v[66:67], v[188:189], v[196:197]
	ds_read_b128 v[64:67], v145 offset:7168
	s_waitcnt lgkmcnt(13)
	v_pk_fma_f32 v[146:147], v[68:69], v[182:183], v[146:147]
	v_pk_fma_f32 v[150:151], v[68:69], v[190:191], v[150:151]
	v_pk_fma_f32 v[148:149], v[70:71], v[184:185], v[148:149]
	v_pk_fma_f32 v[152:153], v[70:71], v[192:193], v[152:153]
	ds_read_b128 v[68:71], v145 offset:7424
	v_add_f32_e32 v146, v146, v147
	v_add_f32_e32 v148, v148, v149
	v_add_f32_e32 v150, v150, v151
	v_add_f32_e32 v152, v152, v153
	v_add_f32_e32 v154, v146, v148
	v_add_f32_e32 v155, v150, v152
	s_waitcnt lgkmcnt(11)
	v_pk_add_f32 v[178:179], v[178:179], v[120:121] op_sel_hi:[1,0] neg_lo:[0,1] neg_hi:[0,1]
	v_add_f32_dpp v154, v154, v154 row_ror:8 row_mask:0xf bank_mask:0xf bound_ctrl:1
	v_pk_add_f32 v[186:187], v[186:187], v[120:121] op_sel:[0,1] op_sel_hi:[1,1] neg_lo:[0,1] neg_hi:[0,1]
	v_add_f32_dpp v155, v155, v155 row_ror:8 row_mask:0xf bank_mask:0xf bound_ctrl:1
	v_pk_add_f32 v[180:181], v[180:181], v[120:121] op_sel_hi:[1,0] neg_lo:[0,1] neg_hi:[0,1]
	v_add_f32_dpp v154, v154, v154 row_ror:4 row_mask:0xf bank_mask:0xf bound_ctrl:1
	v_pk_add_f32 v[188:189], v[188:189], v[120:121] op_sel:[0,1] op_sel_hi:[1,1] neg_lo:[0,1] neg_hi:[0,1]
	v_add_f32_dpp v155, v155, v155 row_ror:4 row_mask:0xf bank_mask:0xf bound_ctrl:1
	v_pk_add_f32 v[182:183], v[182:183], v[120:121] op_sel_hi:[1,0] neg_lo:[0,1] neg_hi:[0,1]
	v_add_f32_dpp v154, v154, v154 row_ror:2 row_mask:0xf bank_mask:0xf bound_ctrl:1
	v_pk_add_f32 v[190:191], v[190:191], v[120:121] op_sel:[0,1] op_sel_hi:[1,1] neg_lo:[0,1] neg_hi:[0,1]
	v_add_f32_dpp v155, v155, v155 row_ror:2 row_mask:0xf bank_mask:0xf bound_ctrl:1
	v_pk_add_f32 v[184:185], v[184:185], v[120:121] op_sel_hi:[1,0] neg_lo:[0,1] neg_hi:[0,1]
	v_add_f32_dpp v154, v154, v154 row_ror:1 row_mask:0xf bank_mask:0xf bound_ctrl:1
	v_pk_add_f32 v[192:193], v[192:193], v[120:121] op_sel:[0,1] op_sel_hi:[1,1] neg_lo:[0,1] neg_hi:[0,1]
	v_add_f32_dpp v155, v155, v155 row_ror:1 row_mask:0xf bank_mask:0xf bound_ctrl:1
	s_waitcnt lgkmcnt(10)
	v_pk_fma_f32 v[178:179], v[88:89], v[178:179], v[120:121] op_sel_hi:[1,1,0]
	s_and_saveexec_b64 s[8:9], s[38:39]
	ds_write_b32 v103, v154 offset:38400
	ds_write_b32 v103, v155 offset:38464
	s_mov_b64 exec, s[8:9]
	v_pk_fma_f32 v[186:187], v[88:89], v[186:187], v[120:121] op_sel:[0,0,1] op_sel_hi:[1,1,1]
	v_pk_fma_f32 v[180:181], v[90:91], v[180:181], v[120:121] op_sel_hi:[1,1,0]
	v_pk_fma_f32 v[188:189], v[90:91], v[188:189], v[120:121] op_sel:[0,0,1] op_sel_hi:[1,1,1]
	s_waitcnt lgkmcnt(11)
	v_pk_fma_f32 v[182:183], v[92:93], v[182:183], v[120:121] op_sel_hi:[1,1,0]
	v_pk_fma_f32 v[190:191], v[92:93], v[190:191], v[120:121] op_sel:[0,0,1] op_sel_hi:[1,1,1]
	v_pk_fma_f32 v[184:185], v[94:95], v[184:185], v[120:121] op_sel_hi:[1,1,0]
	v_pk_fma_f32 v[192:193], v[94:95], v[192:193], v[120:121] op_sel:[0,0,1] op_sel_hi:[1,1,1]
	ds_read2_b32 v[120:121], v195 offset0:224 offset1:240
	ds_read_b128 v[88:91], v145 offset:15872
	ds_read_b128 v[92:95], v145 offset:16128
	s_waitcnt lgkmcnt(13)
	v_pk_fma_f32 v[146:147], v[80:81], v[178:179], v[196:197]
	v_pk_fma_f32 v[150:151], v[80:81], v[186:187], v[196:197]
	v_pk_fma_f32 v[148:149], v[82:83], v[180:181], v[196:197]
	v_pk_fma_f32 v[152:153], v[82:83], v[188:189], v[196:197]
	ds_read_b128 v[80:83], v145 offset:7680
	s_waitcnt lgkmcnt(13)
	v_pk_fma_f32 v[146:147], v[84:85], v[182:183], v[146:147]
	v_pk_fma_f32 v[150:151], v[84:85], v[190:191], v[150:151]
	v_pk_fma_f32 v[148:149], v[86:87], v[184:185], v[148:149]
	v_pk_fma_f32 v[152:153], v[86:87], v[192:193], v[152:153]
	ds_read_b128 v[84:87], v145 offset:7936
	v_add_f32_e32 v146, v146, v147
	v_add_f32_e32 v148, v148, v149
	v_add_f32_e32 v150, v150, v151
	v_add_f32_e32 v152, v152, v153
	v_add_f32_e32 v156, v146, v148
	v_add_f32_e32 v157, v150, v152
	s_waitcnt lgkmcnt(11)
	v_pk_add_f32 v[178:179], v[178:179], v[118:119] op_sel_hi:[1,0] neg_lo:[0,1] neg_hi:[0,1]
	v_add_f32_dpp v156, v156, v156 row_ror:8 row_mask:0xf bank_mask:0xf bound_ctrl:1
	v_pk_add_f32 v[186:187], v[186:187], v[118:119] op_sel:[0,1] op_sel_hi:[1,1] neg_lo:[0,1] neg_hi:[0,1]
	v_add_f32_dpp v157, v157, v157 row_ror:8 row_mask:0xf bank_mask:0xf bound_ctrl:1
	v_pk_add_f32 v[180:181], v[180:181], v[118:119] op_sel_hi:[1,0] neg_lo:[0,1] neg_hi:[0,1]
	v_add_f32_dpp v156, v156, v156 row_ror:4 row_mask:0xf bank_mask:0xf bound_ctrl:1
	v_pk_add_f32 v[188:189], v[188:189], v[118:119] op_sel:[0,1] op_sel_hi:[1,1] neg_lo:[0,1] neg_hi:[0,1]
	v_add_f32_dpp v157, v157, v157 row_ror:4 row_mask:0xf bank_mask:0xf bound_ctrl:1
	v_pk_add_f32 v[182:183], v[182:183], v[118:119] op_sel_hi:[1,0] neg_lo:[0,1] neg_hi:[0,1]
	v_add_f32_dpp v156, v156, v156 row_ror:2 row_mask:0xf bank_mask:0xf bound_ctrl:1
	v_pk_add_f32 v[190:191], v[190:191], v[118:119] op_sel:[0,1] op_sel_hi:[1,1] neg_lo:[0,1] neg_hi:[0,1]
	v_add_f32_dpp v157, v157, v157 row_ror:2 row_mask:0xf bank_mask:0xf bound_ctrl:1
	v_pk_add_f32 v[184:185], v[184:185], v[118:119] op_sel_hi:[1,0] neg_lo:[0,1] neg_hi:[0,1]
	v_add_f32_dpp v156, v156, v156 row_ror:1 row_mask:0xf bank_mask:0xf bound_ctrl:1
	v_pk_add_f32 v[192:193], v[192:193], v[118:119] op_sel:[0,1] op_sel_hi:[1,1] neg_lo:[0,1] neg_hi:[0,1]
	v_add_f32_dpp v157, v157, v157 row_ror:1 row_mask:0xf bank_mask:0xf bound_ctrl:1
	s_waitcnt lgkmcnt(10)
	v_pk_fma_f32 v[178:179], v[72:73], v[178:179], v[118:119] op_sel_hi:[1,1,0]
	s_and_saveexec_b64 s[8:9], s[38:39]
	ds_write_b32 v103, v156 offset:38528
	ds_write_b32 v103, v157 offset:38592
	s_mov_b64 exec, s[8:9]
	v_pk_fma_f32 v[186:187], v[72:73], v[186:187], v[118:119] op_sel:[0,0,1] op_sel_hi:[1,1,1]
	v_pk_fma_f32 v[180:181], v[74:75], v[180:181], v[118:119] op_sel_hi:[1,1,0]
	v_pk_fma_f32 v[188:189], v[74:75], v[188:189], v[118:119] op_sel:[0,0,1] op_sel_hi:[1,1,1]
	s_waitcnt lgkmcnt(11)
	v_pk_fma_f32 v[182:183], v[76:77], v[182:183], v[118:119] op_sel_hi:[1,1,0]
	v_pk_fma_f32 v[190:191], v[76:77], v[190:191], v[118:119] op_sel:[0,0,1] op_sel_hi:[1,1,1]
	v_pk_fma_f32 v[184:185], v[78:79], v[184:185], v[118:119] op_sel_hi:[1,1,0]
	v_pk_fma_f32 v[192:193], v[78:79], v[192:193], v[118:119] op_sel:[0,0,1] op_sel_hi:[1,1,1]
	s_waitcnt lgkmcnt(10)
	v_pk_fma_f32 v[146:147], v[64:65], v[178:179], v[196:197]
	v_pk_fma_f32 v[150:151], v[64:65], v[186:187], v[196:197]
	v_pk_fma_f32 v[148:149], v[66:67], v[180:181], v[196:197]
	v_pk_fma_f32 v[152:153], v[66:67], v[188:189], v[196:197]
	s_waitcnt lgkmcnt(9)
	v_pk_fma_f32 v[146:147], v[68:69], v[182:183], v[146:147]
	v_pk_fma_f32 v[150:151], v[68:69], v[190:191], v[150:151]
	v_pk_fma_f32 v[148:149], v[70:71], v[184:185], v[148:149]
	v_pk_fma_f32 v[152:153], v[70:71], v[192:193], v[152:153]
	v_add_f32_e32 v146, v146, v147
	v_add_f32_e32 v148, v148, v149
	v_add_f32_e32 v150, v150, v151
	v_add_f32_e32 v152, v152, v153
	v_add_f32_e32 v154, v146, v148
	v_add_f32_e32 v155, v150, v152
	s_waitcnt lgkmcnt(6)
	v_pk_add_f32 v[178:179], v[178:179], v[120:121] op_sel_hi:[1,0] neg_lo:[0,1] neg_hi:[0,1]
	v_add_f32_dpp v154, v154, v154 row_ror:8 row_mask:0xf bank_mask:0xf bound_ctrl:1
	v_pk_add_f32 v[186:187], v[186:187], v[120:121] op_sel:[0,1] op_sel_hi:[1,1] neg_lo:[0,1] neg_hi:[0,1]
	v_add_f32_dpp v155, v155, v155 row_ror:8 row_mask:0xf bank_mask:0xf bound_ctrl:1
	v_pk_add_f32 v[180:181], v[180:181], v[120:121] op_sel_hi:[1,0] neg_lo:[0,1] neg_hi:[0,1]
	v_add_f32_dpp v154, v154, v154 row_ror:4 row_mask:0xf bank_mask:0xf bound_ctrl:1
	v_pk_add_f32 v[188:189], v[188:189], v[120:121] op_sel:[0,1] op_sel_hi:[1,1] neg_lo:[0,1] neg_hi:[0,1]
	v_add_f32_dpp v155, v155, v155 row_ror:4 row_mask:0xf bank_mask:0xf bound_ctrl:1
	v_pk_add_f32 v[182:183], v[182:183], v[120:121] op_sel_hi:[1,0] neg_lo:[0,1] neg_hi:[0,1]
	v_add_f32_dpp v154, v154, v154 row_ror:2 row_mask:0xf bank_mask:0xf bound_ctrl:1
	v_pk_add_f32 v[190:191], v[190:191], v[120:121] op_sel:[0,1] op_sel_hi:[1,1] neg_lo:[0,1] neg_hi:[0,1]
	v_add_f32_dpp v155, v155, v155 row_ror:2 row_mask:0xf bank_mask:0xf bound_ctrl:1
	v_pk_add_f32 v[184:185], v[184:185], v[120:121] op_sel_hi:[1,0] neg_lo:[0,1] neg_hi:[0,1]
	v_add_f32_dpp v154, v154, v154 row_ror:1 row_mask:0xf bank_mask:0xf bound_ctrl:1
	v_pk_add_f32 v[192:193], v[192:193], v[120:121] op_sel:[0,1] op_sel_hi:[1,1] neg_lo:[0,1] neg_hi:[0,1]
	v_add_f32_dpp v155, v155, v155 row_ror:1 row_mask:0xf bank_mask:0xf bound_ctrl:1
	s_waitcnt lgkmcnt(5)
	v_pk_fma_f32 v[178:179], v[88:89], v[178:179], v[120:121] op_sel_hi:[1,1,0]
	s_and_saveexec_b64 s[8:9], s[38:39]
	ds_write_b32 v103, v154 offset:38656
	ds_write_b32 v103, v155 offset:38720
	s_mov_b64 exec, s[8:9]
	v_pk_fma_f32 v[186:187], v[88:89], v[186:187], v[120:121] op_sel:[0,0,1] op_sel_hi:[1,1,1]
	v_pk_fma_f32 v[180:181], v[90:91], v[180:181], v[120:121] op_sel_hi:[1,1,0]
	v_pk_fma_f32 v[188:189], v[90:91], v[188:189], v[120:121] op_sel:[0,0,1] op_sel_hi:[1,1,1]
	s_waitcnt lgkmcnt(6)
	v_pk_fma_f32 v[182:183], v[92:93], v[182:183], v[120:121] op_sel_hi:[1,1,0]
	v_pk_fma_f32 v[190:191], v[92:93], v[190:191], v[120:121] op_sel:[0,0,1] op_sel_hi:[1,1,1]
	v_pk_fma_f32 v[184:185], v[94:95], v[184:185], v[120:121] op_sel_hi:[1,1,0]
	v_pk_fma_f32 v[192:193], v[94:95], v[192:193], v[120:121] op_sel:[0,0,1] op_sel_hi:[1,1,1]
	s_waitcnt lgkmcnt(5)
	v_pk_fma_f32 v[146:147], v[80:81], v[178:179], v[196:197]
	v_pk_fma_f32 v[150:151], v[80:81], v[186:187], v[196:197]
	v_pk_fma_f32 v[148:149], v[82:83], v[180:181], v[196:197]
	v_pk_fma_f32 v[152:153], v[82:83], v[188:189], v[196:197]
	s_waitcnt lgkmcnt(4)
	v_pk_fma_f32 v[146:147], v[84:85], v[182:183], v[146:147]
	v_pk_fma_f32 v[150:151], v[84:85], v[190:191], v[150:151]
	v_pk_fma_f32 v[148:149], v[86:87], v[184:185], v[148:149]
	v_pk_fma_f32 v[152:153], v[86:87], v[192:193], v[152:153]
	v_add_f32_e32 v146, v146, v147
	v_add_f32_e32 v148, v148, v149
	v_add_f32_e32 v150, v150, v151
	v_add_f32_e32 v152, v152, v153
	v_add_f32_e32 v156, v146, v148
	v_add_f32_e32 v157, v150, v152
	s_nop 0
	v_add_f32_dpp v156, v156, v156 row_ror:8 row_mask:0xf bank_mask:0xf bound_ctrl:1
	v_add_f32_dpp v157, v157, v157 row_ror:8 row_mask:0xf bank_mask:0xf bound_ctrl:1
	s_nop 0
	v_add_f32_dpp v156, v156, v156 row_ror:4 row_mask:0xf bank_mask:0xf bound_ctrl:1
	v_add_f32_dpp v157, v157, v157 row_ror:4 row_mask:0xf bank_mask:0xf bound_ctrl:1
	s_nop 0
	v_add_f32_dpp v156, v156, v156 row_ror:2 row_mask:0xf bank_mask:0xf bound_ctrl:1
	v_add_f32_dpp v157, v157, v157 row_ror:2 row_mask:0xf bank_mask:0xf bound_ctrl:1
	s_nop 0
	v_add_f32_dpp v156, v156, v156 row_ror:1 row_mask:0xf bank_mask:0xf bound_ctrl:1
	v_add_f32_dpp v157, v157, v157 row_ror:1 row_mask:0xf bank_mask:0xf bound_ctrl:1
	s_and_saveexec_b64 s[8:9], s[38:39]
	ds_write_b32 v103, v156 offset:38784
	ds_write_b32 v103, v157 offset:38848
	s_mov_b64 exec, s[8:9]
	s_waitcnt vmcnt(5)
	v_mul_f32_e32 v64, 0xbfb8aa3b, v44
	v_mul_f32_e32 v65, 0xbfb8aa3b, v45
	v_exp_f32_e32 v64, v64
	v_exp_f32_e32 v65, v65
	v_mul_f32_e32 v66, 0xbfb8aa3b, v46
	v_mul_f32_e32 v67, 0xbfb8aa3b, v47
	v_exp_f32_e32 v66, v66
	v_pk_add_f32 v[64:65], v[64:65], 1.0 op_sel_hi:[1,0]
	v_exp_f32_e32 v67, v67
	v_div_scale_f32 v80, s[8:9], v65, v65, v45
	v_rcp_f32_e32 v81, v80
	v_pk_add_f32 v[66:67], v[66:67], 1.0 op_sel_hi:[1,0]
	v_mul_f32_e32 v72, 0xbfb8aa3b, v48
	v_mul_f32_e32 v73, 0xbfb8aa3b, v49
	v_fma_f32 v82, -v80, v81, 1.0
	v_fmac_f32_e32 v81, v82, v81
	v_div_scale_f32 v82, vcc, v45, v65, v45
	v_mul_f32_e32 v83, v82, v81
	v_fma_f32 v88, -v80, v83, v82
	v_fmac_f32_e32 v83, v88, v81
	v_fma_f32 v80, -v80, v83, v82
	v_div_fmas_f32 v80, v80, v81, v83
	v_div_fixup_f32 v65, v80, v65, v45
	v_div_scale_f32 v80, s[8:9], v64, v64, v44
	v_rcp_f32_e32 v81, v80
	v_exp_f32_e32 v72, v72
	v_exp_f32_e32 v73, v73
	v_mul_f32_e32 v74, 0xbfb8aa3b, v50
	v_fma_f32 v82, -v80, v81, 1.0
	v_fmac_f32_e32 v81, v82, v81
	v_div_scale_f32 v82, vcc, v44, v64, v44
	v_mul_f32_e32 v83, v82, v81
	v_fma_f32 v88, -v80, v83, v82
	v_fmac_f32_e32 v83, v88, v81
	v_fma_f32 v80, -v80, v83, v82
	v_div_fmas_f32 v80, v80, v81, v83
	v_div_fixup_f32 v64, v80, v64, v44
	v_div_scale_f32 v80, s[8:9], v67, v67, v47
	v_rcp_f32_e32 v81, v80
	v_pk_mul_f32 v[64:65], v[64:65], s[18:19] op_sel_hi:[1,0]
	v_mul_f32_e32 v75, 0xbfb8aa3b, v51
	v_exp_f32_e32 v74, v74
	v_fma_f32 v82, -v80, v81, 1.0
	v_fmac_f32_e32 v81, v82, v81
	v_div_scale_f32 v82, vcc, v47, v67, v47
	v_mul_f32_e32 v83, v82, v81
	v_fma_f32 v88, -v80, v83, v82
	v_fmac_f32_e32 v83, v88, v81
	v_fma_f32 v80, -v80, v83, v82
	v_div_fmas_f32 v80, v80, v81, v83
	v_div_fixup_f32 v67, v80, v67, v47
	v_div_scale_f32 v80, s[8:9], v66, v66, v46
	v_rcp_f32_e32 v81, v80
	v_exp_f32_e32 v75, v75
	s_cmpk_gt_u32 s48, 0x78
	v_fma_f32 v82, -v80, v81, 1.0
	v_fmac_f32_e32 v81, v82, v81
	v_div_scale_f32 v82, vcc, v46, v66, v46
	v_mul_f32_e32 v83, v82, v81
	v_fma_f32 v88, -v80, v83, v82
	v_fmac_f32_e32 v83, v88, v81
	v_fma_f32 v80, -v80, v83, v82
	v_div_fmas_f32 v80, v80, v81, v83
	v_div_fixup_f32 v66, v80, v66, v46
	v_pk_mul_f32 v[66:67], v[66:67], s[18:19] op_sel_hi:[1,0]
	ds_write_b128 v141, v[64:67] offset:18432
	v_pk_add_f32 v[64:65], v[72:73], 1.0 op_sel_hi:[1,0]
	v_div_scale_f32 v66, s[8:9], v65, v65, 1.0
	v_rcp_f32_e32 v67, v66
	s_nop 0
	v_fma_f32 v72, -v66, v67, 1.0
	v_fmac_f32_e32 v67, v72, v67
	v_div_scale_f32 v72, vcc, 1.0, v65, 1.0
	v_mul_f32_e32 v73, v72, v67
	v_fma_f32 v80, -v66, v73, v72
	v_fmac_f32_e32 v73, v80, v67
	v_fma_f32 v66, -v66, v73, v72
	v_div_fmas_f32 v66, v66, v67, v73
	v_div_fixup_f32 v65, v66, v65, 1.0
	v_div_scale_f32 v66, s[8:9], v64, v64, 1.0
	v_rcp_f32_e32 v67, v66
	s_nop 0
	v_fma_f32 v72, -v66, v67, 1.0
	v_fmac_f32_e32 v67, v72, v67
	v_div_scale_f32 v72, vcc, 1.0, v64, 1.0
	v_mul_f32_e32 v73, v72, v67
	v_fma_f32 v80, -v66, v73, v72
	v_fmac_f32_e32 v73, v80, v67
	v_fma_f32 v66, -v66, v73, v72
	v_div_fmas_f32 v66, v66, v67, v73
	v_div_fixup_f32 v64, v66, v64, 1.0
	v_pk_add_f32 v[66:67], v[74:75], 1.0 op_sel_hi:[1,0]
	v_pk_fma_f32 v[64:65], v[110:111], v[64:65], v[104:105]
	v_div_scale_f32 v72, s[8:9], v67, v67, 1.0
	v_rcp_f32_e32 v73, v72
	s_nop 0
	v_fma_f32 v74, -v72, v73, 1.0
	v_fmac_f32_e32 v73, v74, v73
	v_div_scale_f32 v74, vcc, 1.0, v67, 1.0
	v_mul_f32_e32 v75, v74, v73
	v_fma_f32 v80, -v72, v75, v74
	v_fmac_f32_e32 v75, v80, v73
	v_fma_f32 v72, -v72, v75, v74
	v_div_fmas_f32 v72, v72, v73, v75
	v_div_fixup_f32 v67, v72, v67, 1.0
	v_div_scale_f32 v72, s[8:9], v66, v66, 1.0
	v_rcp_f32_e32 v73, v72
	s_nop 0
	v_fma_f32 v74, -v72, v73, 1.0
	v_fmac_f32_e32 v73, v74, v73
	v_div_scale_f32 v74, vcc, 1.0, v66, 1.0
	v_mul_f32_e32 v75, v74, v73
	v_fma_f32 v80, -v72, v75, v74
	v_fmac_f32_e32 v75, v80, v73
	v_fma_f32 v72, -v72, v75, v74
	v_div_fmas_f32 v72, v72, v73, v75
	v_div_fixup_f32 v66, v72, v66, 1.0
	v_pk_fma_f32 v[66:67], v[112:113], v[66:67], v[106:107]
	ds_write_b128 v141, v[64:67] offset:26624
	ds_write_b32 v134, v133 offset:34816
	v_mul_f32_e32 v64, 0xbfb8aa3b, v56
	v_mul_f32_e32 v65, 0xbfb8aa3b, v57
	v_exp_f32_e32 v64, v64
	v_exp_f32_e32 v65, v65
	v_mul_f32_e32 v66, 0xbfb8aa3b, v58
	v_mul_f32_e32 v67, 0xbfb8aa3b, v59
	v_exp_f32_e32 v66, v66
	v_pk_add_f32 v[64:65], v[64:65], 1.0 op_sel_hi:[1,0]
	v_exp_f32_e32 v67, v67
	v_div_scale_f32 v80, s[8:9], v65, v65, v57
	v_rcp_f32_e32 v81, v80
	v_pk_add_f32 v[66:67], v[66:67], 1.0 op_sel_hi:[1,0]
	s_waitcnt vmcnt(4)
	v_mul_f32_e32 v72, 0xbfb8aa3b, v60
	v_mul_f32_e32 v73, 0xbfb8aa3b, v61
	v_fma_f32 v82, -v80, v81, 1.0
	v_fmac_f32_e32 v81, v82, v81
	v_div_scale_f32 v82, vcc, v57, v65, v57
	v_mul_f32_e32 v83, v82, v81
	v_fma_f32 v88, -v80, v83, v82
	v_fmac_f32_e32 v83, v88, v81
	v_fma_f32 v80, -v80, v83, v82
	v_div_fmas_f32 v80, v80, v81, v83
	v_div_fixup_f32 v65, v80, v65, v57
	v_div_scale_f32 v80, s[8:9], v64, v64, v56
	v_rcp_f32_e32 v81, v80
	v_exp_f32_e32 v72, v72
	v_exp_f32_e32 v73, v73
	v_mul_f32_e32 v74, 0xbfb8aa3b, v62
	v_fma_f32 v82, -v80, v81, 1.0
	v_fmac_f32_e32 v81, v82, v81
	v_div_scale_f32 v82, vcc, v56, v64, v56
	v_mul_f32_e32 v83, v82, v81
	v_fma_f32 v88, -v80, v83, v82
	v_fmac_f32_e32 v83, v88, v81
	v_fma_f32 v80, -v80, v83, v82
	v_div_fmas_f32 v80, v80, v81, v83
	v_div_fixup_f32 v64, v80, v64, v56
	v_div_scale_f32 v80, s[8:9], v67, v67, v59
	v_rcp_f32_e32 v81, v80
	v_pk_mul_f32 v[64:65], v[64:65], s[18:19] op_sel_hi:[1,0]
	v_mul_f32_e32 v75, 0xbfb8aa3b, v63
	v_exp_f32_e32 v74, v74
	v_fma_f32 v82, -v80, v81, 1.0
	v_fmac_f32_e32 v81, v82, v81
	v_div_scale_f32 v82, vcc, v59, v67, v59
	v_mul_f32_e32 v83, v82, v81
	v_fma_f32 v88, -v80, v83, v82
	v_fmac_f32_e32 v83, v88, v81
	v_fma_f32 v80, -v80, v83, v82
	v_div_fmas_f32 v80, v80, v81, v83
	v_div_fixup_f32 v67, v80, v67, v59
	v_div_scale_f32 v80, s[8:9], v66, v66, v58
	v_rcp_f32_e32 v81, v80
	v_exp_f32_e32 v75, v75
	v_fma_f32 v82, -v80, v81, 1.0
	v_fmac_f32_e32 v81, v82, v81
	v_div_scale_f32 v82, vcc, v58, v66, v58
	v_mul_f32_e32 v83, v82, v81
	v_fma_f32 v88, -v80, v83, v82
	v_fmac_f32_e32 v83, v88, v81
	v_fma_f32 v80, -v80, v83, v82
	v_div_fmas_f32 v80, v80, v81, v83
	v_div_fixup_f32 v66, v80, v66, v58
	v_pk_mul_f32 v[66:67], v[66:67], s[18:19] op_sel_hi:[1,0]
	ds_write_b128 v144, v[64:67] offset:18432
	v_pk_add_f32 v[64:65], v[72:73], 1.0 op_sel_hi:[1,0]
	v_div_scale_f32 v66, s[8:9], v65, v65, 1.0
	v_rcp_f32_e32 v67, v66
	s_nop 0
	v_fma_f32 v72, -v66, v67, 1.0
	v_fmac_f32_e32 v67, v72, v67
	v_div_scale_f32 v72, vcc, 1.0, v65, 1.0
	v_mul_f32_e32 v73, v72, v67
	v_fma_f32 v80, -v66, v73, v72
	v_fmac_f32_e32 v73, v80, v67
	v_fma_f32 v66, -v66, v73, v72
	v_div_fmas_f32 v66, v66, v67, v73
	v_div_fixup_f32 v65, v66, v65, 1.0
	v_div_scale_f32 v66, s[8:9], v64, v64, 1.0
	v_rcp_f32_e32 v67, v66
	s_nop 0
	v_fma_f32 v72, -v66, v67, 1.0
	v_fmac_f32_e32 v67, v72, v67
	v_div_scale_f32 v72, vcc, 1.0, v64, 1.0
	v_mul_f32_e32 v73, v72, v67
	v_fma_f32 v80, -v66, v73, v72
	v_fmac_f32_e32 v73, v80, v67
	v_fma_f32 v66, -v66, v73, v72
	v_div_fmas_f32 v66, v66, v67, v73
	v_div_fixup_f32 v64, v66, v64, 1.0
	v_pk_add_f32 v[66:67], v[74:75], 1.0 op_sel_hi:[1,0]
	v_pk_fma_f32 v[64:65], v[110:111], v[64:65], v[104:105]
	v_div_scale_f32 v72, s[8:9], v67, v67, 1.0
	v_rcp_f32_e32 v73, v72
	s_nop 0
	v_fma_f32 v74, -v72, v73, 1.0
	v_fmac_f32_e32 v73, v74, v73
	v_div_scale_f32 v74, vcc, 1.0, v67, 1.0
	v_mul_f32_e32 v75, v74, v73
	v_fma_f32 v80, -v72, v75, v74
	v_fmac_f32_e32 v75, v80, v73
	v_fma_f32 v72, -v72, v75, v74
	v_div_fmas_f32 v72, v72, v73, v75
	v_div_fixup_f32 v67, v72, v67, 1.0
	v_div_scale_f32 v72, s[8:9], v66, v66, 1.0
	v_rcp_f32_e32 v73, v72
	s_nop 0
	v_fma_f32 v74, -v72, v73, 1.0
	v_fmac_f32_e32 v73, v74, v73
	v_div_scale_f32 v74, vcc, 1.0, v66, 1.0
	v_mul_f32_e32 v75, v74, v73
	v_fma_f32 v80, -v72, v75, v74
	v_fmac_f32_e32 v75, v80, v73
	v_fma_f32 v72, -v72, v75, v74
	v_div_fmas_f32 v72, v72, v73, v75
	v_div_fixup_f32 v66, v72, v66, 1.0
	v_pk_fma_f32 v[66:67], v[112:113], v[66:67], v[106:107]
	ds_write_b128 v144, v[64:67] offset:26624
	ds_write_b32 v134, v135 offset:35840
	s_waitcnt lgkmcnt(0)
	s_barrier
	s_cbranch_scc1 .LBB0_1393
	v_add_u32_e32 v44, 0x70, v98
	v_mov_b64_e32 v[56:57], s[30:31]
	v_mad_i64_i32 v[44:45], s[8:9], v44, s25, v[56:57]
	s_lshl_b32 s94, s46, 2
	v_lshl_add_u64 v[58:59], v[44:45], 0, s[94:95]
	v_mov_b32_e32 v117, v140
	v_lshl_add_u64 v[44:45], v[58:59], 0, v[116:117]
	v_add_co_u32_e32 v46, vcc, 0x4000, v44
	s_lshl_b32 s8, s42, 2
	s_nop 0
	v_addc_co_u32_e32 v47, vcc, 0, v45, vcc
	s_mov_b32 s9, s95
	v_add_co_u32_e32 v48, vcc, 0x5000, v44
	v_lshl_add_u64 v[58:59], v[58:59], 0, s[8:9]
	v_mov_b32_e32 v115, v140
	v_add_u32_e32 v60, 0x70, v96
	v_addc_co_u32_e32 v49, vcc, 0, v45, vcc
	v_lshl_add_u64 v[58:59], v[58:59], 0, v[114:115]
	v_mad_i64_i32 v[56:57], s[22:23], v60, s25, v[56:57]
	v_add_co_u32_e32 v58, vcc, s81, v58
	v_lshl_add_u64 v[60:61], v[56:57], 0, s[94:95]
	s_nop 0
	v_addc_co_u32_e32 v59, vcc, 0, v59, vcc
	v_lshl_add_u64 v[62:63], v[60:61], 0, v[116:117]
	v_add_co_u32_e32 v56, vcc, s80, v62
	v_lshl_add_u64 v[60:61], v[60:61], 0, s[8:9]
	s_nop 0
	v_addc_co_u32_e32 v57, vcc, 0, v63, vcc
	v_add_co_u32_e32 v62, vcc, 0x5000, v62
	v_lshl_add_u64 v[60:61], v[60:61], 0, v[114:115]
	s_nop 0
	v_addc_co_u32_e32 v63, vcc, 0, v63, vcc
	v_add_co_u32_e32 v64, vcc, 0x6000, v60
	global_load_dwordx4 v[44:47], v[46:47], off offset:32
	s_nop 0
	global_load_dwordx4 v[48:51], v[48:49], off offset:32
	s_nop 0
	global_load_dword v133, v[58:59], off offset:32
	s_nop 0
	global_load_dwordx4 v[56:59], v[56:57], off offset:32
	v_addc_co_u32_e32 v65, vcc, 0, v61, vcc
	global_load_dwordx4 v[60:63], v[62:63], off offset:32
	s_nop 0
	global_load_dword v135, v[64:65], off offset:32
.LBB0_1393:
	ds_read2st64_b32 v[64:65], v134 offset0:144 offset1:148
	v_add_u32_e32 v66, 32, v98
	v_ashrrev_i32_e32 v67, 31, v66
	v_lshlrev_b64 v[66:67], 12, v[66:67]
	v_lshl_add_u64 v[66:67], v[108:109], 0, v[66:67]
	s_waitcnt lgkmcnt(0)
	global_store_dword v[66:67], v64, off
	v_add_u32_e32 v66, 32, v96
	v_ashrrev_i32_e32 v67, 31, v66
	v_lshlrev_b64 v[66:67], 12, v[66:67]
	v_lshl_add_u64 v[66:67], v[108:109], 0, v[66:67]
	global_store_dword v[66:67], v65, off
	v_mov_b32_e32 v196, 0
	v_mov_b32_e32 v197, 0
	v_add_u32_e32 v194, 0x8800, v103
	v_add_u32_e32 v195, 0x8c00, v103
	ds_read2_b32 v[118:119], v194 offset0:0 offset1:16
	ds_read_b128 v[72:75], v145 offset:26624
	ds_read_b128 v[76:79], v145 offset:26880
	ds_read_b128 v[64:67], v145 offset:18432
	ds_read_b128 v[68:71], v145 offset:18688
	ds_read2_b32 v[120:121], v194 offset0:32 offset1:48
	ds_read_b128 v[88:91], v145 offset:27136
	ds_read_b128 v[92:95], v145 offset:27392
	ds_read_b128 v[80:83], v145 offset:18944
	ds_read_b128 v[84:87], v145 offset:19200
	s_waitcnt lgkmcnt(9)
	v_pk_add_f32 v[178:179], v[178:179], v[118:119] op_sel_hi:[1,0] neg_lo:[0,1] neg_hi:[0,1]
	v_pk_add_f32 v[186:187], v[186:187], v[118:119] op_sel:[0,1] op_sel_hi:[1,1] neg_lo:[0,1] neg_hi:[0,1]
	v_pk_add_f32 v[180:181], v[180:181], v[118:119] op_sel_hi:[1,0] neg_lo:[0,1] neg_hi:[0,1]
	v_pk_add_f32 v[188:189], v[188:189], v[118:119] op_sel:[0,1] op_sel_hi:[1,1] neg_lo:[0,1] neg_hi:[0,1]
	v_pk_add_f32 v[182:183], v[182:183], v[118:119] op_sel_hi:[1,0] neg_lo:[0,1] neg_hi:[0,1]
	v_pk_add_f32 v[190:191], v[190:191], v[118:119] op_sel:[0,1] op_sel_hi:[1,1] neg_lo:[0,1] neg_hi:[0,1]
	v_pk_add_f32 v[184:185], v[184:185], v[118:119] op_sel_hi:[1,0] neg_lo:[0,1] neg_hi:[0,1]
	v_pk_add_f32 v[192:193], v[192:193], v[118:119] op_sel:[0,1] op_sel_hi:[1,1] neg_lo:[0,1] neg_hi:[0,1]
	s_waitcnt lgkmcnt(8)
	v_pk_fma_f32 v[178:179], v[72:73], v[178:179], v[118:119] op_sel_hi:[1,1,0]
	v_pk_fma_f32 v[186:187], v[72:73], v[186:187], v[118:119] op_sel:[0,0,1] op_sel_hi:[1,1,1]
	v_pk_fma_f32 v[180:181], v[74:75], v[180:181], v[118:119] op_sel_hi:[1,1,0]
	v_pk_fma_f32 v[188:189], v[74:75], v[188:189], v[118:119] op_sel:[0,0,1] op_sel_hi:[1,1,1]
	s_waitcnt lgkmcnt(7)
	v_pk_fma_f32 v[182:183], v[76:77], v[182:183], v[118:119] op_sel_hi:[1,1,0]
	v_pk_fma_f32 v[190:191], v[76:77], v[190:191], v[118:119] op_sel:[0,0,1] op_sel_hi:[1,1,1]
	v_pk_fma_f32 v[184:185], v[78:79], v[184:185], v[118:119] op_sel_hi:[1,1,0]
	v_pk_fma_f32 v[192:193], v[78:79], v[192:193], v[118:119] op_sel:[0,0,1] op_sel_hi:[1,1,1]
	ds_read2_b32 v[118:119], v194 offset0:64 offset1:80
	ds_read_b128 v[72:75], v145 offset:27648
	ds_read_b128 v[76:79], v145 offset:27904
	s_waitcnt lgkmcnt(9)
	v_pk_fma_f32 v[146:147], v[64:65], v[178:179], v[196:197]
	v_pk_fma_f32 v[150:151], v[64:65], v[186:187], v[196:197]
	v_pk_fma_f32 v[148:149], v[66:67], v[180:181], v[196:197]
	v_pk_fma_f32 v[152:153], v[66:67], v[188:189], v[196:197]
	ds_read_b128 v[64:67], v145 offset:19456
	s_waitcnt lgkmcnt(9)
	v_pk_fma_f32 v[146:147], v[68:69], v[182:183], v[146:147]
	v_pk_fma_f32 v[150:151], v[68:69], v[190:191], v[150:151]
	v_pk_fma_f32 v[148:149], v[70:71], v[184:185], v[148:149]
	v_pk_fma_f32 v[152:153], v[70:71], v[192:193], v[152:153]
	ds_read_b128 v[68:71], v145 offset:19712
	v_add_f32_e32 v146, v146, v147
	v_add_f32_e32 v148, v148, v149
	v_add_f32_e32 v150, v150, v151
	v_add_f32_e32 v152, v152, v153
	v_add_f32_e32 v154, v146, v148
	v_add_f32_e32 v155, v150, v152
	s_waitcnt lgkmcnt(9)
	v_pk_add_f32 v[178:179], v[178:179], v[120:121] op_sel_hi:[1,0] neg_lo:[0,1] neg_hi:[0,1]
	v_add_f32_dpp v154, v154, v154 row_ror:8 row_mask:0xf bank_mask:0xf bound_ctrl:1
	v_pk_add_f32 v[186:187], v[186:187], v[120:121] op_sel:[0,1] op_sel_hi:[1,1] neg_lo:[0,1] neg_hi:[0,1]
	v_add_f32_dpp v155, v155, v155 row_ror:8 row_mask:0xf bank_mask:0xf bound_ctrl:1
	v_pk_add_f32 v[180:181], v[180:181], v[120:121] op_sel_hi:[1,0] neg_lo:[0,1] neg_hi:[0,1]
	v_add_f32_dpp v154, v154, v154 row_ror:4 row_mask:0xf bank_mask:0xf bound_ctrl:1
	v_pk_add_f32 v[188:189], v[188:189], v[120:121] op_sel:[0,1] op_sel_hi:[1,1] neg_lo:[0,1] neg_hi:[0,1]
	v_add_f32_dpp v155, v155, v155 row_ror:4 row_mask:0xf bank_mask:0xf bound_ctrl:1
	v_pk_add_f32 v[182:183], v[182:183], v[120:121] op_sel_hi:[1,0] neg_lo:[0,1] neg_hi:[0,1]
	v_add_f32_dpp v154, v154, v154 row_ror:2 row_mask:0xf bank_mask:0xf bound_ctrl:1
	v_pk_add_f32 v[190:191], v[190:191], v[120:121] op_sel:[0,1] op_sel_hi:[1,1] neg_lo:[0,1] neg_hi:[0,1]
	v_add_f32_dpp v155, v155, v155 row_ror:2 row_mask:0xf bank_mask:0xf bound_ctrl:1
	v_pk_add_f32 v[184:185], v[184:185], v[120:121] op_sel_hi:[1,0] neg_lo:[0,1] neg_hi:[0,1]
	v_add_f32_dpp v154, v154, v154 row_ror:1 row_mask:0xf bank_mask:0xf bound_ctrl:1
	v_pk_add_f32 v[192:193], v[192:193], v[120:121] op_sel:[0,1] op_sel_hi:[1,1] neg_lo:[0,1] neg_hi:[0,1]
	v_add_f32_dpp v155, v155, v155 row_ror:1 row_mask:0xf bank_mask:0xf bound_ctrl:1
	s_waitcnt lgkmcnt(8)
	v_pk_fma_f32 v[178:179], v[88:89], v[178:179], v[120:121] op_sel_hi:[1,1,0]
	s_and_saveexec_b64 s[8:9], s[38:39]
	ds_write_b32 v103, v154 offset:38912
	ds_write_b32 v103, v155 offset:38976
	s_mov_b64 exec, s[8:9]
	v_pk_fma_f32 v[186:187], v[88:89], v[186:187], v[120:121] op_sel:[0,0,1] op_sel_hi:[1,1,1]
	v_pk_fma_f32 v[180:181], v[90:91], v[180:181], v[120:121] op_sel_hi:[1,1,0]
	v_pk_fma_f32 v[188:189], v[90:91], v[188:189], v[120:121] op_sel:[0,0,1] op_sel_hi:[1,1,1]
	s_waitcnt lgkmcnt(9)
	v_pk_fma_f32 v[182:183], v[92:93], v[182:183], v[120:121] op_sel_hi:[1,1,0]
	v_pk_fma_f32 v[190:191], v[92:93], v[190:191], v[120:121] op_sel:[0,0,1] op_sel_hi:[1,1,1]
	v_pk_fma_f32 v[184:185], v[94:95], v[184:185], v[120:121] op_sel_hi:[1,1,0]
	v_pk_fma_f32 v[192:193], v[94:95], v[192:193], v[120:121] op_sel:[0,0,1] op_sel_hi:[1,1,1]
	ds_read2_b32 v[120:121], v194 offset0:96 offset1:112
	ds_read_b128 v[88:91], v145 offset:28160
	ds_read_b128 v[92:95], v145 offset:28416
	s_waitcnt lgkmcnt(11)
	v_pk_fma_f32 v[146:147], v[80:81], v[178:179], v[196:197]
	v_pk_fma_f32 v[150:151], v[80:81], v[186:187], v[196:197]
	v_pk_fma_f32 v[148:149], v[82:83], v[180:181], v[196:197]
	v_pk_fma_f32 v[152:153], v[82:83], v[188:189], v[196:197]
	ds_read_b128 v[80:83], v145 offset:19968
	s_waitcnt lgkmcnt(11)
	v_pk_fma_f32 v[146:147], v[84:85], v[182:183], v[146:147]
	v_pk_fma_f32 v[150:151], v[84:85], v[190:191], v[150:151]
	v_pk_fma_f32 v[148:149], v[86:87], v[184:185], v[148:149]
	v_pk_fma_f32 v[152:153], v[86:87], v[192:193], v[152:153]
	ds_read_b128 v[84:87], v145 offset:20224
	v_add_f32_e32 v146, v146, v147
	v_add_f32_e32 v148, v148, v149
	v_add_f32_e32 v150, v150, v151
	v_add_f32_e32 v152, v152, v153
	v_add_f32_e32 v156, v146, v148
	v_add_f32_e32 v157, v150, v152
	s_waitcnt lgkmcnt(11)
	v_pk_add_f32 v[178:179], v[178:179], v[118:119] op_sel_hi:[1,0] neg_lo:[0,1] neg_hi:[0,1]
	v_add_f32_dpp v156, v156, v156 row_ror:8 row_mask:0xf bank_mask:0xf bound_ctrl:1
	v_pk_add_f32 v[186:187], v[186:187], v[118:119] op_sel:[0,1] op_sel_hi:[1,1] neg_lo:[0,1] neg_hi:[0,1]
	v_add_f32_dpp v157, v157, v157 row_ror:8 row_mask:0xf bank_mask:0xf bound_ctrl:1
	v_pk_add_f32 v[180:181], v[180:181], v[118:119] op_sel_hi:[1,0] neg_lo:[0,1] neg_hi:[0,1]
	v_add_f32_dpp v156, v156, v156 row_ror:4 row_mask:0xf bank_mask:0xf bound_ctrl:1
	v_pk_add_f32 v[188:189], v[188:189], v[118:119] op_sel:[0,1] op_sel_hi:[1,1] neg_lo:[0,1] neg_hi:[0,1]
	v_add_f32_dpp v157, v157, v157 row_ror:4 row_mask:0xf bank_mask:0xf bound_ctrl:1
	v_pk_add_f32 v[182:183], v[182:183], v[118:119] op_sel_hi:[1,0] neg_lo:[0,1] neg_hi:[0,1]
	v_add_f32_dpp v156, v156, v156 row_ror:2 row_mask:0xf bank_mask:0xf bound_ctrl:1
	v_pk_add_f32 v[190:191], v[190:191], v[118:119] op_sel:[0,1] op_sel_hi:[1,1] neg_lo:[0,1] neg_hi:[0,1]
	v_add_f32_dpp v157, v157, v157 row_ror:2 row_mask:0xf bank_mask:0xf bound_ctrl:1
	v_pk_add_f32 v[184:185], v[184:185], v[118:119] op_sel_hi:[1,0] neg_lo:[0,1] neg_hi:[0,1]
	v_add_f32_dpp v156, v156, v156 row_ror:1 row_mask:0xf bank_mask:0xf bound_ctrl:1
	v_pk_add_f32 v[192:193], v[192:193], v[118:119] op_sel:[0,1] op_sel_hi:[1,1] neg_lo:[0,1] neg_hi:[0,1]
	v_add_f32_dpp v157, v157, v157 row_ror:1 row_mask:0xf bank_mask:0xf bound_ctrl:1
	s_waitcnt lgkmcnt(10)
	v_pk_fma_f32 v[178:179], v[72:73], v[178:179], v[118:119] op_sel_hi:[1,1,0]
	s_and_saveexec_b64 s[8:9], s[38:39]
	ds_write_b32 v103, v156 offset:39040
	ds_write_b32 v103, v157 offset:39104
	s_mov_b64 exec, s[8:9]
	v_pk_fma_f32 v[186:187], v[72:73], v[186:187], v[118:119] op_sel:[0,0,1] op_sel_hi:[1,1,1]
	v_pk_fma_f32 v[180:181], v[74:75], v[180:181], v[118:119] op_sel_hi:[1,1,0]
	v_pk_fma_f32 v[188:189], v[74:75], v[188:189], v[118:119] op_sel:[0,0,1] op_sel_hi:[1,1,1]
	s_waitcnt lgkmcnt(11)
	v_pk_fma_f32 v[182:183], v[76:77], v[182:183], v[118:119] op_sel_hi:[1,1,0]
	v_pk_fma_f32 v[190:191], v[76:77], v[190:191], v[118:119] op_sel:[0,0,1] op_sel_hi:[1,1,1]
	v_pk_fma_f32 v[184:185], v[78:79], v[184:185], v[118:119] op_sel_hi:[1,1,0]
	v_pk_fma_f32 v[192:193], v[78:79], v[192:193], v[118:119] op_sel:[0,0,1] op_sel_hi:[1,1,1]
	ds_read2_b32 v[118:119], v194 offset0:128 offset1:144
	ds_read_b128 v[72:75], v145 offset:28672
	ds_read_b128 v[76:79], v145 offset:28928
	s_waitcnt lgkmcnt(13)
	v_pk_fma_f32 v[146:147], v[64:65], v[178:179], v[196:197]
	v_pk_fma_f32 v[150:151], v[64:65], v[186:187], v[196:197]
	v_pk_fma_f32 v[148:149], v[66:67], v[180:181], v[196:197]
	v_pk_fma_f32 v[152:153], v[66:67], v[188:189], v[196:197]
	ds_read_b128 v[64:67], v145 offset:20480
	s_waitcnt lgkmcnt(13)
	v_pk_fma_f32 v[146:147], v[68:69], v[182:183], v[146:147]
	v_pk_fma_f32 v[150:151], v[68:69], v[190:191], v[150:151]
	v_pk_fma_f32 v[148:149], v[70:71], v[184:185], v[148:149]
	v_pk_fma_f32 v[152:153], v[70:71], v[192:193], v[152:153]
	ds_read_b128 v[68:71], v145 offset:20736
	v_add_f32_e32 v146, v146, v147
	v_add_f32_e32 v148, v148, v149
	v_add_f32_e32 v150, v150, v151
	v_add_f32_e32 v152, v152, v153
	v_add_f32_e32 v154, v146, v148
	v_add_f32_e32 v155, v150, v152
	s_waitcnt lgkmcnt(11)
	v_pk_add_f32 v[178:179], v[178:179], v[120:121] op_sel_hi:[1,0] neg_lo:[0,1] neg_hi:[0,1]
	v_add_f32_dpp v154, v154, v154 row_ror:8 row_mask:0xf bank_mask:0xf bound_ctrl:1
	v_pk_add_f32 v[186:187], v[186:187], v[120:121] op_sel:[0,1] op_sel_hi:[1,1] neg_lo:[0,1] neg_hi:[0,1]
	v_add_f32_dpp v155, v155, v155 row_ror:8 row_mask:0xf bank_mask:0xf bound_ctrl:1
	v_pk_add_f32 v[180:181], v[180:181], v[120:121] op_sel_hi:[1,0] neg_lo:[0,1] neg_hi:[0,1]
	v_add_f32_dpp v154, v154, v154 row_ror:4 row_mask:0xf bank_mask:0xf bound_ctrl:1
	v_pk_add_f32 v[188:189], v[188:189], v[120:121] op_sel:[0,1] op_sel_hi:[1,1] neg_lo:[0,1] neg_hi:[0,1]
	v_add_f32_dpp v155, v155, v155 row_ror:4 row_mask:0xf bank_mask:0xf bound_ctrl:1
	v_pk_add_f32 v[182:183], v[182:183], v[120:121] op_sel_hi:[1,0] neg_lo:[0,1] neg_hi:[0,1]
	v_add_f32_dpp v154, v154, v154 row_ror:2 row_mask:0xf bank_mask:0xf bound_ctrl:1
	v_pk_add_f32 v[190:191], v[190:191], v[120:121] op_sel:[0,1] op_sel_hi:[1,1] neg_lo:[0,1] neg_hi:[0,1]
	v_add_f32_dpp v155, v155, v155 row_ror:2 row_mask:0xf bank_mask:0xf bound_ctrl:1
	v_pk_add_f32 v[184:185], v[184:185], v[120:121] op_sel_hi:[1,0] neg_lo:[0,1] neg_hi:[0,1]
	v_add_f32_dpp v154, v154, v154 row_ror:1 row_mask:0xf bank_mask:0xf bound_ctrl:1
	v_pk_add_f32 v[192:193], v[192:193], v[120:121] op_sel:[0,1] op_sel_hi:[1,1] neg_lo:[0,1] neg_hi:[0,1]
	v_add_f32_dpp v155, v155, v155 row_ror:1 row_mask:0xf bank_mask:0xf bound_ctrl:1
	s_waitcnt lgkmcnt(10)
	v_pk_fma_f32 v[178:179], v[88:89], v[178:179], v[120:121] op_sel_hi:[1,1,0]
	s_and_saveexec_b64 s[8:9], s[38:39]
	ds_write_b32 v103, v154 offset:39168
	ds_write_b32 v103, v155 offset:39232
	s_mov_b64 exec, s[8:9]
	v_pk_fma_f32 v[186:187], v[88:89], v[186:187], v[120:121] op_sel:[0,0,1] op_sel_hi:[1,1,1]
	v_pk_fma_f32 v[180:181], v[90:91], v[180:181], v[120:121] op_sel_hi:[1,1,0]
	v_pk_fma_f32 v[188:189], v[90:91], v[188:189], v[120:121] op_sel:[0,0,1] op_sel_hi:[1,1,1]
	s_waitcnt lgkmcnt(11)
	v_pk_fma_f32 v[182:183], v[92:93], v[182:183], v[120:121] op_sel_hi:[1,1,0]
	v_pk_fma_f32 v[190:191], v[92:93], v[190:191], v[120:121] op_sel:[0,0,1] op_sel_hi:[1,1,1]
	v_pk_fma_f32 v[184:185], v[94:95], v[184:185], v[120:121] op_sel_hi:[1,1,0]
	v_pk_fma_f32 v[192:193], v[94:95], v[192:193], v[120:121] op_sel:[0,0,1] op_sel_hi:[1,1,1]
	ds_read2_b32 v[120:121], v194 offset0:160 offset1:176
	ds_read_b128 v[88:91], v145 offset:29184
	ds_read_b128 v[92:95], v145 offset:29440
	s_waitcnt lgkmcnt(13)
	v_pk_fma_f32 v[146:147], v[80:81], v[178:179], v[196:197]
	v_pk_fma_f32 v[150:151], v[80:81], v[186:187], v[196:197]
	v_pk_fma_f32 v[148:149], v[82:83], v[180:181], v[196:197]
	v_pk_fma_f32 v[152:153], v[82:83], v[188:189], v[196:197]
	ds_read_b128 v[80:83], v145 offset:20992
	s_waitcnt lgkmcnt(13)
	v_pk_fma_f32 v[146:147], v[84:85], v[182:183], v[146:147]
	v_pk_fma_f32 v[150:151], v[84:85], v[190:191], v[150:151]
	v_pk_fma_f32 v[148:149], v[86:87], v[184:185], v[148:149]
	v_pk_fma_f32 v[152:153], v[86:87], v[192:193], v[152:153]
	ds_read_b128 v[84:87], v145 offset:21248
	v_add_f32_e32 v146, v146, v147
	v_add_f32_e32 v148, v148, v149
	v_add_f32_e32 v150, v150, v151
	v_add_f32_e32 v152, v152, v153
	v_add_f32_e32 v156, v146, v148
	v_add_f32_e32 v157, v150, v152
	s_waitcnt lgkmcnt(11)
	v_pk_add_f32 v[178:179], v[178:179], v[118:119] op_sel_hi:[1,0] neg_lo:[0,1] neg_hi:[0,1]
	v_add_f32_dpp v156, v156, v156 row_ror:8 row_mask:0xf bank_mask:0xf bound_ctrl:1
	v_pk_add_f32 v[186:187], v[186:187], v[118:119] op_sel:[0,1] op_sel_hi:[1,1] neg_lo:[0,1] neg_hi:[0,1]
	v_add_f32_dpp v157, v157, v157 row_ror:8 row_mask:0xf bank_mask:0xf bound_ctrl:1
	v_pk_add_f32 v[180:181], v[180:181], v[118:119] op_sel_hi:[1,0] neg_lo:[0,1] neg_hi:[0,1]
	v_add_f32_dpp v156, v156, v156 row_ror:4 row_mask:0xf bank_mask:0xf bound_ctrl:1
	v_pk_add_f32 v[188:189], v[188:189], v[118:119] op_sel:[0,1] op_sel_hi:[1,1] neg_lo:[0,1] neg_hi:[0,1]
	v_add_f32_dpp v157, v157, v157 row_ror:4 row_mask:0xf bank_mask:0xf bound_ctrl:1
	v_pk_add_f32 v[182:183], v[182:183], v[118:119] op_sel_hi:[1,0] neg_lo:[0,1] neg_hi:[0,1]
	v_add_f32_dpp v156, v156, v156 row_ror:2 row_mask:0xf bank_mask:0xf bound_ctrl:1
	v_pk_add_f32 v[190:191], v[190:191], v[118:119] op_sel:[0,1] op_sel_hi:[1,1] neg_lo:[0,1] neg_hi:[0,1]
	v_add_f32_dpp v157, v157, v157 row_ror:2 row_mask:0xf bank_mask:0xf bound_ctrl:1
	v_pk_add_f32 v[184:185], v[184:185], v[118:119] op_sel_hi:[1,0] neg_lo:[0,1] neg_hi:[0,1]
	v_add_f32_dpp v156, v156, v156 row_ror:1 row_mask:0xf bank_mask:0xf bound_ctrl:1
	v_pk_add_f32 v[192:193], v[192:193], v[118:119] op_sel:[0,1] op_sel_hi:[1,1] neg_lo:[0,1] neg_hi:[0,1]
	v_add_f32_dpp v157, v157, v157 row_ror:1 row_mask:0xf bank_mask:0xf bound_ctrl:1
	s_waitcnt lgkmcnt(10)
	v_pk_fma_f32 v[178:179], v[72:73], v[178:179], v[118:119] op_sel_hi:[1,1,0]
	s_and_saveexec_b64 s[8:9], s[38:39]
	ds_write_b32 v103, v156 offset:39296
	ds_write_b32 v103, v157 offset:39360
	s_mov_b64 exec, s[8:9]
	v_pk_fma_f32 v[186:187], v[72:73], v[186:187], v[118:119] op_sel:[0,0,1] op_sel_hi:[1,1,1]
	v_pk_fma_f32 v[180:181], v[74:75], v[180:181], v[118:119] op_sel_hi:[1,1,0]
	v_pk_fma_f32 v[188:189], v[74:75], v[188:189], v[118:119] op_sel:[0,0,1] op_sel_hi:[1,1,1]
	s_waitcnt lgkmcnt(11)
	v_pk_fma_f32 v[182:183], v[76:77], v[182:183], v[118:119] op_sel_hi:[1,1,0]
	v_pk_fma_f32 v[190:191], v[76:77], v[190:191], v[118:119] op_sel:[0,0,1] op_sel_hi:[1,1,1]
	v_pk_fma_f32 v[184:185], v[78:79], v[184:185], v[118:119] op_sel_hi:[1,1,0]
	v_pk_fma_f32 v[192:193], v[78:79], v[192:193], v[118:119] op_sel:[0,0,1] op_sel_hi:[1,1,1]
	ds_read2_b32 v[118:119], v194 offset0:192 offset1:208
	ds_read_b128 v[72:75], v145 offset:29696
	ds_read_b128 v[76:79], v145 offset:29952
	s_waitcnt lgkmcnt(13)
	v_pk_fma_f32 v[146:147], v[64:65], v[178:179], v[196:197]
	v_pk_fma_f32 v[150:151], v[64:65], v[186:187], v[196:197]
	v_pk_fma_f32 v[148:149], v[66:67], v[180:181], v[196:197]
	v_pk_fma_f32 v[152:153], v[66:67], v[188:189], v[196:197]
	ds_read_b128 v[64:67], v145 offset:21504
	s_waitcnt lgkmcnt(13)
	v_pk_fma_f32 v[146:147], v[68:69], v[182:183], v[146:147]
	v_pk_fma_f32 v[150:151], v[68:69], v[190:191], v[150:151]
	v_pk_fma_f32 v[148:149], v[70:71], v[184:185], v[148:149]
	v_pk_fma_f32 v[152:153], v[70:71], v[192:193], v[152:153]
	ds_read_b128 v[68:71], v145 offset:21760
	v_add_f32_e32 v146, v146, v147
	v_add_f32_e32 v148, v148, v149
	v_add_f32_e32 v150, v150, v151
	v_add_f32_e32 v152, v152, v153
	v_add_f32_e32 v154, v146, v148
	v_add_f32_e32 v155, v150, v152
	s_waitcnt lgkmcnt(11)
	v_pk_add_f32 v[178:179], v[178:179], v[120:121] op_sel_hi:[1,0] neg_lo:[0,1] neg_hi:[0,1]
	v_add_f32_dpp v154, v154, v154 row_ror:8 row_mask:0xf bank_mask:0xf bound_ctrl:1
	v_pk_add_f32 v[186:187], v[186:187], v[120:121] op_sel:[0,1] op_sel_hi:[1,1] neg_lo:[0,1] neg_hi:[0,1]
	v_add_f32_dpp v155, v155, v155 row_ror:8 row_mask:0xf bank_mask:0xf bound_ctrl:1
	v_pk_add_f32 v[180:181], v[180:181], v[120:121] op_sel_hi:[1,0] neg_lo:[0,1] neg_hi:[0,1]
	v_add_f32_dpp v154, v154, v154 row_ror:4 row_mask:0xf bank_mask:0xf bound_ctrl:1
	v_pk_add_f32 v[188:189], v[188:189], v[120:121] op_sel:[0,1] op_sel_hi:[1,1] neg_lo:[0,1] neg_hi:[0,1]
	v_add_f32_dpp v155, v155, v155 row_ror:4 row_mask:0xf bank_mask:0xf bound_ctrl:1
	v_pk_add_f32 v[182:183], v[182:183], v[120:121] op_sel_hi:[1,0] neg_lo:[0,1] neg_hi:[0,1]
	v_add_f32_dpp v154, v154, v154 row_ror:2 row_mask:0xf bank_mask:0xf bound_ctrl:1
	v_pk_add_f32 v[190:191], v[190:191], v[120:121] op_sel:[0,1] op_sel_hi:[1,1] neg_lo:[0,1] neg_hi:[0,1]
	v_add_f32_dpp v155, v155, v155 row_ror:2 row_mask:0xf bank_mask:0xf bound_ctrl:1
	v_pk_add_f32 v[184:185], v[184:185], v[120:121] op_sel_hi:[1,0] neg_lo:[0,1] neg_hi:[0,1]
	v_add_f32_dpp v154, v154, v154 row_ror:1 row_mask:0xf bank_mask:0xf bound_ctrl:1
	v_pk_add_f32 v[192:193], v[192:193], v[120:121] op_sel:[0,1] op_sel_hi:[1,1] neg_lo:[0,1] neg_hi:[0,1]
	v_add_f32_dpp v155, v155, v155 row_ror:1 row_mask:0xf bank_mask:0xf bound_ctrl:1
	s_waitcnt lgkmcnt(10)
	v_pk_fma_f32 v[178:179], v[88:89], v[178:179], v[120:121] op_sel_hi:[1,1,0]
	s_and_saveexec_b64 s[8:9], s[38:39]
	ds_write_b32 v103, v154 offset:39424
	ds_write_b32 v103, v155 offset:39488
	s_mov_b64 exec, s[8:9]
	v_pk_fma_f32 v[186:187], v[88:89], v[186:187], v[120:121] op_sel:[0,0,1] op_sel_hi:[1,1,1]
	v_pk_fma_f32 v[180:181], v[90:91], v[180:181], v[120:121] op_sel_hi:[1,1,0]
	v_pk_fma_f32 v[188:189], v[90:91], v[188:189], v[120:121] op_sel:[0,0,1] op_sel_hi:[1,1,1]
	s_waitcnt lgkmcnt(11)
	v_pk_fma_f32 v[182:183], v[92:93], v[182:183], v[120:121] op_sel_hi:[1,1,0]
	v_pk_fma_f32 v[190:191], v[92:93], v[190:191], v[120:121] op_sel:[0,0,1] op_sel_hi:[1,1,1]
	v_pk_fma_f32 v[184:185], v[94:95], v[184:185], v[120:121] op_sel_hi:[1,1,0]
	v_pk_fma_f32 v[192:193], v[94:95], v[192:193], v[120:121] op_sel:[0,0,1] op_sel_hi:[1,1,1]
	ds_read2_b32 v[120:121], v194 offset0:224 offset1:240
	ds_read_b128 v[88:91], v145 offset:30208
	ds_read_b128 v[92:95], v145 offset:30464
	s_waitcnt lgkmcnt(13)
	v_pk_fma_f32 v[146:147], v[80:81], v[178:179], v[196:197]
	v_pk_fma_f32 v[150:151], v[80:81], v[186:187], v[196:197]
	v_pk_fma_f32 v[148:149], v[82:83], v[180:181], v[196:197]
	v_pk_fma_f32 v[152:153], v[82:83], v[188:189], v[196:197]
	ds_read_b128 v[80:83], v145 offset:22016
	s_waitcnt lgkmcnt(13)
	v_pk_fma_f32 v[146:147], v[84:85], v[182:183], v[146:147]
	v_pk_fma_f32 v[150:151], v[84:85], v[190:191], v[150:151]
	v_pk_fma_f32 v[148:149], v[86:87], v[184:185], v[148:149]
	v_pk_fma_f32 v[152:153], v[86:87], v[192:193], v[152:153]
	ds_read_b128 v[84:87], v145 offset:22272
	v_add_f32_e32 v146, v146, v147
	v_add_f32_e32 v148, v148, v149
	v_add_f32_e32 v150, v150, v151
	v_add_f32_e32 v152, v152, v153
	v_add_f32_e32 v156, v146, v148
	v_add_f32_e32 v157, v150, v152
	s_waitcnt lgkmcnt(11)
	v_pk_add_f32 v[178:179], v[178:179], v[118:119] op_sel_hi:[1,0] neg_lo:[0,1] neg_hi:[0,1]
	v_add_f32_dpp v156, v156, v156 row_ror:8 row_mask:0xf bank_mask:0xf bound_ctrl:1
	v_pk_add_f32 v[186:187], v[186:187], v[118:119] op_sel:[0,1] op_sel_hi:[1,1] neg_lo:[0,1] neg_hi:[0,1]
	v_add_f32_dpp v157, v157, v157 row_ror:8 row_mask:0xf bank_mask:0xf bound_ctrl:1
	v_pk_add_f32 v[180:181], v[180:181], v[118:119] op_sel_hi:[1,0] neg_lo:[0,1] neg_hi:[0,1]
	v_add_f32_dpp v156, v156, v156 row_ror:4 row_mask:0xf bank_mask:0xf bound_ctrl:1
	v_pk_add_f32 v[188:189], v[188:189], v[118:119] op_sel:[0,1] op_sel_hi:[1,1] neg_lo:[0,1] neg_hi:[0,1]
	v_add_f32_dpp v157, v157, v157 row_ror:4 row_mask:0xf bank_mask:0xf bound_ctrl:1
	v_pk_add_f32 v[182:183], v[182:183], v[118:119] op_sel_hi:[1,0] neg_lo:[0,1] neg_hi:[0,1]
	v_add_f32_dpp v156, v156, v156 row_ror:2 row_mask:0xf bank_mask:0xf bound_ctrl:1
	v_pk_add_f32 v[190:191], v[190:191], v[118:119] op_sel:[0,1] op_sel_hi:[1,1] neg_lo:[0,1] neg_hi:[0,1]
	v_add_f32_dpp v157, v157, v157 row_ror:2 row_mask:0xf bank_mask:0xf bound_ctrl:1
	v_pk_add_f32 v[184:185], v[184:185], v[118:119] op_sel_hi:[1,0] neg_lo:[0,1] neg_hi:[0,1]
	v_add_f32_dpp v156, v156, v156 row_ror:1 row_mask:0xf bank_mask:0xf bound_ctrl:1
	v_pk_add_f32 v[192:193], v[192:193], v[118:119] op_sel:[0,1] op_sel_hi:[1,1] neg_lo:[0,1] neg_hi:[0,1]
	v_add_f32_dpp v157, v157, v157 row_ror:1 row_mask:0xf bank_mask:0xf bound_ctrl:1
	s_waitcnt lgkmcnt(10)
	v_pk_fma_f32 v[178:179], v[72:73], v[178:179], v[118:119] op_sel_hi:[1,1,0]
	s_and_saveexec_b64 s[8:9], s[38:39]
	ds_write_b32 v103, v156 offset:39552
	ds_write_b32 v103, v157 offset:39616
	s_mov_b64 exec, s[8:9]
	v_pk_fma_f32 v[186:187], v[72:73], v[186:187], v[118:119] op_sel:[0,0,1] op_sel_hi:[1,1,1]
	v_pk_fma_f32 v[180:181], v[74:75], v[180:181], v[118:119] op_sel_hi:[1,1,0]
	v_pk_fma_f32 v[188:189], v[74:75], v[188:189], v[118:119] op_sel:[0,0,1] op_sel_hi:[1,1,1]
	s_waitcnt lgkmcnt(11)
	v_pk_fma_f32 v[182:183], v[76:77], v[182:183], v[118:119] op_sel_hi:[1,1,0]
	v_pk_fma_f32 v[190:191], v[76:77], v[190:191], v[118:119] op_sel:[0,0,1] op_sel_hi:[1,1,1]
	v_pk_fma_f32 v[184:185], v[78:79], v[184:185], v[118:119] op_sel_hi:[1,1,0]
	v_pk_fma_f32 v[192:193], v[78:79], v[192:193], v[118:119] op_sel:[0,0,1] op_sel_hi:[1,1,1]
	ds_read2_b32 v[118:119], v195 offset0:0 offset1:16
	ds_read_b128 v[72:75], v145 offset:30720
	ds_read_b128 v[76:79], v145 offset:30976
	s_waitcnt lgkmcnt(13)
	v_pk_fma_f32 v[146:147], v[64:65], v[178:179], v[196:197]
	v_pk_fma_f32 v[150:151], v[64:65], v[186:187], v[196:197]
	v_pk_fma_f32 v[148:149], v[66:67], v[180:181], v[196:197]
	v_pk_fma_f32 v[152:153], v[66:67], v[188:189], v[196:197]
	ds_read_b128 v[64:67], v145 offset:22528
	s_waitcnt lgkmcnt(13)
	v_pk_fma_f32 v[146:147], v[68:69], v[182:183], v[146:147]
	v_pk_fma_f32 v[150:151], v[68:69], v[190:191], v[150:151]
	v_pk_fma_f32 v[148:149], v[70:71], v[184:185], v[148:149]
	v_pk_fma_f32 v[152:153], v[70:71], v[192:193], v[152:153]
	ds_read_b128 v[68:71], v145 offset:22784
	v_add_f32_e32 v146, v146, v147
	v_add_f32_e32 v148, v148, v149
	v_add_f32_e32 v150, v150, v151
	v_add_f32_e32 v152, v152, v153
	v_add_f32_e32 v154, v146, v148
	v_add_f32_e32 v155, v150, v152
	s_waitcnt lgkmcnt(11)
	v_pk_add_f32 v[178:179], v[178:179], v[120:121] op_sel_hi:[1,0] neg_lo:[0,1] neg_hi:[0,1]
	v_add_f32_dpp v154, v154, v154 row_ror:8 row_mask:0xf bank_mask:0xf bound_ctrl:1
	v_pk_add_f32 v[186:187], v[186:187], v[120:121] op_sel:[0,1] op_sel_hi:[1,1] neg_lo:[0,1] neg_hi:[0,1]
	v_add_f32_dpp v155, v155, v155 row_ror:8 row_mask:0xf bank_mask:0xf bound_ctrl:1
	v_pk_add_f32 v[180:181], v[180:181], v[120:121] op_sel_hi:[1,0] neg_lo:[0,1] neg_hi:[0,1]
	v_add_f32_dpp v154, v154, v154 row_ror:4 row_mask:0xf bank_mask:0xf bound_ctrl:1
	v_pk_add_f32 v[188:189], v[188:189], v[120:121] op_sel:[0,1] op_sel_hi:[1,1] neg_lo:[0,1] neg_hi:[0,1]
	v_add_f32_dpp v155, v155, v155 row_ror:4 row_mask:0xf bank_mask:0xf bound_ctrl:1
	v_pk_add_f32 v[182:183], v[182:183], v[120:121] op_sel_hi:[1,0] neg_lo:[0,1] neg_hi:[0,1]
	v_add_f32_dpp v154, v154, v154 row_ror:2 row_mask:0xf bank_mask:0xf bound_ctrl:1
	v_pk_add_f32 v[190:191], v[190:191], v[120:121] op_sel:[0,1] op_sel_hi:[1,1] neg_lo:[0,1] neg_hi:[0,1]
	v_add_f32_dpp v155, v155, v155 row_ror:2 row_mask:0xf bank_mask:0xf bound_ctrl:1
	v_pk_add_f32 v[184:185], v[184:185], v[120:121] op_sel_hi:[1,0] neg_lo:[0,1] neg_hi:[0,1]
	v_add_f32_dpp v154, v154, v154 row_ror:1 row_mask:0xf bank_mask:0xf bound_ctrl:1
	v_pk_add_f32 v[192:193], v[192:193], v[120:121] op_sel:[0,1] op_sel_hi:[1,1] neg_lo:[0,1] neg_hi:[0,1]
	v_add_f32_dpp v155, v155, v155 row_ror:1 row_mask:0xf bank_mask:0xf bound_ctrl:1
	s_waitcnt lgkmcnt(10)
	v_pk_fma_f32 v[178:179], v[88:89], v[178:179], v[120:121] op_sel_hi:[1,1,0]
	s_and_saveexec_b64 s[8:9], s[38:39]
	ds_write_b32 v103, v154 offset:39680
	ds_write_b32 v103, v155 offset:39744
	s_mov_b64 exec, s[8:9]
	v_pk_fma_f32 v[186:187], v[88:89], v[186:187], v[120:121] op_sel:[0,0,1] op_sel_hi:[1,1,1]
	v_pk_fma_f32 v[180:181], v[90:91], v[180:181], v[120:121] op_sel_hi:[1,1,0]
	v_pk_fma_f32 v[188:189], v[90:91], v[188:189], v[120:121] op_sel:[0,0,1] op_sel_hi:[1,1,1]
	s_waitcnt lgkmcnt(11)
	v_pk_fma_f32 v[182:183], v[92:93], v[182:183], v[120:121] op_sel_hi:[1,1,0]
	v_pk_fma_f32 v[190:191], v[92:93], v[190:191], v[120:121] op_sel:[0,0,1] op_sel_hi:[1,1,1]
	v_pk_fma_f32 v[184:185], v[94:95], v[184:185], v[120:121] op_sel_hi:[1,1,0]
	v_pk_fma_f32 v[192:193], v[94:95], v[192:193], v[120:121] op_sel:[0,0,1] op_sel_hi:[1,1,1]
	ds_read2_b32 v[120:121], v195 offset0:32 offset1:48
	ds_read_b128 v[88:91], v145 offset:31232
	ds_read_b128 v[92:95], v145 offset:31488
	s_waitcnt lgkmcnt(13)
	v_pk_fma_f32 v[146:147], v[80:81], v[178:179], v[196:197]
	v_pk_fma_f32 v[150:151], v[80:81], v[186:187], v[196:197]
	v_pk_fma_f32 v[148:149], v[82:83], v[180:181], v[196:197]
	v_pk_fma_f32 v[152:153], v[82:83], v[188:189], v[196:197]
	ds_read_b128 v[80:83], v145 offset:23040
	s_waitcnt lgkmcnt(13)
	v_pk_fma_f32 v[146:147], v[84:85], v[182:183], v[146:147]
	v_pk_fma_f32 v[150:151], v[84:85], v[190:191], v[150:151]
	v_pk_fma_f32 v[148:149], v[86:87], v[184:185], v[148:149]
	v_pk_fma_f32 v[152:153], v[86:87], v[192:193], v[152:153]
	ds_read_b128 v[84:87], v145 offset:23296
	v_add_f32_e32 v146, v146, v147
	v_add_f32_e32 v148, v148, v149
	v_add_f32_e32 v150, v150, v151
	v_add_f32_e32 v152, v152, v153
	v_add_f32_e32 v156, v146, v148
	v_add_f32_e32 v157, v150, v152
	s_waitcnt lgkmcnt(11)
	v_pk_add_f32 v[178:179], v[178:179], v[118:119] op_sel_hi:[1,0] neg_lo:[0,1] neg_hi:[0,1]
	v_add_f32_dpp v156, v156, v156 row_ror:8 row_mask:0xf bank_mask:0xf bound_ctrl:1
	v_pk_add_f32 v[186:187], v[186:187], v[118:119] op_sel:[0,1] op_sel_hi:[1,1] neg_lo:[0,1] neg_hi:[0,1]
	v_add_f32_dpp v157, v157, v157 row_ror:8 row_mask:0xf bank_mask:0xf bound_ctrl:1
	v_pk_add_f32 v[180:181], v[180:181], v[118:119] op_sel_hi:[1,0] neg_lo:[0,1] neg_hi:[0,1]
	v_add_f32_dpp v156, v156, v156 row_ror:4 row_mask:0xf bank_mask:0xf bound_ctrl:1
	v_pk_add_f32 v[188:189], v[188:189], v[118:119] op_sel:[0,1] op_sel_hi:[1,1] neg_lo:[0,1] neg_hi:[0,1]
	v_add_f32_dpp v157, v157, v157 row_ror:4 row_mask:0xf bank_mask:0xf bound_ctrl:1
	v_pk_add_f32 v[182:183], v[182:183], v[118:119] op_sel_hi:[1,0] neg_lo:[0,1] neg_hi:[0,1]
	v_add_f32_dpp v156, v156, v156 row_ror:2 row_mask:0xf bank_mask:0xf bound_ctrl:1
	v_pk_add_f32 v[190:191], v[190:191], v[118:119] op_sel:[0,1] op_sel_hi:[1,1] neg_lo:[0,1] neg_hi:[0,1]
	v_add_f32_dpp v157, v157, v157 row_ror:2 row_mask:0xf bank_mask:0xf bound_ctrl:1
	v_pk_add_f32 v[184:185], v[184:185], v[118:119] op_sel_hi:[1,0] neg_lo:[0,1] neg_hi:[0,1]
	v_add_f32_dpp v156, v156, v156 row_ror:1 row_mask:0xf bank_mask:0xf bound_ctrl:1
	v_pk_add_f32 v[192:193], v[192:193], v[118:119] op_sel:[0,1] op_sel_hi:[1,1] neg_lo:[0,1] neg_hi:[0,1]
	v_add_f32_dpp v157, v157, v157 row_ror:1 row_mask:0xf bank_mask:0xf bound_ctrl:1
	s_waitcnt lgkmcnt(10)
	v_pk_fma_f32 v[178:179], v[72:73], v[178:179], v[118:119] op_sel_hi:[1,1,0]
	s_and_saveexec_b64 s[8:9], s[38:39]
	ds_write_b32 v103, v156 offset:39808
	ds_write_b32 v103, v157 offset:39872
	s_mov_b64 exec, s[8:9]
	v_pk_fma_f32 v[186:187], v[72:73], v[186:187], v[118:119] op_sel:[0,0,1] op_sel_hi:[1,1,1]
	v_pk_fma_f32 v[180:181], v[74:75], v[180:181], v[118:119] op_sel_hi:[1,1,0]
	v_pk_fma_f32 v[188:189], v[74:75], v[188:189], v[118:119] op_sel:[0,0,1] op_sel_hi:[1,1,1]
	s_waitcnt lgkmcnt(11)
	v_pk_fma_f32 v[182:183], v[76:77], v[182:183], v[118:119] op_sel_hi:[1,1,0]
	v_pk_fma_f32 v[190:191], v[76:77], v[190:191], v[118:119] op_sel:[0,0,1] op_sel_hi:[1,1,1]
	v_pk_fma_f32 v[184:185], v[78:79], v[184:185], v[118:119] op_sel_hi:[1,1,0]
	v_pk_fma_f32 v[192:193], v[78:79], v[192:193], v[118:119] op_sel:[0,0,1] op_sel_hi:[1,1,1]
	ds_read2_b32 v[118:119], v195 offset0:64 offset1:80
	ds_read_b128 v[72:75], v145 offset:31744
	ds_read_b128 v[76:79], v145 offset:32000
	s_waitcnt lgkmcnt(13)
	v_pk_fma_f32 v[146:147], v[64:65], v[178:179], v[196:197]
	v_pk_fma_f32 v[150:151], v[64:65], v[186:187], v[196:197]
	v_pk_fma_f32 v[148:149], v[66:67], v[180:181], v[196:197]
	v_pk_fma_f32 v[152:153], v[66:67], v[188:189], v[196:197]
	ds_read_b128 v[64:67], v145 offset:23552
	s_waitcnt lgkmcnt(13)
	v_pk_fma_f32 v[146:147], v[68:69], v[182:183], v[146:147]
	v_pk_fma_f32 v[150:151], v[68:69], v[190:191], v[150:151]
	v_pk_fma_f32 v[148:149], v[70:71], v[184:185], v[148:149]
	v_pk_fma_f32 v[152:153], v[70:71], v[192:193], v[152:153]
	ds_read_b128 v[68:71], v145 offset:23808
	v_add_f32_e32 v146, v146, v147
	v_add_f32_e32 v148, v148, v149
	v_add_f32_e32 v150, v150, v151
	v_add_f32_e32 v152, v152, v153
	v_add_f32_e32 v154, v146, v148
	v_add_f32_e32 v155, v150, v152
	s_waitcnt lgkmcnt(11)
	v_pk_add_f32 v[178:179], v[178:179], v[120:121] op_sel_hi:[1,0] neg_lo:[0,1] neg_hi:[0,1]
	v_add_f32_dpp v154, v154, v154 row_ror:8 row_mask:0xf bank_mask:0xf bound_ctrl:1
	v_pk_add_f32 v[186:187], v[186:187], v[120:121] op_sel:[0,1] op_sel_hi:[1,1] neg_lo:[0,1] neg_hi:[0,1]
	v_add_f32_dpp v155, v155, v155 row_ror:8 row_mask:0xf bank_mask:0xf bound_ctrl:1
	v_pk_add_f32 v[180:181], v[180:181], v[120:121] op_sel_hi:[1,0] neg_lo:[0,1] neg_hi:[0,1]
	v_add_f32_dpp v154, v154, v154 row_ror:4 row_mask:0xf bank_mask:0xf bound_ctrl:1
	v_pk_add_f32 v[188:189], v[188:189], v[120:121] op_sel:[0,1] op_sel_hi:[1,1] neg_lo:[0,1] neg_hi:[0,1]
	v_add_f32_dpp v155, v155, v155 row_ror:4 row_mask:0xf bank_mask:0xf bound_ctrl:1
	v_pk_add_f32 v[182:183], v[182:183], v[120:121] op_sel_hi:[1,0] neg_lo:[0,1] neg_hi:[0,1]
	v_add_f32_dpp v154, v154, v154 row_ror:2 row_mask:0xf bank_mask:0xf bound_ctrl:1
	v_pk_add_f32 v[190:191], v[190:191], v[120:121] op_sel:[0,1] op_sel_hi:[1,1] neg_lo:[0,1] neg_hi:[0,1]
	v_add_f32_dpp v155, v155, v155 row_ror:2 row_mask:0xf bank_mask:0xf bound_ctrl:1
	v_pk_add_f32 v[184:185], v[184:185], v[120:121] op_sel_hi:[1,0] neg_lo:[0,1] neg_hi:[0,1]
	v_add_f32_dpp v154, v154, v154 row_ror:1 row_mask:0xf bank_mask:0xf bound_ctrl:1
	v_pk_add_f32 v[192:193], v[192:193], v[120:121] op_sel:[0,1] op_sel_hi:[1,1] neg_lo:[0,1] neg_hi:[0,1]
	v_add_f32_dpp v155, v155, v155 row_ror:1 row_mask:0xf bank_mask:0xf bound_ctrl:1
	s_waitcnt lgkmcnt(10)
	v_pk_fma_f32 v[178:179], v[88:89], v[178:179], v[120:121] op_sel_hi:[1,1,0]
	s_and_saveexec_b64 s[8:9], s[38:39]
	ds_write_b32 v103, v154 offset:39936
	ds_write_b32 v103, v155 offset:40000
	s_mov_b64 exec, s[8:9]
	v_pk_fma_f32 v[186:187], v[88:89], v[186:187], v[120:121] op_sel:[0,0,1] op_sel_hi:[1,1,1]
	v_pk_fma_f32 v[180:181], v[90:91], v[180:181], v[120:121] op_sel_hi:[1,1,0]
	v_pk_fma_f32 v[188:189], v[90:91], v[188:189], v[120:121] op_sel:[0,0,1] op_sel_hi:[1,1,1]
	s_waitcnt lgkmcnt(11)
	v_pk_fma_f32 v[182:183], v[92:93], v[182:183], v[120:121] op_sel_hi:[1,1,0]
	v_pk_fma_f32 v[190:191], v[92:93], v[190:191], v[120:121] op_sel:[0,0,1] op_sel_hi:[1,1,1]
	v_pk_fma_f32 v[184:185], v[94:95], v[184:185], v[120:121] op_sel_hi:[1,1,0]
	v_pk_fma_f32 v[192:193], v[94:95], v[192:193], v[120:121] op_sel:[0,0,1] op_sel_hi:[1,1,1]
	ds_read2_b32 v[120:121], v195 offset0:96 offset1:112
	ds_read_b128 v[88:91], v145 offset:32256
	ds_read_b128 v[92:95], v145 offset:32512
	s_waitcnt lgkmcnt(13)
	v_pk_fma_f32 v[146:147], v[80:81], v[178:179], v[196:197]
	v_pk_fma_f32 v[150:151], v[80:81], v[186:187], v[196:197]
	v_pk_fma_f32 v[148:149], v[82:83], v[180:181], v[196:197]
	v_pk_fma_f32 v[152:153], v[82:83], v[188:189], v[196:197]
	ds_read_b128 v[80:83], v145 offset:24064
	s_waitcnt lgkmcnt(13)
	v_pk_fma_f32 v[146:147], v[84:85], v[182:183], v[146:147]
	v_pk_fma_f32 v[150:151], v[84:85], v[190:191], v[150:151]
	v_pk_fma_f32 v[148:149], v[86:87], v[184:185], v[148:149]
	v_pk_fma_f32 v[152:153], v[86:87], v[192:193], v[152:153]
	ds_read_b128 v[84:87], v145 offset:24320
	v_add_f32_e32 v146, v146, v147
	v_add_f32_e32 v148, v148, v149
	v_add_f32_e32 v150, v150, v151
	v_add_f32_e32 v152, v152, v153
	v_add_f32_e32 v156, v146, v148
	v_add_f32_e32 v157, v150, v152
	s_waitcnt lgkmcnt(11)
	v_pk_add_f32 v[178:179], v[178:179], v[118:119] op_sel_hi:[1,0] neg_lo:[0,1] neg_hi:[0,1]
	v_add_f32_dpp v156, v156, v156 row_ror:8 row_mask:0xf bank_mask:0xf bound_ctrl:1
	v_pk_add_f32 v[186:187], v[186:187], v[118:119] op_sel:[0,1] op_sel_hi:[1,1] neg_lo:[0,1] neg_hi:[0,1]
	v_add_f32_dpp v157, v157, v157 row_ror:8 row_mask:0xf bank_mask:0xf bound_ctrl:1
	v_pk_add_f32 v[180:181], v[180:181], v[118:119] op_sel_hi:[1,0] neg_lo:[0,1] neg_hi:[0,1]
	v_add_f32_dpp v156, v156, v156 row_ror:4 row_mask:0xf bank_mask:0xf bound_ctrl:1
	v_pk_add_f32 v[188:189], v[188:189], v[118:119] op_sel:[0,1] op_sel_hi:[1,1] neg_lo:[0,1] neg_hi:[0,1]
	v_add_f32_dpp v157, v157, v157 row_ror:4 row_mask:0xf bank_mask:0xf bound_ctrl:1
	v_pk_add_f32 v[182:183], v[182:183], v[118:119] op_sel_hi:[1,0] neg_lo:[0,1] neg_hi:[0,1]
	v_add_f32_dpp v156, v156, v156 row_ror:2 row_mask:0xf bank_mask:0xf bound_ctrl:1
	v_pk_add_f32 v[190:191], v[190:191], v[118:119] op_sel:[0,1] op_sel_hi:[1,1] neg_lo:[0,1] neg_hi:[0,1]
	v_add_f32_dpp v157, v157, v157 row_ror:2 row_mask:0xf bank_mask:0xf bound_ctrl:1
	v_pk_add_f32 v[184:185], v[184:185], v[118:119] op_sel_hi:[1,0] neg_lo:[0,1] neg_hi:[0,1]
	v_add_f32_dpp v156, v156, v156 row_ror:1 row_mask:0xf bank_mask:0xf bound_ctrl:1
	v_pk_add_f32 v[192:193], v[192:193], v[118:119] op_sel:[0,1] op_sel_hi:[1,1] neg_lo:[0,1] neg_hi:[0,1]
	v_add_f32_dpp v157, v157, v157 row_ror:1 row_mask:0xf bank_mask:0xf bound_ctrl:1
	s_waitcnt lgkmcnt(10)
	v_pk_fma_f32 v[178:179], v[72:73], v[178:179], v[118:119] op_sel_hi:[1,1,0]
	s_and_saveexec_b64 s[8:9], s[38:39]
	ds_write_b32 v103, v156 offset:40064
	ds_write_b32 v103, v157 offset:40128
	s_mov_b64 exec, s[8:9]
	v_pk_fma_f32 v[186:187], v[72:73], v[186:187], v[118:119] op_sel:[0,0,1] op_sel_hi:[1,1,1]
	v_pk_fma_f32 v[180:181], v[74:75], v[180:181], v[118:119] op_sel_hi:[1,1,0]
	v_pk_fma_f32 v[188:189], v[74:75], v[188:189], v[118:119] op_sel:[0,0,1] op_sel_hi:[1,1,1]
	s_waitcnt lgkmcnt(11)
	v_pk_fma_f32 v[182:183], v[76:77], v[182:183], v[118:119] op_sel_hi:[1,1,0]
	v_pk_fma_f32 v[190:191], v[76:77], v[190:191], v[118:119] op_sel:[0,0,1] op_sel_hi:[1,1,1]
	v_pk_fma_f32 v[184:185], v[78:79], v[184:185], v[118:119] op_sel_hi:[1,1,0]
	v_pk_fma_f32 v[192:193], v[78:79], v[192:193], v[118:119] op_sel:[0,0,1] op_sel_hi:[1,1,1]
	ds_read2_b32 v[118:119], v195 offset0:128 offset1:144
	ds_read_b128 v[72:75], v145 offset:32768
	ds_read_b128 v[76:79], v145 offset:33024
	s_waitcnt lgkmcnt(13)
	v_pk_fma_f32 v[146:147], v[64:65], v[178:179], v[196:197]
	v_pk_fma_f32 v[150:151], v[64:65], v[186:187], v[196:197]
	v_pk_fma_f32 v[148:149], v[66:67], v[180:181], v[196:197]
	v_pk_fma_f32 v[152:153], v[66:67], v[188:189], v[196:197]
	ds_read_b128 v[64:67], v145 offset:24576
	s_waitcnt lgkmcnt(13)
	v_pk_fma_f32 v[146:147], v[68:69], v[182:183], v[146:147]
	v_pk_fma_f32 v[150:151], v[68:69], v[190:191], v[150:151]
	v_pk_fma_f32 v[148:149], v[70:71], v[184:185], v[148:149]
	v_pk_fma_f32 v[152:153], v[70:71], v[192:193], v[152:153]
	ds_read_b128 v[68:71], v145 offset:24832
	v_add_f32_e32 v146, v146, v147
	v_add_f32_e32 v148, v148, v149
	v_add_f32_e32 v150, v150, v151
	v_add_f32_e32 v152, v152, v153
	v_add_f32_e32 v154, v146, v148
	v_add_f32_e32 v155, v150, v152
	s_waitcnt lgkmcnt(11)
	v_pk_add_f32 v[178:179], v[178:179], v[120:121] op_sel_hi:[1,0] neg_lo:[0,1] neg_hi:[0,1]
	v_add_f32_dpp v154, v154, v154 row_ror:8 row_mask:0xf bank_mask:0xf bound_ctrl:1
	v_pk_add_f32 v[186:187], v[186:187], v[120:121] op_sel:[0,1] op_sel_hi:[1,1] neg_lo:[0,1] neg_hi:[0,1]
	v_add_f32_dpp v155, v155, v155 row_ror:8 row_mask:0xf bank_mask:0xf bound_ctrl:1
	v_pk_add_f32 v[180:181], v[180:181], v[120:121] op_sel_hi:[1,0] neg_lo:[0,1] neg_hi:[0,1]
	v_add_f32_dpp v154, v154, v154 row_ror:4 row_mask:0xf bank_mask:0xf bound_ctrl:1
	v_pk_add_f32 v[188:189], v[188:189], v[120:121] op_sel:[0,1] op_sel_hi:[1,1] neg_lo:[0,1] neg_hi:[0,1]
	v_add_f32_dpp v155, v155, v155 row_ror:4 row_mask:0xf bank_mask:0xf bound_ctrl:1
	v_pk_add_f32 v[182:183], v[182:183], v[120:121] op_sel_hi:[1,0] neg_lo:[0,1] neg_hi:[0,1]
	v_add_f32_dpp v154, v154, v154 row_ror:2 row_mask:0xf bank_mask:0xf bound_ctrl:1
	v_pk_add_f32 v[190:191], v[190:191], v[120:121] op_sel:[0,1] op_sel_hi:[1,1] neg_lo:[0,1] neg_hi:[0,1]
	v_add_f32_dpp v155, v155, v155 row_ror:2 row_mask:0xf bank_mask:0xf bound_ctrl:1
	v_pk_add_f32 v[184:185], v[184:185], v[120:121] op_sel_hi:[1,0] neg_lo:[0,1] neg_hi:[0,1]
	v_add_f32_dpp v154, v154, v154 row_ror:1 row_mask:0xf bank_mask:0xf bound_ctrl:1
	v_pk_add_f32 v[192:193], v[192:193], v[120:121] op_sel:[0,1] op_sel_hi:[1,1] neg_lo:[0,1] neg_hi:[0,1]
	v_add_f32_dpp v155, v155, v155 row_ror:1 row_mask:0xf bank_mask:0xf bound_ctrl:1
	s_waitcnt lgkmcnt(10)
	v_pk_fma_f32 v[178:179], v[88:89], v[178:179], v[120:121] op_sel_hi:[1,1,0]
	s_and_saveexec_b64 s[8:9], s[38:39]
	ds_write_b32 v103, v154 offset:40192
	ds_write_b32 v103, v155 offset:40256
	s_mov_b64 exec, s[8:9]
	v_pk_fma_f32 v[186:187], v[88:89], v[186:187], v[120:121] op_sel:[0,0,1] op_sel_hi:[1,1,1]
	v_pk_fma_f32 v[180:181], v[90:91], v[180:181], v[120:121] op_sel_hi:[1,1,0]
	v_pk_fma_f32 v[188:189], v[90:91], v[188:189], v[120:121] op_sel:[0,0,1] op_sel_hi:[1,1,1]
	s_waitcnt lgkmcnt(11)
	v_pk_fma_f32 v[182:183], v[92:93], v[182:183], v[120:121] op_sel_hi:[1,1,0]
	v_pk_fma_f32 v[190:191], v[92:93], v[190:191], v[120:121] op_sel:[0,0,1] op_sel_hi:[1,1,1]
	v_pk_fma_f32 v[184:185], v[94:95], v[184:185], v[120:121] op_sel_hi:[1,1,0]
	v_pk_fma_f32 v[192:193], v[94:95], v[192:193], v[120:121] op_sel:[0,0,1] op_sel_hi:[1,1,1]
	ds_read2_b32 v[120:121], v195 offset0:160 offset1:176
	ds_read_b128 v[88:91], v145 offset:33280
	ds_read_b128 v[92:95], v145 offset:33536
	s_waitcnt lgkmcnt(13)
	v_pk_fma_f32 v[146:147], v[80:81], v[178:179], v[196:197]
	v_pk_fma_f32 v[150:151], v[80:81], v[186:187], v[196:197]
	v_pk_fma_f32 v[148:149], v[82:83], v[180:181], v[196:197]
	v_pk_fma_f32 v[152:153], v[82:83], v[188:189], v[196:197]
	ds_read_b128 v[80:83], v145 offset:25088
	s_waitcnt lgkmcnt(13)
	v_pk_fma_f32 v[146:147], v[84:85], v[182:183], v[146:147]
	v_pk_fma_f32 v[150:151], v[84:85], v[190:191], v[150:151]
	v_pk_fma_f32 v[148:149], v[86:87], v[184:185], v[148:149]
	v_pk_fma_f32 v[152:153], v[86:87], v[192:193], v[152:153]
	ds_read_b128 v[84:87], v145 offset:25344
	v_add_f32_e32 v146, v146, v147
	v_add_f32_e32 v148, v148, v149
	v_add_f32_e32 v150, v150, v151
	v_add_f32_e32 v152, v152, v153
	v_add_f32_e32 v156, v146, v148
	v_add_f32_e32 v157, v150, v152
	s_waitcnt lgkmcnt(11)
	v_pk_add_f32 v[178:179], v[178:179], v[118:119] op_sel_hi:[1,0] neg_lo:[0,1] neg_hi:[0,1]
	v_add_f32_dpp v156, v156, v156 row_ror:8 row_mask:0xf bank_mask:0xf bound_ctrl:1
	v_pk_add_f32 v[186:187], v[186:187], v[118:119] op_sel:[0,1] op_sel_hi:[1,1] neg_lo:[0,1] neg_hi:[0,1]
	v_add_f32_dpp v157, v157, v157 row_ror:8 row_mask:0xf bank_mask:0xf bound_ctrl:1
	v_pk_add_f32 v[180:181], v[180:181], v[118:119] op_sel_hi:[1,0] neg_lo:[0,1] neg_hi:[0,1]
	v_add_f32_dpp v156, v156, v156 row_ror:4 row_mask:0xf bank_mask:0xf bound_ctrl:1
	v_pk_add_f32 v[188:189], v[188:189], v[118:119] op_sel:[0,1] op_sel_hi:[1,1] neg_lo:[0,1] neg_hi:[0,1]
	v_add_f32_dpp v157, v157, v157 row_ror:4 row_mask:0xf bank_mask:0xf bound_ctrl:1
	v_pk_add_f32 v[182:183], v[182:183], v[118:119] op_sel_hi:[1,0] neg_lo:[0,1] neg_hi:[0,1]
	v_add_f32_dpp v156, v156, v156 row_ror:2 row_mask:0xf bank_mask:0xf bound_ctrl:1
	v_pk_add_f32 v[190:191], v[190:191], v[118:119] op_sel:[0,1] op_sel_hi:[1,1] neg_lo:[0,1] neg_hi:[0,1]
	v_add_f32_dpp v157, v157, v157 row_ror:2 row_mask:0xf bank_mask:0xf bound_ctrl:1
	v_pk_add_f32 v[184:185], v[184:185], v[118:119] op_sel_hi:[1,0] neg_lo:[0,1] neg_hi:[0,1]
	v_add_f32_dpp v156, v156, v156 row_ror:1 row_mask:0xf bank_mask:0xf bound_ctrl:1
	v_pk_add_f32 v[192:193], v[192:193], v[118:119] op_sel:[0,1] op_sel_hi:[1,1] neg_lo:[0,1] neg_hi:[0,1]
	v_add_f32_dpp v157, v157, v157 row_ror:1 row_mask:0xf bank_mask:0xf bound_ctrl:1
	s_waitcnt lgkmcnt(10)
	v_pk_fma_f32 v[178:179], v[72:73], v[178:179], v[118:119] op_sel_hi:[1,1,0]
	s_and_saveexec_b64 s[8:9], s[38:39]
	ds_write_b32 v103, v156 offset:40320
	ds_write_b32 v103, v157 offset:40384
	s_mov_b64 exec, s[8:9]
	v_pk_fma_f32 v[186:187], v[72:73], v[186:187], v[118:119] op_sel:[0,0,1] op_sel_hi:[1,1,1]
	v_pk_fma_f32 v[180:181], v[74:75], v[180:181], v[118:119] op_sel_hi:[1,1,0]
	v_pk_fma_f32 v[188:189], v[74:75], v[188:189], v[118:119] op_sel:[0,0,1] op_sel_hi:[1,1,1]
	s_waitcnt lgkmcnt(11)
	v_pk_fma_f32 v[182:183], v[76:77], v[182:183], v[118:119] op_sel_hi:[1,1,0]
	v_pk_fma_f32 v[190:191], v[76:77], v[190:191], v[118:119] op_sel:[0,0,1] op_sel_hi:[1,1,1]
	v_pk_fma_f32 v[184:185], v[78:79], v[184:185], v[118:119] op_sel_hi:[1,1,0]
	v_pk_fma_f32 v[192:193], v[78:79], v[192:193], v[118:119] op_sel:[0,0,1] op_sel_hi:[1,1,1]
	ds_read2_b32 v[118:119], v195 offset0:192 offset1:208
	ds_read_b128 v[72:75], v145 offset:33792
	ds_read_b128 v[76:79], v145 offset:34048
	s_waitcnt lgkmcnt(13)
	v_pk_fma_f32 v[146:147], v[64:65], v[178:179], v[196:197]
	v_pk_fma_f32 v[150:151], v[64:65], v[186:187], v[196:197]
	v_pk_fma_f32 v[148:149], v[66:67], v[180:181], v[196:197]
	v_pk_fma_f32 v[152:153], v[66:67], v[188:189], v[196:197]
	ds_read_b128 v[64:67], v145 offset:25600
	s_waitcnt lgkmcnt(13)
	v_pk_fma_f32 v[146:147], v[68:69], v[182:183], v[146:147]
	v_pk_fma_f32 v[150:151], v[68:69], v[190:191], v[150:151]
	v_pk_fma_f32 v[148:149], v[70:71], v[184:185], v[148:149]
	v_pk_fma_f32 v[152:153], v[70:71], v[192:193], v[152:153]
	ds_read_b128 v[68:71], v145 offset:25856
	v_add_f32_e32 v146, v146, v147
	v_add_f32_e32 v148, v148, v149
	v_add_f32_e32 v150, v150, v151
	v_add_f32_e32 v152, v152, v153
	v_add_f32_e32 v154, v146, v148
	v_add_f32_e32 v155, v150, v152
	s_waitcnt lgkmcnt(11)
	v_pk_add_f32 v[178:179], v[178:179], v[120:121] op_sel_hi:[1,0] neg_lo:[0,1] neg_hi:[0,1]
	v_add_f32_dpp v154, v154, v154 row_ror:8 row_mask:0xf bank_mask:0xf bound_ctrl:1
	v_pk_add_f32 v[186:187], v[186:187], v[120:121] op_sel:[0,1] op_sel_hi:[1,1] neg_lo:[0,1] neg_hi:[0,1]
	v_add_f32_dpp v155, v155, v155 row_ror:8 row_mask:0xf bank_mask:0xf bound_ctrl:1
	v_pk_add_f32 v[180:181], v[180:181], v[120:121] op_sel_hi:[1,0] neg_lo:[0,1] neg_hi:[0,1]
	v_add_f32_dpp v154, v154, v154 row_ror:4 row_mask:0xf bank_mask:0xf bound_ctrl:1
	v_pk_add_f32 v[188:189], v[188:189], v[120:121] op_sel:[0,1] op_sel_hi:[1,1] neg_lo:[0,1] neg_hi:[0,1]
	v_add_f32_dpp v155, v155, v155 row_ror:4 row_mask:0xf bank_mask:0xf bound_ctrl:1
	v_pk_add_f32 v[182:183], v[182:183], v[120:121] op_sel_hi:[1,0] neg_lo:[0,1] neg_hi:[0,1]
	v_add_f32_dpp v154, v154, v154 row_ror:2 row_mask:0xf bank_mask:0xf bound_ctrl:1
	v_pk_add_f32 v[190:191], v[190:191], v[120:121] op_sel:[0,1] op_sel_hi:[1,1] neg_lo:[0,1] neg_hi:[0,1]
	v_add_f32_dpp v155, v155, v155 row_ror:2 row_mask:0xf bank_mask:0xf bound_ctrl:1
	v_pk_add_f32 v[184:185], v[184:185], v[120:121] op_sel_hi:[1,0] neg_lo:[0,1] neg_hi:[0,1]
	v_add_f32_dpp v154, v154, v154 row_ror:1 row_mask:0xf bank_mask:0xf bound_ctrl:1
	v_pk_add_f32 v[192:193], v[192:193], v[120:121] op_sel:[0,1] op_sel_hi:[1,1] neg_lo:[0,1] neg_hi:[0,1]
	v_add_f32_dpp v155, v155, v155 row_ror:1 row_mask:0xf bank_mask:0xf bound_ctrl:1
	s_waitcnt lgkmcnt(10)
	v_pk_fma_f32 v[178:179], v[88:89], v[178:179], v[120:121] op_sel_hi:[1,1,0]
	s_and_saveexec_b64 s[8:9], s[38:39]
	ds_write_b32 v103, v154 offset:40448
	ds_write_b32 v103, v155 offset:40512
	s_mov_b64 exec, s[8:9]
	v_pk_fma_f32 v[186:187], v[88:89], v[186:187], v[120:121] op_sel:[0,0,1] op_sel_hi:[1,1,1]
	v_pk_fma_f32 v[180:181], v[90:91], v[180:181], v[120:121] op_sel_hi:[1,1,0]
	v_pk_fma_f32 v[188:189], v[90:91], v[188:189], v[120:121] op_sel:[0,0,1] op_sel_hi:[1,1,1]
	s_waitcnt lgkmcnt(11)
	v_pk_fma_f32 v[182:183], v[92:93], v[182:183], v[120:121] op_sel_hi:[1,1,0]
	v_pk_fma_f32 v[190:191], v[92:93], v[190:191], v[120:121] op_sel:[0,0,1] op_sel_hi:[1,1,1]
	v_pk_fma_f32 v[184:185], v[94:95], v[184:185], v[120:121] op_sel_hi:[1,1,0]
	v_pk_fma_f32 v[192:193], v[94:95], v[192:193], v[120:121] op_sel:[0,0,1] op_sel_hi:[1,1,1]
	ds_read2_b32 v[120:121], v195 offset0:224 offset1:240
	ds_read_b128 v[88:91], v145 offset:34304
	ds_read_b128 v[92:95], v145 offset:34560
	s_waitcnt lgkmcnt(13)
	v_pk_fma_f32 v[146:147], v[80:81], v[178:179], v[196:197]
	v_pk_fma_f32 v[150:151], v[80:81], v[186:187], v[196:197]
	v_pk_fma_f32 v[148:149], v[82:83], v[180:181], v[196:197]
	v_pk_fma_f32 v[152:153], v[82:83], v[188:189], v[196:197]
	ds_read_b128 v[80:83], v145 offset:26112
	s_waitcnt lgkmcnt(13)
	v_pk_fma_f32 v[146:147], v[84:85], v[182:183], v[146:147]
	v_pk_fma_f32 v[150:151], v[84:85], v[190:191], v[150:151]
	v_pk_fma_f32 v[148:149], v[86:87], v[184:185], v[148:149]
	v_pk_fma_f32 v[152:153], v[86:87], v[192:193], v[152:153]
	ds_read_b128 v[84:87], v145 offset:26368
	v_add_f32_e32 v146, v146, v147
	v_add_f32_e32 v148, v148, v149
	v_add_f32_e32 v150, v150, v151
	v_add_f32_e32 v152, v152, v153
	v_add_f32_e32 v156, v146, v148
	v_add_f32_e32 v157, v150, v152
	s_waitcnt lgkmcnt(11)
	v_pk_add_f32 v[178:179], v[178:179], v[118:119] op_sel_hi:[1,0] neg_lo:[0,1] neg_hi:[0,1]
	v_add_f32_dpp v156, v156, v156 row_ror:8 row_mask:0xf bank_mask:0xf bound_ctrl:1
	v_pk_add_f32 v[186:187], v[186:187], v[118:119] op_sel:[0,1] op_sel_hi:[1,1] neg_lo:[0,1] neg_hi:[0,1]
	v_add_f32_dpp v157, v157, v157 row_ror:8 row_mask:0xf bank_mask:0xf bound_ctrl:1
	v_pk_add_f32 v[180:181], v[180:181], v[118:119] op_sel_hi:[1,0] neg_lo:[0,1] neg_hi:[0,1]
	v_add_f32_dpp v156, v156, v156 row_ror:4 row_mask:0xf bank_mask:0xf bound_ctrl:1
	v_pk_add_f32 v[188:189], v[188:189], v[118:119] op_sel:[0,1] op_sel_hi:[1,1] neg_lo:[0,1] neg_hi:[0,1]
	v_add_f32_dpp v157, v157, v157 row_ror:4 row_mask:0xf bank_mask:0xf bound_ctrl:1
	v_pk_add_f32 v[182:183], v[182:183], v[118:119] op_sel_hi:[1,0] neg_lo:[0,1] neg_hi:[0,1]
	v_add_f32_dpp v156, v156, v156 row_ror:2 row_mask:0xf bank_mask:0xf bound_ctrl:1
	v_pk_add_f32 v[190:191], v[190:191], v[118:119] op_sel:[0,1] op_sel_hi:[1,1] neg_lo:[0,1] neg_hi:[0,1]
	v_add_f32_dpp v157, v157, v157 row_ror:2 row_mask:0xf bank_mask:0xf bound_ctrl:1
	v_pk_add_f32 v[184:185], v[184:185], v[118:119] op_sel_hi:[1,0] neg_lo:[0,1] neg_hi:[0,1]
	v_add_f32_dpp v156, v156, v156 row_ror:1 row_mask:0xf bank_mask:0xf bound_ctrl:1
	v_pk_add_f32 v[192:193], v[192:193], v[118:119] op_sel:[0,1] op_sel_hi:[1,1] neg_lo:[0,1] neg_hi:[0,1]
	v_add_f32_dpp v157, v157, v157 row_ror:1 row_mask:0xf bank_mask:0xf bound_ctrl:1
	s_waitcnt lgkmcnt(10)
	v_pk_fma_f32 v[178:179], v[72:73], v[178:179], v[118:119] op_sel_hi:[1,1,0]
	s_and_saveexec_b64 s[8:9], s[38:39]
	ds_write_b32 v103, v156 offset:40576
	ds_write_b32 v103, v157 offset:40640
	s_mov_b64 exec, s[8:9]
	v_pk_fma_f32 v[186:187], v[72:73], v[186:187], v[118:119] op_sel:[0,0,1] op_sel_hi:[1,1,1]
	v_pk_fma_f32 v[180:181], v[74:75], v[180:181], v[118:119] op_sel_hi:[1,1,0]
	v_pk_fma_f32 v[188:189], v[74:75], v[188:189], v[118:119] op_sel:[0,0,1] op_sel_hi:[1,1,1]
	s_waitcnt lgkmcnt(11)
	v_pk_fma_f32 v[182:183], v[76:77], v[182:183], v[118:119] op_sel_hi:[1,1,0]
	v_pk_fma_f32 v[190:191], v[76:77], v[190:191], v[118:119] op_sel:[0,0,1] op_sel_hi:[1,1,1]
	v_pk_fma_f32 v[184:185], v[78:79], v[184:185], v[118:119] op_sel_hi:[1,1,0]
	v_pk_fma_f32 v[192:193], v[78:79], v[192:193], v[118:119] op_sel:[0,0,1] op_sel_hi:[1,1,1]
	s_waitcnt lgkmcnt(10)
	v_pk_fma_f32 v[146:147], v[64:65], v[178:179], v[196:197]
	v_pk_fma_f32 v[150:151], v[64:65], v[186:187], v[196:197]
	v_pk_fma_f32 v[148:149], v[66:67], v[180:181], v[196:197]
	v_pk_fma_f32 v[152:153], v[66:67], v[188:189], v[196:197]
	s_waitcnt lgkmcnt(9)
	v_pk_fma_f32 v[146:147], v[68:69], v[182:183], v[146:147]
	v_pk_fma_f32 v[150:151], v[68:69], v[190:191], v[150:151]
	v_pk_fma_f32 v[148:149], v[70:71], v[184:185], v[148:149]
	v_pk_fma_f32 v[152:153], v[70:71], v[192:193], v[152:153]
	v_add_f32_e32 v146, v146, v147
	v_add_f32_e32 v148, v148, v149
	v_add_f32_e32 v150, v150, v151
	v_add_f32_e32 v152, v152, v153
	v_add_f32_e32 v154, v146, v148
	v_add_f32_e32 v155, v150, v152
	s_waitcnt lgkmcnt(6)
	v_pk_add_f32 v[178:179], v[178:179], v[120:121] op_sel_hi:[1,0] neg_lo:[0,1] neg_hi:[0,1]
	v_add_f32_dpp v154, v154, v154 row_ror:8 row_mask:0xf bank_mask:0xf bound_ctrl:1
	v_pk_add_f32 v[186:187], v[186:187], v[120:121] op_sel:[0,1] op_sel_hi:[1,1] neg_lo:[0,1] neg_hi:[0,1]
	v_add_f32_dpp v155, v155, v155 row_ror:8 row_mask:0xf bank_mask:0xf bound_ctrl:1
	v_pk_add_f32 v[180:181], v[180:181], v[120:121] op_sel_hi:[1,0] neg_lo:[0,1] neg_hi:[0,1]
	v_add_f32_dpp v154, v154, v154 row_ror:4 row_mask:0xf bank_mask:0xf bound_ctrl:1
	v_pk_add_f32 v[188:189], v[188:189], v[120:121] op_sel:[0,1] op_sel_hi:[1,1] neg_lo:[0,1] neg_hi:[0,1]
	v_add_f32_dpp v155, v155, v155 row_ror:4 row_mask:0xf bank_mask:0xf bound_ctrl:1
	v_pk_add_f32 v[182:183], v[182:183], v[120:121] op_sel_hi:[1,0] neg_lo:[0,1] neg_hi:[0,1]
	v_add_f32_dpp v154, v154, v154 row_ror:2 row_mask:0xf bank_mask:0xf bound_ctrl:1
	v_pk_add_f32 v[190:191], v[190:191], v[120:121] op_sel:[0,1] op_sel_hi:[1,1] neg_lo:[0,1] neg_hi:[0,1]
	v_add_f32_dpp v155, v155, v155 row_ror:2 row_mask:0xf bank_mask:0xf bound_ctrl:1
	v_pk_add_f32 v[184:185], v[184:185], v[120:121] op_sel_hi:[1,0] neg_lo:[0,1] neg_hi:[0,1]
	v_add_f32_dpp v154, v154, v154 row_ror:1 row_mask:0xf bank_mask:0xf bound_ctrl:1
	v_pk_add_f32 v[192:193], v[192:193], v[120:121] op_sel:[0,1] op_sel_hi:[1,1] neg_lo:[0,1] neg_hi:[0,1]
	v_add_f32_dpp v155, v155, v155 row_ror:1 row_mask:0xf bank_mask:0xf bound_ctrl:1
	s_waitcnt lgkmcnt(5)
	v_pk_fma_f32 v[178:179], v[88:89], v[178:179], v[120:121] op_sel_hi:[1,1,0]
	s_and_saveexec_b64 s[8:9], s[38:39]
	ds_write_b32 v103, v154 offset:40704
	ds_write_b32 v103, v155 offset:40768
	s_mov_b64 exec, s[8:9]
	v_pk_fma_f32 v[186:187], v[88:89], v[186:187], v[120:121] op_sel:[0,0,1] op_sel_hi:[1,1,1]
	v_pk_fma_f32 v[180:181], v[90:91], v[180:181], v[120:121] op_sel_hi:[1,1,0]
	v_pk_fma_f32 v[188:189], v[90:91], v[188:189], v[120:121] op_sel:[0,0,1] op_sel_hi:[1,1,1]
	s_waitcnt lgkmcnt(6)
	v_pk_fma_f32 v[182:183], v[92:93], v[182:183], v[120:121] op_sel_hi:[1,1,0]
	v_pk_fma_f32 v[190:191], v[92:93], v[190:191], v[120:121] op_sel:[0,0,1] op_sel_hi:[1,1,1]
	v_pk_fma_f32 v[184:185], v[94:95], v[184:185], v[120:121] op_sel_hi:[1,1,0]
	v_pk_fma_f32 v[192:193], v[94:95], v[192:193], v[120:121] op_sel:[0,0,1] op_sel_hi:[1,1,1]
	s_waitcnt lgkmcnt(5)
	v_pk_fma_f32 v[146:147], v[80:81], v[178:179], v[196:197]
	v_pk_fma_f32 v[150:151], v[80:81], v[186:187], v[196:197]
	v_pk_fma_f32 v[148:149], v[82:83], v[180:181], v[196:197]
	v_pk_fma_f32 v[152:153], v[82:83], v[188:189], v[196:197]
	s_waitcnt lgkmcnt(4)
	v_pk_fma_f32 v[146:147], v[84:85], v[182:183], v[146:147]
	v_pk_fma_f32 v[150:151], v[84:85], v[190:191], v[150:151]
	v_pk_fma_f32 v[148:149], v[86:87], v[184:185], v[148:149]
	v_pk_fma_f32 v[152:153], v[86:87], v[192:193], v[152:153]
	v_add_f32_e32 v146, v146, v147
	v_add_f32_e32 v148, v148, v149
	v_add_f32_e32 v150, v150, v151
	v_add_f32_e32 v152, v152, v153
	v_add_f32_e32 v156, v146, v148
	v_add_f32_e32 v157, v150, v152
	s_nop 0
	v_add_f32_dpp v156, v156, v156 row_ror:8 row_mask:0xf bank_mask:0xf bound_ctrl:1
	v_add_f32_dpp v157, v157, v157 row_ror:8 row_mask:0xf bank_mask:0xf bound_ctrl:1
	s_nop 0
	v_add_f32_dpp v156, v156, v156 row_ror:4 row_mask:0xf bank_mask:0xf bound_ctrl:1
	v_add_f32_dpp v157, v157, v157 row_ror:4 row_mask:0xf bank_mask:0xf bound_ctrl:1
	s_nop 0
	v_add_f32_dpp v156, v156, v156 row_ror:2 row_mask:0xf bank_mask:0xf bound_ctrl:1
	v_add_f32_dpp v157, v157, v157 row_ror:2 row_mask:0xf bank_mask:0xf bound_ctrl:1
	s_nop 0
	v_add_f32_dpp v156, v156, v156 row_ror:1 row_mask:0xf bank_mask:0xf bound_ctrl:1
	v_add_f32_dpp v157, v157, v157 row_ror:1 row_mask:0xf bank_mask:0xf bound_ctrl:1
	s_and_saveexec_b64 s[8:9], s[38:39]
	ds_write_b32 v103, v156 offset:40832
	ds_write_b32 v103, v157 offset:40896
	s_mov_b64 exec, s[8:9]
	s_waitcnt lgkmcnt(0)
	v_mov_b32_e32 v118, v178
	v_mov_b32_e32 v119, v179
	v_mov_b32_e32 v88, v180
	v_mov_b32_e32 v89, v181
	v_mov_b32_e32 v90, v182
	v_mov_b32_e32 v80, v183
	v_mov_b32_e32 v81, v184
	v_mov_b32_e32 v82, v185
	v_mov_b32_e32 v146, v186
	v_mov_b32_e32 v120, v187
	v_mov_b32_e32 v121, v188
	v_mov_b32_e32 v91, v189
	v_mov_b32_e32 v147, v190
	v_mov_b32_e32 v148, v191
	v_mov_b32_e32 v149, v192
	v_mov_b32_e32 v83, v193
	s_branch .LBB0_1284

.LBB0_1454:
	s_or_b64 exec, exec, s[8:9]
	s_waitcnt lgkmcnt(0)
	s_barrier
	v_mov_b32_e32 v196, v64
	v_mov_b32_e32 v197, v65
	v_mov_b32_e32 v198, v66
	v_mov_b32_e32 v199, v67
	v_mov_b32_e32 v200, v76
	v_mov_b32_e32 v201, v77
	v_mov_b32_e32 v202, v78
	v_mov_b32_e32 v203, v79
	v_mov_b32_e32 v204, v72
	v_mov_b32_e32 v205, v73
	v_mov_b32_e32 v206, v74
	v_mov_b32_e32 v207, v75
	v_mov_b32_e32 v208, v68
	v_mov_b32_e32 v209, v69
	v_mov_b32_e32 v210, v70
	v_mov_b32_e32 v211, v71
	v_mov_b32_e32 v192, 0
	v_mov_b32_e32 v193, 0
	ds_read_b128 v[80:83], v188 offset:8192
	ds_read_b128 v[84:87], v188 offset:8448
	ds_read_b128 v[88:91], v188 offset:8704
	ds_read_b128 v[92:95], v188 offset:8960
	ds_read_b32 v134, v140 offset:35136
	ds_read_b32 v135, v189 offset:16384
	ds_read_b32 v132, v140 offset:35072
	ds_read_b128 v[64:67], v188
	ds_read_b128 v[68:71], v188 offset:256
	ds_read_b128 v[72:75], v188 offset:512
	ds_read_b128 v[76:79], v188 offset:768
	ds_read_b128 v[112:115], v188 offset:9216
	ds_read_b128 v[116:119], v188 offset:9472
	ds_read_b128 v[120:123], v188 offset:9728
	ds_read_b128 v[124:127], v188 offset:9984
	ds_read_b32 v154, v140 offset:35140
	ds_read_b32 v155, v189 offset:16448
	ds_read_b32 v152, v140 offset:35076
	ds_read_b128 v[96:99], v188 offset:1024
	ds_read_b128 v[100:103], v188 offset:1280
	ds_read_b128 v[104:107], v188 offset:1536
	ds_read_b128 v[108:111], v188 offset:1792
	s_waitcnt lgkmcnt(15)
	v_mul_f32_e32 v133, v134, v135
	v_pk_mul_f32 v[80:81], v[80:81], v[132:133] op_sel:[0,1] op_sel_hi:[1,1]
	v_pk_mul_f32 v[82:83], v[82:83], v[132:133] op_sel:[0,1] op_sel_hi:[1,1]
	v_pk_mul_f32 v[84:85], v[84:85], v[132:133] op_sel:[0,1] op_sel_hi:[1,1]
	v_pk_mul_f32 v[86:87], v[86:87], v[132:133] op_sel:[0,1] op_sel_hi:[1,1]
	v_pk_mul_f32 v[88:89], v[88:89], v[132:133] op_sel:[0,1] op_sel_hi:[1,1]
	v_pk_mul_f32 v[90:91], v[90:91], v[132:133] op_sel:[0,1] op_sel_hi:[1,1]
	v_pk_mul_f32 v[92:93], v[92:93], v[132:133] op_sel:[0,1] op_sel_hi:[1,1]
	v_pk_mul_f32 v[94:95], v[94:95], v[132:133] op_sel:[0,1] op_sel_hi:[1,1]
	v_pk_fma_f32 v[196:197], v[132:133], v[196:197], v[80:81] op_sel_hi:[0,1,1]
	v_pk_fma_f32 v[198:199], v[132:133], v[198:199], v[82:83] op_sel_hi:[0,1,1]
	v_pk_fma_f32 v[200:201], v[132:133], v[200:201], v[84:85] op_sel_hi:[0,1,1]
	v_pk_fma_f32 v[202:203], v[132:133], v[202:203], v[86:87] op_sel_hi:[0,1,1]
	v_pk_fma_f32 v[204:205], v[132:133], v[204:205], v[88:89] op_sel_hi:[0,1,1]
	v_pk_fma_f32 v[206:207], v[132:133], v[206:207], v[90:91] op_sel_hi:[0,1,1]
	v_pk_fma_f32 v[208:209], v[132:133], v[208:209], v[92:93] op_sel_hi:[0,1,1]
	v_pk_fma_f32 v[210:211], v[132:133], v[210:211], v[94:95] op_sel_hi:[0,1,1]
	ds_read_b128 v[80:83], v188 offset:10240
	ds_read_b128 v[84:87], v188 offset:10496
	ds_read_b128 v[88:91], v188 offset:10752
	ds_read_b128 v[92:95], v188 offset:11008
	ds_read_b32 v134, v140 offset:35144
	ds_read_b32 v135, v189 offset:16512
	ds_read_b32 v132, v140 offset:35080
	s_waitcnt lgkmcnt(15)
	v_pk_fma_f32 v[128:129], v[64:65], v[196:197], v[192:193]
	v_pk_fma_f32 v[130:131], v[66:67], v[198:199], v[192:193]
	ds_read_b128 v[64:67], v188 offset:2048
	s_waitcnt lgkmcnt(15)
	v_pk_fma_f32 v[128:129], v[68:69], v[200:201], v[128:129]
	v_pk_fma_f32 v[130:131], v[70:71], v[202:203], v[130:131]
	ds_read_b128 v[68:71], v188 offset:2304
	s_waitcnt lgkmcnt(15)
	v_pk_fma_f32 v[128:129], v[72:73], v[204:205], v[128:129]
	v_pk_fma_f32 v[130:131], v[74:75], v[206:207], v[130:131]
	ds_read_b128 v[72:75], v188 offset:2560
	s_waitcnt lgkmcnt(15)
	v_pk_fma_f32 v[128:129], v[76:77], v[208:209], v[128:129]
	v_pk_fma_f32 v[130:131], v[78:79], v[210:211], v[130:131]
	ds_read_b128 v[76:79], v188 offset:2816
	v_add_f32_e32 v128, v128, v129
	v_add_f32_e32 v130, v130, v131
	v_add_f32_e32 v190, v128, v130
	s_waitcnt lgkmcnt(15)
	v_mul_f32_e32 v153, v154, v155
	v_pk_mul_f32 v[112:113], v[112:113], v[152:153] op_sel:[0,1] op_sel_hi:[1,1]
	v_add_f32_dpp v190, v190, v190 row_ror:8 row_mask:0xf bank_mask:0xf bound_ctrl:1
	v_pk_mul_f32 v[114:115], v[114:115], v[152:153] op_sel:[0,1] op_sel_hi:[1,1]
	v_pk_mul_f32 v[116:117], v[116:117], v[152:153] op_sel:[0,1] op_sel_hi:[1,1]
	v_add_f32_dpp v190, v190, v190 row_ror:4 row_mask:0xf bank_mask:0xf bound_ctrl:1
	v_pk_mul_f32 v[118:119], v[118:119], v[152:153] op_sel:[0,1] op_sel_hi:[1,1]
	v_pk_mul_f32 v[120:121], v[120:121], v[152:153] op_sel:[0,1] op_sel_hi:[1,1]
	v_add_f32_dpp v190, v190, v190 row_ror:2 row_mask:0xf bank_mask:0xf bound_ctrl:1
	v_pk_mul_f32 v[122:123], v[122:123], v[152:153] op_sel:[0,1] op_sel_hi:[1,1]
	v_pk_mul_f32 v[124:125], v[124:125], v[152:153] op_sel:[0,1] op_sel_hi:[1,1]
	v_add_f32_dpp v190, v190, v190 row_ror:1 row_mask:0xf bank_mask:0xf bound_ctrl:1
	v_pk_mul_f32 v[126:127], v[126:127], v[152:153] op_sel:[0,1] op_sel_hi:[1,1]
	v_pk_fma_f32 v[196:197], v[152:153], v[196:197], v[112:113] op_sel_hi:[0,1,1]
	s_and_saveexec_b64 s[8:9], s[44:45]
	ds_write_b32 v189, v190 offset:34048
	s_mov_b64 exec, s[8:9]
	v_pk_fma_f32 v[198:199], v[152:153], v[198:199], v[114:115] op_sel_hi:[0,1,1]
	v_pk_fma_f32 v[200:201], v[152:153], v[200:201], v[116:117] op_sel_hi:[0,1,1]
	v_pk_fma_f32 v[202:203], v[152:153], v[202:203], v[118:119] op_sel_hi:[0,1,1]
	v_pk_fma_f32 v[204:205], v[152:153], v[204:205], v[120:121] op_sel_hi:[0,1,1]
	v_pk_fma_f32 v[206:207], v[152:153], v[206:207], v[122:123] op_sel_hi:[0,1,1]
	v_pk_fma_f32 v[208:209], v[152:153], v[208:209], v[124:125] op_sel_hi:[0,1,1]
	v_pk_fma_f32 v[210:211], v[152:153], v[210:211], v[126:127] op_sel_hi:[0,1,1]
	ds_read_b128 v[112:115], v188 offset:11264
	ds_read_b128 v[116:119], v188 offset:11520
	ds_read_b128 v[120:123], v188 offset:11776
	ds_read_b128 v[124:127], v188 offset:12032
	ds_read_b32 v154, v140 offset:35148
	ds_read_b32 v155, v189 offset:16576
	ds_read_b32 v152, v140 offset:35084
	s_waitcnt lgkmcnt(15)
	v_pk_fma_f32 v[128:129], v[96:97], v[196:197], v[192:193]
	v_pk_fma_f32 v[130:131], v[98:99], v[198:199], v[192:193]
	ds_read_b128 v[96:99], v188 offset:3072
	s_waitcnt lgkmcnt(15)
	v_pk_fma_f32 v[128:129], v[100:101], v[200:201], v[128:129]
	v_pk_fma_f32 v[130:131], v[102:103], v[202:203], v[130:131]
	ds_read_b128 v[100:103], v188 offset:3328
	s_waitcnt lgkmcnt(15)
	v_pk_fma_f32 v[128:129], v[104:105], v[204:205], v[128:129]
	v_pk_fma_f32 v[130:131], v[106:107], v[206:207], v[130:131]
	ds_read_b128 v[104:107], v188 offset:3584
	s_waitcnt lgkmcnt(15)
	v_pk_fma_f32 v[128:129], v[108:109], v[208:209], v[128:129]
	v_pk_fma_f32 v[130:131], v[110:111], v[210:211], v[130:131]
	ds_read_b128 v[108:111], v188 offset:3840
	v_add_f32_e32 v128, v128, v129
	v_add_f32_e32 v130, v130, v131
	v_add_f32_e32 v191, v128, v130
	s_waitcnt lgkmcnt(15)
	v_mul_f32_e32 v133, v134, v135
	v_pk_mul_f32 v[80:81], v[80:81], v[132:133] op_sel:[0,1] op_sel_hi:[1,1]
	v_add_f32_dpp v191, v191, v191 row_ror:8 row_mask:0xf bank_mask:0xf bound_ctrl:1
	v_pk_mul_f32 v[82:83], v[82:83], v[132:133] op_sel:[0,1] op_sel_hi:[1,1]
	v_pk_mul_f32 v[84:85], v[84:85], v[132:133] op_sel:[0,1] op_sel_hi:[1,1]
	v_add_f32_dpp v191, v191, v191 row_ror:4 row_mask:0xf bank_mask:0xf bound_ctrl:1
	v_pk_mul_f32 v[86:87], v[86:87], v[132:133] op_sel:[0,1] op_sel_hi:[1,1]
	v_pk_mul_f32 v[88:89], v[88:89], v[132:133] op_sel:[0,1] op_sel_hi:[1,1]
	v_add_f32_dpp v191, v191, v191 row_ror:2 row_mask:0xf bank_mask:0xf bound_ctrl:1
	v_pk_mul_f32 v[90:91], v[90:91], v[132:133] op_sel:[0,1] op_sel_hi:[1,1]
	v_pk_mul_f32 v[92:93], v[92:93], v[132:133] op_sel:[0,1] op_sel_hi:[1,1]
	v_add_f32_dpp v191, v191, v191 row_ror:1 row_mask:0xf bank_mask:0xf bound_ctrl:1
	v_pk_mul_f32 v[94:95], v[94:95], v[132:133] op_sel:[0,1] op_sel_hi:[1,1]
	v_pk_fma_f32 v[196:197], v[132:133], v[196:197], v[80:81] op_sel_hi:[0,1,1]
	s_and_saveexec_b64 s[8:9], s[44:45]
	ds_write_b32 v189, v191 offset:34112
	s_mov_b64 exec, s[8:9]
	v_pk_fma_f32 v[198:199], v[132:133], v[198:199], v[82:83] op_sel_hi:[0,1,1]
	v_pk_fma_f32 v[200:201], v[132:133], v[200:201], v[84:85] op_sel_hi:[0,1,1]
	v_pk_fma_f32 v[202:203], v[132:133], v[202:203], v[86:87] op_sel_hi:[0,1,1]
	v_pk_fma_f32 v[204:205], v[132:133], v[204:205], v[88:89] op_sel_hi:[0,1,1]
	v_pk_fma_f32 v[206:207], v[132:133], v[206:207], v[90:91] op_sel_hi:[0,1,1]
	v_pk_fma_f32 v[208:209], v[132:133], v[208:209], v[92:93] op_sel_hi:[0,1,1]
	v_pk_fma_f32 v[210:211], v[132:133], v[210:211], v[94:95] op_sel_hi:[0,1,1]
	ds_read_b128 v[80:83], v188 offset:12288
	ds_read_b128 v[84:87], v188 offset:12544
	ds_read_b128 v[88:91], v188 offset:12800
	ds_read_b128 v[92:95], v188 offset:13056
	ds_read_b32 v134, v140 offset:35152
	ds_read_b32 v135, v189 offset:16640
	ds_read_b32 v132, v140 offset:35088
	s_waitcnt lgkmcnt(15)
	v_pk_fma_f32 v[128:129], v[64:65], v[196:197], v[192:193]
	v_pk_fma_f32 v[130:131], v[66:67], v[198:199], v[192:193]
	ds_read_b128 v[64:67], v188 offset:4096
	s_waitcnt lgkmcnt(15)
	v_pk_fma_f32 v[128:129], v[68:69], v[200:201], v[128:129]
	v_pk_fma_f32 v[130:131], v[70:71], v[202:203], v[130:131]
	ds_read_b128 v[68:71], v188 offset:4352
	s_waitcnt lgkmcnt(15)
	v_pk_fma_f32 v[128:129], v[72:73], v[204:205], v[128:129]
	v_pk_fma_f32 v[130:131], v[74:75], v[206:207], v[130:131]
	ds_read_b128 v[72:75], v188 offset:4608
	s_waitcnt lgkmcnt(15)
	v_pk_fma_f32 v[128:129], v[76:77], v[208:209], v[128:129]
	v_pk_fma_f32 v[130:131], v[78:79], v[210:211], v[130:131]
	ds_read_b128 v[76:79], v188 offset:4864
	v_add_f32_e32 v128, v128, v129
	v_add_f32_e32 v130, v130, v131
	v_add_f32_e32 v190, v128, v130
	s_waitcnt lgkmcnt(15)
	v_mul_f32_e32 v153, v154, v155
	v_pk_mul_f32 v[112:113], v[112:113], v[152:153] op_sel:[0,1] op_sel_hi:[1,1]
	v_add_f32_dpp v190, v190, v190 row_ror:8 row_mask:0xf bank_mask:0xf bound_ctrl:1
	v_pk_mul_f32 v[114:115], v[114:115], v[152:153] op_sel:[0,1] op_sel_hi:[1,1]
	v_pk_mul_f32 v[116:117], v[116:117], v[152:153] op_sel:[0,1] op_sel_hi:[1,1]
	v_add_f32_dpp v190, v190, v190 row_ror:4 row_mask:0xf bank_mask:0xf bound_ctrl:1
	v_pk_mul_f32 v[118:119], v[118:119], v[152:153] op_sel:[0,1] op_sel_hi:[1,1]
	v_pk_mul_f32 v[120:121], v[120:121], v[152:153] op_sel:[0,1] op_sel_hi:[1,1]
	v_add_f32_dpp v190, v190, v190 row_ror:2 row_mask:0xf bank_mask:0xf bound_ctrl:1
	v_pk_mul_f32 v[122:123], v[122:123], v[152:153] op_sel:[0,1] op_sel_hi:[1,1]
	v_pk_mul_f32 v[124:125], v[124:125], v[152:153] op_sel:[0,1] op_sel_hi:[1,1]
	v_add_f32_dpp v190, v190, v190 row_ror:1 row_mask:0xf bank_mask:0xf bound_ctrl:1
	v_pk_mul_f32 v[126:127], v[126:127], v[152:153] op_sel:[0,1] op_sel_hi:[1,1]
	v_pk_fma_f32 v[196:197], v[152:153], v[196:197], v[112:113] op_sel_hi:[0,1,1]
	s_and_saveexec_b64 s[8:9], s[44:45]
	ds_write_b32 v189, v190 offset:34176
	s_mov_b64 exec, s[8:9]
	v_pk_fma_f32 v[198:199], v[152:153], v[198:199], v[114:115] op_sel_hi:[0,1,1]
	v_pk_fma_f32 v[200:201], v[152:153], v[200:201], v[116:117] op_sel_hi:[0,1,1]
	v_pk_fma_f32 v[202:203], v[152:153], v[202:203], v[118:119] op_sel_hi:[0,1,1]
	v_pk_fma_f32 v[204:205], v[152:153], v[204:205], v[120:121] op_sel_hi:[0,1,1]
	v_pk_fma_f32 v[206:207], v[152:153], v[206:207], v[122:123] op_sel_hi:[0,1,1]
	v_pk_fma_f32 v[208:209], v[152:153], v[208:209], v[124:125] op_sel_hi:[0,1,1]
	v_pk_fma_f32 v[210:211], v[152:153], v[210:211], v[126:127] op_sel_hi:[0,1,1]
	ds_read_b128 v[112:115], v188 offset:13312
	ds_read_b128 v[116:119], v188 offset:13568
	ds_read_b128 v[120:123], v188 offset:13824
	ds_read_b128 v[124:127], v188 offset:14080
	ds_read_b32 v154, v140 offset:35156
	ds_read_b32 v155, v189 offset:16704
	ds_read_b32 v152, v140 offset:35092
	s_waitcnt lgkmcnt(15)
	v_pk_fma_f32 v[128:129], v[96:97], v[196:197], v[192:193]
	v_pk_fma_f32 v[130:131], v[98:99], v[198:199], v[192:193]
	ds_read_b128 v[96:99], v188 offset:5120
	s_waitcnt lgkmcnt(15)
	v_pk_fma_f32 v[128:129], v[100:101], v[200:201], v[128:129]
	v_pk_fma_f32 v[130:131], v[102:103], v[202:203], v[130:131]
	ds_read_b128 v[100:103], v188 offset:5376
	s_waitcnt lgkmcnt(15)
	v_pk_fma_f32 v[128:129], v[104:105], v[204:205], v[128:129]
	v_pk_fma_f32 v[130:131], v[106:107], v[206:207], v[130:131]
	ds_read_b128 v[104:107], v188 offset:5632
	s_waitcnt lgkmcnt(15)
	v_pk_fma_f32 v[128:129], v[108:109], v[208:209], v[128:129]
	v_pk_fma_f32 v[130:131], v[110:111], v[210:211], v[130:131]
	ds_read_b128 v[108:111], v188 offset:5888
	v_add_f32_e32 v128, v128, v129
	v_add_f32_e32 v130, v130, v131
	v_add_f32_e32 v191, v128, v130
	s_waitcnt lgkmcnt(15)
	v_mul_f32_e32 v133, v134, v135
	v_pk_mul_f32 v[80:81], v[80:81], v[132:133] op_sel:[0,1] op_sel_hi:[1,1]
	v_add_f32_dpp v191, v191, v191 row_ror:8 row_mask:0xf bank_mask:0xf bound_ctrl:1
	v_pk_mul_f32 v[82:83], v[82:83], v[132:133] op_sel:[0,1] op_sel_hi:[1,1]
	v_pk_mul_f32 v[84:85], v[84:85], v[132:133] op_sel:[0,1] op_sel_hi:[1,1]
	v_add_f32_dpp v191, v191, v191 row_ror:4 row_mask:0xf bank_mask:0xf bound_ctrl:1
	v_pk_mul_f32 v[86:87], v[86:87], v[132:133] op_sel:[0,1] op_sel_hi:[1,1]
	v_pk_mul_f32 v[88:89], v[88:89], v[132:133] op_sel:[0,1] op_sel_hi:[1,1]
	v_add_f32_dpp v191, v191, v191 row_ror:2 row_mask:0xf bank_mask:0xf bound_ctrl:1
	v_pk_mul_f32 v[90:91], v[90:91], v[132:133] op_sel:[0,1] op_sel_hi:[1,1]
	v_pk_mul_f32 v[92:93], v[92:93], v[132:133] op_sel:[0,1] op_sel_hi:[1,1]
	v_add_f32_dpp v191, v191, v191 row_ror:1 row_mask:0xf bank_mask:0xf bound_ctrl:1
	v_pk_mul_f32 v[94:95], v[94:95], v[132:133] op_sel:[0,1] op_sel_hi:[1,1]
	v_pk_fma_f32 v[196:197], v[132:133], v[196:197], v[80:81] op_sel_hi:[0,1,1]
	s_and_saveexec_b64 s[8:9], s[44:45]
	ds_write_b32 v189, v191 offset:34240
	s_mov_b64 exec, s[8:9]
	v_pk_fma_f32 v[198:199], v[132:133], v[198:199], v[82:83] op_sel_hi:[0,1,1]
	v_pk_fma_f32 v[200:201], v[132:133], v[200:201], v[84:85] op_sel_hi:[0,1,1]
	v_pk_fma_f32 v[202:203], v[132:133], v[202:203], v[86:87] op_sel_hi:[0,1,1]
	v_pk_fma_f32 v[204:205], v[132:133], v[204:205], v[88:89] op_sel_hi:[0,1,1]
	v_pk_fma_f32 v[206:207], v[132:133], v[206:207], v[90:91] op_sel_hi:[0,1,1]
	v_pk_fma_f32 v[208:209], v[132:133], v[208:209], v[92:93] op_sel_hi:[0,1,1]
	v_pk_fma_f32 v[210:211], v[132:133], v[210:211], v[94:95] op_sel_hi:[0,1,1]
	ds_read_b128 v[80:83], v188 offset:14336
	ds_read_b128 v[84:87], v188 offset:14592
	ds_read_b128 v[88:91], v188 offset:14848
	ds_read_b128 v[92:95], v188 offset:15104
	ds_read_b32 v134, v140 offset:35160
	ds_read_b32 v135, v189 offset:16768
	ds_read_b32 v132, v140 offset:35096
	s_waitcnt lgkmcnt(15)
	v_pk_fma_f32 v[128:129], v[64:65], v[196:197], v[192:193]
	v_pk_fma_f32 v[130:131], v[66:67], v[198:199], v[192:193]
	ds_read_b128 v[64:67], v188 offset:6144
	s_waitcnt lgkmcnt(15)
	v_pk_fma_f32 v[128:129], v[68:69], v[200:201], v[128:129]
	v_pk_fma_f32 v[130:131], v[70:71], v[202:203], v[130:131]
	ds_read_b128 v[68:71], v188 offset:6400
	s_waitcnt lgkmcnt(15)
	v_pk_fma_f32 v[128:129], v[72:73], v[204:205], v[128:129]
	v_pk_fma_f32 v[130:131], v[74:75], v[206:207], v[130:131]
	ds_read_b128 v[72:75], v188 offset:6656
	s_waitcnt lgkmcnt(15)
	v_pk_fma_f32 v[128:129], v[76:77], v[208:209], v[128:129]
	v_pk_fma_f32 v[130:131], v[78:79], v[210:211], v[130:131]
	ds_read_b128 v[76:79], v188 offset:6912
	v_add_f32_e32 v128, v128, v129
	v_add_f32_e32 v130, v130, v131
	v_add_f32_e32 v190, v128, v130
	s_waitcnt lgkmcnt(15)
	v_mul_f32_e32 v153, v154, v155
	v_pk_mul_f32 v[112:113], v[112:113], v[152:153] op_sel:[0,1] op_sel_hi:[1,1]
	v_add_f32_dpp v190, v190, v190 row_ror:8 row_mask:0xf bank_mask:0xf bound_ctrl:1
	v_pk_mul_f32 v[114:115], v[114:115], v[152:153] op_sel:[0,1] op_sel_hi:[1,1]
	v_pk_mul_f32 v[116:117], v[116:117], v[152:153] op_sel:[0,1] op_sel_hi:[1,1]
	v_add_f32_dpp v190, v190, v190 row_ror:4 row_mask:0xf bank_mask:0xf bound_ctrl:1
	v_pk_mul_f32 v[118:119], v[118:119], v[152:153] op_sel:[0,1] op_sel_hi:[1,1]
	v_pk_mul_f32 v[120:121], v[120:121], v[152:153] op_sel:[0,1] op_sel_hi:[1,1]
	v_add_f32_dpp v190, v190, v190 row_ror:2 row_mask:0xf bank_mask:0xf bound_ctrl:1
	v_pk_mul_f32 v[122:123], v[122:123], v[152:153] op_sel:[0,1] op_sel_hi:[1,1]
	v_pk_mul_f32 v[124:125], v[124:125], v[152:153] op_sel:[0,1] op_sel_hi:[1,1]
	v_add_f32_dpp v190, v190, v190 row_ror:1 row_mask:0xf bank_mask:0xf bound_ctrl:1
	v_pk_mul_f32 v[126:127], v[126:127], v[152:153] op_sel:[0,1] op_sel_hi:[1,1]
	v_pk_fma_f32 v[196:197], v[152:153], v[196:197], v[112:113] op_sel_hi:[0,1,1]
	s_and_saveexec_b64 s[8:9], s[44:45]
	ds_write_b32 v189, v190 offset:34304
	s_mov_b64 exec, s[8:9]
	v_pk_fma_f32 v[198:199], v[152:153], v[198:199], v[114:115] op_sel_hi:[0,1,1]
	v_pk_fma_f32 v[200:201], v[152:153], v[200:201], v[116:117] op_sel_hi:[0,1,1]
	v_pk_fma_f32 v[202:203], v[152:153], v[202:203], v[118:119] op_sel_hi:[0,1,1]
	v_pk_fma_f32 v[204:205], v[152:153], v[204:205], v[120:121] op_sel_hi:[0,1,1]
	v_pk_fma_f32 v[206:207], v[152:153], v[206:207], v[122:123] op_sel_hi:[0,1,1]
	v_pk_fma_f32 v[208:209], v[152:153], v[208:209], v[124:125] op_sel_hi:[0,1,1]
	v_pk_fma_f32 v[210:211], v[152:153], v[210:211], v[126:127] op_sel_hi:[0,1,1]
	ds_read_b128 v[112:115], v188 offset:15360
	ds_read_b128 v[116:119], v188 offset:15616
	ds_read_b128 v[120:123], v188 offset:15872
	ds_read_b128 v[124:127], v188 offset:16128
	ds_read_b32 v154, v140 offset:35164
	ds_read_b32 v155, v189 offset:16832
	ds_read_b32 v152, v140 offset:35100
	s_waitcnt lgkmcnt(15)
	v_pk_fma_f32 v[128:129], v[96:97], v[196:197], v[192:193]
	v_pk_fma_f32 v[130:131], v[98:99], v[198:199], v[192:193]
	ds_read_b128 v[96:99], v188 offset:7168
	s_waitcnt lgkmcnt(15)
	v_pk_fma_f32 v[128:129], v[100:101], v[200:201], v[128:129]
	v_pk_fma_f32 v[130:131], v[102:103], v[202:203], v[130:131]
	ds_read_b128 v[100:103], v188 offset:7424
	s_waitcnt lgkmcnt(15)
	v_pk_fma_f32 v[128:129], v[104:105], v[204:205], v[128:129]
	v_pk_fma_f32 v[130:131], v[106:107], v[206:207], v[130:131]
	ds_read_b128 v[104:107], v188 offset:7680
	s_waitcnt lgkmcnt(15)
	v_pk_fma_f32 v[128:129], v[108:109], v[208:209], v[128:129]
	v_pk_fma_f32 v[130:131], v[110:111], v[210:211], v[130:131]
	ds_read_b128 v[108:111], v188 offset:7936
	v_add_f32_e32 v128, v128, v129
	v_add_f32_e32 v130, v130, v131
	v_add_f32_e32 v191, v128, v130
	s_waitcnt lgkmcnt(15)
	v_mul_f32_e32 v133, v134, v135
	v_pk_mul_f32 v[80:81], v[80:81], v[132:133] op_sel:[0,1] op_sel_hi:[1,1]
	v_add_f32_dpp v191, v191, v191 row_ror:8 row_mask:0xf bank_mask:0xf bound_ctrl:1
	v_pk_mul_f32 v[82:83], v[82:83], v[132:133] op_sel:[0,1] op_sel_hi:[1,1]
	v_pk_mul_f32 v[84:85], v[84:85], v[132:133] op_sel:[0,1] op_sel_hi:[1,1]
	v_add_f32_dpp v191, v191, v191 row_ror:4 row_mask:0xf bank_mask:0xf bound_ctrl:1
	v_pk_mul_f32 v[86:87], v[86:87], v[132:133] op_sel:[0,1] op_sel_hi:[1,1]
	v_pk_mul_f32 v[88:89], v[88:89], v[132:133] op_sel:[0,1] op_sel_hi:[1,1]
	v_add_f32_dpp v191, v191, v191 row_ror:2 row_mask:0xf bank_mask:0xf bound_ctrl:1
	v_pk_mul_f32 v[90:91], v[90:91], v[132:133] op_sel:[0,1] op_sel_hi:[1,1]
	v_pk_mul_f32 v[92:93], v[92:93], v[132:133] op_sel:[0,1] op_sel_hi:[1,1]
	v_add_f32_dpp v191, v191, v191 row_ror:1 row_mask:0xf bank_mask:0xf bound_ctrl:1
	v_pk_mul_f32 v[94:95], v[94:95], v[132:133] op_sel:[0,1] op_sel_hi:[1,1]
	v_pk_fma_f32 v[196:197], v[132:133], v[196:197], v[80:81] op_sel_hi:[0,1,1]
	s_and_saveexec_b64 s[8:9], s[44:45]
	ds_write_b32 v189, v191 offset:34368
	s_mov_b64 exec, s[8:9]
	v_pk_fma_f32 v[198:199], v[132:133], v[198:199], v[82:83] op_sel_hi:[0,1,1]
	v_pk_fma_f32 v[200:201], v[132:133], v[200:201], v[84:85] op_sel_hi:[0,1,1]
	v_pk_fma_f32 v[202:203], v[132:133], v[202:203], v[86:87] op_sel_hi:[0,1,1]
	v_pk_fma_f32 v[204:205], v[132:133], v[204:205], v[88:89] op_sel_hi:[0,1,1]
	v_pk_fma_f32 v[206:207], v[132:133], v[206:207], v[90:91] op_sel_hi:[0,1,1]
	v_pk_fma_f32 v[208:209], v[132:133], v[208:209], v[92:93] op_sel_hi:[0,1,1]
	v_pk_fma_f32 v[210:211], v[132:133], v[210:211], v[94:95] op_sel_hi:[0,1,1]
	s_waitcnt lgkmcnt(15)
	v_pk_fma_f32 v[128:129], v[64:65], v[196:197], v[192:193]
	v_pk_fma_f32 v[130:131], v[66:67], v[198:199], v[192:193]
	v_pk_fma_f32 v[128:129], v[68:69], v[200:201], v[128:129]
	v_pk_fma_f32 v[130:131], v[70:71], v[202:203], v[130:131]
	s_waitcnt lgkmcnt(14)
	v_pk_fma_f32 v[128:129], v[72:73], v[204:205], v[128:129]
	v_pk_fma_f32 v[130:131], v[74:75], v[206:207], v[130:131]
	s_waitcnt lgkmcnt(13)
	v_pk_fma_f32 v[128:129], v[76:77], v[208:209], v[128:129]
	v_pk_fma_f32 v[130:131], v[78:79], v[210:211], v[130:131]
	v_add_f32_e32 v128, v128, v129
	v_add_f32_e32 v130, v130, v131
	v_add_f32_e32 v190, v128, v130
	s_waitcnt lgkmcnt(6)
	v_mul_f32_e32 v153, v154, v155
	v_pk_mul_f32 v[112:113], v[112:113], v[152:153] op_sel:[0,1] op_sel_hi:[1,1]
	v_add_f32_dpp v190, v190, v190 row_ror:8 row_mask:0xf bank_mask:0xf bound_ctrl:1
	v_pk_mul_f32 v[114:115], v[114:115], v[152:153] op_sel:[0,1] op_sel_hi:[1,1]
	v_pk_mul_f32 v[116:117], v[116:117], v[152:153] op_sel:[0,1] op_sel_hi:[1,1]
	v_add_f32_dpp v190, v190, v190 row_ror:4 row_mask:0xf bank_mask:0xf bound_ctrl:1
	v_pk_mul_f32 v[118:119], v[118:119], v[152:153] op_sel:[0,1] op_sel_hi:[1,1]
	v_pk_mul_f32 v[120:121], v[120:121], v[152:153] op_sel:[0,1] op_sel_hi:[1,1]
	v_add_f32_dpp v190, v190, v190 row_ror:2 row_mask:0xf bank_mask:0xf bound_ctrl:1
	v_pk_mul_f32 v[122:123], v[122:123], v[152:153] op_sel:[0,1] op_sel_hi:[1,1]
	v_pk_mul_f32 v[124:125], v[124:125], v[152:153] op_sel:[0,1] op_sel_hi:[1,1]
	v_add_f32_dpp v190, v190, v190 row_ror:1 row_mask:0xf bank_mask:0xf bound_ctrl:1
	v_pk_mul_f32 v[126:127], v[126:127], v[152:153] op_sel:[0,1] op_sel_hi:[1,1]
	s_waitcnt lgkmcnt(5)
	v_pk_fma_f32 v[196:197], v[152:153], v[196:197], v[112:113] op_sel_hi:[0,1,1]
	s_and_saveexec_b64 s[8:9], s[44:45]
	ds_write_b32 v189, v190 offset:34432
	s_mov_b64 exec, s[8:9]
	v_pk_fma_f32 v[198:199], v[152:153], v[198:199], v[114:115] op_sel_hi:[0,1,1]
	v_pk_fma_f32 v[200:201], v[152:153], v[200:201], v[116:117] op_sel_hi:[0,1,1]
	v_pk_fma_f32 v[202:203], v[152:153], v[202:203], v[118:119] op_sel_hi:[0,1,1]
	v_pk_fma_f32 v[204:205], v[152:153], v[204:205], v[120:121] op_sel_hi:[0,1,1]
	v_pk_fma_f32 v[206:207], v[152:153], v[206:207], v[122:123] op_sel_hi:[0,1,1]
	v_pk_fma_f32 v[208:209], v[152:153], v[208:209], v[124:125] op_sel_hi:[0,1,1]
	v_pk_fma_f32 v[210:211], v[152:153], v[210:211], v[126:127] op_sel_hi:[0,1,1]
	s_waitcnt lgkmcnt(5)
	v_pk_fma_f32 v[128:129], v[96:97], v[196:197], v[192:193]
	v_pk_fma_f32 v[130:131], v[98:99], v[198:199], v[192:193]
	s_waitcnt lgkmcnt(4)
	v_pk_fma_f32 v[128:129], v[100:101], v[200:201], v[128:129]
	v_pk_fma_f32 v[130:131], v[102:103], v[202:203], v[130:131]
	s_waitcnt lgkmcnt(3)
	v_pk_fma_f32 v[128:129], v[104:105], v[204:205], v[128:129]
	v_pk_fma_f32 v[130:131], v[106:107], v[206:207], v[130:131]
	s_waitcnt lgkmcnt(2)
	v_pk_fma_f32 v[128:129], v[108:109], v[208:209], v[128:129]
	v_pk_fma_f32 v[130:131], v[110:111], v[210:211], v[130:131]
	v_add_f32_e32 v128, v128, v129
	v_add_f32_e32 v130, v130, v131
	v_add_f32_e32 v191, v128, v130
	s_nop 1
	v_add_f32_dpp v191, v191, v191 row_ror:8 row_mask:0xf bank_mask:0xf bound_ctrl:1
	s_nop 1
	v_add_f32_dpp v191, v191, v191 row_ror:4 row_mask:0xf bank_mask:0xf bound_ctrl:1
	s_nop 1
	v_add_f32_dpp v191, v191, v191 row_ror:2 row_mask:0xf bank_mask:0xf bound_ctrl:1
	s_nop 1
	v_add_f32_dpp v191, v191, v191 row_ror:1 row_mask:0xf bank_mask:0xf bound_ctrl:1
	s_and_saveexec_b64 s[8:9], s[44:45]
	ds_write_b32 v189, v191 offset:34496
	s_mov_b64 exec, s[8:9]
	s_waitcnt vmcnt(11)
	ds_write_b128 v185, v[16:19] offset:17024
	s_waitcnt vmcnt(9)
	ds_write_b128 v186, v[24:27] offset:17024
	ds_write_b128 v185, v[20:23] offset:25216
	s_waitcnt vmcnt(8)
	ds_write_b128 v186, v[28:31] offset:25216
	s_and_saveexec_b64 s[8:9], s[42:43]
	ds_write_b32 v144, v184 offset:33408
	s_or_b64 exec, exec, s[8:9]
	s_and_saveexec_b64 s[8:9], s[40:41]
	s_cbranch_execz .LBB0_1474
	v_add_f32_e32 v64, v156, v157
	v_mul_f32_e64 v65, |v64|, s62
	v_exp_f32_e32 v65, v65
	v_min_f32_e32 v64, 0, v64
	v_add_f32_e32 v65, 1.0, v65
	v_cmp_gt_f32_e32 vcc, s5, v65
	s_nop 1
	v_cndmask_b32_e64 v66, 0, 32, vcc
	v_ldexp_f32 v65, v65, v66
	v_log_f32_e32 v65, v65
	v_cndmask_b32_e32 v67, 0, v171, vcc
	v_add_f32_e32 v66, v145, v179
	v_mul_f32_e32 v68, 0x3f317217, v65
	v_fma_f32 v68, v65, s76, -v68
	v_fmac_f32_e32 v68, 0x3377d1cf, v65
	v_fmac_f32_e32 v68, 0x3f317217, v65
	v_cmp_lt_f32_e64 vcc, |v65|, s77
	s_nop 1
	v_cndmask_b32_e32 v65, v65, v68, vcc
	v_sub_f32_e32 v65, v65, v67
	v_sub_f32_e32 v64, v64, v65
	v_add_u32_e32 v65, 0x8400, v144
	ds_write2_b32 v65, v66, v64 offset0:32 offset1:48

.LBB0_1485:
	s_or_b64 exec, exec, s[8:9]
	s_waitcnt lgkmcnt(0)
	s_barrier
	v_mov_b32_e32 v192, 0
	v_mov_b32_e32 v193, 0
	ds_read_b128 v[80:83], v188 offset:25216
	ds_read_b128 v[84:87], v188 offset:25472
	ds_read_b128 v[88:91], v188 offset:25728
	ds_read_b128 v[92:95], v188 offset:25984
	ds_read_b32 v134, v140 offset:35136
	ds_read_b32 v135, v189 offset:33408
	ds_read_b32 v132, v140 offset:35072
	ds_read_b128 v[64:67], v188 offset:17024
	ds_read_b128 v[68:71], v188 offset:17280
	ds_read_b128 v[72:75], v188 offset:17536
	ds_read_b128 v[76:79], v188 offset:17792
	ds_read_b128 v[112:115], v188 offset:26240
	ds_read_b128 v[116:119], v188 offset:26496
	ds_read_b128 v[120:123], v188 offset:26752
	ds_read_b128 v[124:127], v188 offset:27008
	ds_read_b32 v154, v140 offset:35140
	ds_read_b32 v155, v189 offset:33472
	ds_read_b32 v152, v140 offset:35076
	ds_read_b128 v[96:99], v188 offset:18048
	ds_read_b128 v[100:103], v188 offset:18304
	ds_read_b128 v[104:107], v188 offset:18560
	ds_read_b128 v[108:111], v188 offset:18816
	s_waitcnt lgkmcnt(15)
	v_mul_f32_e32 v133, v134, v135
	v_pk_mul_f32 v[80:81], v[80:81], v[132:133] op_sel:[0,1] op_sel_hi:[1,1]
	v_pk_mul_f32 v[82:83], v[82:83], v[132:133] op_sel:[0,1] op_sel_hi:[1,1]
	v_pk_mul_f32 v[84:85], v[84:85], v[132:133] op_sel:[0,1] op_sel_hi:[1,1]
	v_pk_mul_f32 v[86:87], v[86:87], v[132:133] op_sel:[0,1] op_sel_hi:[1,1]
	v_pk_mul_f32 v[88:89], v[88:89], v[132:133] op_sel:[0,1] op_sel_hi:[1,1]
	v_pk_mul_f32 v[90:91], v[90:91], v[132:133] op_sel:[0,1] op_sel_hi:[1,1]
	v_pk_mul_f32 v[92:93], v[92:93], v[132:133] op_sel:[0,1] op_sel_hi:[1,1]
	v_pk_mul_f32 v[94:95], v[94:95], v[132:133] op_sel:[0,1] op_sel_hi:[1,1]
	v_pk_fma_f32 v[196:197], v[132:133], v[196:197], v[80:81] op_sel_hi:[0,1,1]
	v_pk_fma_f32 v[198:199], v[132:133], v[198:199], v[82:83] op_sel_hi:[0,1,1]
	v_pk_fma_f32 v[200:201], v[132:133], v[200:201], v[84:85] op_sel_hi:[0,1,1]
	v_pk_fma_f32 v[202:203], v[132:133], v[202:203], v[86:87] op_sel_hi:[0,1,1]
	v_pk_fma_f32 v[204:205], v[132:133], v[204:205], v[88:89] op_sel_hi:[0,1,1]
	v_pk_fma_f32 v[206:207], v[132:133], v[206:207], v[90:91] op_sel_hi:[0,1,1]
	v_pk_fma_f32 v[208:209], v[132:133], v[208:209], v[92:93] op_sel_hi:[0,1,1]
	v_pk_fma_f32 v[210:211], v[132:133], v[210:211], v[94:95] op_sel_hi:[0,1,1]
	ds_read_b128 v[80:83], v188 offset:27264
	ds_read_b128 v[84:87], v188 offset:27520
	ds_read_b128 v[88:91], v188 offset:27776
	ds_read_b128 v[92:95], v188 offset:28032
	ds_read_b32 v134, v140 offset:35144
	ds_read_b32 v135, v189 offset:33536
	ds_read_b32 v132, v140 offset:35080
	s_waitcnt lgkmcnt(15)
	v_pk_fma_f32 v[128:129], v[64:65], v[196:197], v[192:193]
	v_pk_fma_f32 v[130:131], v[66:67], v[198:199], v[192:193]
	ds_read_b128 v[64:67], v188 offset:19072
	s_waitcnt lgkmcnt(15)
	v_pk_fma_f32 v[128:129], v[68:69], v[200:201], v[128:129]
	v_pk_fma_f32 v[130:131], v[70:71], v[202:203], v[130:131]
	ds_read_b128 v[68:71], v188 offset:19328
	s_waitcnt lgkmcnt(15)
	v_pk_fma_f32 v[128:129], v[72:73], v[204:205], v[128:129]
	v_pk_fma_f32 v[130:131], v[74:75], v[206:207], v[130:131]
	ds_read_b128 v[72:75], v188 offset:19584
	s_waitcnt lgkmcnt(15)
	v_pk_fma_f32 v[128:129], v[76:77], v[208:209], v[128:129]
	v_pk_fma_f32 v[130:131], v[78:79], v[210:211], v[130:131]
	ds_read_b128 v[76:79], v188 offset:19840
	v_add_f32_e32 v128, v128, v129
	v_add_f32_e32 v130, v130, v131
	v_add_f32_e32 v190, v128, v130
	s_waitcnt lgkmcnt(15)
	v_mul_f32_e32 v153, v154, v155
	v_pk_mul_f32 v[112:113], v[112:113], v[152:153] op_sel:[0,1] op_sel_hi:[1,1]
	v_add_f32_dpp v190, v190, v190 row_ror:8 row_mask:0xf bank_mask:0xf bound_ctrl:1
	v_pk_mul_f32 v[114:115], v[114:115], v[152:153] op_sel:[0,1] op_sel_hi:[1,1]
	v_pk_mul_f32 v[116:117], v[116:117], v[152:153] op_sel:[0,1] op_sel_hi:[1,1]
	v_add_f32_dpp v190, v190, v190 row_ror:4 row_mask:0xf bank_mask:0xf bound_ctrl:1
	v_pk_mul_f32 v[118:119], v[118:119], v[152:153] op_sel:[0,1] op_sel_hi:[1,1]
	v_pk_mul_f32 v[120:121], v[120:121], v[152:153] op_sel:[0,1] op_sel_hi:[1,1]
	v_add_f32_dpp v190, v190, v190 row_ror:2 row_mask:0xf bank_mask:0xf bound_ctrl:1
	v_pk_mul_f32 v[122:123], v[122:123], v[152:153] op_sel:[0,1] op_sel_hi:[1,1]
	v_pk_mul_f32 v[124:125], v[124:125], v[152:153] op_sel:[0,1] op_sel_hi:[1,1]
	v_add_f32_dpp v190, v190, v190 row_ror:1 row_mask:0xf bank_mask:0xf bound_ctrl:1
	v_pk_mul_f32 v[126:127], v[126:127], v[152:153] op_sel:[0,1] op_sel_hi:[1,1]
	v_pk_fma_f32 v[196:197], v[152:153], v[196:197], v[112:113] op_sel_hi:[0,1,1]
	s_and_saveexec_b64 s[8:9], s[44:45]
	ds_write_b32 v189, v190 offset:34560
	s_mov_b64 exec, s[8:9]
	v_pk_fma_f32 v[198:199], v[152:153], v[198:199], v[114:115] op_sel_hi:[0,1,1]
	v_pk_fma_f32 v[200:201], v[152:153], v[200:201], v[116:117] op_sel_hi:[0,1,1]
	v_pk_fma_f32 v[202:203], v[152:153], v[202:203], v[118:119] op_sel_hi:[0,1,1]
	v_pk_fma_f32 v[204:205], v[152:153], v[204:205], v[120:121] op_sel_hi:[0,1,1]
	v_pk_fma_f32 v[206:207], v[152:153], v[206:207], v[122:123] op_sel_hi:[0,1,1]
	v_pk_fma_f32 v[208:209], v[152:153], v[208:209], v[124:125] op_sel_hi:[0,1,1]
	v_pk_fma_f32 v[210:211], v[152:153], v[210:211], v[126:127] op_sel_hi:[0,1,1]
	ds_read_b128 v[112:115], v188 offset:28288
	ds_read_b128 v[116:119], v188 offset:28544
	ds_read_b128 v[120:123], v188 offset:28800
	ds_read_b128 v[124:127], v188 offset:29056
	ds_read_b32 v154, v140 offset:35148
	ds_read_b32 v155, v189 offset:33600
	ds_read_b32 v152, v140 offset:35084
	s_waitcnt lgkmcnt(15)
	v_pk_fma_f32 v[128:129], v[96:97], v[196:197], v[192:193]
	v_pk_fma_f32 v[130:131], v[98:99], v[198:199], v[192:193]
	ds_read_b128 v[96:99], v188 offset:20096
	s_waitcnt lgkmcnt(15)
	v_pk_fma_f32 v[128:129], v[100:101], v[200:201], v[128:129]
	v_pk_fma_f32 v[130:131], v[102:103], v[202:203], v[130:131]
	ds_read_b128 v[100:103], v188 offset:20352
	s_waitcnt lgkmcnt(15)
	v_pk_fma_f32 v[128:129], v[104:105], v[204:205], v[128:129]
	v_pk_fma_f32 v[130:131], v[106:107], v[206:207], v[130:131]
	ds_read_b128 v[104:107], v188 offset:20608
	s_waitcnt lgkmcnt(15)
	v_pk_fma_f32 v[128:129], v[108:109], v[208:209], v[128:129]
	v_pk_fma_f32 v[130:131], v[110:111], v[210:211], v[130:131]
	ds_read_b128 v[108:111], v188 offset:20864
	v_add_f32_e32 v128, v128, v129
	v_add_f32_e32 v130, v130, v131
	v_add_f32_e32 v191, v128, v130
	s_waitcnt lgkmcnt(15)
	v_mul_f32_e32 v133, v134, v135
	v_pk_mul_f32 v[80:81], v[80:81], v[132:133] op_sel:[0,1] op_sel_hi:[1,1]
	v_add_f32_dpp v191, v191, v191 row_ror:8 row_mask:0xf bank_mask:0xf bound_ctrl:1
	v_pk_mul_f32 v[82:83], v[82:83], v[132:133] op_sel:[0,1] op_sel_hi:[1,1]
	v_pk_mul_f32 v[84:85], v[84:85], v[132:133] op_sel:[0,1] op_sel_hi:[1,1]
	v_add_f32_dpp v191, v191, v191 row_ror:4 row_mask:0xf bank_mask:0xf bound_ctrl:1
	v_pk_mul_f32 v[86:87], v[86:87], v[132:133] op_sel:[0,1] op_sel_hi:[1,1]
	v_pk_mul_f32 v[88:89], v[88:89], v[132:133] op_sel:[0,1] op_sel_hi:[1,1]
	v_add_f32_dpp v191, v191, v191 row_ror:2 row_mask:0xf bank_mask:0xf bound_ctrl:1
	v_pk_mul_f32 v[90:91], v[90:91], v[132:133] op_sel:[0,1] op_sel_hi:[1,1]
	v_pk_mul_f32 v[92:93], v[92:93], v[132:133] op_sel:[0,1] op_sel_hi:[1,1]
	v_add_f32_dpp v191, v191, v191 row_ror:1 row_mask:0xf bank_mask:0xf bound_ctrl:1
	v_pk_mul_f32 v[94:95], v[94:95], v[132:133] op_sel:[0,1] op_sel_hi:[1,1]
	v_pk_fma_f32 v[196:197], v[132:133], v[196:197], v[80:81] op_sel_hi:[0,1,1]
	s_and_saveexec_b64 s[8:9], s[44:45]
	ds_write_b32 v189, v191 offset:34624
	s_mov_b64 exec, s[8:9]
	v_pk_fma_f32 v[198:199], v[132:133], v[198:199], v[82:83] op_sel_hi:[0,1,1]
	v_pk_fma_f32 v[200:201], v[132:133], v[200:201], v[84:85] op_sel_hi:[0,1,1]
	v_pk_fma_f32 v[202:203], v[132:133], v[202:203], v[86:87] op_sel_hi:[0,1,1]
	v_pk_fma_f32 v[204:205], v[132:133], v[204:205], v[88:89] op_sel_hi:[0,1,1]
	v_pk_fma_f32 v[206:207], v[132:133], v[206:207], v[90:91] op_sel_hi:[0,1,1]
	v_pk_fma_f32 v[208:209], v[132:133], v[208:209], v[92:93] op_sel_hi:[0,1,1]
	v_pk_fma_f32 v[210:211], v[132:133], v[210:211], v[94:95] op_sel_hi:[0,1,1]
	ds_read_b128 v[80:83], v188 offset:29312
	ds_read_b128 v[84:87], v188 offset:29568
	ds_read_b128 v[88:91], v188 offset:29824
	ds_read_b128 v[92:95], v188 offset:30080
	ds_read_b32 v134, v140 offset:35152
	ds_read_b32 v135, v189 offset:33664
	ds_read_b32 v132, v140 offset:35088
	s_waitcnt lgkmcnt(15)
	v_pk_fma_f32 v[128:129], v[64:65], v[196:197], v[192:193]
	v_pk_fma_f32 v[130:131], v[66:67], v[198:199], v[192:193]
	ds_read_b128 v[64:67], v188 offset:21120
	s_waitcnt lgkmcnt(15)
	v_pk_fma_f32 v[128:129], v[68:69], v[200:201], v[128:129]
	v_pk_fma_f32 v[130:131], v[70:71], v[202:203], v[130:131]
	ds_read_b128 v[68:71], v188 offset:21376
	s_waitcnt lgkmcnt(15)
	v_pk_fma_f32 v[128:129], v[72:73], v[204:205], v[128:129]
	v_pk_fma_f32 v[130:131], v[74:75], v[206:207], v[130:131]
	ds_read_b128 v[72:75], v188 offset:21632
	s_waitcnt lgkmcnt(15)
	v_pk_fma_f32 v[128:129], v[76:77], v[208:209], v[128:129]
	v_pk_fma_f32 v[130:131], v[78:79], v[210:211], v[130:131]
	ds_read_b128 v[76:79], v188 offset:21888
	v_add_f32_e32 v128, v128, v129
	v_add_f32_e32 v130, v130, v131
	v_add_f32_e32 v190, v128, v130
	s_waitcnt lgkmcnt(15)
	v_mul_f32_e32 v153, v154, v155
	v_pk_mul_f32 v[112:113], v[112:113], v[152:153] op_sel:[0,1] op_sel_hi:[1,1]
	v_add_f32_dpp v190, v190, v190 row_ror:8 row_mask:0xf bank_mask:0xf bound_ctrl:1
	v_pk_mul_f32 v[114:115], v[114:115], v[152:153] op_sel:[0,1] op_sel_hi:[1,1]
	v_pk_mul_f32 v[116:117], v[116:117], v[152:153] op_sel:[0,1] op_sel_hi:[1,1]
	v_add_f32_dpp v190, v190, v190 row_ror:4 row_mask:0xf bank_mask:0xf bound_ctrl:1
	v_pk_mul_f32 v[118:119], v[118:119], v[152:153] op_sel:[0,1] op_sel_hi:[1,1]
	v_pk_mul_f32 v[120:121], v[120:121], v[152:153] op_sel:[0,1] op_sel_hi:[1,1]
	v_add_f32_dpp v190, v190, v190 row_ror:2 row_mask:0xf bank_mask:0xf bound_ctrl:1
	v_pk_mul_f32 v[122:123], v[122:123], v[152:153] op_sel:[0,1] op_sel_hi:[1,1]
	v_pk_mul_f32 v[124:125], v[124:125], v[152:153] op_sel:[0,1] op_sel_hi:[1,1]
	v_add_f32_dpp v190, v190, v190 row_ror:1 row_mask:0xf bank_mask:0xf bound_ctrl:1
	v_pk_mul_f32 v[126:127], v[126:127], v[152:153] op_sel:[0,1] op_sel_hi:[1,1]
	v_pk_fma_f32 v[196:197], v[152:153], v[196:197], v[112:113] op_sel_hi:[0,1,1]
	s_and_saveexec_b64 s[8:9], s[44:45]
	ds_write_b32 v189, v190 offset:34688
	s_mov_b64 exec, s[8:9]
	v_pk_fma_f32 v[198:199], v[152:153], v[198:199], v[114:115] op_sel_hi:[0,1,1]
	v_pk_fma_f32 v[200:201], v[152:153], v[200:201], v[116:117] op_sel_hi:[0,1,1]
	v_pk_fma_f32 v[202:203], v[152:153], v[202:203], v[118:119] op_sel_hi:[0,1,1]
	v_pk_fma_f32 v[204:205], v[152:153], v[204:205], v[120:121] op_sel_hi:[0,1,1]
	v_pk_fma_f32 v[206:207], v[152:153], v[206:207], v[122:123] op_sel_hi:[0,1,1]
	v_pk_fma_f32 v[208:209], v[152:153], v[208:209], v[124:125] op_sel_hi:[0,1,1]
	v_pk_fma_f32 v[210:211], v[152:153], v[210:211], v[126:127] op_sel_hi:[0,1,1]
	ds_read_b128 v[112:115], v188 offset:30336
	ds_read_b128 v[116:119], v188 offset:30592
	ds_read_b128 v[120:123], v188 offset:30848
	ds_read_b128 v[124:127], v188 offset:31104
	ds_read_b32 v154, v140 offset:35156
	ds_read_b32 v155, v189 offset:33728
	ds_read_b32 v152, v140 offset:35092
	s_waitcnt lgkmcnt(15)
	v_pk_fma_f32 v[128:129], v[96:97], v[196:197], v[192:193]
	v_pk_fma_f32 v[130:131], v[98:99], v[198:199], v[192:193]
	ds_read_b128 v[96:99], v188 offset:22144
	s_waitcnt lgkmcnt(15)
	v_pk_fma_f32 v[128:129], v[100:101], v[200:201], v[128:129]
	v_pk_fma_f32 v[130:131], v[102:103], v[202:203], v[130:131]
	ds_read_b128 v[100:103], v188 offset:22400
	s_waitcnt lgkmcnt(15)
	v_pk_fma_f32 v[128:129], v[104:105], v[204:205], v[128:129]
	v_pk_fma_f32 v[130:131], v[106:107], v[206:207], v[130:131]
	ds_read_b128 v[104:107], v188 offset:22656
	s_waitcnt lgkmcnt(15)
	v_pk_fma_f32 v[128:129], v[108:109], v[208:209], v[128:129]
	v_pk_fma_f32 v[130:131], v[110:111], v[210:211], v[130:131]
	ds_read_b128 v[108:111], v188 offset:22912
	v_add_f32_e32 v128, v128, v129
	v_add_f32_e32 v130, v130, v131
	v_add_f32_e32 v191, v128, v130
	s_waitcnt lgkmcnt(15)
	v_mul_f32_e32 v133, v134, v135
	v_pk_mul_f32 v[80:81], v[80:81], v[132:133] op_sel:[0,1] op_sel_hi:[1,1]
	v_add_f32_dpp v191, v191, v191 row_ror:8 row_mask:0xf bank_mask:0xf bound_ctrl:1
	v_pk_mul_f32 v[82:83], v[82:83], v[132:133] op_sel:[0,1] op_sel_hi:[1,1]
	v_pk_mul_f32 v[84:85], v[84:85], v[132:133] op_sel:[0,1] op_sel_hi:[1,1]
	v_add_f32_dpp v191, v191, v191 row_ror:4 row_mask:0xf bank_mask:0xf bound_ctrl:1
	v_pk_mul_f32 v[86:87], v[86:87], v[132:133] op_sel:[0,1] op_sel_hi:[1,1]
	v_pk_mul_f32 v[88:89], v[88:89], v[132:133] op_sel:[0,1] op_sel_hi:[1,1]
	v_add_f32_dpp v191, v191, v191 row_ror:2 row_mask:0xf bank_mask:0xf bound_ctrl:1
	v_pk_mul_f32 v[90:91], v[90:91], v[132:133] op_sel:[0,1] op_sel_hi:[1,1]
	v_pk_mul_f32 v[92:93], v[92:93], v[132:133] op_sel:[0,1] op_sel_hi:[1,1]
	v_add_f32_dpp v191, v191, v191 row_ror:1 row_mask:0xf bank_mask:0xf bound_ctrl:1
	v_pk_mul_f32 v[94:95], v[94:95], v[132:133] op_sel:[0,1] op_sel_hi:[1,1]
	v_pk_fma_f32 v[196:197], v[132:133], v[196:197], v[80:81] op_sel_hi:[0,1,1]
	s_and_saveexec_b64 s[8:9], s[44:45]
	ds_write_b32 v189, v191 offset:34752
	s_mov_b64 exec, s[8:9]
	v_pk_fma_f32 v[198:199], v[132:133], v[198:199], v[82:83] op_sel_hi:[0,1,1]
	v_pk_fma_f32 v[200:201], v[132:133], v[200:201], v[84:85] op_sel_hi:[0,1,1]
	v_pk_fma_f32 v[202:203], v[132:133], v[202:203], v[86:87] op_sel_hi:[0,1,1]
	v_pk_fma_f32 v[204:205], v[132:133], v[204:205], v[88:89] op_sel_hi:[0,1,1]
	v_pk_fma_f32 v[206:207], v[132:133], v[206:207], v[90:91] op_sel_hi:[0,1,1]
	v_pk_fma_f32 v[208:209], v[132:133], v[208:209], v[92:93] op_sel_hi:[0,1,1]
	v_pk_fma_f32 v[210:211], v[132:133], v[210:211], v[94:95] op_sel_hi:[0,1,1]
	ds_read_b128 v[80:83], v188 offset:31360
	ds_read_b128 v[84:87], v188 offset:31616
	ds_read_b128 v[88:91], v188 offset:31872
	ds_read_b128 v[92:95], v188 offset:32128
	ds_read_b32 v134, v140 offset:35160
	ds_read_b32 v135, v189 offset:33792
	ds_read_b32 v132, v140 offset:35096
	s_waitcnt lgkmcnt(15)
	v_pk_fma_f32 v[128:129], v[64:65], v[196:197], v[192:193]
	v_pk_fma_f32 v[130:131], v[66:67], v[198:199], v[192:193]
	ds_read_b128 v[64:67], v188 offset:23168
	s_waitcnt lgkmcnt(15)
	v_pk_fma_f32 v[128:129], v[68:69], v[200:201], v[128:129]
	v_pk_fma_f32 v[130:131], v[70:71], v[202:203], v[130:131]
	ds_read_b128 v[68:71], v188 offset:23424
	s_waitcnt lgkmcnt(15)
	v_pk_fma_f32 v[128:129], v[72:73], v[204:205], v[128:129]
	v_pk_fma_f32 v[130:131], v[74:75], v[206:207], v[130:131]
	ds_read_b128 v[72:75], v188 offset:23680
	s_waitcnt lgkmcnt(15)
	v_pk_fma_f32 v[128:129], v[76:77], v[208:209], v[128:129]
	v_pk_fma_f32 v[130:131], v[78:79], v[210:211], v[130:131]
	ds_read_b128 v[76:79], v188 offset:23936
	v_add_f32_e32 v128, v128, v129
	v_add_f32_e32 v130, v130, v131
	v_add_f32_e32 v190, v128, v130
	s_waitcnt lgkmcnt(15)
	v_mul_f32_e32 v153, v154, v155
	v_pk_mul_f32 v[112:113], v[112:113], v[152:153] op_sel:[0,1] op_sel_hi:[1,1]
	v_add_f32_dpp v190, v190, v190 row_ror:8 row_mask:0xf bank_mask:0xf bound_ctrl:1
	v_pk_mul_f32 v[114:115], v[114:115], v[152:153] op_sel:[0,1] op_sel_hi:[1,1]
	v_pk_mul_f32 v[116:117], v[116:117], v[152:153] op_sel:[0,1] op_sel_hi:[1,1]
	v_add_f32_dpp v190, v190, v190 row_ror:4 row_mask:0xf bank_mask:0xf bound_ctrl:1
	v_pk_mul_f32 v[118:119], v[118:119], v[152:153] op_sel:[0,1] op_sel_hi:[1,1]
	v_pk_mul_f32 v[120:121], v[120:121], v[152:153] op_sel:[0,1] op_sel_hi:[1,1]
	v_add_f32_dpp v190, v190, v190 row_ror:2 row_mask:0xf bank_mask:0xf bound_ctrl:1
	v_pk_mul_f32 v[122:123], v[122:123], v[152:153] op_sel:[0,1] op_sel_hi:[1,1]
	v_pk_mul_f32 v[124:125], v[124:125], v[152:153] op_sel:[0,1] op_sel_hi:[1,1]
	v_add_f32_dpp v190, v190, v190 row_ror:1 row_mask:0xf bank_mask:0xf bound_ctrl:1
	v_pk_mul_f32 v[126:127], v[126:127], v[152:153] op_sel:[0,1] op_sel_hi:[1,1]
	v_pk_fma_f32 v[196:197], v[152:153], v[196:197], v[112:113] op_sel_hi:[0,1,1]
	s_and_saveexec_b64 s[8:9], s[44:45]
	ds_write_b32 v189, v190 offset:34816
	s_mov_b64 exec, s[8:9]
	v_pk_fma_f32 v[198:199], v[152:153], v[198:199], v[114:115] op_sel_hi:[0,1,1]
	v_pk_fma_f32 v[200:201], v[152:153], v[200:201], v[116:117] op_sel_hi:[0,1,1]
	v_pk_fma_f32 v[202:203], v[152:153], v[202:203], v[118:119] op_sel_hi:[0,1,1]
	v_pk_fma_f32 v[204:205], v[152:153], v[204:205], v[120:121] op_sel_hi:[0,1,1]
	v_pk_fma_f32 v[206:207], v[152:153], v[206:207], v[122:123] op_sel_hi:[0,1,1]
	v_pk_fma_f32 v[208:209], v[152:153], v[208:209], v[124:125] op_sel_hi:[0,1,1]
	v_pk_fma_f32 v[210:211], v[152:153], v[210:211], v[126:127] op_sel_hi:[0,1,1]
	ds_read_b128 v[112:115], v188 offset:32384
	ds_read_b128 v[116:119], v188 offset:32640
	ds_read_b128 v[120:123], v188 offset:32896
	ds_read_b128 v[124:127], v188 offset:33152
	ds_read_b32 v154, v140 offset:35164
	ds_read_b32 v155, v189 offset:33856
	ds_read_b32 v152, v140 offset:35100
	s_waitcnt lgkmcnt(15)
	v_pk_fma_f32 v[128:129], v[96:97], v[196:197], v[192:193]
	v_pk_fma_f32 v[130:131], v[98:99], v[198:199], v[192:193]
	ds_read_b128 v[96:99], v188 offset:24192
	s_waitcnt lgkmcnt(15)
	v_pk_fma_f32 v[128:129], v[100:101], v[200:201], v[128:129]
	v_pk_fma_f32 v[130:131], v[102:103], v[202:203], v[130:131]
	ds_read_b128 v[100:103], v188 offset:24448
	s_waitcnt lgkmcnt(15)
	v_pk_fma_f32 v[128:129], v[104:105], v[204:205], v[128:129]
	v_pk_fma_f32 v[130:131], v[106:107], v[206:207], v[130:131]
	ds_read_b128 v[104:107], v188 offset:24704
	s_waitcnt lgkmcnt(15)
	v_pk_fma_f32 v[128:129], v[108:109], v[208:209], v[128:129]
	v_pk_fma_f32 v[130:131], v[110:111], v[210:211], v[130:131]
	ds_read_b128 v[108:111], v188 offset:24960
	v_add_f32_e32 v128, v128, v129
	v_add_f32_e32 v130, v130, v131
	v_add_f32_e32 v191, v128, v130
	s_waitcnt lgkmcnt(15)
	v_mul_f32_e32 v133, v134, v135
	v_pk_mul_f32 v[80:81], v[80:81], v[132:133] op_sel:[0,1] op_sel_hi:[1,1]
	v_add_f32_dpp v191, v191, v191 row_ror:8 row_mask:0xf bank_mask:0xf bound_ctrl:1
	v_pk_mul_f32 v[82:83], v[82:83], v[132:133] op_sel:[0,1] op_sel_hi:[1,1]
	v_pk_mul_f32 v[84:85], v[84:85], v[132:133] op_sel:[0,1] op_sel_hi:[1,1]
	v_add_f32_dpp v191, v191, v191 row_ror:4 row_mask:0xf bank_mask:0xf bound_ctrl:1
	v_pk_mul_f32 v[86:87], v[86:87], v[132:133] op_sel:[0,1] op_sel_hi:[1,1]
	v_pk_mul_f32 v[88:89], v[88:89], v[132:133] op_sel:[0,1] op_sel_hi:[1,1]
	v_add_f32_dpp v191, v191, v191 row_ror:2 row_mask:0xf bank_mask:0xf bound_ctrl:1
	v_pk_mul_f32 v[90:91], v[90:91], v[132:133] op_sel:[0,1] op_sel_hi:[1,1]
	v_pk_mul_f32 v[92:93], v[92:93], v[132:133] op_sel:[0,1] op_sel_hi:[1,1]
	v_add_f32_dpp v191, v191, v191 row_ror:1 row_mask:0xf bank_mask:0xf bound_ctrl:1
	v_pk_mul_f32 v[94:95], v[94:95], v[132:133] op_sel:[0,1] op_sel_hi:[1,1]
	v_pk_fma_f32 v[196:197], v[132:133], v[196:197], v[80:81] op_sel_hi:[0,1,1]
	s_and_saveexec_b64 s[8:9], s[44:45]
	ds_write_b32 v189, v191 offset:34880
	s_mov_b64 exec, s[8:9]
	v_pk_fma_f32 v[198:199], v[132:133], v[198:199], v[82:83] op_sel_hi:[0,1,1]
	v_pk_fma_f32 v[200:201], v[132:133], v[200:201], v[84:85] op_sel_hi:[0,1,1]
	v_pk_fma_f32 v[202:203], v[132:133], v[202:203], v[86:87] op_sel_hi:[0,1,1]
	v_pk_fma_f32 v[204:205], v[132:133], v[204:205], v[88:89] op_sel_hi:[0,1,1]
	v_pk_fma_f32 v[206:207], v[132:133], v[206:207], v[90:91] op_sel_hi:[0,1,1]
	v_pk_fma_f32 v[208:209], v[132:133], v[208:209], v[92:93] op_sel_hi:[0,1,1]
	v_pk_fma_f32 v[210:211], v[132:133], v[210:211], v[94:95] op_sel_hi:[0,1,1]
	s_waitcnt lgkmcnt(15)
	v_pk_fma_f32 v[128:129], v[64:65], v[196:197], v[192:193]
	v_pk_fma_f32 v[130:131], v[66:67], v[198:199], v[192:193]
	v_pk_fma_f32 v[128:129], v[68:69], v[200:201], v[128:129]
	v_pk_fma_f32 v[130:131], v[70:71], v[202:203], v[130:131]
	s_waitcnt lgkmcnt(14)
	v_pk_fma_f32 v[128:129], v[72:73], v[204:205], v[128:129]
	v_pk_fma_f32 v[130:131], v[74:75], v[206:207], v[130:131]
	s_waitcnt lgkmcnt(13)
	v_pk_fma_f32 v[128:129], v[76:77], v[208:209], v[128:129]
	v_pk_fma_f32 v[130:131], v[78:79], v[210:211], v[130:131]
	v_add_f32_e32 v128, v128, v129
	v_add_f32_e32 v130, v130, v131
	v_add_f32_e32 v190, v128, v130
	s_waitcnt lgkmcnt(6)
	v_mul_f32_e32 v153, v154, v155
	v_pk_mul_f32 v[112:113], v[112:113], v[152:153] op_sel:[0,1] op_sel_hi:[1,1]
	v_add_f32_dpp v190, v190, v190 row_ror:8 row_mask:0xf bank_mask:0xf bound_ctrl:1
	v_pk_mul_f32 v[114:115], v[114:115], v[152:153] op_sel:[0,1] op_sel_hi:[1,1]
	v_pk_mul_f32 v[116:117], v[116:117], v[152:153] op_sel:[0,1] op_sel_hi:[1,1]
	v_add_f32_dpp v190, v190, v190 row_ror:4 row_mask:0xf bank_mask:0xf bound_ctrl:1
	v_pk_mul_f32 v[118:119], v[118:119], v[152:153] op_sel:[0,1] op_sel_hi:[1,1]
	v_pk_mul_f32 v[120:121], v[120:121], v[152:153] op_sel:[0,1] op_sel_hi:[1,1]
	v_add_f32_dpp v190, v190, v190 row_ror:2 row_mask:0xf bank_mask:0xf bound_ctrl:1
	v_pk_mul_f32 v[122:123], v[122:123], v[152:153] op_sel:[0,1] op_sel_hi:[1,1]
	v_pk_mul_f32 v[124:125], v[124:125], v[152:153] op_sel:[0,1] op_sel_hi:[1,1]
	v_add_f32_dpp v190, v190, v190 row_ror:1 row_mask:0xf bank_mask:0xf bound_ctrl:1
	v_pk_mul_f32 v[126:127], v[126:127], v[152:153] op_sel:[0,1] op_sel_hi:[1,1]
	s_waitcnt lgkmcnt(5)
	v_pk_fma_f32 v[196:197], v[152:153], v[196:197], v[112:113] op_sel_hi:[0,1,1]
	s_and_saveexec_b64 s[8:9], s[44:45]
	ds_write_b32 v189, v190 offset:34944
	s_mov_b64 exec, s[8:9]
	v_pk_fma_f32 v[198:199], v[152:153], v[198:199], v[114:115] op_sel_hi:[0,1,1]
	v_pk_fma_f32 v[200:201], v[152:153], v[200:201], v[116:117] op_sel_hi:[0,1,1]
	v_pk_fma_f32 v[202:203], v[152:153], v[202:203], v[118:119] op_sel_hi:[0,1,1]
	v_pk_fma_f32 v[204:205], v[152:153], v[204:205], v[120:121] op_sel_hi:[0,1,1]
	v_pk_fma_f32 v[206:207], v[152:153], v[206:207], v[122:123] op_sel_hi:[0,1,1]
	v_pk_fma_f32 v[208:209], v[152:153], v[208:209], v[124:125] op_sel_hi:[0,1,1]
	v_pk_fma_f32 v[210:211], v[152:153], v[210:211], v[126:127] op_sel_hi:[0,1,1]
	s_waitcnt lgkmcnt(5)
	v_pk_fma_f32 v[128:129], v[96:97], v[196:197], v[192:193]
	v_pk_fma_f32 v[130:131], v[98:99], v[198:199], v[192:193]
	s_waitcnt lgkmcnt(4)
	v_pk_fma_f32 v[128:129], v[100:101], v[200:201], v[128:129]
	v_pk_fma_f32 v[130:131], v[102:103], v[202:203], v[130:131]
	s_waitcnt lgkmcnt(3)
	v_pk_fma_f32 v[128:129], v[104:105], v[204:205], v[128:129]
	v_pk_fma_f32 v[130:131], v[106:107], v[206:207], v[130:131]
	s_waitcnt lgkmcnt(2)
	v_pk_fma_f32 v[128:129], v[108:109], v[208:209], v[128:129]
	v_pk_fma_f32 v[130:131], v[110:111], v[210:211], v[130:131]
	v_add_f32_e32 v128, v128, v129
	v_add_f32_e32 v130, v130, v131
	v_add_f32_e32 v191, v128, v130
	s_nop 1
	v_add_f32_dpp v191, v191, v191 row_ror:8 row_mask:0xf bank_mask:0xf bound_ctrl:1
	s_nop 1
	v_add_f32_dpp v191, v191, v191 row_ror:4 row_mask:0xf bank_mask:0xf bound_ctrl:1
	s_nop 1
	v_add_f32_dpp v191, v191, v191 row_ror:2 row_mask:0xf bank_mask:0xf bound_ctrl:1
	s_nop 1
	v_add_f32_dpp v191, v191, v191 row_ror:1 row_mask:0xf bank_mask:0xf bound_ctrl:1
	s_and_saveexec_b64 s[8:9], s[44:45]
	ds_write_b32 v189, v191 offset:35008
	s_mov_b64 exec, s[8:9]
	s_waitcnt vmcnt(7)
	ds_write_b128 v185, v[32:35]
	s_waitcnt vmcnt(5)
	ds_write_b128 v186, v[40:43]
	ds_write_b128 v185, v[36:39] offset:8192
	s_waitcnt vmcnt(4)
	ds_write_b128 v186, v[44:47] offset:8192
	s_and_saveexec_b64 s[8:9], s[42:43]
	ds_write_b32 v144, v184 offset:16384
	s_or_b64 exec, exec, s[8:9]
	s_and_saveexec_b64 s[8:9], s[40:41]
	s_cbranch_execz .LBB0_1505
	v_add_f32_e32 v64, v156, v182
	v_mul_f32_e64 v65, |v64|, s62
	v_exp_f32_e32 v65, v65
	v_min_f32_e32 v64, 0, v64
	v_add_f32_e32 v65, 1.0, v65
	v_cmp_gt_f32_e32 vcc, s5, v65
	s_nop 1
	v_cndmask_b32_e64 v66, 0, 32, vcc
	v_ldexp_f32 v65, v65, v66
	v_log_f32_e32 v65, v65
	v_cndmask_b32_e32 v67, 0, v171, vcc
	v_add_f32_e32 v66, v145, v180
	v_mul_f32_e32 v68, 0x3f317217, v65
	v_fma_f32 v68, v65, s76, -v68
	v_fmac_f32_e32 v68, 0x3377d1cf, v65
	v_fmac_f32_e32 v68, 0x3f317217, v65
	v_cmp_lt_f32_e64 vcc, |v65|, s77
	s_nop 1
	v_cndmask_b32_e32 v65, v65, v68, vcc
	v_sub_f32_e32 v65, v65, v67
	v_sub_f32_e32 v64, v64, v65
	v_add_u32_e32 v65, 0x4000, v144
	ds_write2_b32 v65, v66, v64 offset0:128 offset1:144

.LBB0_1516:
	s_or_b64 exec, exec, s[8:9]
	s_waitcnt lgkmcnt(0)
	s_barrier
	v_mov_b32_e32 v192, 0
	v_mov_b32_e32 v193, 0
	ds_read_b128 v[80:83], v188 offset:8192
	ds_read_b128 v[84:87], v188 offset:8448
	ds_read_b128 v[88:91], v188 offset:8704
	ds_read_b128 v[92:95], v188 offset:8960
	ds_read_b32 v134, v140 offset:35136
	ds_read_b32 v135, v189 offset:16384
	ds_read_b32 v132, v140 offset:35072
	ds_read_b128 v[64:67], v188
	ds_read_b128 v[68:71], v188 offset:256
	ds_read_b128 v[72:75], v188 offset:512
	ds_read_b128 v[76:79], v188 offset:768
	ds_read_b128 v[112:115], v188 offset:9216
	ds_read_b128 v[116:119], v188 offset:9472
	ds_read_b128 v[120:123], v188 offset:9728
	ds_read_b128 v[124:127], v188 offset:9984
	ds_read_b32 v154, v140 offset:35140
	ds_read_b32 v155, v189 offset:16448
	ds_read_b32 v152, v140 offset:35076
	ds_read_b128 v[96:99], v188 offset:1024
	ds_read_b128 v[100:103], v188 offset:1280
	ds_read_b128 v[104:107], v188 offset:1536
	ds_read_b128 v[108:111], v188 offset:1792
	s_waitcnt lgkmcnt(15)
	v_mul_f32_e32 v133, v134, v135
	v_pk_mul_f32 v[80:81], v[80:81], v[132:133] op_sel:[0,1] op_sel_hi:[1,1]
	v_pk_mul_f32 v[82:83], v[82:83], v[132:133] op_sel:[0,1] op_sel_hi:[1,1]
	v_pk_mul_f32 v[84:85], v[84:85], v[132:133] op_sel:[0,1] op_sel_hi:[1,1]
	v_pk_mul_f32 v[86:87], v[86:87], v[132:133] op_sel:[0,1] op_sel_hi:[1,1]
	v_pk_mul_f32 v[88:89], v[88:89], v[132:133] op_sel:[0,1] op_sel_hi:[1,1]
	v_pk_mul_f32 v[90:91], v[90:91], v[132:133] op_sel:[0,1] op_sel_hi:[1,1]
	v_pk_mul_f32 v[92:93], v[92:93], v[132:133] op_sel:[0,1] op_sel_hi:[1,1]
	v_pk_mul_f32 v[94:95], v[94:95], v[132:133] op_sel:[0,1] op_sel_hi:[1,1]
	v_pk_fma_f32 v[196:197], v[132:133], v[196:197], v[80:81] op_sel_hi:[0,1,1]
	v_pk_fma_f32 v[198:199], v[132:133], v[198:199], v[82:83] op_sel_hi:[0,1,1]
	v_pk_fma_f32 v[200:201], v[132:133], v[200:201], v[84:85] op_sel_hi:[0,1,1]
	v_pk_fma_f32 v[202:203], v[132:133], v[202:203], v[86:87] op_sel_hi:[0,1,1]
	v_pk_fma_f32 v[204:205], v[132:133], v[204:205], v[88:89] op_sel_hi:[0,1,1]
	v_pk_fma_f32 v[206:207], v[132:133], v[206:207], v[90:91] op_sel_hi:[0,1,1]
	v_pk_fma_f32 v[208:209], v[132:133], v[208:209], v[92:93] op_sel_hi:[0,1,1]
	v_pk_fma_f32 v[210:211], v[132:133], v[210:211], v[94:95] op_sel_hi:[0,1,1]
	ds_read_b128 v[80:83], v188 offset:10240
	ds_read_b128 v[84:87], v188 offset:10496
	ds_read_b128 v[88:91], v188 offset:10752
	ds_read_b128 v[92:95], v188 offset:11008
	ds_read_b32 v134, v140 offset:35144
	ds_read_b32 v135, v189 offset:16512
	ds_read_b32 v132, v140 offset:35080
	s_waitcnt lgkmcnt(15)
	v_pk_fma_f32 v[128:129], v[64:65], v[196:197], v[192:193]
	v_pk_fma_f32 v[130:131], v[66:67], v[198:199], v[192:193]
	ds_read_b128 v[64:67], v188 offset:2048
	s_waitcnt lgkmcnt(15)
	v_pk_fma_f32 v[128:129], v[68:69], v[200:201], v[128:129]
	v_pk_fma_f32 v[130:131], v[70:71], v[202:203], v[130:131]
	ds_read_b128 v[68:71], v188 offset:2304
	s_waitcnt lgkmcnt(15)
	v_pk_fma_f32 v[128:129], v[72:73], v[204:205], v[128:129]
	v_pk_fma_f32 v[130:131], v[74:75], v[206:207], v[130:131]
	ds_read_b128 v[72:75], v188 offset:2560
	s_waitcnt lgkmcnt(15)
	v_pk_fma_f32 v[128:129], v[76:77], v[208:209], v[128:129]
	v_pk_fma_f32 v[130:131], v[78:79], v[210:211], v[130:131]
	ds_read_b128 v[76:79], v188 offset:2816
	v_add_f32_e32 v128, v128, v129
	v_add_f32_e32 v130, v130, v131
	v_add_f32_e32 v190, v128, v130
	s_waitcnt lgkmcnt(15)
	v_mul_f32_e32 v153, v154, v155
	v_pk_mul_f32 v[112:113], v[112:113], v[152:153] op_sel:[0,1] op_sel_hi:[1,1]
	v_add_f32_dpp v190, v190, v190 row_ror:8 row_mask:0xf bank_mask:0xf bound_ctrl:1
	v_pk_mul_f32 v[114:115], v[114:115], v[152:153] op_sel:[0,1] op_sel_hi:[1,1]
	v_pk_mul_f32 v[116:117], v[116:117], v[152:153] op_sel:[0,1] op_sel_hi:[1,1]
	v_add_f32_dpp v190, v190, v190 row_ror:4 row_mask:0xf bank_mask:0xf bound_ctrl:1
	v_pk_mul_f32 v[118:119], v[118:119], v[152:153] op_sel:[0,1] op_sel_hi:[1,1]
	v_pk_mul_f32 v[120:121], v[120:121], v[152:153] op_sel:[0,1] op_sel_hi:[1,1]
	v_add_f32_dpp v190, v190, v190 row_ror:2 row_mask:0xf bank_mask:0xf bound_ctrl:1
	v_pk_mul_f32 v[122:123], v[122:123], v[152:153] op_sel:[0,1] op_sel_hi:[1,1]
	v_pk_mul_f32 v[124:125], v[124:125], v[152:153] op_sel:[0,1] op_sel_hi:[1,1]
	v_add_f32_dpp v190, v190, v190 row_ror:1 row_mask:0xf bank_mask:0xf bound_ctrl:1
	v_pk_mul_f32 v[126:127], v[126:127], v[152:153] op_sel:[0,1] op_sel_hi:[1,1]
	v_pk_fma_f32 v[196:197], v[152:153], v[196:197], v[112:113] op_sel_hi:[0,1,1]
	s_and_saveexec_b64 s[8:9], s[44:45]
	ds_write_b32 v189, v190 offset:34048
	s_mov_b64 exec, s[8:9]
	v_pk_fma_f32 v[198:199], v[152:153], v[198:199], v[114:115] op_sel_hi:[0,1,1]
	v_pk_fma_f32 v[200:201], v[152:153], v[200:201], v[116:117] op_sel_hi:[0,1,1]
	v_pk_fma_f32 v[202:203], v[152:153], v[202:203], v[118:119] op_sel_hi:[0,1,1]
	v_pk_fma_f32 v[204:205], v[152:153], v[204:205], v[120:121] op_sel_hi:[0,1,1]
	v_pk_fma_f32 v[206:207], v[152:153], v[206:207], v[122:123] op_sel_hi:[0,1,1]
	v_pk_fma_f32 v[208:209], v[152:153], v[208:209], v[124:125] op_sel_hi:[0,1,1]
	v_pk_fma_f32 v[210:211], v[152:153], v[210:211], v[126:127] op_sel_hi:[0,1,1]
	ds_read_b128 v[112:115], v188 offset:11264
	ds_read_b128 v[116:119], v188 offset:11520
	ds_read_b128 v[120:123], v188 offset:11776
	ds_read_b128 v[124:127], v188 offset:12032
	ds_read_b32 v154, v140 offset:35148
	ds_read_b32 v155, v189 offset:16576
	ds_read_b32 v152, v140 offset:35084
	s_waitcnt lgkmcnt(15)
	v_pk_fma_f32 v[128:129], v[96:97], v[196:197], v[192:193]
	v_pk_fma_f32 v[130:131], v[98:99], v[198:199], v[192:193]
	ds_read_b128 v[96:99], v188 offset:3072
	s_waitcnt lgkmcnt(15)
	v_pk_fma_f32 v[128:129], v[100:101], v[200:201], v[128:129]
	v_pk_fma_f32 v[130:131], v[102:103], v[202:203], v[130:131]
	ds_read_b128 v[100:103], v188 offset:3328
	s_waitcnt lgkmcnt(15)
	v_pk_fma_f32 v[128:129], v[104:105], v[204:205], v[128:129]
	v_pk_fma_f32 v[130:131], v[106:107], v[206:207], v[130:131]
	ds_read_b128 v[104:107], v188 offset:3584
	s_waitcnt lgkmcnt(15)
	v_pk_fma_f32 v[128:129], v[108:109], v[208:209], v[128:129]
	v_pk_fma_f32 v[130:131], v[110:111], v[210:211], v[130:131]
	ds_read_b128 v[108:111], v188 offset:3840
	v_add_f32_e32 v128, v128, v129
	v_add_f32_e32 v130, v130, v131
	v_add_f32_e32 v191, v128, v130
	s_waitcnt lgkmcnt(15)
	v_mul_f32_e32 v133, v134, v135
	v_pk_mul_f32 v[80:81], v[80:81], v[132:133] op_sel:[0,1] op_sel_hi:[1,1]
	v_add_f32_dpp v191, v191, v191 row_ror:8 row_mask:0xf bank_mask:0xf bound_ctrl:1
	v_pk_mul_f32 v[82:83], v[82:83], v[132:133] op_sel:[0,1] op_sel_hi:[1,1]
	v_pk_mul_f32 v[84:85], v[84:85], v[132:133] op_sel:[0,1] op_sel_hi:[1,1]
	v_add_f32_dpp v191, v191, v191 row_ror:4 row_mask:0xf bank_mask:0xf bound_ctrl:1
	v_pk_mul_f32 v[86:87], v[86:87], v[132:133] op_sel:[0,1] op_sel_hi:[1,1]
	v_pk_mul_f32 v[88:89], v[88:89], v[132:133] op_sel:[0,1] op_sel_hi:[1,1]
	v_add_f32_dpp v191, v191, v191 row_ror:2 row_mask:0xf bank_mask:0xf bound_ctrl:1
	v_pk_mul_f32 v[90:91], v[90:91], v[132:133] op_sel:[0,1] op_sel_hi:[1,1]
	v_pk_mul_f32 v[92:93], v[92:93], v[132:133] op_sel:[0,1] op_sel_hi:[1,1]
	v_add_f32_dpp v191, v191, v191 row_ror:1 row_mask:0xf bank_mask:0xf bound_ctrl:1
	v_pk_mul_f32 v[94:95], v[94:95], v[132:133] op_sel:[0,1] op_sel_hi:[1,1]
	v_pk_fma_f32 v[196:197], v[132:133], v[196:197], v[80:81] op_sel_hi:[0,1,1]
	s_and_saveexec_b64 s[8:9], s[44:45]
	ds_write_b32 v189, v191 offset:34112
	s_mov_b64 exec, s[8:9]
	v_pk_fma_f32 v[198:199], v[132:133], v[198:199], v[82:83] op_sel_hi:[0,1,1]
	v_pk_fma_f32 v[200:201], v[132:133], v[200:201], v[84:85] op_sel_hi:[0,1,1]
	v_pk_fma_f32 v[202:203], v[132:133], v[202:203], v[86:87] op_sel_hi:[0,1,1]
	v_pk_fma_f32 v[204:205], v[132:133], v[204:205], v[88:89] op_sel_hi:[0,1,1]
	v_pk_fma_f32 v[206:207], v[132:133], v[206:207], v[90:91] op_sel_hi:[0,1,1]
	v_pk_fma_f32 v[208:209], v[132:133], v[208:209], v[92:93] op_sel_hi:[0,1,1]
	v_pk_fma_f32 v[210:211], v[132:133], v[210:211], v[94:95] op_sel_hi:[0,1,1]
	ds_read_b128 v[80:83], v188 offset:12288
	ds_read_b128 v[84:87], v188 offset:12544
	ds_read_b128 v[88:91], v188 offset:12800
	ds_read_b128 v[92:95], v188 offset:13056
	ds_read_b32 v134, v140 offset:35152
	ds_read_b32 v135, v189 offset:16640
	ds_read_b32 v132, v140 offset:35088
	s_waitcnt lgkmcnt(15)
	v_pk_fma_f32 v[128:129], v[64:65], v[196:197], v[192:193]
	v_pk_fma_f32 v[130:131], v[66:67], v[198:199], v[192:193]
	ds_read_b128 v[64:67], v188 offset:4096
	s_waitcnt lgkmcnt(15)
	v_pk_fma_f32 v[128:129], v[68:69], v[200:201], v[128:129]
	v_pk_fma_f32 v[130:131], v[70:71], v[202:203], v[130:131]
	ds_read_b128 v[68:71], v188 offset:4352
	s_waitcnt lgkmcnt(15)
	v_pk_fma_f32 v[128:129], v[72:73], v[204:205], v[128:129]
	v_pk_fma_f32 v[130:131], v[74:75], v[206:207], v[130:131]
	ds_read_b128 v[72:75], v188 offset:4608
	s_waitcnt lgkmcnt(15)
	v_pk_fma_f32 v[128:129], v[76:77], v[208:209], v[128:129]
	v_pk_fma_f32 v[130:131], v[78:79], v[210:211], v[130:131]
	ds_read_b128 v[76:79], v188 offset:4864
	v_add_f32_e32 v128, v128, v129
	v_add_f32_e32 v130, v130, v131
	v_add_f32_e32 v190, v128, v130
	s_waitcnt lgkmcnt(15)
	v_mul_f32_e32 v153, v154, v155
	v_pk_mul_f32 v[112:113], v[112:113], v[152:153] op_sel:[0,1] op_sel_hi:[1,1]
	v_add_f32_dpp v190, v190, v190 row_ror:8 row_mask:0xf bank_mask:0xf bound_ctrl:1
	v_pk_mul_f32 v[114:115], v[114:115], v[152:153] op_sel:[0,1] op_sel_hi:[1,1]
	v_pk_mul_f32 v[116:117], v[116:117], v[152:153] op_sel:[0,1] op_sel_hi:[1,1]
	v_add_f32_dpp v190, v190, v190 row_ror:4 row_mask:0xf bank_mask:0xf bound_ctrl:1
	v_pk_mul_f32 v[118:119], v[118:119], v[152:153] op_sel:[0,1] op_sel_hi:[1,1]
	v_pk_mul_f32 v[120:121], v[120:121], v[152:153] op_sel:[0,1] op_sel_hi:[1,1]
	v_add_f32_dpp v190, v190, v190 row_ror:2 row_mask:0xf bank_mask:0xf bound_ctrl:1
	v_pk_mul_f32 v[122:123], v[122:123], v[152:153] op_sel:[0,1] op_sel_hi:[1,1]
	v_pk_mul_f32 v[124:125], v[124:125], v[152:153] op_sel:[0,1] op_sel_hi:[1,1]
	v_add_f32_dpp v190, v190, v190 row_ror:1 row_mask:0xf bank_mask:0xf bound_ctrl:1
	v_pk_mul_f32 v[126:127], v[126:127], v[152:153] op_sel:[0,1] op_sel_hi:[1,1]
	v_pk_fma_f32 v[196:197], v[152:153], v[196:197], v[112:113] op_sel_hi:[0,1,1]
	s_and_saveexec_b64 s[8:9], s[44:45]
	ds_write_b32 v189, v190 offset:34176
	s_mov_b64 exec, s[8:9]
	v_pk_fma_f32 v[198:199], v[152:153], v[198:199], v[114:115] op_sel_hi:[0,1,1]
	v_pk_fma_f32 v[200:201], v[152:153], v[200:201], v[116:117] op_sel_hi:[0,1,1]
	v_pk_fma_f32 v[202:203], v[152:153], v[202:203], v[118:119] op_sel_hi:[0,1,1]
	v_pk_fma_f32 v[204:205], v[152:153], v[204:205], v[120:121] op_sel_hi:[0,1,1]
	v_pk_fma_f32 v[206:207], v[152:153], v[206:207], v[122:123] op_sel_hi:[0,1,1]
	v_pk_fma_f32 v[208:209], v[152:153], v[208:209], v[124:125] op_sel_hi:[0,1,1]
	v_pk_fma_f32 v[210:211], v[152:153], v[210:211], v[126:127] op_sel_hi:[0,1,1]
	ds_read_b128 v[112:115], v188 offset:13312
	ds_read_b128 v[116:119], v188 offset:13568
	ds_read_b128 v[120:123], v188 offset:13824
	ds_read_b128 v[124:127], v188 offset:14080
	ds_read_b32 v154, v140 offset:35156
	ds_read_b32 v155, v189 offset:16704
	ds_read_b32 v152, v140 offset:35092
	s_waitcnt lgkmcnt(15)
	v_pk_fma_f32 v[128:129], v[96:97], v[196:197], v[192:193]
	v_pk_fma_f32 v[130:131], v[98:99], v[198:199], v[192:193]
	ds_read_b128 v[96:99], v188 offset:5120
	s_waitcnt lgkmcnt(15)
	v_pk_fma_f32 v[128:129], v[100:101], v[200:201], v[128:129]
	v_pk_fma_f32 v[130:131], v[102:103], v[202:203], v[130:131]
	ds_read_b128 v[100:103], v188 offset:5376
	s_waitcnt lgkmcnt(15)
	v_pk_fma_f32 v[128:129], v[104:105], v[204:205], v[128:129]
	v_pk_fma_f32 v[130:131], v[106:107], v[206:207], v[130:131]
	ds_read_b128 v[104:107], v188 offset:5632
	s_waitcnt lgkmcnt(15)
	v_pk_fma_f32 v[128:129], v[108:109], v[208:209], v[128:129]
	v_pk_fma_f32 v[130:131], v[110:111], v[210:211], v[130:131]
	ds_read_b128 v[108:111], v188 offset:5888
	v_add_f32_e32 v128, v128, v129
	v_add_f32_e32 v130, v130, v131
	v_add_f32_e32 v191, v128, v130
	s_waitcnt lgkmcnt(15)
	v_mul_f32_e32 v133, v134, v135
	v_pk_mul_f32 v[80:81], v[80:81], v[132:133] op_sel:[0,1] op_sel_hi:[1,1]
	v_add_f32_dpp v191, v191, v191 row_ror:8 row_mask:0xf bank_mask:0xf bound_ctrl:1
	v_pk_mul_f32 v[82:83], v[82:83], v[132:133] op_sel:[0,1] op_sel_hi:[1,1]
	v_pk_mul_f32 v[84:85], v[84:85], v[132:133] op_sel:[0,1] op_sel_hi:[1,1]
	v_add_f32_dpp v191, v191, v191 row_ror:4 row_mask:0xf bank_mask:0xf bound_ctrl:1
	v_pk_mul_f32 v[86:87], v[86:87], v[132:133] op_sel:[0,1] op_sel_hi:[1,1]
	v_pk_mul_f32 v[88:89], v[88:89], v[132:133] op_sel:[0,1] op_sel_hi:[1,1]
	v_add_f32_dpp v191, v191, v191 row_ror:2 row_mask:0xf bank_mask:0xf bound_ctrl:1
	v_pk_mul_f32 v[90:91], v[90:91], v[132:133] op_sel:[0,1] op_sel_hi:[1,1]
	v_pk_mul_f32 v[92:93], v[92:93], v[132:133] op_sel:[0,1] op_sel_hi:[1,1]
	v_add_f32_dpp v191, v191, v191 row_ror:1 row_mask:0xf bank_mask:0xf bound_ctrl:1
	v_pk_mul_f32 v[94:95], v[94:95], v[132:133] op_sel:[0,1] op_sel_hi:[1,1]
	v_pk_fma_f32 v[196:197], v[132:133], v[196:197], v[80:81] op_sel_hi:[0,1,1]
	s_and_saveexec_b64 s[8:9], s[44:45]
	ds_write_b32 v189, v191 offset:34240
	s_mov_b64 exec, s[8:9]
	v_pk_fma_f32 v[198:199], v[132:133], v[198:199], v[82:83] op_sel_hi:[0,1,1]
	v_pk_fma_f32 v[200:201], v[132:133], v[200:201], v[84:85] op_sel_hi:[0,1,1]
	v_pk_fma_f32 v[202:203], v[132:133], v[202:203], v[86:87] op_sel_hi:[0,1,1]
	v_pk_fma_f32 v[204:205], v[132:133], v[204:205], v[88:89] op_sel_hi:[0,1,1]
	v_pk_fma_f32 v[206:207], v[132:133], v[206:207], v[90:91] op_sel_hi:[0,1,1]
	v_pk_fma_f32 v[208:209], v[132:133], v[208:209], v[92:93] op_sel_hi:[0,1,1]
	v_pk_fma_f32 v[210:211], v[132:133], v[210:211], v[94:95] op_sel_hi:[0,1,1]
	ds_read_b128 v[80:83], v188 offset:14336
	ds_read_b128 v[84:87], v188 offset:14592
	ds_read_b128 v[88:91], v188 offset:14848
	ds_read_b128 v[92:95], v188 offset:15104
	ds_read_b32 v134, v140 offset:35160
	ds_read_b32 v135, v189 offset:16768
	ds_read_b32 v132, v140 offset:35096
	s_waitcnt lgkmcnt(15)
	v_pk_fma_f32 v[128:129], v[64:65], v[196:197], v[192:193]
	v_pk_fma_f32 v[130:131], v[66:67], v[198:199], v[192:193]
	ds_read_b128 v[64:67], v188 offset:6144
	s_waitcnt lgkmcnt(15)
	v_pk_fma_f32 v[128:129], v[68:69], v[200:201], v[128:129]
	v_pk_fma_f32 v[130:131], v[70:71], v[202:203], v[130:131]
	ds_read_b128 v[68:71], v188 offset:6400
	s_waitcnt lgkmcnt(15)
	v_pk_fma_f32 v[128:129], v[72:73], v[204:205], v[128:129]
	v_pk_fma_f32 v[130:131], v[74:75], v[206:207], v[130:131]
	ds_read_b128 v[72:75], v188 offset:6656
	s_waitcnt lgkmcnt(15)
	v_pk_fma_f32 v[128:129], v[76:77], v[208:209], v[128:129]
	v_pk_fma_f32 v[130:131], v[78:79], v[210:211], v[130:131]
	ds_read_b128 v[76:79], v188 offset:6912
	v_add_f32_e32 v128, v128, v129
	v_add_f32_e32 v130, v130, v131
	v_add_f32_e32 v190, v128, v130
	s_waitcnt lgkmcnt(15)
	v_mul_f32_e32 v153, v154, v155
	v_pk_mul_f32 v[112:113], v[112:113], v[152:153] op_sel:[0,1] op_sel_hi:[1,1]
	v_add_f32_dpp v190, v190, v190 row_ror:8 row_mask:0xf bank_mask:0xf bound_ctrl:1
	v_pk_mul_f32 v[114:115], v[114:115], v[152:153] op_sel:[0,1] op_sel_hi:[1,1]
	v_pk_mul_f32 v[116:117], v[116:117], v[152:153] op_sel:[0,1] op_sel_hi:[1,1]
	v_add_f32_dpp v190, v190, v190 row_ror:4 row_mask:0xf bank_mask:0xf bound_ctrl:1
	v_pk_mul_f32 v[118:119], v[118:119], v[152:153] op_sel:[0,1] op_sel_hi:[1,1]
	v_pk_mul_f32 v[120:121], v[120:121], v[152:153] op_sel:[0,1] op_sel_hi:[1,1]
	v_add_f32_dpp v190, v190, v190 row_ror:2 row_mask:0xf bank_mask:0xf bound_ctrl:1
	v_pk_mul_f32 v[122:123], v[122:123], v[152:153] op_sel:[0,1] op_sel_hi:[1,1]
	v_pk_mul_f32 v[124:125], v[124:125], v[152:153] op_sel:[0,1] op_sel_hi:[1,1]
	v_add_f32_dpp v190, v190, v190 row_ror:1 row_mask:0xf bank_mask:0xf bound_ctrl:1
	v_pk_mul_f32 v[126:127], v[126:127], v[152:153] op_sel:[0,1] op_sel_hi:[1,1]
	v_pk_fma_f32 v[196:197], v[152:153], v[196:197], v[112:113] op_sel_hi:[0,1,1]
	s_and_saveexec_b64 s[8:9], s[44:45]
	ds_write_b32 v189, v190 offset:34304
	s_mov_b64 exec, s[8:9]
	v_pk_fma_f32 v[198:199], v[152:153], v[198:199], v[114:115] op_sel_hi:[0,1,1]
	v_pk_fma_f32 v[200:201], v[152:153], v[200:201], v[116:117] op_sel_hi:[0,1,1]
	v_pk_fma_f32 v[202:203], v[152:153], v[202:203], v[118:119] op_sel_hi:[0,1,1]
	v_pk_fma_f32 v[204:205], v[152:153], v[204:205], v[120:121] op_sel_hi:[0,1,1]
	v_pk_fma_f32 v[206:207], v[152:153], v[206:207], v[122:123] op_sel_hi:[0,1,1]
	v_pk_fma_f32 v[208:209], v[152:153], v[208:209], v[124:125] op_sel_hi:[0,1,1]
	v_pk_fma_f32 v[210:211], v[152:153], v[210:211], v[126:127] op_sel_hi:[0,1,1]
	ds_read_b128 v[112:115], v188 offset:15360
	ds_read_b128 v[116:119], v188 offset:15616
	ds_read_b128 v[120:123], v188 offset:15872
	ds_read_b128 v[124:127], v188 offset:16128
	ds_read_b32 v154, v140 offset:35164
	ds_read_b32 v155, v189 offset:16832
	ds_read_b32 v152, v140 offset:35100
	s_waitcnt lgkmcnt(15)
	v_pk_fma_f32 v[128:129], v[96:97], v[196:197], v[192:193]
	v_pk_fma_f32 v[130:131], v[98:99], v[198:199], v[192:193]
	ds_read_b128 v[96:99], v188 offset:7168
	s_waitcnt lgkmcnt(15)
	v_pk_fma_f32 v[128:129], v[100:101], v[200:201], v[128:129]
	v_pk_fma_f32 v[130:131], v[102:103], v[202:203], v[130:131]
	ds_read_b128 v[100:103], v188 offset:7424
	s_waitcnt lgkmcnt(15)
	v_pk_fma_f32 v[128:129], v[104:105], v[204:205], v[128:129]
	v_pk_fma_f32 v[130:131], v[106:107], v[206:207], v[130:131]
	ds_read_b128 v[104:107], v188 offset:7680
	s_waitcnt lgkmcnt(15)
	v_pk_fma_f32 v[128:129], v[108:109], v[208:209], v[128:129]
	v_pk_fma_f32 v[130:131], v[110:111], v[210:211], v[130:131]
	ds_read_b128 v[108:111], v188 offset:7936
	v_add_f32_e32 v128, v128, v129
	v_add_f32_e32 v130, v130, v131
	v_add_f32_e32 v191, v128, v130
	s_waitcnt lgkmcnt(15)
	v_mul_f32_e32 v133, v134, v135
	v_pk_mul_f32 v[80:81], v[80:81], v[132:133] op_sel:[0,1] op_sel_hi:[1,1]
	v_add_f32_dpp v191, v191, v191 row_ror:8 row_mask:0xf bank_mask:0xf bound_ctrl:1
	v_pk_mul_f32 v[82:83], v[82:83], v[132:133] op_sel:[0,1] op_sel_hi:[1,1]
	v_pk_mul_f32 v[84:85], v[84:85], v[132:133] op_sel:[0,1] op_sel_hi:[1,1]
	v_add_f32_dpp v191, v191, v191 row_ror:4 row_mask:0xf bank_mask:0xf bound_ctrl:1
	v_pk_mul_f32 v[86:87], v[86:87], v[132:133] op_sel:[0,1] op_sel_hi:[1,1]
	v_pk_mul_f32 v[88:89], v[88:89], v[132:133] op_sel:[0,1] op_sel_hi:[1,1]
	v_add_f32_dpp v191, v191, v191 row_ror:2 row_mask:0xf bank_mask:0xf bound_ctrl:1
	v_pk_mul_f32 v[90:91], v[90:91], v[132:133] op_sel:[0,1] op_sel_hi:[1,1]
	v_pk_mul_f32 v[92:93], v[92:93], v[132:133] op_sel:[0,1] op_sel_hi:[1,1]
	v_add_f32_dpp v191, v191, v191 row_ror:1 row_mask:0xf bank_mask:0xf bound_ctrl:1
	v_pk_mul_f32 v[94:95], v[94:95], v[132:133] op_sel:[0,1] op_sel_hi:[1,1]
	v_pk_fma_f32 v[196:197], v[132:133], v[196:197], v[80:81] op_sel_hi:[0,1,1]
	s_and_saveexec_b64 s[8:9], s[44:45]
	ds_write_b32 v189, v191 offset:34368
	s_mov_b64 exec, s[8:9]
	v_pk_fma_f32 v[198:199], v[132:133], v[198:199], v[82:83] op_sel_hi:[0,1,1]
	v_pk_fma_f32 v[200:201], v[132:133], v[200:201], v[84:85] op_sel_hi:[0,1,1]
	v_pk_fma_f32 v[202:203], v[132:133], v[202:203], v[86:87] op_sel_hi:[0,1,1]
	v_pk_fma_f32 v[204:205], v[132:133], v[204:205], v[88:89] op_sel_hi:[0,1,1]
	v_pk_fma_f32 v[206:207], v[132:133], v[206:207], v[90:91] op_sel_hi:[0,1,1]
	v_pk_fma_f32 v[208:209], v[132:133], v[208:209], v[92:93] op_sel_hi:[0,1,1]
	v_pk_fma_f32 v[210:211], v[132:133], v[210:211], v[94:95] op_sel_hi:[0,1,1]
	s_waitcnt lgkmcnt(15)
	v_pk_fma_f32 v[128:129], v[64:65], v[196:197], v[192:193]
	v_pk_fma_f32 v[130:131], v[66:67], v[198:199], v[192:193]
	v_pk_fma_f32 v[128:129], v[68:69], v[200:201], v[128:129]
	v_pk_fma_f32 v[130:131], v[70:71], v[202:203], v[130:131]
	s_waitcnt lgkmcnt(14)
	v_pk_fma_f32 v[128:129], v[72:73], v[204:205], v[128:129]
	v_pk_fma_f32 v[130:131], v[74:75], v[206:207], v[130:131]
	s_waitcnt lgkmcnt(13)
	v_pk_fma_f32 v[128:129], v[76:77], v[208:209], v[128:129]
	v_pk_fma_f32 v[130:131], v[78:79], v[210:211], v[130:131]
	v_add_f32_e32 v128, v128, v129
	v_add_f32_e32 v130, v130, v131
	v_add_f32_e32 v190, v128, v130
	s_waitcnt lgkmcnt(6)
	v_mul_f32_e32 v153, v154, v155
	v_pk_mul_f32 v[112:113], v[112:113], v[152:153] op_sel:[0,1] op_sel_hi:[1,1]
	v_add_f32_dpp v190, v190, v190 row_ror:8 row_mask:0xf bank_mask:0xf bound_ctrl:1
	v_pk_mul_f32 v[114:115], v[114:115], v[152:153] op_sel:[0,1] op_sel_hi:[1,1]
	v_pk_mul_f32 v[116:117], v[116:117], v[152:153] op_sel:[0,1] op_sel_hi:[1,1]
	v_add_f32_dpp v190, v190, v190 row_ror:4 row_mask:0xf bank_mask:0xf bound_ctrl:1
	v_pk_mul_f32 v[118:119], v[118:119], v[152:153] op_sel:[0,1] op_sel_hi:[1,1]
	v_pk_mul_f32 v[120:121], v[120:121], v[152:153] op_sel:[0,1] op_sel_hi:[1,1]
	v_add_f32_dpp v190, v190, v190 row_ror:2 row_mask:0xf bank_mask:0xf bound_ctrl:1
	v_pk_mul_f32 v[122:123], v[122:123], v[152:153] op_sel:[0,1] op_sel_hi:[1,1]
	v_pk_mul_f32 v[124:125], v[124:125], v[152:153] op_sel:[0,1] op_sel_hi:[1,1]
	v_add_f32_dpp v190, v190, v190 row_ror:1 row_mask:0xf bank_mask:0xf bound_ctrl:1
	v_pk_mul_f32 v[126:127], v[126:127], v[152:153] op_sel:[0,1] op_sel_hi:[1,1]
	s_waitcnt lgkmcnt(5)
	v_pk_fma_f32 v[196:197], v[152:153], v[196:197], v[112:113] op_sel_hi:[0,1,1]
	s_and_saveexec_b64 s[8:9], s[44:45]
	ds_write_b32 v189, v190 offset:34432
	s_mov_b64 exec, s[8:9]
	v_pk_fma_f32 v[198:199], v[152:153], v[198:199], v[114:115] op_sel_hi:[0,1,1]
	v_pk_fma_f32 v[200:201], v[152:153], v[200:201], v[116:117] op_sel_hi:[0,1,1]
	v_pk_fma_f32 v[202:203], v[152:153], v[202:203], v[118:119] op_sel_hi:[0,1,1]
	v_pk_fma_f32 v[204:205], v[152:153], v[204:205], v[120:121] op_sel_hi:[0,1,1]
	v_pk_fma_f32 v[206:207], v[152:153], v[206:207], v[122:123] op_sel_hi:[0,1,1]
	v_pk_fma_f32 v[208:209], v[152:153], v[208:209], v[124:125] op_sel_hi:[0,1,1]
	v_pk_fma_f32 v[210:211], v[152:153], v[210:211], v[126:127] op_sel_hi:[0,1,1]
	s_waitcnt lgkmcnt(5)
	v_pk_fma_f32 v[128:129], v[96:97], v[196:197], v[192:193]
	v_pk_fma_f32 v[130:131], v[98:99], v[198:199], v[192:193]
	s_waitcnt lgkmcnt(4)
	v_pk_fma_f32 v[128:129], v[100:101], v[200:201], v[128:129]
	v_pk_fma_f32 v[130:131], v[102:103], v[202:203], v[130:131]
	s_waitcnt lgkmcnt(3)
	v_pk_fma_f32 v[128:129], v[104:105], v[204:205], v[128:129]
	v_pk_fma_f32 v[130:131], v[106:107], v[206:207], v[130:131]
	s_waitcnt lgkmcnt(2)
	v_pk_fma_f32 v[128:129], v[108:109], v[208:209], v[128:129]
	v_pk_fma_f32 v[130:131], v[110:111], v[210:211], v[130:131]
	v_add_f32_e32 v128, v128, v129
	v_add_f32_e32 v130, v130, v131
	v_add_f32_e32 v191, v128, v130
	s_nop 1
	v_add_f32_dpp v191, v191, v191 row_ror:8 row_mask:0xf bank_mask:0xf bound_ctrl:1
	s_nop 1
	v_add_f32_dpp v191, v191, v191 row_ror:4 row_mask:0xf bank_mask:0xf bound_ctrl:1
	s_nop 1
	v_add_f32_dpp v191, v191, v191 row_ror:2 row_mask:0xf bank_mask:0xf bound_ctrl:1
	s_nop 1
	v_add_f32_dpp v191, v191, v191 row_ror:1 row_mask:0xf bank_mask:0xf bound_ctrl:1
	s_and_saveexec_b64 s[8:9], s[44:45]
	ds_write_b32 v189, v191 offset:34496
	s_mov_b64 exec, s[8:9]
	s_waitcnt vmcnt(3)
	ds_write_b128 v185, v[48:51] offset:17024
	s_waitcnt vmcnt(1)
	ds_write_b128 v186, v[56:59] offset:17024
	ds_write_b128 v185, v[52:55] offset:25216
	s_waitcnt vmcnt(0)
	ds_write_b128 v186, v[60:63] offset:25216
	s_and_saveexec_b64 s[8:9], s[42:43]
	ds_write_b32 v144, v184 offset:33408
	s_or_b64 exec, exec, s[8:9]
	s_and_saveexec_b64 s[8:9], s[40:41]
	s_cbranch_execz .LBB0_1536
	v_add_f32_e32 v64, v156, v181
	v_mul_f32_e64 v65, |v64|, s62
	v_exp_f32_e32 v65, v65
	v_min_f32_e32 v64, 0, v64
	v_add_f32_e32 v65, 1.0, v65
	v_cmp_gt_f32_e32 vcc, s5, v65
	s_nop 1
	v_cndmask_b32_e64 v66, 0, 32, vcc
	v_ldexp_f32 v65, v65, v66
	v_log_f32_e32 v65, v65
	v_cndmask_b32_e32 v67, 0, v171, vcc
	v_add_f32_e32 v66, v145, v187
	v_mul_f32_e32 v68, 0x3f317217, v65
	v_fma_f32 v68, v65, s76, -v68
	v_fmac_f32_e32 v68, 0x3377d1cf, v65
	v_fmac_f32_e32 v68, 0x3f317217, v65
	v_cmp_lt_f32_e64 vcc, |v65|, s77
	s_nop 1
	v_cndmask_b32_e32 v65, v65, v68, vcc
	v_sub_f32_e32 v65, v65, v67
	v_sub_f32_e32 v64, v64, v65
	v_add_u32_e32 v65, 0x8400, v144
	ds_write2_b32 v65, v66, v64 offset0:32 offset1:48

.LBB0_1547:
	s_or_b64 exec, exec, s[8:9]
	s_waitcnt lgkmcnt(0)
	s_barrier
	v_mov_b32_e32 v192, 0
	v_mov_b32_e32 v193, 0
	ds_read_b128 v[80:83], v188 offset:25216
	ds_read_b128 v[84:87], v188 offset:25472
	ds_read_b128 v[88:91], v188 offset:25728
	ds_read_b128 v[92:95], v188 offset:25984
	ds_read_b32 v134, v140 offset:35136
	ds_read_b32 v135, v189 offset:33408
	ds_read_b32 v132, v140 offset:35072
	ds_read_b128 v[64:67], v188 offset:17024
	ds_read_b128 v[68:71], v188 offset:17280
	ds_read_b128 v[72:75], v188 offset:17536
	ds_read_b128 v[76:79], v188 offset:17792
	ds_read_b128 v[112:115], v188 offset:26240
	ds_read_b128 v[116:119], v188 offset:26496
	ds_read_b128 v[120:123], v188 offset:26752
	ds_read_b128 v[124:127], v188 offset:27008
	ds_read_b32 v154, v140 offset:35140
	ds_read_b32 v155, v189 offset:33472
	ds_read_b32 v152, v140 offset:35076
	ds_read_b128 v[96:99], v188 offset:18048
	ds_read_b128 v[100:103], v188 offset:18304
	ds_read_b128 v[104:107], v188 offset:18560
	ds_read_b128 v[108:111], v188 offset:18816
	s_waitcnt lgkmcnt(15)
	v_mul_f32_e32 v133, v134, v135
	v_pk_mul_f32 v[80:81], v[80:81], v[132:133] op_sel:[0,1] op_sel_hi:[1,1]
	v_pk_mul_f32 v[82:83], v[82:83], v[132:133] op_sel:[0,1] op_sel_hi:[1,1]
	v_pk_mul_f32 v[84:85], v[84:85], v[132:133] op_sel:[0,1] op_sel_hi:[1,1]
	v_pk_mul_f32 v[86:87], v[86:87], v[132:133] op_sel:[0,1] op_sel_hi:[1,1]
	v_pk_mul_f32 v[88:89], v[88:89], v[132:133] op_sel:[0,1] op_sel_hi:[1,1]
	v_pk_mul_f32 v[90:91], v[90:91], v[132:133] op_sel:[0,1] op_sel_hi:[1,1]
	v_pk_mul_f32 v[92:93], v[92:93], v[132:133] op_sel:[0,1] op_sel_hi:[1,1]
	v_pk_mul_f32 v[94:95], v[94:95], v[132:133] op_sel:[0,1] op_sel_hi:[1,1]
	v_pk_fma_f32 v[196:197], v[132:133], v[196:197], v[80:81] op_sel_hi:[0,1,1]
	v_pk_fma_f32 v[198:199], v[132:133], v[198:199], v[82:83] op_sel_hi:[0,1,1]
	v_pk_fma_f32 v[200:201], v[132:133], v[200:201], v[84:85] op_sel_hi:[0,1,1]
	v_pk_fma_f32 v[202:203], v[132:133], v[202:203], v[86:87] op_sel_hi:[0,1,1]
	v_pk_fma_f32 v[204:205], v[132:133], v[204:205], v[88:89] op_sel_hi:[0,1,1]
	v_pk_fma_f32 v[206:207], v[132:133], v[206:207], v[90:91] op_sel_hi:[0,1,1]
	v_pk_fma_f32 v[208:209], v[132:133], v[208:209], v[92:93] op_sel_hi:[0,1,1]
	v_pk_fma_f32 v[210:211], v[132:133], v[210:211], v[94:95] op_sel_hi:[0,1,1]
	ds_read_b128 v[80:83], v188 offset:27264
	ds_read_b128 v[84:87], v188 offset:27520
	ds_read_b128 v[88:91], v188 offset:27776
	ds_read_b128 v[92:95], v188 offset:28032
	ds_read_b32 v134, v140 offset:35144
	ds_read_b32 v135, v189 offset:33536
	ds_read_b32 v132, v140 offset:35080
	s_waitcnt lgkmcnt(15)
	v_pk_fma_f32 v[128:129], v[64:65], v[196:197], v[192:193]
	v_pk_fma_f32 v[130:131], v[66:67], v[198:199], v[192:193]
	ds_read_b128 v[64:67], v188 offset:19072
	s_waitcnt lgkmcnt(15)
	v_pk_fma_f32 v[128:129], v[68:69], v[200:201], v[128:129]
	v_pk_fma_f32 v[130:131], v[70:71], v[202:203], v[130:131]
	ds_read_b128 v[68:71], v188 offset:19328
	s_waitcnt lgkmcnt(15)
	v_pk_fma_f32 v[128:129], v[72:73], v[204:205], v[128:129]
	v_pk_fma_f32 v[130:131], v[74:75], v[206:207], v[130:131]
	ds_read_b128 v[72:75], v188 offset:19584
	s_waitcnt lgkmcnt(15)
	v_pk_fma_f32 v[128:129], v[76:77], v[208:209], v[128:129]
	v_pk_fma_f32 v[130:131], v[78:79], v[210:211], v[130:131]
	ds_read_b128 v[76:79], v188 offset:19840
	v_add_f32_e32 v128, v128, v129
	v_add_f32_e32 v130, v130, v131
	v_add_f32_e32 v190, v128, v130
	s_waitcnt lgkmcnt(15)
	v_mul_f32_e32 v153, v154, v155
	v_pk_mul_f32 v[112:113], v[112:113], v[152:153] op_sel:[0,1] op_sel_hi:[1,1]
	v_add_f32_dpp v190, v190, v190 row_ror:8 row_mask:0xf bank_mask:0xf bound_ctrl:1
	v_pk_mul_f32 v[114:115], v[114:115], v[152:153] op_sel:[0,1] op_sel_hi:[1,1]
	v_pk_mul_f32 v[116:117], v[116:117], v[152:153] op_sel:[0,1] op_sel_hi:[1,1]
	v_add_f32_dpp v190, v190, v190 row_ror:4 row_mask:0xf bank_mask:0xf bound_ctrl:1
	v_pk_mul_f32 v[118:119], v[118:119], v[152:153] op_sel:[0,1] op_sel_hi:[1,1]
	v_pk_mul_f32 v[120:121], v[120:121], v[152:153] op_sel:[0,1] op_sel_hi:[1,1]
	v_add_f32_dpp v190, v190, v190 row_ror:2 row_mask:0xf bank_mask:0xf bound_ctrl:1
	v_pk_mul_f32 v[122:123], v[122:123], v[152:153] op_sel:[0,1] op_sel_hi:[1,1]
	v_pk_mul_f32 v[124:125], v[124:125], v[152:153] op_sel:[0,1] op_sel_hi:[1,1]
	v_add_f32_dpp v190, v190, v190 row_ror:1 row_mask:0xf bank_mask:0xf bound_ctrl:1
	v_pk_mul_f32 v[126:127], v[126:127], v[152:153] op_sel:[0,1] op_sel_hi:[1,1]
	v_pk_fma_f32 v[196:197], v[152:153], v[196:197], v[112:113] op_sel_hi:[0,1,1]
	s_and_saveexec_b64 s[8:9], s[44:45]
	ds_write_b32 v189, v190 offset:34560
	s_mov_b64 exec, s[8:9]
	v_pk_fma_f32 v[198:199], v[152:153], v[198:199], v[114:115] op_sel_hi:[0,1,1]
	v_pk_fma_f32 v[200:201], v[152:153], v[200:201], v[116:117] op_sel_hi:[0,1,1]
	v_pk_fma_f32 v[202:203], v[152:153], v[202:203], v[118:119] op_sel_hi:[0,1,1]
	v_pk_fma_f32 v[204:205], v[152:153], v[204:205], v[120:121] op_sel_hi:[0,1,1]
	v_pk_fma_f32 v[206:207], v[152:153], v[206:207], v[122:123] op_sel_hi:[0,1,1]
	v_pk_fma_f32 v[208:209], v[152:153], v[208:209], v[124:125] op_sel_hi:[0,1,1]
	v_pk_fma_f32 v[210:211], v[152:153], v[210:211], v[126:127] op_sel_hi:[0,1,1]
	ds_read_b128 v[112:115], v188 offset:28288
	ds_read_b128 v[116:119], v188 offset:28544
	ds_read_b128 v[120:123], v188 offset:28800
	ds_read_b128 v[124:127], v188 offset:29056
	ds_read_b32 v154, v140 offset:35148
	ds_read_b32 v155, v189 offset:33600
	ds_read_b32 v152, v140 offset:35084
	s_waitcnt lgkmcnt(15)
	v_pk_fma_f32 v[128:129], v[96:97], v[196:197], v[192:193]
	v_pk_fma_f32 v[130:131], v[98:99], v[198:199], v[192:193]
	ds_read_b128 v[96:99], v188 offset:20096
	s_waitcnt lgkmcnt(15)
	v_pk_fma_f32 v[128:129], v[100:101], v[200:201], v[128:129]
	v_pk_fma_f32 v[130:131], v[102:103], v[202:203], v[130:131]
	ds_read_b128 v[100:103], v188 offset:20352
	s_waitcnt lgkmcnt(15)
	v_pk_fma_f32 v[128:129], v[104:105], v[204:205], v[128:129]
	v_pk_fma_f32 v[130:131], v[106:107], v[206:207], v[130:131]
	ds_read_b128 v[104:107], v188 offset:20608
	s_waitcnt lgkmcnt(15)
	v_pk_fma_f32 v[128:129], v[108:109], v[208:209], v[128:129]
	v_pk_fma_f32 v[130:131], v[110:111], v[210:211], v[130:131]
	ds_read_b128 v[108:111], v188 offset:20864
	v_add_f32_e32 v128, v128, v129
	v_add_f32_e32 v130, v130, v131
	v_add_f32_e32 v191, v128, v130
	s_waitcnt lgkmcnt(15)
	v_mul_f32_e32 v133, v134, v135
	v_pk_mul_f32 v[80:81], v[80:81], v[132:133] op_sel:[0,1] op_sel_hi:[1,1]
	v_add_f32_dpp v191, v191, v191 row_ror:8 row_mask:0xf bank_mask:0xf bound_ctrl:1
	v_pk_mul_f32 v[82:83], v[82:83], v[132:133] op_sel:[0,1] op_sel_hi:[1,1]
	v_pk_mul_f32 v[84:85], v[84:85], v[132:133] op_sel:[0,1] op_sel_hi:[1,1]
	v_add_f32_dpp v191, v191, v191 row_ror:4 row_mask:0xf bank_mask:0xf bound_ctrl:1
	v_pk_mul_f32 v[86:87], v[86:87], v[132:133] op_sel:[0,1] op_sel_hi:[1,1]
	v_pk_mul_f32 v[88:89], v[88:89], v[132:133] op_sel:[0,1] op_sel_hi:[1,1]
	v_add_f32_dpp v191, v191, v191 row_ror:2 row_mask:0xf bank_mask:0xf bound_ctrl:1
	v_pk_mul_f32 v[90:91], v[90:91], v[132:133] op_sel:[0,1] op_sel_hi:[1,1]
	v_pk_mul_f32 v[92:93], v[92:93], v[132:133] op_sel:[0,1] op_sel_hi:[1,1]
	v_add_f32_dpp v191, v191, v191 row_ror:1 row_mask:0xf bank_mask:0xf bound_ctrl:1
	v_pk_mul_f32 v[94:95], v[94:95], v[132:133] op_sel:[0,1] op_sel_hi:[1,1]
	v_pk_fma_f32 v[196:197], v[132:133], v[196:197], v[80:81] op_sel_hi:[0,1,1]
	s_and_saveexec_b64 s[8:9], s[44:45]
	ds_write_b32 v189, v191 offset:34624
	s_mov_b64 exec, s[8:9]
	v_pk_fma_f32 v[198:199], v[132:133], v[198:199], v[82:83] op_sel_hi:[0,1,1]
	v_pk_fma_f32 v[200:201], v[132:133], v[200:201], v[84:85] op_sel_hi:[0,1,1]
	v_pk_fma_f32 v[202:203], v[132:133], v[202:203], v[86:87] op_sel_hi:[0,1,1]
	v_pk_fma_f32 v[204:205], v[132:133], v[204:205], v[88:89] op_sel_hi:[0,1,1]
	v_pk_fma_f32 v[206:207], v[132:133], v[206:207], v[90:91] op_sel_hi:[0,1,1]
	v_pk_fma_f32 v[208:209], v[132:133], v[208:209], v[92:93] op_sel_hi:[0,1,1]
	v_pk_fma_f32 v[210:211], v[132:133], v[210:211], v[94:95] op_sel_hi:[0,1,1]
	ds_read_b128 v[80:83], v188 offset:29312
	ds_read_b128 v[84:87], v188 offset:29568
	ds_read_b128 v[88:91], v188 offset:29824
	ds_read_b128 v[92:95], v188 offset:30080
	ds_read_b32 v134, v140 offset:35152
	ds_read_b32 v135, v189 offset:33664
	ds_read_b32 v132, v140 offset:35088
	s_waitcnt lgkmcnt(15)
	v_pk_fma_f32 v[128:129], v[64:65], v[196:197], v[192:193]
	v_pk_fma_f32 v[130:131], v[66:67], v[198:199], v[192:193]
	ds_read_b128 v[64:67], v188 offset:21120
	s_waitcnt lgkmcnt(15)
	v_pk_fma_f32 v[128:129], v[68:69], v[200:201], v[128:129]
	v_pk_fma_f32 v[130:131], v[70:71], v[202:203], v[130:131]
	ds_read_b128 v[68:71], v188 offset:21376
	s_waitcnt lgkmcnt(15)
	v_pk_fma_f32 v[128:129], v[72:73], v[204:205], v[128:129]
	v_pk_fma_f32 v[130:131], v[74:75], v[206:207], v[130:131]
	ds_read_b128 v[72:75], v188 offset:21632
	s_waitcnt lgkmcnt(15)
	v_pk_fma_f32 v[128:129], v[76:77], v[208:209], v[128:129]
	v_pk_fma_f32 v[130:131], v[78:79], v[210:211], v[130:131]
	ds_read_b128 v[76:79], v188 offset:21888
	v_add_f32_e32 v128, v128, v129
	v_add_f32_e32 v130, v130, v131
	v_add_f32_e32 v190, v128, v130
	s_waitcnt lgkmcnt(15)
	v_mul_f32_e32 v153, v154, v155
	v_pk_mul_f32 v[112:113], v[112:113], v[152:153] op_sel:[0,1] op_sel_hi:[1,1]
	v_add_f32_dpp v190, v190, v190 row_ror:8 row_mask:0xf bank_mask:0xf bound_ctrl:1
	v_pk_mul_f32 v[114:115], v[114:115], v[152:153] op_sel:[0,1] op_sel_hi:[1,1]
	v_pk_mul_f32 v[116:117], v[116:117], v[152:153] op_sel:[0,1] op_sel_hi:[1,1]
	v_add_f32_dpp v190, v190, v190 row_ror:4 row_mask:0xf bank_mask:0xf bound_ctrl:1
	v_pk_mul_f32 v[118:119], v[118:119], v[152:153] op_sel:[0,1] op_sel_hi:[1,1]
	v_pk_mul_f32 v[120:121], v[120:121], v[152:153] op_sel:[0,1] op_sel_hi:[1,1]
	v_add_f32_dpp v190, v190, v190 row_ror:2 row_mask:0xf bank_mask:0xf bound_ctrl:1
	v_pk_mul_f32 v[122:123], v[122:123], v[152:153] op_sel:[0,1] op_sel_hi:[1,1]
	v_pk_mul_f32 v[124:125], v[124:125], v[152:153] op_sel:[0,1] op_sel_hi:[1,1]
	v_add_f32_dpp v190, v190, v190 row_ror:1 row_mask:0xf bank_mask:0xf bound_ctrl:1
	v_pk_mul_f32 v[126:127], v[126:127], v[152:153] op_sel:[0,1] op_sel_hi:[1,1]
	v_pk_fma_f32 v[196:197], v[152:153], v[196:197], v[112:113] op_sel_hi:[0,1,1]
	s_and_saveexec_b64 s[8:9], s[44:45]
	ds_write_b32 v189, v190 offset:34688
	s_mov_b64 exec, s[8:9]
	v_pk_fma_f32 v[198:199], v[152:153], v[198:199], v[114:115] op_sel_hi:[0,1,1]
	v_pk_fma_f32 v[200:201], v[152:153], v[200:201], v[116:117] op_sel_hi:[0,1,1]
	v_pk_fma_f32 v[202:203], v[152:153], v[202:203], v[118:119] op_sel_hi:[0,1,1]
	v_pk_fma_f32 v[204:205], v[152:153], v[204:205], v[120:121] op_sel_hi:[0,1,1]
	v_pk_fma_f32 v[206:207], v[152:153], v[206:207], v[122:123] op_sel_hi:[0,1,1]
	v_pk_fma_f32 v[208:209], v[152:153], v[208:209], v[124:125] op_sel_hi:[0,1,1]
	v_pk_fma_f32 v[210:211], v[152:153], v[210:211], v[126:127] op_sel_hi:[0,1,1]
	ds_read_b128 v[112:115], v188 offset:30336
	ds_read_b128 v[116:119], v188 offset:30592
	ds_read_b128 v[120:123], v188 offset:30848
	ds_read_b128 v[124:127], v188 offset:31104
	ds_read_b32 v154, v140 offset:35156
	ds_read_b32 v155, v189 offset:33728
	ds_read_b32 v152, v140 offset:35092
	s_waitcnt lgkmcnt(15)
	v_pk_fma_f32 v[128:129], v[96:97], v[196:197], v[192:193]
	v_pk_fma_f32 v[130:131], v[98:99], v[198:199], v[192:193]
	ds_read_b128 v[96:99], v188 offset:22144
	s_waitcnt lgkmcnt(15)
	v_pk_fma_f32 v[128:129], v[100:101], v[200:201], v[128:129]
	v_pk_fma_f32 v[130:131], v[102:103], v[202:203], v[130:131]
	ds_read_b128 v[100:103], v188 offset:22400
	s_waitcnt lgkmcnt(15)
	v_pk_fma_f32 v[128:129], v[104:105], v[204:205], v[128:129]
	v_pk_fma_f32 v[130:131], v[106:107], v[206:207], v[130:131]
	ds_read_b128 v[104:107], v188 offset:22656
	s_waitcnt lgkmcnt(15)
	v_pk_fma_f32 v[128:129], v[108:109], v[208:209], v[128:129]
	v_pk_fma_f32 v[130:131], v[110:111], v[210:211], v[130:131]
	ds_read_b128 v[108:111], v188 offset:22912
	v_add_f32_e32 v128, v128, v129
	v_add_f32_e32 v130, v130, v131
	v_add_f32_e32 v191, v128, v130
	s_waitcnt lgkmcnt(15)
	v_mul_f32_e32 v133, v134, v135
	v_pk_mul_f32 v[80:81], v[80:81], v[132:133] op_sel:[0,1] op_sel_hi:[1,1]
	v_add_f32_dpp v191, v191, v191 row_ror:8 row_mask:0xf bank_mask:0xf bound_ctrl:1
	v_pk_mul_f32 v[82:83], v[82:83], v[132:133] op_sel:[0,1] op_sel_hi:[1,1]
	v_pk_mul_f32 v[84:85], v[84:85], v[132:133] op_sel:[0,1] op_sel_hi:[1,1]
	v_add_f32_dpp v191, v191, v191 row_ror:4 row_mask:0xf bank_mask:0xf bound_ctrl:1
	v_pk_mul_f32 v[86:87], v[86:87], v[132:133] op_sel:[0,1] op_sel_hi:[1,1]
	v_pk_mul_f32 v[88:89], v[88:89], v[132:133] op_sel:[0,1] op_sel_hi:[1,1]
	v_add_f32_dpp v191, v191, v191 row_ror:2 row_mask:0xf bank_mask:0xf bound_ctrl:1
	v_pk_mul_f32 v[90:91], v[90:91], v[132:133] op_sel:[0,1] op_sel_hi:[1,1]
	v_pk_mul_f32 v[92:93], v[92:93], v[132:133] op_sel:[0,1] op_sel_hi:[1,1]
	v_add_f32_dpp v191, v191, v191 row_ror:1 row_mask:0xf bank_mask:0xf bound_ctrl:1
	v_pk_mul_f32 v[94:95], v[94:95], v[132:133] op_sel:[0,1] op_sel_hi:[1,1]
	v_pk_fma_f32 v[196:197], v[132:133], v[196:197], v[80:81] op_sel_hi:[0,1,1]
	s_and_saveexec_b64 s[8:9], s[44:45]
	ds_write_b32 v189, v191 offset:34752
	s_mov_b64 exec, s[8:9]
	v_pk_fma_f32 v[198:199], v[132:133], v[198:199], v[82:83] op_sel_hi:[0,1,1]
	v_pk_fma_f32 v[200:201], v[132:133], v[200:201], v[84:85] op_sel_hi:[0,1,1]
	v_pk_fma_f32 v[202:203], v[132:133], v[202:203], v[86:87] op_sel_hi:[0,1,1]
	v_pk_fma_f32 v[204:205], v[132:133], v[204:205], v[88:89] op_sel_hi:[0,1,1]
	v_pk_fma_f32 v[206:207], v[132:133], v[206:207], v[90:91] op_sel_hi:[0,1,1]
	v_pk_fma_f32 v[208:209], v[132:133], v[208:209], v[92:93] op_sel_hi:[0,1,1]
	v_pk_fma_f32 v[210:211], v[132:133], v[210:211], v[94:95] op_sel_hi:[0,1,1]
	ds_read_b128 v[80:83], v188 offset:31360
	ds_read_b128 v[84:87], v188 offset:31616
	ds_read_b128 v[88:91], v188 offset:31872
	ds_read_b128 v[92:95], v188 offset:32128
	ds_read_b32 v134, v140 offset:35160
	ds_read_b32 v135, v189 offset:33792
	ds_read_b32 v132, v140 offset:35096
	s_waitcnt lgkmcnt(15)
	v_pk_fma_f32 v[128:129], v[64:65], v[196:197], v[192:193]
	v_pk_fma_f32 v[130:131], v[66:67], v[198:199], v[192:193]
	ds_read_b128 v[64:67], v188 offset:23168
	s_waitcnt lgkmcnt(15)
	v_pk_fma_f32 v[128:129], v[68:69], v[200:201], v[128:129]
	v_pk_fma_f32 v[130:131], v[70:71], v[202:203], v[130:131]
	ds_read_b128 v[68:71], v188 offset:23424
	s_waitcnt lgkmcnt(15)
	v_pk_fma_f32 v[128:129], v[72:73], v[204:205], v[128:129]
	v_pk_fma_f32 v[130:131], v[74:75], v[206:207], v[130:131]
	ds_read_b128 v[72:75], v188 offset:23680
	s_waitcnt lgkmcnt(15)
	v_pk_fma_f32 v[128:129], v[76:77], v[208:209], v[128:129]
	v_pk_fma_f32 v[130:131], v[78:79], v[210:211], v[130:131]
	ds_read_b128 v[76:79], v188 offset:23936
	v_add_f32_e32 v128, v128, v129
	v_add_f32_e32 v130, v130, v131
	v_add_f32_e32 v190, v128, v130
	s_waitcnt lgkmcnt(15)
	v_mul_f32_e32 v153, v154, v155
	v_pk_mul_f32 v[112:113], v[112:113], v[152:153] op_sel:[0,1] op_sel_hi:[1,1]
	v_add_f32_dpp v190, v190, v190 row_ror:8 row_mask:0xf bank_mask:0xf bound_ctrl:1
	v_pk_mul_f32 v[114:115], v[114:115], v[152:153] op_sel:[0,1] op_sel_hi:[1,1]
	v_pk_mul_f32 v[116:117], v[116:117], v[152:153] op_sel:[0,1] op_sel_hi:[1,1]
	v_add_f32_dpp v190, v190, v190 row_ror:4 row_mask:0xf bank_mask:0xf bound_ctrl:1
	v_pk_mul_f32 v[118:119], v[118:119], v[152:153] op_sel:[0,1] op_sel_hi:[1,1]
	v_pk_mul_f32 v[120:121], v[120:121], v[152:153] op_sel:[0,1] op_sel_hi:[1,1]
	v_add_f32_dpp v190, v190, v190 row_ror:2 row_mask:0xf bank_mask:0xf bound_ctrl:1
	v_pk_mul_f32 v[122:123], v[122:123], v[152:153] op_sel:[0,1] op_sel_hi:[1,1]
	v_pk_mul_f32 v[124:125], v[124:125], v[152:153] op_sel:[0,1] op_sel_hi:[1,1]
	v_add_f32_dpp v190, v190, v190 row_ror:1 row_mask:0xf bank_mask:0xf bound_ctrl:1
	v_pk_mul_f32 v[126:127], v[126:127], v[152:153] op_sel:[0,1] op_sel_hi:[1,1]
	v_pk_fma_f32 v[196:197], v[152:153], v[196:197], v[112:113] op_sel_hi:[0,1,1]
	s_and_saveexec_b64 s[8:9], s[44:45]
	ds_write_b32 v189, v190 offset:34816
	s_mov_b64 exec, s[8:9]
	v_pk_fma_f32 v[198:199], v[152:153], v[198:199], v[114:115] op_sel_hi:[0,1,1]
	v_pk_fma_f32 v[200:201], v[152:153], v[200:201], v[116:117] op_sel_hi:[0,1,1]
	v_pk_fma_f32 v[202:203], v[152:153], v[202:203], v[118:119] op_sel_hi:[0,1,1]
	v_pk_fma_f32 v[204:205], v[152:153], v[204:205], v[120:121] op_sel_hi:[0,1,1]
	v_pk_fma_f32 v[206:207], v[152:153], v[206:207], v[122:123] op_sel_hi:[0,1,1]
	v_pk_fma_f32 v[208:209], v[152:153], v[208:209], v[124:125] op_sel_hi:[0,1,1]
	v_pk_fma_f32 v[210:211], v[152:153], v[210:211], v[126:127] op_sel_hi:[0,1,1]
	ds_read_b128 v[112:115], v188 offset:32384
	ds_read_b128 v[116:119], v188 offset:32640
	ds_read_b128 v[120:123], v188 offset:32896
	ds_read_b128 v[124:127], v188 offset:33152
	ds_read_b32 v154, v140 offset:35164
	ds_read_b32 v155, v189 offset:33856
	ds_read_b32 v152, v140 offset:35100
	s_waitcnt lgkmcnt(15)
	v_pk_fma_f32 v[128:129], v[96:97], v[196:197], v[192:193]
	v_pk_fma_f32 v[130:131], v[98:99], v[198:199], v[192:193]
	ds_read_b128 v[96:99], v188 offset:24192
	s_waitcnt lgkmcnt(15)
	v_pk_fma_f32 v[128:129], v[100:101], v[200:201], v[128:129]
	v_pk_fma_f32 v[130:131], v[102:103], v[202:203], v[130:131]
	ds_read_b128 v[100:103], v188 offset:24448
	s_waitcnt lgkmcnt(15)
	v_pk_fma_f32 v[128:129], v[104:105], v[204:205], v[128:129]
	v_pk_fma_f32 v[130:131], v[106:107], v[206:207], v[130:131]
	ds_read_b128 v[104:107], v188 offset:24704
	s_waitcnt lgkmcnt(15)
	v_pk_fma_f32 v[128:129], v[108:109], v[208:209], v[128:129]
	v_pk_fma_f32 v[130:131], v[110:111], v[210:211], v[130:131]
	ds_read_b128 v[108:111], v188 offset:24960
	v_add_f32_e32 v128, v128, v129
	v_add_f32_e32 v130, v130, v131
	v_add_f32_e32 v191, v128, v130
	s_waitcnt lgkmcnt(15)
	v_mul_f32_e32 v133, v134, v135
	v_pk_mul_f32 v[80:81], v[80:81], v[132:133] op_sel:[0,1] op_sel_hi:[1,1]
	v_add_f32_dpp v191, v191, v191 row_ror:8 row_mask:0xf bank_mask:0xf bound_ctrl:1
	v_pk_mul_f32 v[82:83], v[82:83], v[132:133] op_sel:[0,1] op_sel_hi:[1,1]
	v_pk_mul_f32 v[84:85], v[84:85], v[132:133] op_sel:[0,1] op_sel_hi:[1,1]
	v_add_f32_dpp v191, v191, v191 row_ror:4 row_mask:0xf bank_mask:0xf bound_ctrl:1
	v_pk_mul_f32 v[86:87], v[86:87], v[132:133] op_sel:[0,1] op_sel_hi:[1,1]
	v_pk_mul_f32 v[88:89], v[88:89], v[132:133] op_sel:[0,1] op_sel_hi:[1,1]
	v_add_f32_dpp v191, v191, v191 row_ror:2 row_mask:0xf bank_mask:0xf bound_ctrl:1
	v_pk_mul_f32 v[90:91], v[90:91], v[132:133] op_sel:[0,1] op_sel_hi:[1,1]
	v_pk_mul_f32 v[92:93], v[92:93], v[132:133] op_sel:[0,1] op_sel_hi:[1,1]
	v_add_f32_dpp v191, v191, v191 row_ror:1 row_mask:0xf bank_mask:0xf bound_ctrl:1
	v_pk_mul_f32 v[94:95], v[94:95], v[132:133] op_sel:[0,1] op_sel_hi:[1,1]
	v_pk_fma_f32 v[196:197], v[132:133], v[196:197], v[80:81] op_sel_hi:[0,1,1]
	s_and_saveexec_b64 s[8:9], s[44:45]
	ds_write_b32 v189, v191 offset:34880
	s_mov_b64 exec, s[8:9]
	v_pk_fma_f32 v[198:199], v[132:133], v[198:199], v[82:83] op_sel_hi:[0,1,1]
	v_pk_fma_f32 v[200:201], v[132:133], v[200:201], v[84:85] op_sel_hi:[0,1,1]
	v_pk_fma_f32 v[202:203], v[132:133], v[202:203], v[86:87] op_sel_hi:[0,1,1]
	v_pk_fma_f32 v[204:205], v[132:133], v[204:205], v[88:89] op_sel_hi:[0,1,1]
	v_pk_fma_f32 v[206:207], v[132:133], v[206:207], v[90:91] op_sel_hi:[0,1,1]
	v_pk_fma_f32 v[208:209], v[132:133], v[208:209], v[92:93] op_sel_hi:[0,1,1]
	v_pk_fma_f32 v[210:211], v[132:133], v[210:211], v[94:95] op_sel_hi:[0,1,1]
	s_waitcnt lgkmcnt(15)
	v_pk_fma_f32 v[128:129], v[64:65], v[196:197], v[192:193]
	v_pk_fma_f32 v[130:131], v[66:67], v[198:199], v[192:193]
	v_pk_fma_f32 v[128:129], v[68:69], v[200:201], v[128:129]
	v_pk_fma_f32 v[130:131], v[70:71], v[202:203], v[130:131]
	s_waitcnt lgkmcnt(14)
	v_pk_fma_f32 v[128:129], v[72:73], v[204:205], v[128:129]
	v_pk_fma_f32 v[130:131], v[74:75], v[206:207], v[130:131]
	s_waitcnt lgkmcnt(13)
	v_pk_fma_f32 v[128:129], v[76:77], v[208:209], v[128:129]
	v_pk_fma_f32 v[130:131], v[78:79], v[210:211], v[130:131]
	v_add_f32_e32 v128, v128, v129
	v_add_f32_e32 v130, v130, v131
	v_add_f32_e32 v190, v128, v130
	s_waitcnt lgkmcnt(6)
	v_mul_f32_e32 v153, v154, v155
	v_pk_mul_f32 v[112:113], v[112:113], v[152:153] op_sel:[0,1] op_sel_hi:[1,1]
	v_add_f32_dpp v190, v190, v190 row_ror:8 row_mask:0xf bank_mask:0xf bound_ctrl:1
	v_pk_mul_f32 v[114:115], v[114:115], v[152:153] op_sel:[0,1] op_sel_hi:[1,1]
	v_pk_mul_f32 v[116:117], v[116:117], v[152:153] op_sel:[0,1] op_sel_hi:[1,1]
	v_add_f32_dpp v190, v190, v190 row_ror:4 row_mask:0xf bank_mask:0xf bound_ctrl:1
	v_pk_mul_f32 v[118:119], v[118:119], v[152:153] op_sel:[0,1] op_sel_hi:[1,1]
	v_pk_mul_f32 v[120:121], v[120:121], v[152:153] op_sel:[0,1] op_sel_hi:[1,1]
	v_add_f32_dpp v190, v190, v190 row_ror:2 row_mask:0xf bank_mask:0xf bound_ctrl:1
	v_pk_mul_f32 v[122:123], v[122:123], v[152:153] op_sel:[0,1] op_sel_hi:[1,1]
	v_pk_mul_f32 v[124:125], v[124:125], v[152:153] op_sel:[0,1] op_sel_hi:[1,1]
	v_add_f32_dpp v190, v190, v190 row_ror:1 row_mask:0xf bank_mask:0xf bound_ctrl:1
	v_pk_mul_f32 v[126:127], v[126:127], v[152:153] op_sel:[0,1] op_sel_hi:[1,1]
	s_waitcnt lgkmcnt(5)
	v_pk_fma_f32 v[196:197], v[152:153], v[196:197], v[112:113] op_sel_hi:[0,1,1]
	s_and_saveexec_b64 s[8:9], s[44:45]
	ds_write_b32 v189, v190 offset:34944
	s_mov_b64 exec, s[8:9]
	v_pk_fma_f32 v[198:199], v[152:153], v[198:199], v[114:115] op_sel_hi:[0,1,1]
	v_pk_fma_f32 v[200:201], v[152:153], v[200:201], v[116:117] op_sel_hi:[0,1,1]
	v_pk_fma_f32 v[202:203], v[152:153], v[202:203], v[118:119] op_sel_hi:[0,1,1]
	v_pk_fma_f32 v[204:205], v[152:153], v[204:205], v[120:121] op_sel_hi:[0,1,1]
	v_pk_fma_f32 v[206:207], v[152:153], v[206:207], v[122:123] op_sel_hi:[0,1,1]
	v_pk_fma_f32 v[208:209], v[152:153], v[208:209], v[124:125] op_sel_hi:[0,1,1]
	v_pk_fma_f32 v[210:211], v[152:153], v[210:211], v[126:127] op_sel_hi:[0,1,1]
	s_waitcnt lgkmcnt(5)
	v_pk_fma_f32 v[128:129], v[96:97], v[196:197], v[192:193]
	v_pk_fma_f32 v[130:131], v[98:99], v[198:199], v[192:193]
	s_waitcnt lgkmcnt(4)
	v_pk_fma_f32 v[128:129], v[100:101], v[200:201], v[128:129]
	v_pk_fma_f32 v[130:131], v[102:103], v[202:203], v[130:131]
	s_waitcnt lgkmcnt(3)
	v_pk_fma_f32 v[128:129], v[104:105], v[204:205], v[128:129]
	v_pk_fma_f32 v[130:131], v[106:107], v[206:207], v[130:131]
	s_waitcnt lgkmcnt(2)
	v_pk_fma_f32 v[128:129], v[108:109], v[208:209], v[128:129]
	v_pk_fma_f32 v[130:131], v[110:111], v[210:211], v[130:131]
	v_add_f32_e32 v128, v128, v129
	v_add_f32_e32 v130, v130, v131
	v_add_f32_e32 v191, v128, v130
	s_nop 1
	v_add_f32_dpp v191, v191, v191 row_ror:8 row_mask:0xf bank_mask:0xf bound_ctrl:1
	s_nop 1
	v_add_f32_dpp v191, v191, v191 row_ror:4 row_mask:0xf bank_mask:0xf bound_ctrl:1
	s_nop 1
	v_add_f32_dpp v191, v191, v191 row_ror:2 row_mask:0xf bank_mask:0xf bound_ctrl:1
	s_nop 1
	v_add_f32_dpp v191, v191, v191 row_ror:1 row_mask:0xf bank_mask:0xf bound_ctrl:1
	s_and_saveexec_b64 s[8:9], s[44:45]
	ds_write_b32 v189, v191 offset:35008
	s_mov_b64 exec, s[8:9]
	s_waitcnt lgkmcnt(0)
	v_mov_b32_e32 v64, v196
	v_mov_b32_e32 v65, v197
	v_mov_b32_e32 v66, v198
	v_mov_b32_e32 v67, v199
	v_mov_b32_e32 v76, v200
	v_mov_b32_e32 v77, v201
	v_mov_b32_e32 v78, v202
	v_mov_b32_e32 v79, v203
	v_mov_b32_e32 v72, v204
	v_mov_b32_e32 v73, v205
	v_mov_b32_e32 v74, v206
	v_mov_b32_e32 v75, v207
	v_mov_b32_e32 v68, v208
	v_mov_b32_e32 v69, v209
	v_mov_b32_e32 v70, v210
	v_mov_b32_e32 v71, v211
	s_branch .LBB0_1438
